# FFN-up epilogue: conv weight/bias vector loads issued before the halo block and barrier; remaining s_setprio flips (GEMM tails, short-K GEMMs) removed
# speedup vs baseline: 1.0003x; 1.0003x over previous
; #define LDA(dst, b, h) for (int m = 0; m < 4; ++m) for (int k = 0; k < 2; ++k) \
;     dst[m][k] = *reinterpret_cast<const bf16x8*>((char*)SA(b, h) + a_thr + (m * 2 + k) * 1024)
; #define LDB(dst, b, h) for (int n = 0; n < 2; ++n) for (int k = 0; k < 2; ++k) \
;     dst[n][k] = *reinterpret_cast<const bf16x8*>((char*)SB(b, h) + b_thr + (n * 2 + k) * 1024)
; #define MMA(ai, bj, At, Btf) do { __builtin_amdgcn_s_setprio(1); \
;     for (int m = 0; m < 4; ++m) for (int n = 0; n < 2; ++n) for (int k = 0; k < 2; ++k) \
;       acc[ai][bj][m][n] = __builtin_amdgcn_mfma_f32_16x16x32_bf16(Btf[n][k], At[m][k], acc[ai][bj][m][n], 0, 0, 0); \
;     __builtin_amdgcn_s_setprio(0); } while (0)
; #define WAIT_V(n) asm volatile("s_waitcnt vmcnt(" #n ")" ::: "memory")
; #define WAIT_L(n) asm volatile("s_waitcnt lgkmcnt(" #n ")" ::: "memory")
; #define BAR __builtin_amdgcn_s_barrier()
; #define SCHED __builtin_amdgcn_sched_barrier(0)
; template <bool OVL, bool PANEL = false, class Epi>
; __device__ __forceinline__ void gemm_phase(const bf16_t* __restrict__ A, long lda, const bf16_t* __restrict__ Bt, long ldb, int nM, int nN, int K,
;                                            const Epi& epi, bf16_t* shm, int w0) {
;     ...
;       LDB(B0, 0, 0); SCHED; LDA(At, 0, 0); STAGE(SA(1, 1), A, lda, aoff, brow + HALF, t + 1);
;       WAIT_L(8); BAR; WAIT_L(0); MMA(0, 0, At, B0); BAR; SCHED;
;       LDB(B1, 0, 1); STAGE(SB(0, 0), Bt, ldb, boff, bcol, t + 2);
;       BAR; WAIT_L(0); MMA(0, 1, At, B1); BAR;
;       LDA(At, 0, 1); STAGE(SA(0, 0), A, lda, aoff, brow, t + 2);
;       BAR; WAIT_L(0); MMA(1, 0, At, B0); BAR; SCHED;
;       STAGE(SB(0, 1), Bt, ldb, boff, bcol + HALF, t + 2);
;       WAIT_V(6); BAR; MMA(1, 1, At, B1); BAR;
.LBB0_125:
	ds_read_b128 v[138:141], v218
	ds_read_b128 v[142:145], v218 offset:1024
	ds_read_b128 v[146:149], v218 offset:2048
	ds_read_b128 v[150:153], v218 offset:3072
	s_add_u32 s8, s4, s6
	s_addc_u32 s9, s5, s7
	ds_read_b128 v[154:157], v213
	ds_read_b128 v[158:161], v213 offset:1024
	ds_read_b128 v[162:165], v213 offset:2048
	ds_read_b128 v[166:169], v213 offset:3072
	ds_read_b128 v[170:173], v213 offset:4096
	ds_read_b128 v[174:177], v213 offset:5120
	ds_read_b128 v[178:181], v213 offset:6144
	ds_read_b128 v[182:185], v213 offset:7168
	s_mov_b32 m0, s25
	s_add_u32 s98, s8, s14
	s_addc_u32 s99, s9, s15
	global_load_lds_dwordx4 v203, s[98:99]
	s_mov_b32 m0, s32
	s_add_u32 s98, s8, s16
	s_addc_u32 s99, s9, s17
	global_load_lds_dwordx4 v203, s[98:99]
	s_waitcnt lgkmcnt(8)
	s_waitcnt vmcnt(10)
	s_barrier
	s_waitcnt lgkmcnt(0)
	s_waitcnt lgkmcnt(0)
	v_mfma_f32_16x16x32_bf16 v[126:129], v[138:141], v[154:157], v[126:129]
	v_mfma_f32_16x16x32_bf16 v[122:125], v[146:149], v[154:157], v[122:125]
	v_mfma_f32_16x16x32_bf16 v[118:121], v[138:141], v[162:165], v[118:121]
	v_mfma_f32_16x16x32_bf16 v[114:117], v[146:149], v[162:165], v[114:117]
	v_mfma_f32_16x16x32_bf16 v[110:113], v[138:141], v[170:173], v[110:113]
	v_mfma_f32_16x16x32_bf16 v[106:109], v[146:149], v[170:173], v[106:109]
	v_mfma_f32_16x16x32_bf16 v[102:105], v[138:141], v[178:181], v[102:105]
	v_mfma_f32_16x16x32_bf16 v[98:101], v[146:149], v[178:181], v[98:101]
	v_mfma_f32_16x16x32_bf16 v[126:129], v[142:145], v[158:161], v[126:129]
	v_mfma_f32_16x16x32_bf16 v[122:125], v[150:153], v[158:161], v[122:125]
	v_mfma_f32_16x16x32_bf16 v[118:121], v[142:145], v[166:169], v[118:121]
	v_mfma_f32_16x16x32_bf16 v[114:117], v[150:153], v[166:169], v[114:117]
	v_mfma_f32_16x16x32_bf16 v[110:113], v[142:145], v[174:177], v[110:113]
	v_mfma_f32_16x16x32_bf16 v[106:109], v[150:153], v[174:177], v[106:109]
	v_mfma_f32_16x16x32_bf16 v[102:105], v[142:145], v[182:185], v[102:105]
	v_mfma_f32_16x16x32_bf16 v[98:101], v[150:153], v[182:185], v[98:101]
	s_barrier
	s_add_u32 vcc_lo, s0, s6
	ds_read_b128 v[186:189], v219
	ds_read_b128 v[190:193], v219 offset:1024
	ds_read_b128 v[194:197], v219 offset:2048
	ds_read_b128 v[198:201], v219 offset:3072
	s_addc_u32 vcc_hi, s1, s7
	s_mov_b32 m0, s44
	s_add_u32 s98, vcc_lo, s34
	s_addc_u32 s99, vcc_hi, s35
	global_load_lds_dwordx4 v203, s[98:99]
	s_mov_b32 m0, s45
	s_add_u32 s98, vcc_lo, s18
	s_addc_u32 s99, vcc_hi, s19
	global_load_lds_dwordx4 v203, s[98:99]
	s_waitcnt vmcnt(10)
	s_barrier
	s_waitcnt lgkmcnt(0)
	s_waitcnt lgkmcnt(0)
	v_mfma_f32_16x16x32_bf16 v[94:97], v[186:189], v[154:157], v[94:97]
	v_mfma_f32_16x16x32_bf16 v[90:93], v[194:197], v[154:157], v[90:93]
	v_mfma_f32_16x16x32_bf16 v[86:89], v[186:189], v[162:165], v[86:89]
	v_mfma_f32_16x16x32_bf16 v[82:85], v[194:197], v[162:165], v[82:85]
	v_mfma_f32_16x16x32_bf16 v[78:81], v[186:189], v[170:173], v[78:81]
	v_mfma_f32_16x16x32_bf16 v[74:77], v[194:197], v[170:173], v[74:77]
	v_mfma_f32_16x16x32_bf16 v[70:73], v[186:189], v[178:181], v[70:73]
	v_mfma_f32_16x16x32_bf16 v[66:69], v[194:197], v[178:181], v[66:69]
	v_mfma_f32_16x16x32_bf16 v[94:97], v[190:193], v[158:161], v[94:97]
	v_mfma_f32_16x16x32_bf16 v[90:93], v[198:201], v[158:161], v[90:93]
	v_mfma_f32_16x16x32_bf16 v[86:89], v[190:193], v[166:169], v[86:89]
	v_mfma_f32_16x16x32_bf16 v[82:85], v[198:201], v[166:169], v[82:85]
	v_mfma_f32_16x16x32_bf16 v[78:81], v[190:193], v[174:177], v[78:81]
	v_mfma_f32_16x16x32_bf16 v[74:77], v[198:201], v[174:177], v[74:77]
	v_mfma_f32_16x16x32_bf16 v[70:73], v[190:193], v[182:185], v[70:73]
	v_mfma_f32_16x16x32_bf16 v[66:69], v[198:201], v[182:185], v[66:69]
	s_barrier
	ds_read_b128 v[154:157], v213 offset:16384
	ds_read_b128 v[158:161], v213 offset:17408
	ds_read_b128 v[162:165], v213 offset:18432
	ds_read_b128 v[166:169], v213 offset:19456
	ds_read_b128 v[170:173], v213 offset:20480
	ds_read_b128 v[174:177], v213 offset:21504
	ds_read_b128 v[178:181], v213 offset:22528
	ds_read_b128 v[182:185], v213 offset:23552
	s_mov_b32 m0, s46
	s_add_u32 s98, s8, s34
	s_addc_u32 s99, s9, s35
	global_load_lds_dwordx4 v203, s[98:99]
	s_mov_b32 m0, s47
	s_add_u32 s98, s8, s18
	s_addc_u32 s99, s9, s19
	global_load_lds_dwordx4 v203, s[98:99]
	s_barrier
	s_waitcnt lgkmcnt(0)
	s_waitcnt lgkmcnt(0)
	v_mfma_f32_16x16x32_bf16 v[62:65], v[138:141], v[154:157], v[62:65]
	v_mfma_f32_16x16x32_bf16 v[58:61], v[146:149], v[154:157], v[58:61]
	v_mfma_f32_16x16x32_bf16 v[54:57], v[138:141], v[162:165], v[54:57]
	v_mfma_f32_16x16x32_bf16 v[50:53], v[146:149], v[162:165], v[50:53]
	v_mfma_f32_16x16x32_bf16 v[46:49], v[138:141], v[170:173], v[46:49]
	v_mfma_f32_16x16x32_bf16 v[42:45], v[146:149], v[170:173], v[42:45]
	v_mfma_f32_16x16x32_bf16 v[38:41], v[138:141], v[178:181], v[38:41]
	v_mfma_f32_16x16x32_bf16 v[34:37], v[146:149], v[178:181], v[34:37]
	v_mfma_f32_16x16x32_bf16 v[62:65], v[142:145], v[158:161], v[62:65]
	v_mfma_f32_16x16x32_bf16 v[58:61], v[150:153], v[158:161], v[58:61]
	v_mfma_f32_16x16x32_bf16 v[54:57], v[142:145], v[166:169], v[54:57]
	v_mfma_f32_16x16x32_bf16 v[50:53], v[150:153], v[166:169], v[50:53]
	v_mfma_f32_16x16x32_bf16 v[46:49], v[142:145], v[174:177], v[46:49]
	v_mfma_f32_16x16x32_bf16 v[42:45], v[150:153], v[174:177], v[42:45]
	v_mfma_f32_16x16x32_bf16 v[38:41], v[142:145], v[182:185], v[38:41]
	v_mfma_f32_16x16x32_bf16 v[34:37], v[150:153], v[182:185], v[34:37]
	s_barrier
	s_mov_b32 m0, s48
	s_add_u32 s98, vcc_lo, s30
	s_addc_u32 s99, vcc_hi, s31
	global_load_lds_dwordx4 v203, s[98:99]
	s_mov_b32 m0, s49
	s_add_u32 s98, vcc_lo, s40
	s_addc_u32 s99, vcc_hi, s41
	global_load_lds_dwordx4 v203, s[98:99]
	s_waitcnt vmcnt(10)
	s_barrier
; #define LDA(dst, b, h) for (int m = 0; m < 4; ++m) for (int k = 0; k < 2; ++k) \
;     dst[m][k] = *reinterpret_cast<const bf16x8*>((char*)SA(b, h) + a_thr + (m * 2 + k) * 1024)
; #define LDB(dst, b, h) for (int n = 0; n < 2; ++n) for (int k = 0; k < 2; ++k) \
;     dst[n][k] = *reinterpret_cast<const bf16x8*>((char*)SB(b, h) + b_thr + (n * 2 + k) * 1024)
; #define MMA(ai, bj, At, Btf) do { __builtin_amdgcn_s_setprio(1); \
;     for (int m = 0; m < 4; ++m) for (int n = 0; n < 2; ++n) for (int k = 0; k < 2; ++k) \
;       acc[ai][bj][m][n] = __builtin_amdgcn_mfma_f32_16x16x32_bf16(Btf[n][k], At[m][k], acc[ai][bj][m][n], 0, 0, 0); \
;     __builtin_amdgcn_s_setprio(0); } while (0)
; #define WAIT_V(n) asm volatile("s_waitcnt vmcnt(" #n ")" ::: "memory")
; #define WAIT_L(n) asm volatile("s_waitcnt lgkmcnt(" #n ")" ::: "memory")
; #define BAR __builtin_amdgcn_s_barrier()
; #define SCHED __builtin_amdgcn_sched_barrier(0)
; template <bool OVL, bool PANEL = false, class Epi>
; __device__ __forceinline__ void gemm_phase(const bf16_t* __restrict__ A, long lda, const bf16_t* __restrict__ Bt, long ldb, int nM, int nN, int K,
;                                            const Epi& epi, bf16_t* shm, int w0) {
;     ...
;       WAIT_V(6); BAR; MMA(1, 1, At, B1); BAR;
;       LDB(B0, 1, 0); SCHED; LDA(At, 1, 0); STAGE(SA(0, 1), A, lda, aoff, brow + HALF, t + 2);
;       WAIT_L(8); BAR; WAIT_L(0); MMA(0, 0, At, B0); BAR; SCHED;
;       LDB(B1, 1, 1); STAGE(SB(1, 0), Bt, ldb, boff, bcol, t + 3);
;       BAR; WAIT_L(0); MMA(0, 1, At, B1); BAR;
	v_mfma_f32_16x16x32_bf16 v[30:33], v[186:189], v[154:157], v[30:33]
	v_mfma_f32_16x16x32_bf16 v[26:29], v[194:197], v[154:157], v[26:29]
	v_mfma_f32_16x16x32_bf16 v[22:25], v[186:189], v[162:165], v[22:25]
	v_mfma_f32_16x16x32_bf16 v[18:21], v[194:197], v[162:165], v[18:21]
	v_mfma_f32_16x16x32_bf16 v[14:17], v[186:189], v[170:173], v[14:17]
	v_mfma_f32_16x16x32_bf16 v[10:13], v[194:197], v[170:173], v[10:13]
	v_mfma_f32_16x16x32_bf16 v[6:9], v[186:189], v[178:181], v[6:9]
	v_mfma_f32_16x16x32_bf16 v[2:5], v[194:197], v[178:181], v[2:5]
	v_mfma_f32_16x16x32_bf16 v[30:33], v[190:193], v[158:161], v[30:33]
	v_mfma_f32_16x16x32_bf16 v[26:29], v[198:201], v[158:161], v[26:29]
	v_mfma_f32_16x16x32_bf16 v[22:25], v[190:193], v[166:169], v[22:25]
	v_mfma_f32_16x16x32_bf16 v[18:21], v[198:201], v[166:169], v[18:21]
	v_mfma_f32_16x16x32_bf16 v[14:17], v[190:193], v[174:177], v[14:17]
	v_mfma_f32_16x16x32_bf16 v[10:13], v[198:201], v[174:177], v[10:13]
	v_mfma_f32_16x16x32_bf16 v[6:9], v[190:193], v[182:185], v[6:9]
	v_mfma_f32_16x16x32_bf16 v[2:5], v[198:201], v[182:185], v[2:5]
	s_barrier
	ds_read_b128 v[138:141], v220
	ds_read_b128 v[142:145], v220 offset:1024
	ds_read_b128 v[146:149], v220 offset:2048
	ds_read_b128 v[150:153], v220 offset:3072
	ds_read_b128 v[154:157], v213 offset:32768
	ds_read_b128 v[158:161], v213 offset:33792
	ds_read_b128 v[162:165], v213 offset:34816
	ds_read_b128 v[166:169], v213 offset:35840
	ds_read_b128 v[170:173], v213 offset:36864
	ds_read_b128 v[174:177], v213 offset:37888
	ds_read_b128 v[178:181], v213 offset:38912
	ds_read_b128 v[182:185], v213 offset:39936
	s_mov_b32 m0, s50
	s_add_u32 s98, s8, s30
	s_addc_u32 s99, s9, s31
	global_load_lds_dwordx4 v203, s[98:99]
	s_mov_b32 m0, s51
	s_add_u32 s98, s8, s40
	s_addc_u32 s99, s9, s41
	global_load_lds_dwordx4 v203, s[98:99]
	s_waitcnt lgkmcnt(8)
	s_waitcnt vmcnt(10)
	s_barrier
	s_waitcnt lgkmcnt(0)
	s_waitcnt lgkmcnt(0)
	v_mfma_f32_16x16x32_bf16 v[126:129], v[138:141], v[154:157], v[126:129]
	v_mfma_f32_16x16x32_bf16 v[122:125], v[146:149], v[154:157], v[122:125]
	v_mfma_f32_16x16x32_bf16 v[118:121], v[138:141], v[162:165], v[118:121]
	v_mfma_f32_16x16x32_bf16 v[114:117], v[146:149], v[162:165], v[114:117]
	v_mfma_f32_16x16x32_bf16 v[110:113], v[138:141], v[170:173], v[110:113]
	v_mfma_f32_16x16x32_bf16 v[106:109], v[146:149], v[170:173], v[106:109]
	v_mfma_f32_16x16x32_bf16 v[102:105], v[138:141], v[178:181], v[102:105]
	v_mfma_f32_16x16x32_bf16 v[98:101], v[146:149], v[178:181], v[98:101]
	v_mfma_f32_16x16x32_bf16 v[126:129], v[142:145], v[158:161], v[126:129]
	v_mfma_f32_16x16x32_bf16 v[122:125], v[150:153], v[158:161], v[122:125]
	v_mfma_f32_16x16x32_bf16 v[118:121], v[142:145], v[166:169], v[118:121]
	v_mfma_f32_16x16x32_bf16 v[114:117], v[150:153], v[166:169], v[114:117]
	v_mfma_f32_16x16x32_bf16 v[110:113], v[142:145], v[174:177], v[110:113]
	v_mfma_f32_16x16x32_bf16 v[106:109], v[150:153], v[174:177], v[106:109]
	v_mfma_f32_16x16x32_bf16 v[102:105], v[142:145], v[182:185], v[102:105]
	v_mfma_f32_16x16x32_bf16 v[98:101], v[150:153], v[182:185], v[98:101]
	s_barrier
	ds_read_b128 v[186:189], v221
	ds_read_b128 v[190:193], v221 offset:1024
	ds_read_b128 v[194:197], v221 offset:2048
	ds_read_b128 v[198:201], v221 offset:3072
	s_mov_b32 m0, s52
	s_add_u32 s98, vcc_lo, s94
	s_addc_u32 s99, vcc_hi, s95
	global_load_lds_dwordx4 v203, s[98:99]
	s_mov_b32 m0, s53
	s_add_u32 s98, vcc_lo, s42
	s_addc_u32 s99, vcc_hi, s43
	global_load_lds_dwordx4 v203, s[98:99]
	s_waitcnt vmcnt(10)
	s_barrier
	s_waitcnt lgkmcnt(0)
	s_waitcnt lgkmcnt(0)
	v_mfma_f32_16x16x32_bf16 v[94:97], v[186:189], v[154:157], v[94:97]
	v_mfma_f32_16x16x32_bf16 v[90:93], v[194:197], v[154:157], v[90:93]
	v_mfma_f32_16x16x32_bf16 v[86:89], v[186:189], v[162:165], v[86:89]
	v_mfma_f32_16x16x32_bf16 v[82:85], v[194:197], v[162:165], v[82:85]
	v_mfma_f32_16x16x32_bf16 v[78:81], v[186:189], v[170:173], v[78:81]
	v_mfma_f32_16x16x32_bf16 v[74:77], v[194:197], v[170:173], v[74:77]
	v_mfma_f32_16x16x32_bf16 v[70:73], v[186:189], v[178:181], v[70:73]
	v_mfma_f32_16x16x32_bf16 v[66:69], v[194:197], v[178:181], v[66:69]
	v_mfma_f32_16x16x32_bf16 v[94:97], v[190:193], v[158:161], v[94:97]
	v_mfma_f32_16x16x32_bf16 v[90:93], v[198:201], v[158:161], v[90:93]
	v_mfma_f32_16x16x32_bf16 v[86:89], v[190:193], v[166:169], v[86:89]
	v_mfma_f32_16x16x32_bf16 v[82:85], v[198:201], v[166:169], v[82:85]
	v_mfma_f32_16x16x32_bf16 v[78:81], v[190:193], v[174:177], v[78:81]
	v_mfma_f32_16x16x32_bf16 v[74:77], v[198:201], v[174:177], v[74:77]
	v_mfma_f32_16x16x32_bf16 v[70:73], v[190:193], v[182:185], v[70:73]
	v_mfma_f32_16x16x32_bf16 v[66:69], v[198:201], v[182:185], v[66:69]
	s_barrier
; #define LDA(dst, b, h) for (int m = 0; m < 4; ++m) for (int k = 0; k < 2; ++k) \
;     dst[m][k] = *reinterpret_cast<const bf16x8*>((char*)SA(b, h) + a_thr + (m * 2 + k) * 1024)
; #define LDB(dst, b, h) for (int n = 0; n < 2; ++n) for (int k = 0; k < 2; ++k) \
;     dst[n][k] = *reinterpret_cast<const bf16x8*>((char*)SB(b, h) + b_thr + (n * 2 + k) * 1024)
; #define MMA(ai, bj, At, Btf) do { __builtin_amdgcn_s_setprio(1); \
;     for (int m = 0; m < 4; ++m) for (int n = 0; n < 2; ++n) for (int k = 0; k < 2; ++k) \
;       acc[ai][bj][m][n] = __builtin_amdgcn_mfma_f32_16x16x32_bf16(Btf[n][k], At[m][k], acc[ai][bj][m][n], 0, 0, 0); \
;     __builtin_amdgcn_s_setprio(0); } while (0)
; #define WAIT_V(n) asm volatile("s_waitcnt vmcnt(" #n ")" ::: "memory")
; #define WAIT_L(n) asm volatile("s_waitcnt lgkmcnt(" #n ")" ::: "memory")
; #define BAR __builtin_amdgcn_s_barrier()
; #define SCHED __builtin_amdgcn_sched_barrier(0)
; template <bool OVL, bool PANEL = false, class Epi>
; __device__ __forceinline__ void gemm_phase(const bf16_t* __restrict__ A, long lda, const bf16_t* __restrict__ Bt, long ldb, int nM, int nN, int K,
;                                            const Epi& epi, bf16_t* shm, int w0) {
;     ...
;       LDA(At, 1, 1); STAGE(SA(1, 0), A, lda, aoff, brow, t + 3);
;       BAR; WAIT_L(0); MMA(1, 0, At, B0); BAR; SCHED;
;       STAGE(SB(1, 1), Bt, ldb, boff, bcol + HALF, t + 3);
;       WAIT_V(6); BAR; MMA(1, 1, At, B1); BAR;
;     }
;     { LDB(B0, 0, 0); LDA(At, 0, 0); STAGE(SA(1, 1), A, lda, aoff, brow + HALF, nt - 1);
	ds_read_b128 v[154:157], v213 offset:49152
	ds_read_b128 v[158:161], v213 offset:50176
	ds_read_b128 v[162:165], v213 offset:51200
	ds_read_b128 v[166:169], v213 offset:52224
	ds_read_b128 v[170:173], v213 offset:53248
	ds_read_b128 v[174:177], v213 offset:54272
	ds_read_b128 v[178:181], v213 offset:55296
	ds_read_b128 v[182:185], v213 offset:56320
	s_mov_b32 m0, s54
	s_add_u32 s98, s8, s94
	s_addc_u32 s99, s9, s95
	global_load_lds_dwordx4 v203, s[98:99]
	s_mov_b32 m0, s55
	s_add_u32 s98, s8, s42
	s_addc_u32 s99, s9, s43
	global_load_lds_dwordx4 v203, s[98:99]
	s_barrier
	s_waitcnt lgkmcnt(0)
	s_waitcnt lgkmcnt(0)
	v_mfma_f32_16x16x32_bf16 v[62:65], v[138:141], v[154:157], v[62:65]
	v_mfma_f32_16x16x32_bf16 v[58:61], v[146:149], v[154:157], v[58:61]
	v_mfma_f32_16x16x32_bf16 v[54:57], v[138:141], v[162:165], v[54:57]
	v_mfma_f32_16x16x32_bf16 v[50:53], v[146:149], v[162:165], v[50:53]
	v_mfma_f32_16x16x32_bf16 v[46:49], v[138:141], v[170:173], v[46:49]
	v_mfma_f32_16x16x32_bf16 v[42:45], v[146:149], v[170:173], v[42:45]
	v_mfma_f32_16x16x32_bf16 v[38:41], v[138:141], v[178:181], v[38:41]
	v_mfma_f32_16x16x32_bf16 v[34:37], v[146:149], v[178:181], v[34:37]
	v_mfma_f32_16x16x32_bf16 v[62:65], v[142:145], v[158:161], v[62:65]
	v_mfma_f32_16x16x32_bf16 v[58:61], v[150:153], v[158:161], v[58:61]
	v_mfma_f32_16x16x32_bf16 v[54:57], v[142:145], v[166:169], v[54:57]
	v_mfma_f32_16x16x32_bf16 v[50:53], v[150:153], v[166:169], v[50:53]
	v_mfma_f32_16x16x32_bf16 v[46:49], v[142:145], v[174:177], v[46:49]
	v_mfma_f32_16x16x32_bf16 v[42:45], v[150:153], v[174:177], v[42:45]
	v_mfma_f32_16x16x32_bf16 v[38:41], v[142:145], v[182:185], v[38:41]
	v_mfma_f32_16x16x32_bf16 v[34:37], v[150:153], v[182:185], v[34:37]
	s_barrier
	s_mov_b64 s[8:9], 0xb0180
	s_mov_b64 s[8:9], 0x108180
	s_mov_b32 m0, s60
	s_add_u32 s98, vcc_lo, 0xb0180
	s_addc_u32 s99, vcc_hi, 0
	global_load_lds_dwordx4 v203, s[98:99]
	s_mov_b32 m0, s61
	s_add_u32 s98, vcc_lo, 0x108180
	s_addc_u32 s99, vcc_hi, 0
	global_load_lds_dwordx4 v203, s[98:99]
	s_waitcnt vmcnt(10)
	s_barrier
	v_mfma_f32_16x16x32_bf16 v[30:33], v[186:189], v[154:157], v[30:33]
	v_mfma_f32_16x16x32_bf16 v[26:29], v[194:197], v[154:157], v[26:29]
	v_mfma_f32_16x16x32_bf16 v[22:25], v[186:189], v[162:165], v[22:25]
	v_mfma_f32_16x16x32_bf16 v[18:21], v[194:197], v[162:165], v[18:21]
	v_mfma_f32_16x16x32_bf16 v[14:17], v[186:189], v[170:173], v[14:17]
	v_mfma_f32_16x16x32_bf16 v[10:13], v[194:197], v[170:173], v[10:13]
	v_mfma_f32_16x16x32_bf16 v[6:9], v[186:189], v[178:181], v[6:9]
	v_mfma_f32_16x16x32_bf16 v[2:5], v[194:197], v[178:181], v[2:5]
	v_mfma_f32_16x16x32_bf16 v[30:33], v[190:193], v[158:161], v[30:33]
	v_mfma_f32_16x16x32_bf16 v[26:29], v[198:201], v[158:161], v[26:29]
	v_mfma_f32_16x16x32_bf16 v[22:25], v[190:193], v[166:169], v[22:25]
	v_mfma_f32_16x16x32_bf16 v[18:21], v[198:201], v[166:169], v[18:21]
	v_mfma_f32_16x16x32_bf16 v[14:17], v[190:193], v[174:177], v[14:17]
	v_mfma_f32_16x16x32_bf16 v[10:13], v[198:201], v[174:177], v[10:13]
	v_mfma_f32_16x16x32_bf16 v[6:9], v[190:193], v[182:185], v[6:9]
	v_mfma_f32_16x16x32_bf16 v[2:5], v[198:201], v[182:185], v[2:5]
	s_add_i32 s2, s2, 2
	s_add_u32 s6, s6, 0x100
	s_addc_u32 s7, s7, 0
	s_cmp_gt_u32 s2, 39
	s_barrier
	s_cbranch_scc0 .LBB0_125
	s_waitcnt vmcnt(6)
	s_or_b32 s0, s28, 0x80
	s_mul_hi_i32 s1, s0, 0x1600
	s_mulk_i32 s0, 0x1600
	v_readlane_b32 s2, v250, 49
	v_add_u32_e32 v227, 16, v212
	s_add_u32 s0, s2, s0
	v_readlane_b32 s2, v250, 50
	v_add_u32_e32 v0, 0x10000, v227
	s_addc_u32 s1, s2, s1
	v_readfirstlane_b32 s2, v136
	ds_read_b128 v[130:133], v0
	ds_read_b128 v[138:141], v0 offset:1024
	ds_read_b128 v[142:145], v0 offset:2048
	ds_read_b128 v[146:149], v0 offset:3072
	ds_read_b128 v[150:153], v213
	ds_read_b128 v[154:157], v213 offset:1024
	ds_read_b128 v[158:161], v213 offset:2048
	ds_read_b128 v[162:165], v213 offset:3072
	ds_read_b128 v[166:169], v213 offset:4096
	ds_read_b128 v[170:173], v213 offset:5120
	ds_read_b128 v[174:177], v213 offset:6144
	ds_read_b128 v[178:181], v213 offset:7168
	v_mov_b32_e32 v0, v203
	s_mov_b32 m0, s2
	s_nop 0
	v_lshl_add_u64 v[134:135], s[0:1], 0, v[0:1]
	global_load_lds_dwordx4 v0, s[0:1]
	v_readfirstlane_b32 s0, v137
	v_lshl_add_u64 v[134:135], v[134:135], 0, s[26:27]
	s_mov_b32 m0, s0
	s_nop 0
	global_load_lds_dwordx4 v[134:135], off
	s_barrier
	s_waitcnt lgkmcnt(0)

; #define LDA(dst, b, h) for (int m = 0; m < 4; ++m) for (int k = 0; k < 2; ++k) \
;     dst[m][k] = *reinterpret_cast<const bf16x8*>((char*)SA(b, h) + a_thr + (m * 2 + k) * 1024)
; #define LDB(dst, b, h) for (int n = 0; n < 2; ++n) for (int k = 0; k < 2; ++k) \
;     dst[n][k] = *reinterpret_cast<const bf16x8*>((char*)SB(b, h) + b_thr + (n * 2 + k) * 1024)
; #define MMA(ai, bj, At, Btf) do { __builtin_amdgcn_s_setprio(1); \
;     for (int m = 0; m < 4; ++m) for (int n = 0; n < 2; ++n) for (int k = 0; k < 2; ++k) \
;       acc[ai][bj][m][n] = __builtin_amdgcn_mfma_f32_16x16x32_bf16(Btf[n][k], At[m][k], acc[ai][bj][m][n], 0, 0, 0); \
;     __builtin_amdgcn_s_setprio(0); } while (0)
; #define WAIT_L(n) asm volatile("s_waitcnt lgkmcnt(" #n ")" ::: "memory")
; #define BAR __builtin_amdgcn_s_barrier()
; template <bool OVL, bool PANEL = false, class Epi>
; __device__ __forceinline__ void gemm_phase(const bf16_t* __restrict__ A, long lda, const bf16_t* __restrict__ Bt, long ldb, int nM, int nN, int K,
;                                            const Epi& epi, bf16_t* shm, int w0) {
;     ...
;     { LDB(B0, 0, 0); LDA(At, 0, 0); STAGE(SA(1, 1), A, lda, aoff, brow + HALF, nt - 1);
;       BAR; WAIT_L(0); MMA(0, 0, At, B0); BAR;
	s_waitcnt lgkmcnt(0)
	v_mfma_f32_16x16x32_bf16 v[126:129], v[130:133], v[150:153], v[126:129]
	v_mfma_f32_16x16x32_bf16 v[122:125], v[142:145], v[150:153], v[122:125]
	v_mfma_f32_16x16x32_bf16 v[118:121], v[130:133], v[158:161], v[118:121]
	v_mfma_f32_16x16x32_bf16 v[114:117], v[142:145], v[158:161], v[114:117]
	v_mfma_f32_16x16x32_bf16 v[110:113], v[130:133], v[166:169], v[110:113]
	v_mfma_f32_16x16x32_bf16 v[106:109], v[142:145], v[166:169], v[106:109]
	v_mfma_f32_16x16x32_bf16 v[102:105], v[130:133], v[174:177], v[102:105]
	v_mfma_f32_16x16x32_bf16 v[98:101], v[142:145], v[174:177], v[98:101]
	v_mfma_f32_16x16x32_bf16 v[126:129], v[138:141], v[154:157], v[126:129]
	v_mfma_f32_16x16x32_bf16 v[122:125], v[146:149], v[154:157], v[122:125]
	v_mfma_f32_16x16x32_bf16 v[118:121], v[138:141], v[162:165], v[118:121]
	v_mfma_f32_16x16x32_bf16 v[114:117], v[146:149], v[162:165], v[114:117]
	v_mfma_f32_16x16x32_bf16 v[110:113], v[138:141], v[170:173], v[110:113]
	v_mfma_f32_16x16x32_bf16 v[106:109], v[146:149], v[170:173], v[106:109]
	v_mfma_f32_16x16x32_bf16 v[102:105], v[138:141], v[178:181], v[102:105]
	v_mfma_f32_16x16x32_bf16 v[98:101], v[146:149], v[178:181], v[98:101]

; #define LDB(dst, b, h) for (int n = 0; n < 2; ++n) for (int k = 0; k < 2; ++k) \
;     dst[n][k] = *reinterpret_cast<const bf16x8*>((char*)SB(b, h) + b_thr + (n * 2 + k) * 1024)
; #define MMA(ai, bj, At, Btf) do { __builtin_amdgcn_s_setprio(1); \
;     for (int m = 0; m < 4; ++m) for (int n = 0; n < 2; ++n) for (int k = 0; k < 2; ++k) \
;       acc[ai][bj][m][n] = __builtin_amdgcn_mfma_f32_16x16x32_bf16(Btf[n][k], At[m][k], acc[ai][bj][m][n], 0, 0, 0); \
;     __builtin_amdgcn_s_setprio(0); } while (0)
; #define WAIT_L(n) asm volatile("s_waitcnt lgkmcnt(" #n ")" ::: "memory")
; #define BAR __builtin_amdgcn_s_barrier()
; template <bool OVL, bool PANEL = false, class Epi>
; __device__ __forceinline__ void gemm_phase(const bf16_t* __restrict__ A, long lda, const bf16_t* __restrict__ Bt, long ldb, int nM, int nN, int K,
;                                            const Epi& epi, bf16_t* shm, int w0) {
;     ...
;       LDB(B1, 0, 1); BAR; WAIT_L(0); MMA(0, 1, At, B1); BAR;
	v_add_u32_e32 v0, 0x14000, v227
	s_barrier
	ds_read_b128 v[134:137], v0
	ds_read_b128 v[182:185], v0 offset:1024
	ds_read_b128 v[186:189], v0 offset:2048
	ds_read_b128 v[190:193], v0 offset:3072
	s_barrier
	s_waitcnt lgkmcnt(0)

; #define LDB(dst, b, h) for (int n = 0; n < 2; ++n) for (int k = 0; k < 2; ++k) \
;     dst[n][k] = *reinterpret_cast<const bf16x8*>((char*)SB(b, h) + b_thr + (n * 2 + k) * 1024)
; #define MMA(ai, bj, At, Btf) do { __builtin_amdgcn_s_setprio(1); \
;     for (int m = 0; m < 4; ++m) for (int n = 0; n < 2; ++n) for (int k = 0; k < 2; ++k) \
;       acc[ai][bj][m][n] = __builtin_amdgcn_mfma_f32_16x16x32_bf16(Btf[n][k], At[m][k], acc[ai][bj][m][n], 0, 0, 0); \
;     __builtin_amdgcn_s_setprio(0); } while (0)
; #define WAIT_L(n) asm volatile("s_waitcnt lgkmcnt(" #n ")" ::: "memory")
; #define BAR __builtin_amdgcn_s_barrier()
; template <bool OVL, bool PANEL = false, class Epi>
; __device__ __forceinline__ void gemm_phase(const bf16_t* __restrict__ A, long lda, const bf16_t* __restrict__ Bt, long ldb, int nM, int nN, int K,
;                                            const Epi& epi, bf16_t* shm, int w0) {
;     ...
;       LDB(B1, 0, 1); BAR; WAIT_L(0); MMA(0, 1, At, B1); BAR;
	s_waitcnt lgkmcnt(0)
	v_mfma_f32_16x16x32_bf16 v[94:97], v[134:137], v[150:153], v[94:97]
	v_mfma_f32_16x16x32_bf16 v[90:93], v[186:189], v[150:153], v[90:93]
	v_mfma_f32_16x16x32_bf16 v[86:89], v[134:137], v[158:161], v[86:89]
	v_mfma_f32_16x16x32_bf16 v[82:85], v[186:189], v[158:161], v[82:85]
	v_mfma_f32_16x16x32_bf16 v[78:81], v[134:137], v[166:169], v[78:81]
	v_mfma_f32_16x16x32_bf16 v[66:69], v[186:189], v[174:177], v[66:69]
	v_mfma_f32_16x16x32_bf16 v[94:97], v[182:185], v[154:157], v[94:97]
	v_mfma_f32_16x16x32_bf16 v[90:93], v[190:193], v[154:157], v[90:93]
	v_mfma_f32_16x16x32_bf16 v[86:89], v[182:185], v[162:165], v[86:89]
	v_mfma_f32_16x16x32_bf16 v[82:85], v[190:193], v[162:165], v[82:85]
	v_mfma_f32_16x16x32_bf16 v[78:81], v[182:185], v[170:173], v[78:81]
	v_mfma_f32_16x16x32_bf16 v[74:77], v[186:189], v[166:169], v[74:77]
	v_mfma_f32_16x16x32_bf16 v[70:73], v[134:137], v[174:177], v[70:73]
	v_mfma_f32_16x16x32_bf16 v[66:69], v[190:193], v[178:181], v[66:69]
	v_mfma_f32_16x16x32_bf16 v[150:153], v[190:193], v[170:173], v[74:77]
	v_mfma_f32_16x16x32_bf16 v[154:157], v[182:185], v[178:181], v[70:73]

; #define LDA(dst, b, h) for (int m = 0; m < 4; ++m) for (int k = 0; k < 2; ++k) \
;     dst[m][k] = *reinterpret_cast<const bf16x8*>((char*)SA(b, h) + a_thr + (m * 2 + k) * 1024)
; #define MMA(ai, bj, At, Btf) do { __builtin_amdgcn_s_setprio(1); \
;     for (int m = 0; m < 4; ++m) for (int n = 0; n < 2; ++n) for (int k = 0; k < 2; ++k) \
;       acc[ai][bj][m][n] = __builtin_amdgcn_mfma_f32_16x16x32_bf16(Btf[n][k], At[m][k], acc[ai][bj][m][n], 0, 0, 0); \
;     __builtin_amdgcn_s_setprio(0); } while (0)
; #define WAIT_V(n) asm volatile("s_waitcnt vmcnt(" #n ")" ::: "memory")
; #define WAIT_L(n) asm volatile("s_waitcnt lgkmcnt(" #n ")" ::: "memory")
; #define BAR __builtin_amdgcn_s_barrier()
; template <bool OVL, bool PANEL = false, class Epi>
; __device__ __forceinline__ void gemm_phase(const bf16_t* __restrict__ A, long lda, const bf16_t* __restrict__ Bt, long ldb, int nM, int nN, int K,
;                                            const Epi& epi, bf16_t* shm, int w0) {
;     ...
;       LDA(At, 0, 1); WAIT_V(4); BAR; WAIT_L(0); MMA(1, 0, At, B0); MMA(1, 1, At, B1); BAR; }
	s_barrier
	s_nop 2
	ds_read_b128 v[70:73], v213 offset:16384
	ds_read_b128 v[74:77], v213 offset:17408
	ds_read_b128 v[158:161], v213 offset:18432
	ds_read_b128 v[162:165], v213 offset:19456
	ds_read_b128 v[166:169], v213 offset:20480
	ds_read_b128 v[170:173], v213 offset:21504
	ds_read_b128 v[174:177], v213 offset:22528
	ds_read_b128 v[178:181], v213 offset:23552
	s_waitcnt vmcnt(4)
	s_barrier
	s_waitcnt lgkmcnt(0)

; #define LDA(dst, b, h) for (int m = 0; m < 4; ++m) for (int k = 0; k < 2; ++k) \
;     dst[m][k] = *reinterpret_cast<const bf16x8*>((char*)SA(b, h) + a_thr + (m * 2 + k) * 1024)
; #define MMA(ai, bj, At, Btf) do { __builtin_amdgcn_s_setprio(1); \
;     for (int m = 0; m < 4; ++m) for (int n = 0; n < 2; ++n) for (int k = 0; k < 2; ++k) \
;       acc[ai][bj][m][n] = __builtin_amdgcn_mfma_f32_16x16x32_bf16(Btf[n][k], At[m][k], acc[ai][bj][m][n], 0, 0, 0); \
;     __builtin_amdgcn_s_setprio(0); } while (0)
; #define WAIT_V(n) asm volatile("s_waitcnt vmcnt(" #n ")" ::: "memory")
; #define WAIT_L(n) asm volatile("s_waitcnt lgkmcnt(" #n ")" ::: "memory")
; #define BAR __builtin_amdgcn_s_barrier()
; template <bool OVL, bool PANEL = false, class Epi>
; __device__ __forceinline__ void gemm_phase(const bf16_t* __restrict__ A, long lda, const bf16_t* __restrict__ Bt, long ldb, int nM, int nN, int K,
;                                            const Epi& epi, bf16_t* shm, int w0) {
;     ...
;       LDA(At, 0, 1); WAIT_V(4); BAR; WAIT_L(0); MMA(1, 0, At, B0); MMA(1, 1, At, B1); BAR; }
	s_waitcnt lgkmcnt(0)
	v_mfma_f32_16x16x32_bf16 v[58:61], v[142:145], v[70:73], v[58:61]
	v_mfma_f32_16x16x32_bf16 v[54:57], v[130:133], v[158:161], v[54:57]
	v_mfma_f32_16x16x32_bf16 v[62:65], v[130:133], v[70:73], v[62:65]
	v_mfma_f32_16x16x32_bf16 v[58:61], v[146:149], v[74:77], v[58:61]
	v_mfma_f32_16x16x32_bf16 v[54:57], v[138:141], v[162:165], v[54:57]
	v_mfma_f32_16x16x32_bf16 v[50:53], v[142:145], v[158:161], v[50:53]
	v_mfma_f32_16x16x32_bf16 v[46:49], v[130:133], v[166:169], v[46:49]
	v_mfma_f32_16x16x32_bf16 v[42:45], v[142:145], v[166:169], v[42:45]
	v_mfma_f32_16x16x32_bf16 v[38:41], v[130:133], v[174:177], v[38:41]
	v_mfma_f32_16x16x32_bf16 v[34:37], v[142:145], v[174:177], v[34:37]
	v_mfma_f32_16x16x32_bf16 v[194:197], v[138:141], v[74:77], v[62:65]
	v_mfma_f32_16x16x32_bf16 v[198:201], v[146:149], v[162:165], v[50:53]
	v_mfma_f32_16x16x32_bf16 v[214:217], v[138:141], v[170:173], v[46:49]
	v_mfma_f32_16x16x32_bf16 v[218:221], v[146:149], v[170:173], v[42:45]
	v_mfma_f32_16x16x32_bf16 v[130:133], v[138:141], v[178:181], v[38:41]
	v_mfma_f32_16x16x32_bf16 v[138:141], v[146:149], v[178:181], v[34:37]


; #define LDA(dst, b, h) for (int m = 0; m < 4; ++m) for (int k = 0; k < 2; ++k) \
;     dst[m][k] = *reinterpret_cast<const bf16x8*>((char*)SA(b, h) + a_thr + (m * 2 + k) * 1024)
; #define MMA(ai, bj, At, Btf) do { __builtin_amdgcn_s_setprio(1); \
;     for (int m = 0; m < 4; ++m) for (int n = 0; n < 2; ++n) for (int k = 0; k < 2; ++k) \
;       acc[ai][bj][m][n] = __builtin_amdgcn_mfma_f32_16x16x32_bf16(Btf[n][k], At[m][k], acc[ai][bj][m][n], 0, 0, 0); \
;     __builtin_amdgcn_s_setprio(0); } while (0)
; #define WAIT_V(n) asm volatile("s_waitcnt vmcnt(" #n ")" ::: "memory")
; #define WAIT_L(n) asm volatile("s_waitcnt lgkmcnt(" #n ")" ::: "memory")
; #define BAR __builtin_amdgcn_s_barrier()
; template <bool OVL, bool PANEL = false, class Epi>
; __device__ __forceinline__ void gemm_phase(const bf16_t* __restrict__ A, long lda, const bf16_t* __restrict__ Bt, long ldb, int nM, int nN, int K,
;                                            const Epi& epi, bf16_t* shm, int w0) {
;     ...
;       LDA(At, 0, 1); WAIT_V(4); BAR; WAIT_L(0); MMA(1, 0, At, B0); MMA(1, 1, At, B1); BAR; }
	v_mfma_f32_16x16x32_bf16 v[30:33], v[134:137], v[70:73], v[30:33]
	v_mfma_f32_16x16x32_bf16 v[26:29], v[186:189], v[70:73], v[26:29]
	v_mfma_f32_16x16x32_bf16 v[22:25], v[134:137], v[158:161], v[22:25]
	v_mfma_f32_16x16x32_bf16 v[18:21], v[186:189], v[158:161], v[18:21]
	v_mfma_f32_16x16x32_bf16 v[14:17], v[134:137], v[166:169], v[14:17]
	v_mfma_f32_16x16x32_bf16 v[10:13], v[186:189], v[166:169], v[10:13]
	v_mfma_f32_16x16x32_bf16 v[6:9], v[134:137], v[174:177], v[6:9]
	v_mfma_f32_16x16x32_bf16 v[2:5], v[186:189], v[174:177], v[2:5]
	v_mfma_f32_16x16x32_bf16 v[142:145], v[182:185], v[74:77], v[30:33]
	v_mfma_f32_16x16x32_bf16 v[146:149], v[190:193], v[74:77], v[26:29]
	v_mfma_f32_16x16x32_bf16 v[222:225], v[182:185], v[162:165], v[22:25]
	v_mfma_f32_16x16x32_bf16 v[158:161], v[190:193], v[162:165], v[18:21]
	v_mfma_f32_16x16x32_bf16 v[162:165], v[182:185], v[170:173], v[14:17]
	v_mfma_f32_16x16x32_bf16 v[166:169], v[190:193], v[170:173], v[10:13]
	v_mfma_f32_16x16x32_bf16 v[134:137], v[182:185], v[178:181], v[6:9]
	v_mfma_f32_16x16x32_bf16 v[170:173], v[190:193], v[178:181], v[2:5]

; #define LDA(dst, b, h) for (int m = 0; m < 4; ++m) for (int k = 0; k < 2; ++k) \
;     dst[m][k] = *reinterpret_cast<const bf16x8*>((char*)SA(b, h) + a_thr + (m * 2 + k) * 1024)
; #define LDB(dst, b, h) for (int n = 0; n < 2; ++n) for (int k = 0; k < 2; ++k) \
;     dst[n][k] = *reinterpret_cast<const bf16x8*>((char*)SB(b, h) + b_thr + (n * 2 + k) * 1024)
; #define MMA(ai, bj, At, Btf) do { __builtin_amdgcn_s_setprio(1); \
;     for (int m = 0; m < 4; ++m) for (int n = 0; n < 2; ++n) for (int k = 0; k < 2; ++k) \
;       acc[ai][bj][m][n] = __builtin_amdgcn_mfma_f32_16x16x32_bf16(Btf[n][k], At[m][k], acc[ai][bj][m][n], 0, 0, 0); \
;     __builtin_amdgcn_s_setprio(0); } while (0)
; #define WAIT_V(n) asm volatile("s_waitcnt vmcnt(" #n ")" ::: "memory")
; #define WAIT_L(n) asm volatile("s_waitcnt lgkmcnt(" #n ")" ::: "memory")
; #define BAR __builtin_amdgcn_s_barrier()
; template <bool OVL, bool PANEL = false, class Epi>
; __device__ __forceinline__ void gemm_phase(const bf16_t* __restrict__ A, long lda, const bf16_t* __restrict__ Bt, long ldb, int nM, int nN, int K,
;                                            const Epi& epi, bf16_t* shm, int w0) {
;     ...
;     { LDB(B0, 1, 0); LDA(At, 1, 0); WAIT_V(2); BAR; WAIT_L(0); MMA(0, 0, At, B0); BAR;
	v_add_u32_e32 v0, 0x18000, v227
	s_barrier
	ds_read_b128 v[34:37], v0
	ds_read_b128 v[174:177], v0 offset:1024
	ds_read_b128 v[178:181], v0 offset:2048
	ds_read_b128 v[182:185], v0 offset:3072
	ds_read_b128 v[18:21], v213 offset:32768
	ds_read_b128 v[22:25], v213 offset:33792
	ds_read_b128 v[26:29], v213 offset:34816
	ds_read_b128 v[50:53], v213 offset:35840
	ds_read_b128 v[186:189], v213 offset:36864
	ds_read_b128 v[190:193], v213 offset:37888
	ds_read_b128 v[228:231], v213 offset:38912
	ds_read_b128 v[232:235], v213 offset:39936
	s_waitcnt vmcnt(2)
	s_barrier
	s_waitcnt lgkmcnt(0)

; #define LDA(dst, b, h) for (int m = 0; m < 4; ++m) for (int k = 0; k < 2; ++k) \
;     dst[m][k] = *reinterpret_cast<const bf16x8*>((char*)SA(b, h) + a_thr + (m * 2 + k) * 1024)
; #define LDB(dst, b, h) for (int n = 0; n < 2; ++n) for (int k = 0; k < 2; ++k) \
;     dst[n][k] = *reinterpret_cast<const bf16x8*>((char*)SB(b, h) + b_thr + (n * 2 + k) * 1024)
; #define MMA(ai, bj, At, Btf) do { __builtin_amdgcn_s_setprio(1); \
;     for (int m = 0; m < 4; ++m) for (int n = 0; n < 2; ++n) for (int k = 0; k < 2; ++k) \
;       acc[ai][bj][m][n] = __builtin_amdgcn_mfma_f32_16x16x32_bf16(Btf[n][k], At[m][k], acc[ai][bj][m][n], 0, 0, 0); \
;     __builtin_amdgcn_s_setprio(0); } while (0)
; #define WAIT_V(n) asm volatile("s_waitcnt vmcnt(" #n ")" ::: "memory")
; #define WAIT_L(n) asm volatile("s_waitcnt lgkmcnt(" #n ")" ::: "memory")
; #define BAR __builtin_amdgcn_s_barrier()
; template <bool OVL, bool PANEL = false, class Epi>
; __device__ __forceinline__ void gemm_phase(const bf16_t* __restrict__ A, long lda, const bf16_t* __restrict__ Bt, long ldb, int nM, int nN, int K,
;                                            const Epi& epi, bf16_t* shm, int w0) {
;     ...
;     { LDB(B0, 1, 0); LDA(At, 1, 0); WAIT_V(2); BAR; WAIT_L(0); MMA(0, 0, At, B0); BAR;
	s_waitcnt lgkmcnt(0)
	v_mfma_f32_16x16x32_bf16 v[6:9], v[178:181], v[18:21], v[122:125]
	v_mfma_f32_16x16x32_bf16 v[10:13], v[178:181], v[26:29], v[114:117]
	v_mfma_f32_16x16x32_bf16 v[14:17], v[178:181], v[186:189], v[106:109]
	v_mfma_f32_16x16x32_bf16 v[2:5], v[34:37], v[18:21], v[126:129]
	v_mfma_f32_16x16x32_bf16 v[30:33], v[182:185], v[22:25], v[6:9]
	v_mfma_f32_16x16x32_bf16 v[6:9], v[34:37], v[26:29], v[118:121]
	v_mfma_f32_16x16x32_bf16 v[38:41], v[182:185], v[50:53], v[10:13]
	v_mfma_f32_16x16x32_bf16 v[10:13], v[34:37], v[186:189], v[110:113]
	v_mfma_f32_16x16x32_bf16 v[42:45], v[182:185], v[190:193], v[14:17]
	v_mfma_f32_16x16x32_bf16 v[14:17], v[34:37], v[228:231], v[102:105]
	v_mfma_f32_16x16x32_bf16 v[46:49], v[178:181], v[228:231], v[98:101]
	v_mfma_f32_16x16x32_bf16 v[2:5], v[174:177], v[22:25], v[2:5]
	v_mfma_f32_16x16x32_bf16 v[6:9], v[174:177], v[50:53], v[6:9]
	v_mfma_f32_16x16x32_bf16 v[10:13], v[174:177], v[190:193], v[10:13]
	v_mfma_f32_16x16x32_bf16 v[14:17], v[174:177], v[232:235], v[14:17]
	v_mfma_f32_16x16x32_bf16 v[46:49], v[182:185], v[232:235], v[46:49]

; #define LDB(dst, b, h) for (int n = 0; n < 2; ++n) for (int k = 0; k < 2; ++k) \
;     dst[n][k] = *reinterpret_cast<const bf16x8*>((char*)SB(b, h) + b_thr + (n * 2 + k) * 1024)
; #define MMA(ai, bj, At, Btf) do { __builtin_amdgcn_s_setprio(1); \
;     for (int m = 0; m < 4; ++m) for (int n = 0; n < 2; ++n) for (int k = 0; k < 2; ++k) \
;       acc[ai][bj][m][n] = __builtin_amdgcn_mfma_f32_16x16x32_bf16(Btf[n][k], At[m][k], acc[ai][bj][m][n], 0, 0, 0); \
;     __builtin_amdgcn_s_setprio(0); } while (0)
; #define WAIT_V(n) asm volatile("s_waitcnt vmcnt(" #n ")" ::: "memory")
; #define WAIT_L(n) asm volatile("s_waitcnt lgkmcnt(" #n ")" ::: "memory")
; #define BAR __builtin_amdgcn_s_barrier()
; template <bool OVL, bool PANEL = false, class Epi>
; __device__ __forceinline__ void gemm_phase(const bf16_t* __restrict__ A, long lda, const bf16_t* __restrict__ Bt, long ldb, int nM, int nN, int K,
;                                            const Epi& epi, bf16_t* shm, int w0) {
;     ...
;       LDB(B1, 1, 1); WAIT_V(0); BAR; WAIT_L(0); MMA(0, 1, At, B1); BAR;
	v_add_u32_e32 v0, 0x1c000, v227
	s_barrier
	ds_read_b128 v[102:105], v0
	ds_read_b128 v[236:239], v0 offset:1024
	ds_read_b128 v[240:243], v0 offset:2048
	ds_read_b128 v[244:247], v0 offset:3072
	s_waitcnt vmcnt(0)
	s_barrier
	s_waitcnt lgkmcnt(0)

; #define LDB(dst, b, h) for (int n = 0; n < 2; ++n) for (int k = 0; k < 2; ++k) \
;     dst[n][k] = *reinterpret_cast<const bf16x8*>((char*)SB(b, h) + b_thr + (n * 2 + k) * 1024)
; #define MMA(ai, bj, At, Btf) do { __builtin_amdgcn_s_setprio(1); \
;     for (int m = 0; m < 4; ++m) for (int n = 0; n < 2; ++n) for (int k = 0; k < 2; ++k) \
;       acc[ai][bj][m][n] = __builtin_amdgcn_mfma_f32_16x16x32_bf16(Btf[n][k], At[m][k], acc[ai][bj][m][n], 0, 0, 0); \
;     __builtin_amdgcn_s_setprio(0); } while (0)
; #define WAIT_V(n) asm volatile("s_waitcnt vmcnt(" #n ")" ::: "memory")
; #define WAIT_L(n) asm volatile("s_waitcnt lgkmcnt(" #n ")" ::: "memory")
; #define BAR __builtin_amdgcn_s_barrier()
; template <bool OVL, bool PANEL = false, class Epi>
; __device__ __forceinline__ void gemm_phase(const bf16_t* __restrict__ A, long lda, const bf16_t* __restrict__ Bt, long ldb, int nM, int nN, int K,
;                                            const Epi& epi, bf16_t* shm, int w0) {
;     ...
;       LDB(B1, 1, 1); WAIT_V(0); BAR; WAIT_L(0); MMA(0, 1, At, B1); BAR;
	s_waitcnt lgkmcnt(0)
	v_mfma_f32_16x16x32_bf16 v[62:65], v[102:105], v[18:21], v[94:97]
	v_mfma_f32_16x16x32_bf16 v[18:21], v[240:243], v[18:21], v[90:93]
	v_mfma_f32_16x16x32_bf16 v[98:101], v[244:247], v[22:25], v[18:21]
	v_mfma_f32_16x16x32_bf16 v[18:21], v[102:105], v[26:29], v[86:89]
	v_mfma_f32_16x16x32_bf16 v[70:73], v[236:239], v[50:53], v[18:21]
	v_mfma_f32_16x16x32_bf16 v[18:21], v[240:243], v[26:29], v[82:85]
	v_mfma_f32_16x16x32_bf16 v[106:109], v[244:247], v[50:53], v[18:21]
	v_mfma_f32_16x16x32_bf16 v[18:21], v[102:105], v[186:189], v[78:81]
	v_mfma_f32_16x16x32_bf16 v[74:77], v[236:239], v[190:193], v[18:21]
	v_mfma_f32_16x16x32_bf16 v[18:21], v[240:243], v[186:189], v[150:153]
	v_mfma_f32_16x16x32_bf16 v[110:113], v[244:247], v[190:193], v[18:21]
	v_mfma_f32_16x16x32_bf16 v[18:21], v[102:105], v[228:231], v[154:157]
	v_mfma_f32_16x16x32_bf16 v[78:81], v[236:239], v[232:235], v[18:21]
	v_mfma_f32_16x16x32_bf16 v[18:21], v[240:243], v[228:231], v[66:69]
	v_mfma_f32_16x16x32_bf16 v[62:65], v[236:239], v[22:25], v[62:65]
	v_mfma_f32_16x16x32_bf16 v[114:117], v[244:247], v[232:235], v[18:21]

; #define LDA(dst, b, h) for (int m = 0; m < 4; ++m) for (int k = 0; k < 2; ++k) \
;     dst[m][k] = *reinterpret_cast<const bf16x8*>((char*)SA(b, h) + a_thr + (m * 2 + k) * 1024)
; #define MMA(ai, bj, At, Btf) do { __builtin_amdgcn_s_setprio(1); \
;     for (int m = 0; m < 4; ++m) for (int n = 0; n < 2; ++n) for (int k = 0; k < 2; ++k) \
;       acc[ai][bj][m][n] = __builtin_amdgcn_mfma_f32_16x16x32_bf16(Btf[n][k], At[m][k], acc[ai][bj][m][n], 0, 0, 0); \
;     __builtin_amdgcn_s_setprio(0); } while (0)
; #define WAIT_L(n) asm volatile("s_waitcnt lgkmcnt(" #n ")" ::: "memory")
; #define BAR __builtin_amdgcn_s_barrier()
; template <bool OVL, bool PANEL = false, class Epi>
; __device__ __forceinline__ void gemm_phase(const bf16_t* __restrict__ A, long lda, const bf16_t* __restrict__ Bt, long ldb, int nM, int nN, int K,
;                                            const Epi& epi, bf16_t* shm, int w0) {
;     ...
;       LDA(At, 1, 1); BAR; WAIT_L(0); MMA(1, 0, At, B0); MMA(1, 1, At, B1); BAR; }
	s_barrier
	ds_read_b128 v[86:89], v213 offset:49152
	ds_read_b128 v[90:93], v213 offset:50176
	ds_read_b128 v[94:97], v213 offset:51200
	ds_read_b128 v[118:121], v213 offset:52224
	ds_read_b128 v[150:153], v213 offset:53248
	ds_read_b128 v[154:157], v213 offset:54272
	ds_read_b128 v[186:189], v213 offset:55296
	ds_read_b128 v[190:193], v213 offset:56320
	s_barrier
	s_waitcnt lgkmcnt(0)

; #define LDA(dst, b, h) for (int m = 0; m < 4; ++m) for (int k = 0; k < 2; ++k) \
;     dst[m][k] = *reinterpret_cast<const bf16x8*>((char*)SA(b, h) + a_thr + (m * 2 + k) * 1024)
; #define MMA(ai, bj, At, Btf) do { __builtin_amdgcn_s_setprio(1); \
;     for (int m = 0; m < 4; ++m) for (int n = 0; n < 2; ++n) for (int k = 0; k < 2; ++k) \
;       acc[ai][bj][m][n] = __builtin_amdgcn_mfma_f32_16x16x32_bf16(Btf[n][k], At[m][k], acc[ai][bj][m][n], 0, 0, 0); \
;     __builtin_amdgcn_s_setprio(0); } while (0)
; #define WAIT_L(n) asm volatile("s_waitcnt lgkmcnt(" #n ")" ::: "memory")
; #define BAR __builtin_amdgcn_s_barrier()
; template <bool OVL, bool PANEL = false, class Epi>
; __device__ __forceinline__ void gemm_phase(const bf16_t* __restrict__ A, long lda, const bf16_t* __restrict__ Bt, long ldb, int nM, int nN, int K,
;                                            const Epi& epi, bf16_t* shm, int w0) {
;     ...
;       LDA(At, 1, 1); BAR; WAIT_L(0); MMA(1, 0, At, B0); MMA(1, 1, At, B1); BAR; }
	s_waitcnt lgkmcnt(0)
	v_mfma_f32_16x16x32_bf16 v[22:25], v[178:181], v[86:89], v[58:61]
	v_mfma_f32_16x16x32_bf16 v[26:29], v[178:181], v[94:97], v[198:201]
	v_mfma_f32_16x16x32_bf16 v[18:21], v[34:37], v[86:89], v[194:197]
	v_mfma_f32_16x16x32_bf16 v[50:53], v[182:185], v[90:93], v[22:25]
	v_mfma_f32_16x16x32_bf16 v[22:25], v[34:37], v[94:97], v[54:57]
	v_mfma_f32_16x16x32_bf16 v[54:57], v[182:185], v[118:121], v[26:29]
	v_mfma_f32_16x16x32_bf16 v[26:29], v[34:37], v[150:153], v[214:217]
	v_mfma_f32_16x16x32_bf16 v[58:61], v[178:181], v[150:153], v[218:221]
	v_mfma_f32_16x16x32_bf16 v[34:37], v[34:37], v[186:189], v[130:133]
	v_mfma_f32_16x16x32_bf16 v[66:69], v[178:181], v[186:189], v[138:141]
	v_mfma_f32_16x16x32_bf16 v[18:21], v[174:177], v[90:93], v[18:21]
	v_mfma_f32_16x16x32_bf16 v[22:25], v[174:177], v[118:121], v[22:25]
	v_mfma_f32_16x16x32_bf16 v[26:29], v[174:177], v[154:157], v[26:29]
	v_mfma_f32_16x16x32_bf16 v[58:61], v[182:185], v[154:157], v[58:61]
	v_mfma_f32_16x16x32_bf16 v[34:37], v[174:177], v[190:193], v[34:37]
	v_mfma_f32_16x16x32_bf16 v[66:69], v[182:185], v[190:193], v[66:69]


; #define LDA(dst, b, h) for (int m = 0; m < 4; ++m) for (int k = 0; k < 2; ++k) \
;     dst[m][k] = *reinterpret_cast<const bf16x8*>((char*)SA(b, h) + a_thr + (m * 2 + k) * 1024)
; #define MMA(ai, bj, At, Btf) do { __builtin_amdgcn_s_setprio(1); \
;     for (int m = 0; m < 4; ++m) for (int n = 0; n < 2; ++n) for (int k = 0; k < 2; ++k) \
;       acc[ai][bj][m][n] = __builtin_amdgcn_mfma_f32_16x16x32_bf16(Btf[n][k], At[m][k], acc[ai][bj][m][n], 0, 0, 0); \
;     __builtin_amdgcn_s_setprio(0); } while (0)
; #define WAIT_L(n) asm volatile("s_waitcnt lgkmcnt(" #n ")" ::: "memory")
; #define BAR __builtin_amdgcn_s_barrier()
; template <bool OVL, bool PANEL = false, class Epi>
; __device__ __forceinline__ void gemm_phase(const bf16_t* __restrict__ A, long lda, const bf16_t* __restrict__ Bt, long ldb, int nM, int nN, int K,
;                                            const Epi& epi, bf16_t* shm, int w0) {
;     ...
;       LDA(At, 1, 1); BAR; WAIT_L(0); MMA(1, 0, At, B0); MMA(1, 1, At, B1); BAR; }
	v_mfma_f32_16x16x32_bf16 v[82:85], v[102:105], v[86:89], v[142:145]
	v_mfma_f32_16x16x32_bf16 v[86:89], v[240:243], v[86:89], v[146:149]
	v_mfma_f32_16x16x32_bf16 v[82:85], v[236:239], v[90:93], v[82:85]
	v_mfma_f32_16x16x32_bf16 v[122:125], v[244:247], v[90:93], v[86:89]
	v_mfma_f32_16x16x32_bf16 v[86:89], v[102:105], v[94:97], v[222:225]
	v_mfma_f32_16x16x32_bf16 v[90:93], v[240:243], v[94:97], v[158:161]
	v_mfma_f32_16x16x32_bf16 v[94:97], v[240:243], v[150:153], v[166:169]
	v_mfma_f32_16x16x32_bf16 v[86:89], v[236:239], v[118:121], v[86:89]
	v_mfma_f32_16x16x32_bf16 v[126:129], v[244:247], v[118:121], v[90:93]
	v_mfma_f32_16x16x32_bf16 v[118:121], v[244:247], v[154:157], v[94:97]
	v_mfma_f32_16x16x32_bf16 v[94:97], v[102:105], v[186:189], v[134:137]
	v_mfma_f32_16x16x32_bf16 v[90:93], v[102:105], v[150:153], v[162:165]
	v_mfma_f32_16x16x32_bf16 v[102:105], v[236:239], v[190:193], v[94:97]
	v_mfma_f32_16x16x32_bf16 v[94:97], v[240:243], v[186:189], v[170:173]
	v_mfma_f32_16x16x32_bf16 v[90:93], v[236:239], v[154:157], v[90:93]
	v_mfma_f32_16x16x32_bf16 v[94:97], v[244:247], v[190:193], v[94:97]

; #define LDA(dst, b, h) for (int m = 0; m < 4; ++m) for (int k = 0; k < 2; ++k) \
;     dst[m][k] = *reinterpret_cast<const bf16x8*>((char*)SA(b, h) + a_thr + (m * 2 + k) * 1024)
; #define MMA(ai, bj, At, Btf) do { __builtin_amdgcn_s_setprio(1); \
;     for (int m = 0; m < 4; ++m) for (int n = 0; n < 2; ++n) for (int k = 0; k < 2; ++k) \
;       acc[ai][bj][m][n] = __builtin_amdgcn_mfma_f32_16x16x32_bf16(Btf[n][k], At[m][k], acc[ai][bj][m][n], 0, 0, 0); \
;     __builtin_amdgcn_s_setprio(0); } while (0)
; #define WAIT_L(n) asm volatile("s_waitcnt lgkmcnt(" #n ")" ::: "memory")
; #define BAR __builtin_amdgcn_s_barrier()
; template <bool OVL, bool PANEL = false, class Epi>
; __device__ __forceinline__ void gemm_phase(const bf16_t* __restrict__ A, long lda, const bf16_t* __restrict__ Bt, long ldb, int nM, int nN, int K,
;                                            const Epi& epi, bf16_t* shm, int w0) {
;     ...
;       LDA(At, 1, 1); BAR; WAIT_L(0); MMA(1, 0, At, B0); MMA(1, 1, At, B1); BAR; }
;     if (wr == 0) BAR;
	s_barrier
	s_and_saveexec_b64 s[0:1], s[58:59]
	s_cbranch_execz .LBB0_128
	s_barrier

; #define LDA(dst, b, h) for (int m = 0; m < 4; ++m) for (int k = 0; k < 2; ++k) \
;     dst[m][k] = *reinterpret_cast<const bf16x8*>((char*)SA(b, h) + a_thr + (m * 2 + k) * 1024)
; #define LDB(dst, b, h) for (int n = 0; n < 2; ++n) for (int k = 0; k < 2; ++k) \
;     dst[n][k] = *reinterpret_cast<const bf16x8*>((char*)SB(b, h) + b_thr + (n * 2 + k) * 1024)
; #define MMA(ai, bj, At, Btf) do { __builtin_amdgcn_s_setprio(1); \
;     for (int m = 0; m < 4; ++m) for (int n = 0; n < 2; ++n) for (int k = 0; k < 2; ++k) \
;       acc[ai][bj][m][n] = __builtin_amdgcn_mfma_f32_16x16x32_bf16(Btf[n][k], At[m][k], acc[ai][bj][m][n], 0, 0, 0); \
;     __builtin_amdgcn_s_setprio(0); } while (0)
; #define WAIT_V(n) asm volatile("s_waitcnt vmcnt(" #n ")" ::: "memory")
; #define WAIT_L(n) asm volatile("s_waitcnt lgkmcnt(" #n ")" ::: "memory")
; #define BAR __builtin_amdgcn_s_barrier()
; #define SCHED __builtin_amdgcn_sched_barrier(0)
; template <bool OVL, bool PANEL = false, class Epi>
; __device__ __forceinline__ void gemm_phase(const bf16_t* __restrict__ A, long lda, const bf16_t* __restrict__ Bt, long ldb, int nM, int nN, int K,
;                                            const Epi& epi, bf16_t* shm, int w0) {
;     ...
;       LDB(B0, 0, 0); SCHED; LDA(At, 0, 0); STAGE(SA(1, 1), A, lda, aoff, brow + HALF, t + 1);
;       WAIT_L(8); BAR; WAIT_L(0); MMA(0, 0, At, B0); BAR; SCHED;
;       LDB(B1, 0, 1); STAGE(SB(0, 0), Bt, ldb, boff, bcol, t + 2);
;       BAR; WAIT_L(0); MMA(0, 1, At, B1); BAR;
;       LDA(At, 0, 1); STAGE(SA(0, 0), A, lda, aoff, brow, t + 2);
;       BAR; WAIT_L(0); MMA(1, 0, At, B0); BAR; SCHED;
;       STAGE(SB(0, 1), Bt, ldb, boff, bcol + HALF, t + 2);
;       WAIT_V(6); BAR; MMA(1, 1, At, B1); BAR;
.LBB0_386:
	ds_read_b128 v[150:153], v218
	ds_read_b128 v[154:157], v218 offset:1024
	ds_read_b128 v[158:161], v218 offset:2048
	ds_read_b128 v[162:165], v218 offset:3072
	s_add_u32 s42, s10, vcc_lo
	s_addc_u32 s43, s11, vcc_hi
	ds_read_b128 v[166:169], v141
	ds_read_b128 v[170:173], v141 offset:1024
	ds_read_b128 v[174:177], v141 offset:2048
	ds_read_b128 v[178:181], v141 offset:3072
	ds_read_b128 v[182:185], v141 offset:4096
	ds_read_b128 v[186:189], v141 offset:5120
	ds_read_b128 v[190:193], v141 offset:6144
	ds_read_b128 v[194:197], v141 offset:7168
	s_mov_b32 m0, s16
	s_add_u32 s98, s42, s28
	s_addc_u32 s99, s43, s29
	global_load_lds_dwordx4 v131, s[98:99]
	s_mov_b32 m0, s32
	s_add_u32 s98, s42, s36
	s_addc_u32 s99, s43, s37
	global_load_lds_dwordx4 v131, s[98:99]
	s_waitcnt lgkmcnt(8)
	s_waitcnt vmcnt(10)
	s_barrier
	s_waitcnt lgkmcnt(0)
	s_waitcnt lgkmcnt(0)
	v_mfma_f32_16x16x32_bf16 v[126:129], v[150:153], v[166:169], v[126:129]
	v_mfma_f32_16x16x32_bf16 v[122:125], v[158:161], v[166:169], v[122:125]
	v_mfma_f32_16x16x32_bf16 v[118:121], v[150:153], v[174:177], v[118:121]
	v_mfma_f32_16x16x32_bf16 v[114:117], v[158:161], v[174:177], v[114:117]
	v_mfma_f32_16x16x32_bf16 v[110:113], v[150:153], v[182:185], v[110:113]
	v_mfma_f32_16x16x32_bf16 v[106:109], v[158:161], v[182:185], v[106:109]
	v_mfma_f32_16x16x32_bf16 v[102:105], v[150:153], v[190:193], v[102:105]
	v_mfma_f32_16x16x32_bf16 v[98:101], v[158:161], v[190:193], v[98:101]
	v_mfma_f32_16x16x32_bf16 v[126:129], v[154:157], v[170:173], v[126:129]
	v_mfma_f32_16x16x32_bf16 v[122:125], v[162:165], v[170:173], v[122:125]
	v_mfma_f32_16x16x32_bf16 v[118:121], v[154:157], v[178:181], v[118:121]
	v_mfma_f32_16x16x32_bf16 v[114:117], v[162:165], v[178:181], v[114:117]
	v_mfma_f32_16x16x32_bf16 v[110:113], v[154:157], v[186:189], v[110:113]
	v_mfma_f32_16x16x32_bf16 v[106:109], v[162:165], v[186:189], v[106:109]
	v_mfma_f32_16x16x32_bf16 v[102:105], v[154:157], v[194:197], v[102:105]
	v_mfma_f32_16x16x32_bf16 v[98:101], v[162:165], v[194:197], v[98:101]
	s_barrier
	s_add_u32 s66, s8, vcc_lo
	ds_read_b128 v[198:201], v219
	ds_read_b128 v[202:205], v219 offset:1024
	ds_read_b128 v[206:209], v219 offset:2048
	ds_read_b128 v[210:213], v219 offset:3072
	s_addc_u32 s67, s9, vcc_hi
	s_mov_b32 m0, s46
	s_add_u32 s98, s66, s34
	s_addc_u32 s99, s67, s35
	global_load_lds_dwordx4 v131, s[98:99]
	s_mov_b32 m0, s47
	s_add_u32 s98, s66, s64
	s_addc_u32 s99, s67, s65
	global_load_lds_dwordx4 v131, s[98:99]
	s_waitcnt vmcnt(10)
	s_barrier
	s_waitcnt lgkmcnt(0)
	s_waitcnt lgkmcnt(0)
	v_mfma_f32_16x16x32_bf16 v[94:97], v[198:201], v[166:169], v[94:97]
	v_mfma_f32_16x16x32_bf16 v[90:93], v[206:209], v[166:169], v[90:93]
	v_mfma_f32_16x16x32_bf16 v[86:89], v[198:201], v[174:177], v[86:89]
	v_mfma_f32_16x16x32_bf16 v[82:85], v[206:209], v[174:177], v[82:85]
	v_mfma_f32_16x16x32_bf16 v[78:81], v[198:201], v[182:185], v[78:81]
	v_mfma_f32_16x16x32_bf16 v[74:77], v[206:209], v[182:185], v[74:77]
	v_mfma_f32_16x16x32_bf16 v[70:73], v[198:201], v[190:193], v[70:73]
	v_mfma_f32_16x16x32_bf16 v[66:69], v[206:209], v[190:193], v[66:69]
	v_mfma_f32_16x16x32_bf16 v[94:97], v[202:205], v[170:173], v[94:97]
	v_mfma_f32_16x16x32_bf16 v[90:93], v[210:213], v[170:173], v[90:93]
	v_mfma_f32_16x16x32_bf16 v[86:89], v[202:205], v[178:181], v[86:89]
	v_mfma_f32_16x16x32_bf16 v[82:85], v[210:213], v[178:181], v[82:85]
	v_mfma_f32_16x16x32_bf16 v[78:81], v[202:205], v[186:189], v[78:81]
	v_mfma_f32_16x16x32_bf16 v[74:77], v[210:213], v[186:189], v[74:77]
	v_mfma_f32_16x16x32_bf16 v[70:73], v[202:205], v[194:197], v[70:73]
	v_mfma_f32_16x16x32_bf16 v[66:69], v[210:213], v[194:197], v[66:69]
	s_barrier
	ds_read_b128 v[166:169], v141 offset:16384
	ds_read_b128 v[170:173], v141 offset:17408
	ds_read_b128 v[174:177], v141 offset:18432
	ds_read_b128 v[178:181], v141 offset:19456
	ds_read_b128 v[182:185], v141 offset:20480
	ds_read_b128 v[186:189], v141 offset:21504
	ds_read_b128 v[190:193], v141 offset:22528
	ds_read_b128 v[194:197], v141 offset:23552
	s_mov_b32 m0, s48
	s_add_u32 s98, s42, s34
	s_addc_u32 s99, s43, s35
	global_load_lds_dwordx4 v131, s[98:99]
	s_mov_b32 m0, s49
	s_add_u32 s98, s42, s64
	s_addc_u32 s99, s43, s65
	global_load_lds_dwordx4 v131, s[98:99]
	s_barrier
	s_waitcnt lgkmcnt(0)
	s_waitcnt lgkmcnt(0)
	v_mfma_f32_16x16x32_bf16 v[62:65], v[150:153], v[166:169], v[62:65]
	v_mfma_f32_16x16x32_bf16 v[58:61], v[158:161], v[166:169], v[58:61]
	v_mfma_f32_16x16x32_bf16 v[54:57], v[150:153], v[174:177], v[54:57]
	v_mfma_f32_16x16x32_bf16 v[50:53], v[158:161], v[174:177], v[50:53]
	v_mfma_f32_16x16x32_bf16 v[46:49], v[150:153], v[182:185], v[46:49]
	v_mfma_f32_16x16x32_bf16 v[42:45], v[158:161], v[182:185], v[42:45]
	v_mfma_f32_16x16x32_bf16 v[38:41], v[150:153], v[190:193], v[38:41]
	v_mfma_f32_16x16x32_bf16 v[34:37], v[158:161], v[190:193], v[34:37]
	v_mfma_f32_16x16x32_bf16 v[62:65], v[154:157], v[170:173], v[62:65]
	v_mfma_f32_16x16x32_bf16 v[58:61], v[162:165], v[170:173], v[58:61]
	v_mfma_f32_16x16x32_bf16 v[54:57], v[154:157], v[178:181], v[54:57]
	v_mfma_f32_16x16x32_bf16 v[50:53], v[162:165], v[178:181], v[50:53]
	v_mfma_f32_16x16x32_bf16 v[46:49], v[154:157], v[186:189], v[46:49]
	v_mfma_f32_16x16x32_bf16 v[42:45], v[162:165], v[186:189], v[42:45]
	v_mfma_f32_16x16x32_bf16 v[38:41], v[154:157], v[194:197], v[38:41]
	v_mfma_f32_16x16x32_bf16 v[34:37], v[162:165], v[194:197], v[34:37]
	s_barrier
	s_mov_b32 m0, s50
	s_add_u32 s98, s66, s68
	s_addc_u32 s99, s67, s69
	global_load_lds_dwordx4 v131, s[98:99]
	s_mov_b32 m0, s51
	s_add_u32 s98, s66, s70
	s_addc_u32 s99, s67, s71
	global_load_lds_dwordx4 v131, s[98:99]
	s_waitcnt vmcnt(10)
	s_barrier
; #define LDA(dst, b, h) for (int m = 0; m < 4; ++m) for (int k = 0; k < 2; ++k) \
;     dst[m][k] = *reinterpret_cast<const bf16x8*>((char*)SA(b, h) + a_thr + (m * 2 + k) * 1024)
; #define LDB(dst, b, h) for (int n = 0; n < 2; ++n) for (int k = 0; k < 2; ++k) \
;     dst[n][k] = *reinterpret_cast<const bf16x8*>((char*)SB(b, h) + b_thr + (n * 2 + k) * 1024)
; #define MMA(ai, bj, At, Btf) do { __builtin_amdgcn_s_setprio(1); \
;     for (int m = 0; m < 4; ++m) for (int n = 0; n < 2; ++n) for (int k = 0; k < 2; ++k) \
;       acc[ai][bj][m][n] = __builtin_amdgcn_mfma_f32_16x16x32_bf16(Btf[n][k], At[m][k], acc[ai][bj][m][n], 0, 0, 0); \
;     __builtin_amdgcn_s_setprio(0); } while (0)
; #define WAIT_V(n) asm volatile("s_waitcnt vmcnt(" #n ")" ::: "memory")
; #define WAIT_L(n) asm volatile("s_waitcnt lgkmcnt(" #n ")" ::: "memory")
; #define BAR __builtin_amdgcn_s_barrier()
; #define SCHED __builtin_amdgcn_sched_barrier(0)
; template <bool OVL, bool PANEL = false, class Epi>
; __device__ __forceinline__ void gemm_phase(const bf16_t* __restrict__ A, long lda, const bf16_t* __restrict__ Bt, long ldb, int nM, int nN, int K,
;                                            const Epi& epi, bf16_t* shm, int w0) {
;     ...
;       WAIT_V(6); BAR; MMA(1, 1, At, B1); BAR;
;       LDB(B0, 1, 0); SCHED; LDA(At, 1, 0); STAGE(SA(0, 1), A, lda, aoff, brow + HALF, t + 2);
;       WAIT_L(8); BAR; WAIT_L(0); MMA(0, 0, At, B0); BAR; SCHED;
;       LDB(B1, 1, 1); STAGE(SB(1, 0), Bt, ldb, boff, bcol, t + 3);
;       BAR; WAIT_L(0); MMA(0, 1, At, B1); BAR;
	v_mfma_f32_16x16x32_bf16 v[30:33], v[198:201], v[166:169], v[30:33]
	v_mfma_f32_16x16x32_bf16 v[26:29], v[206:209], v[166:169], v[26:29]
	v_mfma_f32_16x16x32_bf16 v[22:25], v[198:201], v[174:177], v[22:25]
	v_mfma_f32_16x16x32_bf16 v[18:21], v[206:209], v[174:177], v[18:21]
	v_mfma_f32_16x16x32_bf16 v[14:17], v[198:201], v[182:185], v[14:17]
	v_mfma_f32_16x16x32_bf16 v[10:13], v[206:209], v[182:185], v[10:13]
	v_mfma_f32_16x16x32_bf16 v[6:9], v[198:201], v[190:193], v[6:9]
	v_mfma_f32_16x16x32_bf16 v[2:5], v[206:209], v[190:193], v[2:5]
	v_mfma_f32_16x16x32_bf16 v[30:33], v[202:205], v[170:173], v[30:33]
	v_mfma_f32_16x16x32_bf16 v[26:29], v[210:213], v[170:173], v[26:29]
	v_mfma_f32_16x16x32_bf16 v[22:25], v[202:205], v[178:181], v[22:25]
	v_mfma_f32_16x16x32_bf16 v[18:21], v[210:213], v[178:181], v[18:21]
	v_mfma_f32_16x16x32_bf16 v[14:17], v[202:205], v[186:189], v[14:17]
	v_mfma_f32_16x16x32_bf16 v[10:13], v[210:213], v[186:189], v[10:13]
	v_mfma_f32_16x16x32_bf16 v[6:9], v[202:205], v[194:197], v[6:9]
	v_mfma_f32_16x16x32_bf16 v[2:5], v[210:213], v[194:197], v[2:5]
	s_barrier
	ds_read_b128 v[150:153], v220
	ds_read_b128 v[154:157], v220 offset:1024
	ds_read_b128 v[158:161], v220 offset:2048
	ds_read_b128 v[162:165], v220 offset:3072
	ds_read_b128 v[166:169], v141 offset:32768
	ds_read_b128 v[170:173], v141 offset:33792
	ds_read_b128 v[174:177], v141 offset:34816
	ds_read_b128 v[178:181], v141 offset:35840
	ds_read_b128 v[182:185], v141 offset:36864
	ds_read_b128 v[186:189], v141 offset:37888
	ds_read_b128 v[190:193], v141 offset:38912
	ds_read_b128 v[194:197], v141 offset:39936
	s_mov_b32 m0, s52
	s_add_u32 s98, s42, s68
	s_addc_u32 s99, s43, s69
	global_load_lds_dwordx4 v131, s[98:99]
	s_mov_b32 m0, s53
	s_add_u32 s98, s42, s70
	s_addc_u32 s99, s43, s71
	global_load_lds_dwordx4 v131, s[98:99]
	s_waitcnt lgkmcnt(8)
	s_waitcnt vmcnt(10)
	s_barrier
	s_waitcnt lgkmcnt(0)
	s_waitcnt lgkmcnt(0)
	v_mfma_f32_16x16x32_bf16 v[126:129], v[150:153], v[166:169], v[126:129]
	v_mfma_f32_16x16x32_bf16 v[122:125], v[158:161], v[166:169], v[122:125]
	v_mfma_f32_16x16x32_bf16 v[118:121], v[150:153], v[174:177], v[118:121]
	v_mfma_f32_16x16x32_bf16 v[114:117], v[158:161], v[174:177], v[114:117]
	v_mfma_f32_16x16x32_bf16 v[110:113], v[150:153], v[182:185], v[110:113]
	v_mfma_f32_16x16x32_bf16 v[106:109], v[158:161], v[182:185], v[106:109]
	v_mfma_f32_16x16x32_bf16 v[102:105], v[150:153], v[190:193], v[102:105]
	v_mfma_f32_16x16x32_bf16 v[98:101], v[158:161], v[190:193], v[98:101]
	v_mfma_f32_16x16x32_bf16 v[126:129], v[154:157], v[170:173], v[126:129]
	v_mfma_f32_16x16x32_bf16 v[122:125], v[162:165], v[170:173], v[122:125]
	v_mfma_f32_16x16x32_bf16 v[118:121], v[154:157], v[178:181], v[118:121]
	v_mfma_f32_16x16x32_bf16 v[114:117], v[162:165], v[178:181], v[114:117]
	v_mfma_f32_16x16x32_bf16 v[110:113], v[154:157], v[186:189], v[110:113]
	v_mfma_f32_16x16x32_bf16 v[106:109], v[162:165], v[186:189], v[106:109]
	v_mfma_f32_16x16x32_bf16 v[102:105], v[154:157], v[194:197], v[102:105]
	v_mfma_f32_16x16x32_bf16 v[98:101], v[162:165], v[194:197], v[98:101]
	s_barrier
	ds_read_b128 v[198:201], v221
	ds_read_b128 v[202:205], v221 offset:1024
	ds_read_b128 v[206:209], v221 offset:2048
	ds_read_b128 v[210:213], v221 offset:3072
	s_mov_b32 m0, s54
	s_add_u32 s98, s66, s94
	s_addc_u32 s99, s67, s95
	global_load_lds_dwordx4 v131, s[98:99]
	s_mov_b32 m0, s55
	s_add_u32 s98, s66, s72
	s_addc_u32 s99, s67, s73
	global_load_lds_dwordx4 v131, s[98:99]
	s_waitcnt vmcnt(10)
	s_barrier
	s_waitcnt lgkmcnt(0)
	s_waitcnt lgkmcnt(0)
	v_mfma_f32_16x16x32_bf16 v[94:97], v[198:201], v[166:169], v[94:97]
	v_mfma_f32_16x16x32_bf16 v[90:93], v[206:209], v[166:169], v[90:93]
	v_mfma_f32_16x16x32_bf16 v[86:89], v[198:201], v[174:177], v[86:89]
	v_mfma_f32_16x16x32_bf16 v[82:85], v[206:209], v[174:177], v[82:85]
	v_mfma_f32_16x16x32_bf16 v[78:81], v[198:201], v[182:185], v[78:81]
	v_mfma_f32_16x16x32_bf16 v[74:77], v[206:209], v[182:185], v[74:77]
	v_mfma_f32_16x16x32_bf16 v[70:73], v[198:201], v[190:193], v[70:73]
	v_mfma_f32_16x16x32_bf16 v[66:69], v[206:209], v[190:193], v[66:69]
	v_mfma_f32_16x16x32_bf16 v[94:97], v[202:205], v[170:173], v[94:97]
	v_mfma_f32_16x16x32_bf16 v[90:93], v[210:213], v[170:173], v[90:93]
	v_mfma_f32_16x16x32_bf16 v[86:89], v[202:205], v[178:181], v[86:89]
	v_mfma_f32_16x16x32_bf16 v[82:85], v[210:213], v[178:181], v[82:85]
	v_mfma_f32_16x16x32_bf16 v[78:81], v[202:205], v[186:189], v[78:81]
	v_mfma_f32_16x16x32_bf16 v[74:77], v[210:213], v[186:189], v[74:77]
	v_mfma_f32_16x16x32_bf16 v[70:73], v[202:205], v[194:197], v[70:73]
	v_mfma_f32_16x16x32_bf16 v[66:69], v[210:213], v[194:197], v[66:69]
	s_barrier
; #define LDA(dst, b, h) for (int m = 0; m < 4; ++m) for (int k = 0; k < 2; ++k) \
;     dst[m][k] = *reinterpret_cast<const bf16x8*>((char*)SA(b, h) + a_thr + (m * 2 + k) * 1024)
; #define LDB(dst, b, h) for (int n = 0; n < 2; ++n) for (int k = 0; k < 2; ++k) \
;     dst[n][k] = *reinterpret_cast<const bf16x8*>((char*)SB(b, h) + b_thr + (n * 2 + k) * 1024)
; #define MMA(ai, bj, At, Btf) do { __builtin_amdgcn_s_setprio(1); \
;     for (int m = 0; m < 4; ++m) for (int n = 0; n < 2; ++n) for (int k = 0; k < 2; ++k) \
;       acc[ai][bj][m][n] = __builtin_amdgcn_mfma_f32_16x16x32_bf16(Btf[n][k], At[m][k], acc[ai][bj][m][n], 0, 0, 0); \
;     __builtin_amdgcn_s_setprio(0); } while (0)
; #define WAIT_V(n) asm volatile("s_waitcnt vmcnt(" #n ")" ::: "memory")
; #define WAIT_L(n) asm volatile("s_waitcnt lgkmcnt(" #n ")" ::: "memory")
; #define BAR __builtin_amdgcn_s_barrier()
; #define SCHED __builtin_amdgcn_sched_barrier(0)
; template <bool OVL, bool PANEL = false, class Epi>
; __device__ __forceinline__ void gemm_phase(const bf16_t* __restrict__ A, long lda, const bf16_t* __restrict__ Bt, long ldb, int nM, int nN, int K,
;                                            const Epi& epi, bf16_t* shm, int w0) {
;     ...
;       LDA(At, 1, 1); STAGE(SA(1, 0), A, lda, aoff, brow, t + 3);
;       BAR; WAIT_L(0); MMA(1, 0, At, B0); BAR; SCHED;
;       STAGE(SB(1, 1), Bt, ldb, boff, bcol + HALF, t + 3);
;       WAIT_V(6); BAR; MMA(1, 1, At, B1); BAR;
;     }
;     { LDB(B0, 0, 0); LDA(At, 0, 0); STAGE(SA(1, 1), A, lda, aoff, brow + HALF, nt - 1);
	ds_read_b128 v[166:169], v141 offset:49152
	ds_read_b128 v[170:173], v141 offset:50176
	ds_read_b128 v[174:177], v141 offset:51200
	ds_read_b128 v[178:181], v141 offset:52224
	ds_read_b128 v[182:185], v141 offset:53248
	ds_read_b128 v[186:189], v141 offset:54272
	ds_read_b128 v[190:193], v141 offset:55296
	ds_read_b128 v[194:197], v141 offset:56320
	s_mov_b32 m0, s56
	s_add_u32 s98, s42, s94
	s_addc_u32 s99, s43, s95
	global_load_lds_dwordx4 v131, s[98:99]
	s_mov_b32 m0, s57
	s_add_u32 s98, s42, s72
	s_addc_u32 s99, s43, s73
	global_load_lds_dwordx4 v131, s[98:99]
	s_barrier
	s_waitcnt lgkmcnt(0)
	s_waitcnt lgkmcnt(0)
	v_mfma_f32_16x16x32_bf16 v[62:65], v[150:153], v[166:169], v[62:65]
	v_mfma_f32_16x16x32_bf16 v[58:61], v[158:161], v[166:169], v[58:61]
	v_mfma_f32_16x16x32_bf16 v[54:57], v[150:153], v[174:177], v[54:57]
	v_mfma_f32_16x16x32_bf16 v[50:53], v[158:161], v[174:177], v[50:53]
	v_mfma_f32_16x16x32_bf16 v[46:49], v[150:153], v[182:185], v[46:49]
	v_mfma_f32_16x16x32_bf16 v[42:45], v[158:161], v[182:185], v[42:45]
	v_mfma_f32_16x16x32_bf16 v[38:41], v[150:153], v[190:193], v[38:41]
	v_mfma_f32_16x16x32_bf16 v[34:37], v[158:161], v[190:193], v[34:37]
	v_mfma_f32_16x16x32_bf16 v[62:65], v[154:157], v[170:173], v[62:65]
	v_mfma_f32_16x16x32_bf16 v[58:61], v[162:165], v[170:173], v[58:61]
	v_mfma_f32_16x16x32_bf16 v[54:57], v[154:157], v[178:181], v[54:57]
	v_mfma_f32_16x16x32_bf16 v[50:53], v[162:165], v[178:181], v[50:53]
	v_mfma_f32_16x16x32_bf16 v[46:49], v[154:157], v[186:189], v[46:49]
	v_mfma_f32_16x16x32_bf16 v[42:45], v[162:165], v[186:189], v[42:45]
	v_mfma_f32_16x16x32_bf16 v[38:41], v[154:157], v[194:197], v[38:41]
	v_mfma_f32_16x16x32_bf16 v[34:37], v[162:165], v[194:197], v[34:37]
	s_barrier
	s_mov_b32 m0, s58
	s_add_u32 s98, s66, s30
	s_addc_u32 s99, s67, s31
	global_load_lds_dwordx4 v131, s[98:99]
	s_mov_b32 m0, s59
	s_add_u32 s98, s66, s44
	s_addc_u32 s99, s67, s45
	global_load_lds_dwordx4 v131, s[98:99]
	s_waitcnt vmcnt(10)
	s_barrier
	v_mfma_f32_16x16x32_bf16 v[30:33], v[198:201], v[166:169], v[30:33]
	v_mfma_f32_16x16x32_bf16 v[26:29], v[206:209], v[166:169], v[26:29]
	v_mfma_f32_16x16x32_bf16 v[22:25], v[198:201], v[174:177], v[22:25]
	v_mfma_f32_16x16x32_bf16 v[18:21], v[206:209], v[174:177], v[18:21]
	v_mfma_f32_16x16x32_bf16 v[14:17], v[198:201], v[182:185], v[14:17]
	v_mfma_f32_16x16x32_bf16 v[10:13], v[206:209], v[182:185], v[10:13]
	v_mfma_f32_16x16x32_bf16 v[6:9], v[198:201], v[190:193], v[6:9]
	v_mfma_f32_16x16x32_bf16 v[2:5], v[206:209], v[190:193], v[2:5]
	v_mfma_f32_16x16x32_bf16 v[30:33], v[202:205], v[170:173], v[30:33]
	v_mfma_f32_16x16x32_bf16 v[26:29], v[210:213], v[170:173], v[26:29]
	v_mfma_f32_16x16x32_bf16 v[22:25], v[202:205], v[178:181], v[22:25]
	v_mfma_f32_16x16x32_bf16 v[18:21], v[210:213], v[178:181], v[18:21]
	v_mfma_f32_16x16x32_bf16 v[14:17], v[202:205], v[186:189], v[14:17]
	v_mfma_f32_16x16x32_bf16 v[10:13], v[210:213], v[186:189], v[10:13]
	v_mfma_f32_16x16x32_bf16 v[6:9], v[202:205], v[194:197], v[6:9]
	v_mfma_f32_16x16x32_bf16 v[2:5], v[210:213], v[194:197], v[2:5]
	s_add_i32 s18, s18, 2
	s_add_u32 vcc_lo, vcc_lo, 0x100
	s_addc_u32 vcc_hi, vcc_hi, 0
	s_cmp_lt_u32 s18, 12
	s_barrier
	s_cbranch_scc1 .LBB0_386
	s_waitcnt vmcnt(6)
	s_or_b32 s8, s2, 0x80
	s_mov_b32 s9, s3
	v_readlane_b32 s44, v252, 20
	s_lshl_b64 s[8:9], s[8:9], 11
	v_readlane_b32 s50, v252, 26
	v_add_u32_e32 v214, 16, v140
	v_readlane_b32 s51, v252, 27
	s_add_u32 s8, s50, s8
	v_add_u32_e32 v0, 0x10000, v214
	s_addc_u32 s9, s51, s9
	ds_read_b128 v[142:145], v0
	ds_read_b128 v[150:153], v0 offset:1024
	ds_read_b128 v[154:157], v0 offset:2048
	ds_read_b128 v[158:161], v0 offset:3072
	ds_read_b128 v[162:165], v141
	ds_read_b128 v[166:169], v141 offset:1024
	ds_read_b128 v[170:173], v141 offset:2048
	ds_read_b128 v[174:177], v141 offset:3072
	ds_read_b128 v[178:181], v141 offset:4096
	ds_read_b128 v[182:185], v141 offset:5120
	ds_read_b128 v[186:189], v141 offset:6144
	ds_read_b128 v[190:193], v141 offset:7168
	v_mov_b32_e32 v0, v131
	v_readlane_b32 s45, v252, 21
	v_lshl_add_u64 v[146:147], s[8:9], 0, v[0:1]
	s_mov_b64 s[8:9], 0x780
	v_lshl_add_u64 v[194:195], v[146:147], 0, s[8:9]
	v_readfirstlane_b32 s8, v148
	s_mov_b32 m0, s8
	s_mov_b64 s[8:9], 0x20780
	v_lshl_add_u64 v[146:147], v[146:147], 0, s[8:9]
	v_readfirstlane_b32 s8, v149
	global_load_lds_dwordx4 v[194:195], off
	s_mov_b32 m0, s8
	v_readlane_b32 s46, v252, 22
	global_load_lds_dwordx4 v[146:147], off
	s_barrier
	s_waitcnt lgkmcnt(0)
	v_readlane_b32 s47, v252, 23
	v_readlane_b32 s48, v252, 24
	v_readlane_b32 s49, v252, 25
	v_readlane_b32 s52, v252, 28
	v_readlane_b32 s53, v252, 29
	v_readlane_b32 s54, v252, 30
	v_readlane_b32 s55, v252, 31
	v_readlane_b32 s56, v252, 32
	v_readlane_b32 s57, v252, 33
	v_readlane_b32 s58, v252, 34
	v_readlane_b32 s59, v252, 35

; #define LDA(dst, b, h) for (int m = 0; m < 4; ++m) for (int k = 0; k < 2; ++k) \
;     dst[m][k] = *reinterpret_cast<const bf16x8*>((char*)SA(b, h) + a_thr + (m * 2 + k) * 1024)
; #define LDB(dst, b, h) for (int n = 0; n < 2; ++n) for (int k = 0; k < 2; ++k) \
;     dst[n][k] = *reinterpret_cast<const bf16x8*>((char*)SB(b, h) + b_thr + (n * 2 + k) * 1024)
; #define MMA(ai, bj, At, Btf) do { __builtin_amdgcn_s_setprio(1); \
;     for (int m = 0; m < 4; ++m) for (int n = 0; n < 2; ++n) for (int k = 0; k < 2; ++k) \
;       acc[ai][bj][m][n] = __builtin_amdgcn_mfma_f32_16x16x32_bf16(Btf[n][k], At[m][k], acc[ai][bj][m][n], 0, 0, 0); \
;     __builtin_amdgcn_s_setprio(0); } while (0)
; #define WAIT_L(n) asm volatile("s_waitcnt lgkmcnt(" #n ")" ::: "memory")
; #define BAR __builtin_amdgcn_s_barrier()
; template <bool OVL, bool PANEL = false, class Epi>
; __device__ __forceinline__ void gemm_phase(const bf16_t* __restrict__ A, long lda, const bf16_t* __restrict__ Bt, long ldb, int nM, int nN, int K,
;                                            const Epi& epi, bf16_t* shm, int w0) {
;     ...
;     { LDB(B0, 0, 0); LDA(At, 0, 0); STAGE(SA(1, 1), A, lda, aoff, brow + HALF, nt - 1);
;       BAR; WAIT_L(0); MMA(0, 0, At, B0); BAR;
	s_waitcnt lgkmcnt(0)
	v_mfma_f32_16x16x32_bf16 v[126:129], v[142:145], v[162:165], v[126:129]
	v_mfma_f32_16x16x32_bf16 v[122:125], v[154:157], v[162:165], v[122:125]
	v_mfma_f32_16x16x32_bf16 v[118:121], v[142:145], v[170:173], v[118:121]
	v_mfma_f32_16x16x32_bf16 v[114:117], v[154:157], v[170:173], v[114:117]
	v_mfma_f32_16x16x32_bf16 v[110:113], v[142:145], v[178:181], v[110:113]
	v_mfma_f32_16x16x32_bf16 v[106:109], v[154:157], v[178:181], v[106:109]
	v_mfma_f32_16x16x32_bf16 v[98:101], v[154:157], v[186:189], v[98:101]
	v_mfma_f32_16x16x32_bf16 v[126:129], v[150:153], v[166:169], v[126:129]
	v_mfma_f32_16x16x32_bf16 v[122:125], v[158:161], v[166:169], v[122:125]
	v_mfma_f32_16x16x32_bf16 v[118:121], v[150:153], v[174:177], v[118:121]
	v_mfma_f32_16x16x32_bf16 v[114:117], v[158:161], v[174:177], v[114:117]
	v_mfma_f32_16x16x32_bf16 v[110:113], v[150:153], v[182:185], v[110:113]
	v_mfma_f32_16x16x32_bf16 v[106:109], v[158:161], v[182:185], v[106:109]
	v_mfma_f32_16x16x32_bf16 v[102:105], v[142:145], v[186:189], v[102:105]
	v_mfma_f32_16x16x32_bf16 v[98:101], v[158:161], v[190:193], v[98:101]
	v_mfma_f32_16x16x32_bf16 v[146:149], v[150:153], v[190:193], v[102:105]

; #define LDB(dst, b, h) for (int n = 0; n < 2; ++n) for (int k = 0; k < 2; ++k) \
;     dst[n][k] = *reinterpret_cast<const bf16x8*>((char*)SB(b, h) + b_thr + (n * 2 + k) * 1024)
; #define MMA(ai, bj, At, Btf) do { __builtin_amdgcn_s_setprio(1); \
;     for (int m = 0; m < 4; ++m) for (int n = 0; n < 2; ++n) for (int k = 0; k < 2; ++k) \
;       acc[ai][bj][m][n] = __builtin_amdgcn_mfma_f32_16x16x32_bf16(Btf[n][k], At[m][k], acc[ai][bj][m][n], 0, 0, 0); \
;     __builtin_amdgcn_s_setprio(0); } while (0)
; #define WAIT_L(n) asm volatile("s_waitcnt lgkmcnt(" #n ")" ::: "memory")
; #define BAR __builtin_amdgcn_s_barrier()
; template <bool OVL, bool PANEL = false, class Epi>
; __device__ __forceinline__ void gemm_phase(const bf16_t* __restrict__ A, long lda, const bf16_t* __restrict__ Bt, long ldb, int nM, int nN, int K,
;                                            const Epi& epi, bf16_t* shm, int w0) {
;     ...
;       LDB(B1, 0, 1); BAR; WAIT_L(0); MMA(0, 1, At, B1); BAR;
	v_add_u32_e32 v0, 0x14000, v214
	s_barrier
	s_nop 2
	ds_read_b128 v[102:105], v0
	ds_read_b128 v[194:197], v0 offset:1024
	ds_read_b128 v[198:201], v0 offset:2048
	ds_read_b128 v[202:205], v0 offset:3072
	s_barrier
	s_waitcnt lgkmcnt(0)

; #define LDB(dst, b, h) for (int n = 0; n < 2; ++n) for (int k = 0; k < 2; ++k) \
;     dst[n][k] = *reinterpret_cast<const bf16x8*>((char*)SB(b, h) + b_thr + (n * 2 + k) * 1024)
; #define MMA(ai, bj, At, Btf) do { __builtin_amdgcn_s_setprio(1); \
;     for (int m = 0; m < 4; ++m) for (int n = 0; n < 2; ++n) for (int k = 0; k < 2; ++k) \
;       acc[ai][bj][m][n] = __builtin_amdgcn_mfma_f32_16x16x32_bf16(Btf[n][k], At[m][k], acc[ai][bj][m][n], 0, 0, 0); \
;     __builtin_amdgcn_s_setprio(0); } while (0)
; #define WAIT_L(n) asm volatile("s_waitcnt lgkmcnt(" #n ")" ::: "memory")
; #define BAR __builtin_amdgcn_s_barrier()
; template <bool OVL, bool PANEL = false, class Epi>
; __device__ __forceinline__ void gemm_phase(const bf16_t* __restrict__ A, long lda, const bf16_t* __restrict__ Bt, long ldb, int nM, int nN, int K,
;                                            const Epi& epi, bf16_t* shm, int w0) {
;     ...
;       LDB(B1, 0, 1); BAR; WAIT_L(0); MMA(0, 1, At, B1); BAR;
	s_waitcnt lgkmcnt(0)
	v_mfma_f32_16x16x32_bf16 v[94:97], v[102:105], v[162:165], v[94:97]
	v_mfma_f32_16x16x32_bf16 v[86:89], v[102:105], v[170:173], v[86:89]
	v_mfma_f32_16x16x32_bf16 v[78:81], v[102:105], v[178:181], v[78:81]
	v_mfma_f32_16x16x32_bf16 v[74:77], v[198:201], v[178:181], v[74:77]
	v_mfma_f32_16x16x32_bf16 v[94:97], v[194:197], v[166:169], v[94:97]
	v_mfma_f32_16x16x32_bf16 v[90:93], v[198:201], v[162:165], v[90:93]
	v_mfma_f32_16x16x32_bf16 v[86:89], v[194:197], v[174:177], v[86:89]
	v_mfma_f32_16x16x32_bf16 v[82:85], v[198:201], v[170:173], v[82:85]
	v_mfma_f32_16x16x32_bf16 v[78:81], v[194:197], v[182:185], v[78:81]
	v_mfma_f32_16x16x32_bf16 v[74:77], v[202:205], v[182:185], v[74:77]
	v_mfma_f32_16x16x32_bf16 v[70:73], v[102:105], v[186:189], v[70:73]
	v_mfma_f32_16x16x32_bf16 v[66:69], v[198:201], v[186:189], v[66:69]
	v_mfma_f32_16x16x32_bf16 v[162:165], v[202:205], v[166:169], v[90:93]
	v_mfma_f32_16x16x32_bf16 v[166:169], v[202:205], v[174:177], v[82:85]
	v_mfma_f32_16x16x32_bf16 v[170:173], v[194:197], v[190:193], v[70:73]
	v_mfma_f32_16x16x32_bf16 v[174:177], v[202:205], v[190:193], v[66:69]

; #define LDA(dst, b, h) for (int m = 0; m < 4; ++m) for (int k = 0; k < 2; ++k) \
;     dst[m][k] = *reinterpret_cast<const bf16x8*>((char*)SA(b, h) + a_thr + (m * 2 + k) * 1024)
; #define MMA(ai, bj, At, Btf) do { __builtin_amdgcn_s_setprio(1); \
;     for (int m = 0; m < 4; ++m) for (int n = 0; n < 2; ++n) for (int k = 0; k < 2; ++k) \
;       acc[ai][bj][m][n] = __builtin_amdgcn_mfma_f32_16x16x32_bf16(Btf[n][k], At[m][k], acc[ai][bj][m][n], 0, 0, 0); \
;     __builtin_amdgcn_s_setprio(0); } while (0)
; #define WAIT_V(n) asm volatile("s_waitcnt vmcnt(" #n ")" ::: "memory")
; #define WAIT_L(n) asm volatile("s_waitcnt lgkmcnt(" #n ")" ::: "memory")
; #define BAR __builtin_amdgcn_s_barrier()
; template <bool OVL, bool PANEL = false, class Epi>
; __device__ __forceinline__ void gemm_phase(const bf16_t* __restrict__ A, long lda, const bf16_t* __restrict__ Bt, long ldb, int nM, int nN, int K,
;                                            const Epi& epi, bf16_t* shm, int w0) {
;     ...
;       LDA(At, 0, 1); WAIT_V(4); BAR; WAIT_L(0); MMA(1, 0, At, B0); MMA(1, 1, At, B1); BAR; }
	s_barrier
	s_nop 1
	ds_read_b128 v[66:69], v141 offset:16384
	ds_read_b128 v[70:73], v141 offset:17408
	ds_read_b128 v[82:85], v141 offset:18432
	ds_read_b128 v[90:93], v141 offset:19456
	ds_read_b128 v[178:181], v141 offset:20480
	ds_read_b128 v[182:185], v141 offset:21504
	ds_read_b128 v[186:189], v141 offset:22528
	ds_read_b128 v[190:193], v141 offset:23552
	s_waitcnt vmcnt(4)
	s_barrier
	s_waitcnt lgkmcnt(0)

; #define LDA(dst, b, h) for (int m = 0; m < 4; ++m) for (int k = 0; k < 2; ++k) \
;     dst[m][k] = *reinterpret_cast<const bf16x8*>((char*)SA(b, h) + a_thr + (m * 2 + k) * 1024)
; #define MMA(ai, bj, At, Btf) do { __builtin_amdgcn_s_setprio(1); \
;     for (int m = 0; m < 4; ++m) for (int n = 0; n < 2; ++n) for (int k = 0; k < 2; ++k) \
;       acc[ai][bj][m][n] = __builtin_amdgcn_mfma_f32_16x16x32_bf16(Btf[n][k], At[m][k], acc[ai][bj][m][n], 0, 0, 0); \
;     __builtin_amdgcn_s_setprio(0); } while (0)
; #define WAIT_V(n) asm volatile("s_waitcnt vmcnt(" #n ")" ::: "memory")
; #define WAIT_L(n) asm volatile("s_waitcnt lgkmcnt(" #n ")" ::: "memory")
; #define BAR __builtin_amdgcn_s_barrier()
; template <bool OVL, bool PANEL = false, class Epi>
; __device__ __forceinline__ void gemm_phase(const bf16_t* __restrict__ A, long lda, const bf16_t* __restrict__ Bt, long ldb, int nM, int nN, int K,
;                                            const Epi& epi, bf16_t* shm, int w0) {
;     ...
;       LDA(At, 0, 1); WAIT_V(4); BAR; WAIT_L(0); MMA(1, 0, At, B0); MMA(1, 1, At, B1); BAR; }
	s_waitcnt lgkmcnt(0)
	v_mfma_f32_16x16x32_bf16 v[62:65], v[142:145], v[66:69], v[62:65]
	v_mfma_f32_16x16x32_bf16 v[54:57], v[142:145], v[82:85], v[54:57]
	v_mfma_f32_16x16x32_bf16 v[46:49], v[142:145], v[178:181], v[46:49]
	v_mfma_f32_16x16x32_bf16 v[42:45], v[154:157], v[178:181], v[42:45]
	v_mfma_f32_16x16x32_bf16 v[38:41], v[142:145], v[186:189], v[38:41]
	v_mfma_f32_16x16x32_bf16 v[34:37], v[154:157], v[186:189], v[34:37]
	v_mfma_f32_16x16x32_bf16 v[62:65], v[150:153], v[70:73], v[62:65]
	v_mfma_f32_16x16x32_bf16 v[58:61], v[154:157], v[66:69], v[58:61]
	v_mfma_f32_16x16x32_bf16 v[54:57], v[150:153], v[90:93], v[54:57]
	v_mfma_f32_16x16x32_bf16 v[50:53], v[154:157], v[82:85], v[50:53]
	v_mfma_f32_16x16x32_bf16 v[46:49], v[150:153], v[182:185], v[46:49]
	v_mfma_f32_16x16x32_bf16 v[42:45], v[158:161], v[182:185], v[42:45]
	v_mfma_f32_16x16x32_bf16 v[38:41], v[150:153], v[190:193], v[38:41]
	v_mfma_f32_16x16x32_bf16 v[34:37], v[158:161], v[190:193], v[34:37]
	v_mfma_f32_16x16x32_bf16 v[206:209], v[158:161], v[70:73], v[58:61]
	v_mfma_f32_16x16x32_bf16 v[210:213], v[158:161], v[90:93], v[50:53]


; #define LDA(dst, b, h) for (int m = 0; m < 4; ++m) for (int k = 0; k < 2; ++k) \
;     dst[m][k] = *reinterpret_cast<const bf16x8*>((char*)SA(b, h) + a_thr + (m * 2 + k) * 1024)
; #define MMA(ai, bj, At, Btf) do { __builtin_amdgcn_s_setprio(1); \
;     for (int m = 0; m < 4; ++m) for (int n = 0; n < 2; ++n) for (int k = 0; k < 2; ++k) \
;       acc[ai][bj][m][n] = __builtin_amdgcn_mfma_f32_16x16x32_bf16(Btf[n][k], At[m][k], acc[ai][bj][m][n], 0, 0, 0); \
;     __builtin_amdgcn_s_setprio(0); } while (0)
; #define WAIT_V(n) asm volatile("s_waitcnt vmcnt(" #n ")" ::: "memory")
; #define WAIT_L(n) asm volatile("s_waitcnt lgkmcnt(" #n ")" ::: "memory")
; #define BAR __builtin_amdgcn_s_barrier()
; template <bool OVL, bool PANEL = false, class Epi>
; __device__ __forceinline__ void gemm_phase(const bf16_t* __restrict__ A, long lda, const bf16_t* __restrict__ Bt, long ldb, int nM, int nN, int K,
;                                            const Epi& epi, bf16_t* shm, int w0) {
;     ...
;       LDA(At, 0, 1); WAIT_V(4); BAR; WAIT_L(0); MMA(1, 0, At, B0); MMA(1, 1, At, B1); BAR; }
	v_mfma_f32_16x16x32_bf16 v[30:33], v[102:105], v[66:69], v[30:33]
	v_mfma_f32_16x16x32_bf16 v[26:29], v[198:201], v[66:69], v[26:29]
	v_mfma_f32_16x16x32_bf16 v[22:25], v[102:105], v[82:85], v[22:25]
	v_mfma_f32_16x16x32_bf16 v[18:21], v[198:201], v[82:85], v[18:21]
	v_mfma_f32_16x16x32_bf16 v[14:17], v[102:105], v[178:181], v[14:17]
	v_mfma_f32_16x16x32_bf16 v[10:13], v[198:201], v[178:181], v[10:13]
	v_mfma_f32_16x16x32_bf16 v[6:9], v[102:105], v[186:189], v[6:9]
	v_mfma_f32_16x16x32_bf16 v[2:5], v[198:201], v[186:189], v[2:5]
	v_mfma_f32_16x16x32_bf16 v[30:33], v[194:197], v[70:73], v[30:33]
	v_mfma_f32_16x16x32_bf16 v[26:29], v[202:205], v[70:73], v[26:29]
	v_mfma_f32_16x16x32_bf16 v[22:25], v[194:197], v[90:93], v[22:25]
	v_mfma_f32_16x16x32_bf16 v[18:21], v[202:205], v[90:93], v[18:21]
	v_mfma_f32_16x16x32_bf16 v[14:17], v[194:197], v[182:185], v[14:17]
	v_mfma_f32_16x16x32_bf16 v[10:13], v[202:205], v[182:185], v[10:13]
	v_mfma_f32_16x16x32_bf16 v[6:9], v[194:197], v[190:193], v[6:9]
	v_mfma_f32_16x16x32_bf16 v[2:5], v[202:205], v[190:193], v[2:5]

; #define LDA(dst, b, h) for (int m = 0; m < 4; ++m) for (int k = 0; k < 2; ++k) \
;     dst[m][k] = *reinterpret_cast<const bf16x8*>((char*)SA(b, h) + a_thr + (m * 2 + k) * 1024)
; #define LDB(dst, b, h) for (int n = 0; n < 2; ++n) for (int k = 0; k < 2; ++k) \
;     dst[n][k] = *reinterpret_cast<const bf16x8*>((char*)SB(b, h) + b_thr + (n * 2 + k) * 1024)
; #define MMA(ai, bj, At, Btf) do { __builtin_amdgcn_s_setprio(1); \
;     for (int m = 0; m < 4; ++m) for (int n = 0; n < 2; ++n) for (int k = 0; k < 2; ++k) \
;       acc[ai][bj][m][n] = __builtin_amdgcn_mfma_f32_16x16x32_bf16(Btf[n][k], At[m][k], acc[ai][bj][m][n], 0, 0, 0); \
;     __builtin_amdgcn_s_setprio(0); } while (0)
; #define WAIT_V(n) asm volatile("s_waitcnt vmcnt(" #n ")" ::: "memory")
; #define WAIT_L(n) asm volatile("s_waitcnt lgkmcnt(" #n ")" ::: "memory")
; #define BAR __builtin_amdgcn_s_barrier()
; template <bool OVL, bool PANEL = false, class Epi>
; __device__ __forceinline__ void gemm_phase(const bf16_t* __restrict__ A, long lda, const bf16_t* __restrict__ Bt, long ldb, int nM, int nN, int K,
;                                            const Epi& epi, bf16_t* shm, int w0) {
;     ...
;     { LDB(B0, 1, 0); LDA(At, 1, 0); WAIT_V(2); BAR; WAIT_L(0); MMA(0, 0, At, B0); BAR;
	v_add_u32_e32 v0, 0x18000, v214
	s_barrier
	ds_read_b128 v[142:145], v0
	ds_read_b128 v[150:153], v0 offset:1024
	ds_read_b128 v[154:157], v0 offset:2048
	ds_read_b128 v[158:161], v0 offset:3072
	ds_read_b128 v[50:53], v141 offset:32768
	ds_read_b128 v[58:61], v141 offset:33792
	ds_read_b128 v[66:69], v141 offset:34816
	ds_read_b128 v[70:73], v141 offset:35840
	ds_read_b128 v[178:181], v141 offset:36864
	ds_read_b128 v[182:185], v141 offset:37888
	ds_read_b128 v[186:189], v141 offset:38912
	ds_read_b128 v[190:193], v141 offset:39936
	s_waitcnt vmcnt(2)
	s_barrier
	s_waitcnt lgkmcnt(0)

; #define LDA(dst, b, h) for (int m = 0; m < 4; ++m) for (int k = 0; k < 2; ++k) \
;     dst[m][k] = *reinterpret_cast<const bf16x8*>((char*)SA(b, h) + a_thr + (m * 2 + k) * 1024)
; #define LDB(dst, b, h) for (int n = 0; n < 2; ++n) for (int k = 0; k < 2; ++k) \
;     dst[n][k] = *reinterpret_cast<const bf16x8*>((char*)SB(b, h) + b_thr + (n * 2 + k) * 1024)
; #define MMA(ai, bj, At, Btf) do { __builtin_amdgcn_s_setprio(1); \
;     for (int m = 0; m < 4; ++m) for (int n = 0; n < 2; ++n) for (int k = 0; k < 2; ++k) \
;       acc[ai][bj][m][n] = __builtin_amdgcn_mfma_f32_16x16x32_bf16(Btf[n][k], At[m][k], acc[ai][bj][m][n], 0, 0, 0); \
;     __builtin_amdgcn_s_setprio(0); } while (0)
; #define WAIT_V(n) asm volatile("s_waitcnt vmcnt(" #n ")" ::: "memory")
; #define WAIT_L(n) asm volatile("s_waitcnt lgkmcnt(" #n ")" ::: "memory")
; #define BAR __builtin_amdgcn_s_barrier()
; template <bool OVL, bool PANEL = false, class Epi>
; __device__ __forceinline__ void gemm_phase(const bf16_t* __restrict__ A, long lda, const bf16_t* __restrict__ Bt, long ldb, int nM, int nN, int K,
;                                            const Epi& epi, bf16_t* shm, int w0) {
;     ...
;     { LDB(B0, 1, 0); LDA(At, 1, 0); WAIT_V(2); BAR; WAIT_L(0); MMA(0, 0, At, B0); BAR;
	s_waitcnt lgkmcnt(0)
	v_mfma_f32_16x16x32_bf16 v[82:85], v[142:145], v[50:53], v[126:129]
	v_mfma_f32_16x16x32_bf16 v[126:129], v[150:153], v[58:61], v[82:85]
	v_mfma_f32_16x16x32_bf16 v[82:85], v[154:157], v[50:53], v[122:125]
	v_mfma_f32_16x16x32_bf16 v[122:125], v[158:161], v[58:61], v[82:85]
	v_mfma_f32_16x16x32_bf16 v[82:85], v[142:145], v[66:69], v[118:121]
	v_mfma_f32_16x16x32_bf16 v[118:121], v[150:153], v[70:73], v[82:85]
	v_mfma_f32_16x16x32_bf16 v[82:85], v[154:157], v[66:69], v[114:117]
	v_mfma_f32_16x16x32_bf16 v[114:117], v[158:161], v[70:73], v[82:85]
	v_mfma_f32_16x16x32_bf16 v[82:85], v[142:145], v[178:181], v[110:113]
	v_mfma_f32_16x16x32_bf16 v[110:113], v[150:153], v[182:185], v[82:85]
	v_mfma_f32_16x16x32_bf16 v[82:85], v[154:157], v[178:181], v[106:109]
	v_mfma_f32_16x16x32_bf16 v[102:105], v[158:161], v[182:185], v[82:85]
	v_mfma_f32_16x16x32_bf16 v[82:85], v[142:145], v[186:189], v[146:149]
	v_mfma_f32_16x16x32_bf16 v[90:93], v[150:153], v[190:193], v[82:85]
	v_mfma_f32_16x16x32_bf16 v[82:85], v[154:157], v[186:189], v[98:101]
	v_mfma_f32_16x16x32_bf16 v[82:85], v[158:161], v[190:193], v[82:85]

; #define LDB(dst, b, h) for (int n = 0; n < 2; ++n) for (int k = 0; k < 2; ++k) \
;     dst[n][k] = *reinterpret_cast<const bf16x8*>((char*)SB(b, h) + b_thr + (n * 2 + k) * 1024)
; #define MMA(ai, bj, At, Btf) do { __builtin_amdgcn_s_setprio(1); \
;     for (int m = 0; m < 4; ++m) for (int n = 0; n < 2; ++n) for (int k = 0; k < 2; ++k) \
;       acc[ai][bj][m][n] = __builtin_amdgcn_mfma_f32_16x16x32_bf16(Btf[n][k], At[m][k], acc[ai][bj][m][n], 0, 0, 0); \
;     __builtin_amdgcn_s_setprio(0); } while (0)
; #define WAIT_V(n) asm volatile("s_waitcnt vmcnt(" #n ")" ::: "memory")
; #define WAIT_L(n) asm volatile("s_waitcnt lgkmcnt(" #n ")" ::: "memory")
; #define BAR __builtin_amdgcn_s_barrier()
; template <bool OVL, bool PANEL = false, class Epi>
; __device__ __forceinline__ void gemm_phase(const bf16_t* __restrict__ A, long lda, const bf16_t* __restrict__ Bt, long ldb, int nM, int nN, int K,
;                                            const Epi& epi, bf16_t* shm, int w0) {
;     ...
;       LDB(B1, 1, 1); WAIT_V(0); BAR; WAIT_L(0); MMA(0, 1, At, B1); BAR;
	v_add_u32_e32 v0, 0x1c000, v214
	s_barrier
	ds_read_b128 v[146:149], v0
	ds_read_b128 v[194:197], v0 offset:1024
	ds_read_b128 v[198:201], v0 offset:2048
	ds_read_b128 v[202:205], v0 offset:3072
	s_waitcnt vmcnt(0)
	s_barrier
	s_waitcnt lgkmcnt(0)

; #define LDB(dst, b, h) for (int n = 0; n < 2; ++n) for (int k = 0; k < 2; ++k) \
;     dst[n][k] = *reinterpret_cast<const bf16x8*>((char*)SB(b, h) + b_thr + (n * 2 + k) * 1024)
; #define MMA(ai, bj, At, Btf) do { __builtin_amdgcn_s_setprio(1); \
;     for (int m = 0; m < 4; ++m) for (int n = 0; n < 2; ++n) for (int k = 0; k < 2; ++k) \
;       acc[ai][bj][m][n] = __builtin_amdgcn_mfma_f32_16x16x32_bf16(Btf[n][k], At[m][k], acc[ai][bj][m][n], 0, 0, 0); \
;     __builtin_amdgcn_s_setprio(0); } while (0)
; #define WAIT_V(n) asm volatile("s_waitcnt vmcnt(" #n ")" ::: "memory")
; #define WAIT_L(n) asm volatile("s_waitcnt lgkmcnt(" #n ")" ::: "memory")
; #define BAR __builtin_amdgcn_s_barrier()
; template <bool OVL, bool PANEL = false, class Epi>
; __device__ __forceinline__ void gemm_phase(const bf16_t* __restrict__ A, long lda, const bf16_t* __restrict__ Bt, long ldb, int nM, int nN, int K,
;                                            const Epi& epi, bf16_t* shm, int w0) {
;     ...
;       LDB(B1, 1, 1); WAIT_V(0); BAR; WAIT_L(0); MMA(0, 1, At, B1); BAR;
	s_waitcnt lgkmcnt(0)
	v_mfma_f32_16x16x32_bf16 v[94:97], v[146:149], v[50:53], v[94:97]
	v_mfma_f32_16x16x32_bf16 v[50:53], v[198:201], v[50:53], v[162:165]
	v_mfma_f32_16x16x32_bf16 v[98:101], v[202:205], v[58:61], v[50:53]
	v_mfma_f32_16x16x32_bf16 v[50:53], v[146:149], v[66:69], v[86:89]
	v_mfma_f32_16x16x32_bf16 v[106:109], v[194:197], v[58:61], v[94:97]
	v_mfma_f32_16x16x32_bf16 v[94:97], v[194:197], v[70:73], v[50:53]
	v_mfma_f32_16x16x32_bf16 v[50:53], v[198:201], v[66:69], v[166:169]
	v_mfma_f32_16x16x32_bf16 v[86:89], v[202:205], v[70:73], v[50:53]
	v_mfma_f32_16x16x32_bf16 v[50:53], v[146:149], v[178:181], v[78:81]
	v_mfma_f32_16x16x32_bf16 v[70:73], v[194:197], v[182:185], v[50:53]
	v_mfma_f32_16x16x32_bf16 v[50:53], v[198:201], v[178:181], v[74:77]
	v_mfma_f32_16x16x32_bf16 v[66:69], v[202:205], v[182:185], v[50:53]
	v_mfma_f32_16x16x32_bf16 v[50:53], v[146:149], v[186:189], v[170:173]
	v_mfma_f32_16x16x32_bf16 v[58:61], v[194:197], v[190:193], v[50:53]
	v_mfma_f32_16x16x32_bf16 v[50:53], v[198:201], v[186:189], v[174:177]
	v_mfma_f32_16x16x32_bf16 v[50:53], v[202:205], v[190:193], v[50:53]

; #define LDA(dst, b, h) for (int m = 0; m < 4; ++m) for (int k = 0; k < 2; ++k) \
;     dst[m][k] = *reinterpret_cast<const bf16x8*>((char*)SA(b, h) + a_thr + (m * 2 + k) * 1024)
; #define MMA(ai, bj, At, Btf) do { __builtin_amdgcn_s_setprio(1); \
;     for (int m = 0; m < 4; ++m) for (int n = 0; n < 2; ++n) for (int k = 0; k < 2; ++k) \
;       acc[ai][bj][m][n] = __builtin_amdgcn_mfma_f32_16x16x32_bf16(Btf[n][k], At[m][k], acc[ai][bj][m][n], 0, 0, 0); \
;     __builtin_amdgcn_s_setprio(0); } while (0)
; #define WAIT_L(n) asm volatile("s_waitcnt lgkmcnt(" #n ")" ::: "memory")
; #define BAR __builtin_amdgcn_s_barrier()
; template <bool OVL, bool PANEL = false, class Epi>
; __device__ __forceinline__ void gemm_phase(const bf16_t* __restrict__ A, long lda, const bf16_t* __restrict__ Bt, long ldb, int nM, int nN, int K,
;                                            const Epi& epi, bf16_t* shm, int w0) {
;     ...
;       LDA(At, 1, 1); BAR; WAIT_L(0); MMA(1, 0, At, B0); MMA(1, 1, At, B1); BAR; }
	s_barrier
	ds_read_b128 v[162:165], v141 offset:49152
	ds_read_b128 v[166:169], v141 offset:50176
	ds_read_b128 v[170:173], v141 offset:51200
	ds_read_b128 v[174:177], v141 offset:52224
	ds_read_b128 v[178:181], v141 offset:53248
	ds_read_b128 v[182:185], v141 offset:54272
	ds_read_b128 v[186:189], v141 offset:55296
	ds_read_b128 v[190:193], v141 offset:56320
	s_barrier
	s_waitcnt lgkmcnt(0)

; #define LDA(dst, b, h) for (int m = 0; m < 4; ++m) for (int k = 0; k < 2; ++k) \
;     dst[m][k] = *reinterpret_cast<const bf16x8*>((char*)SA(b, h) + a_thr + (m * 2 + k) * 1024)
; #define MMA(ai, bj, At, Btf) do { __builtin_amdgcn_s_setprio(1); \
;     for (int m = 0; m < 4; ++m) for (int n = 0; n < 2; ++n) for (int k = 0; k < 2; ++k) \
;       acc[ai][bj][m][n] = __builtin_amdgcn_mfma_f32_16x16x32_bf16(Btf[n][k], At[m][k], acc[ai][bj][m][n], 0, 0, 0); \
;     __builtin_amdgcn_s_setprio(0); } while (0)
; #define WAIT_L(n) asm volatile("s_waitcnt lgkmcnt(" #n ")" ::: "memory")
; #define BAR __builtin_amdgcn_s_barrier()
; template <bool OVL, bool PANEL = false, class Epi>
; __device__ __forceinline__ void gemm_phase(const bf16_t* __restrict__ A, long lda, const bf16_t* __restrict__ Bt, long ldb, int nM, int nN, int K,
;                                            const Epi& epi, bf16_t* shm, int w0) {
;     ...
;       LDA(At, 1, 1); BAR; WAIT_L(0); MMA(1, 0, At, B0); MMA(1, 1, At, B1); BAR; }
	s_waitcnt lgkmcnt(0)
	v_mfma_f32_16x16x32_bf16 v[62:65], v[142:145], v[162:165], v[62:65]
	v_mfma_f32_16x16x32_bf16 v[78:81], v[150:153], v[166:169], v[62:65]
	v_mfma_f32_16x16x32_bf16 v[62:65], v[154:157], v[162:165], v[206:209]
	v_mfma_f32_16x16x32_bf16 v[54:57], v[142:145], v[170:173], v[54:57]
	v_mfma_f32_16x16x32_bf16 v[74:77], v[158:161], v[166:169], v[62:65]
	v_mfma_f32_16x16x32_bf16 v[62:65], v[150:153], v[174:177], v[54:57]
	v_mfma_f32_16x16x32_bf16 v[54:57], v[154:157], v[170:173], v[210:213]
	v_mfma_f32_16x16x32_bf16 v[46:49], v[142:145], v[178:181], v[46:49]
	v_mfma_f32_16x16x32_bf16 v[42:45], v[154:157], v[178:181], v[42:45]
	v_mfma_f32_16x16x32_bf16 v[38:41], v[142:145], v[186:189], v[38:41]
	v_mfma_f32_16x16x32_bf16 v[34:37], v[154:157], v[186:189], v[34:37]
	v_mfma_f32_16x16x32_bf16 v[54:57], v[158:161], v[174:177], v[54:57]
	v_mfma_f32_16x16x32_bf16 v[46:49], v[150:153], v[182:185], v[46:49]
	v_mfma_f32_16x16x32_bf16 v[42:45], v[158:161], v[182:185], v[42:45]
	v_mfma_f32_16x16x32_bf16 v[38:41], v[150:153], v[190:193], v[38:41]
	v_mfma_f32_16x16x32_bf16 v[34:37], v[158:161], v[190:193], v[34:37]


; #define LDA(dst, b, h) for (int m = 0; m < 4; ++m) for (int k = 0; k < 2; ++k) \
;     dst[m][k] = *reinterpret_cast<const bf16x8*>((char*)SA(b, h) + a_thr + (m * 2 + k) * 1024)
; #define MMA(ai, bj, At, Btf) do { __builtin_amdgcn_s_setprio(1); \
;     for (int m = 0; m < 4; ++m) for (int n = 0; n < 2; ++n) for (int k = 0; k < 2; ++k) \
;       acc[ai][bj][m][n] = __builtin_amdgcn_mfma_f32_16x16x32_bf16(Btf[n][k], At[m][k], acc[ai][bj][m][n], 0, 0, 0); \
;     __builtin_amdgcn_s_setprio(0); } while (0)
; #define WAIT_L(n) asm volatile("s_waitcnt lgkmcnt(" #n ")" ::: "memory")
; #define BAR __builtin_amdgcn_s_barrier()
; template <bool OVL, bool PANEL = false, class Epi>
; __device__ __forceinline__ void gemm_phase(const bf16_t* __restrict__ A, long lda, const bf16_t* __restrict__ Bt, long ldb, int nM, int nN, int K,
;                                            const Epi& epi, bf16_t* shm, int w0) {
;     ...
;       LDA(At, 1, 1); BAR; WAIT_L(0); MMA(1, 0, At, B0); MMA(1, 1, At, B1); BAR; }
	v_mfma_f32_16x16x32_bf16 v[30:33], v[146:149], v[162:165], v[30:33]
	v_mfma_f32_16x16x32_bf16 v[26:29], v[198:201], v[162:165], v[26:29]
	v_mfma_f32_16x16x32_bf16 v[22:25], v[146:149], v[170:173], v[22:25]
	v_mfma_f32_16x16x32_bf16 v[18:21], v[198:201], v[170:173], v[18:21]
	v_mfma_f32_16x16x32_bf16 v[14:17], v[146:149], v[178:181], v[14:17]
	v_mfma_f32_16x16x32_bf16 v[10:13], v[198:201], v[178:181], v[10:13]
	v_mfma_f32_16x16x32_bf16 v[6:9], v[146:149], v[186:189], v[6:9]
	v_mfma_f32_16x16x32_bf16 v[2:5], v[198:201], v[186:189], v[2:5]
	v_mfma_f32_16x16x32_bf16 v[30:33], v[194:197], v[166:169], v[30:33]
	v_mfma_f32_16x16x32_bf16 v[26:29], v[202:205], v[166:169], v[26:29]
	v_mfma_f32_16x16x32_bf16 v[22:25], v[194:197], v[174:177], v[22:25]
	v_mfma_f32_16x16x32_bf16 v[18:21], v[202:205], v[174:177], v[18:21]
	v_mfma_f32_16x16x32_bf16 v[14:17], v[194:197], v[182:185], v[14:17]
	v_mfma_f32_16x16x32_bf16 v[10:13], v[202:205], v[182:185], v[10:13]
	v_mfma_f32_16x16x32_bf16 v[6:9], v[194:197], v[190:193], v[6:9]
	v_mfma_f32_16x16x32_bf16 v[2:5], v[202:205], v[190:193], v[2:5]

; #define LDA(dst, b, h) for (int m = 0; m < 4; ++m) for (int k = 0; k < 2; ++k) \
;     dst[m][k] = *reinterpret_cast<const bf16x8*>((char*)SA(b, h) + a_thr + (m * 2 + k) * 1024)
; #define MMA(ai, bj, At, Btf) do { __builtin_amdgcn_s_setprio(1); \
;     for (int m = 0; m < 4; ++m) for (int n = 0; n < 2; ++n) for (int k = 0; k < 2; ++k) \
;       acc[ai][bj][m][n] = __builtin_amdgcn_mfma_f32_16x16x32_bf16(Btf[n][k], At[m][k], acc[ai][bj][m][n], 0, 0, 0); \
;     __builtin_amdgcn_s_setprio(0); } while (0)
; #define WAIT_L(n) asm volatile("s_waitcnt lgkmcnt(" #n ")" ::: "memory")
; #define BAR __builtin_amdgcn_s_barrier()
; template <bool OVL, bool PANEL = false, class Epi>
; __device__ __forceinline__ void gemm_phase(const bf16_t* __restrict__ A, long lda, const bf16_t* __restrict__ Bt, long ldb, int nM, int nN, int K,
;                                            const Epi& epi, bf16_t* shm, int w0) {
;     ...
;       LDA(At, 1, 1); BAR; WAIT_L(0); MMA(1, 0, At, B0); MMA(1, 1, At, B1); BAR; }
;     if (wr == 0) BAR;
	s_barrier
	s_and_saveexec_b64 s[8:9], s[78:79]
	s_cbranch_execz .LBB0_389
	s_barrier

; __device__ __forceinline__ unsigned pk2(float lo, float hi) { const f2_t v = {lo, hi}; return __builtin_bit_cast(unsigned, __builtin_convertvector(v, bf2_t)); }
;   __device__ __forceinline__ void operator()(const f32x4 (&acc)[2][2][4][2], int pm, int pn, int wr_, int wc_, int fr_, int fq_, bf16_t* shm, int tid) const {
;     bf16_t* Us = shm;
;     const int wr = tid >> 8, wc = (tid >> 6) & 3, fr = tid & 15, fq = (tid >> 4) & 3;
; #pragma unroll
;     for (int ai = 0; ai < 2; ++ai)
; #pragma unroll
;       for (int bj = 0; bj < 2; ++bj)
; #pragma unroll
;         for (int m = 0; m < 4; ++m)
; #pragma unroll
;           for (int n = 0; n < 2; ++n) {
;             const f32x4 v = acc[ai][bj][m][n];
;             u32x2 w; w.x = pk2(v[0], v[1]); w.y = pk2(v[2], v[3]);
;             *(u32x2*)(Us + (ai * 128 + wr * 64 + m * 16 + fr + 1) * USTR + bj * 128 + wc * 32 + n * 16 + fq * 4) = w;
;           }
;     if (tid < 64) {
;       const int after = tid >> 5, c = (tid & 31) * 8;
;       u32x4 hv = {0, 0, 0, 0};
;       if (pm < 256) {
;         if (!after && (pm & 7) != 0) hv = *(const u32x4*)(HU + (long)((pm - 1) * 2 + 1) * 5632 + pn * 256 + c);
;         if (after && ((pm + 1) & 7) != 0) hv = *(const u32x4*)(HU + (long)((pm + 1) * 2) * 5632 + pn * 256 + c);
;       }
;       *(u32x4*)(Us + (after ? 257 : 0) * USTR + c) = hv;
;     }
;     __syncthreads();
;     {
;       const int cg = tid & 15, rs = tid >> 4, f0 = pn * 128 + cg * 8;
;       float wa[3][8], wg[3][8], ba[8], bg[8];
; #pragma unroll
;       for (int t = 0; t < 3; ++t)
; #pragma unroll
;         for (int e = 0; e < 8; e += 4) {
;           const f32x4 x = *(const f32x4*)(cw + t * 5632 + f0 + e), y = *(const f32x4*)(cw + t * 5632 + 2816 + f0 + e);
;           wa[t][e] = x[0]; wa[t][e + 1] = x[1]; wa[t][e + 2] = x[2]; wa[t][e + 3] = x[3];
;           wg[t][e] = y[0]; wg[t][e + 1] = y[1]; wg[t][e + 2] = y[2]; wg[t][e + 3] = y[3];
;         }
; #pragma unroll
;       for (int e = 0; e < 8; e += 4) {
;         const f32x4 x = *(const f32x4*)(cb + f0 + e), y = *(const f32x4*)(cb + 2816 + f0 + e);
;         ba[e] = x[0]; ba[e + 1] = x[1]; ba[e + 2] = x[2]; ba[e + 3] = x[3]; bg[e] = y[0]; bg[e + 1] = y[1]; bg[e + 2] = y[2]; bg[e + 3] = y[3];
;       }
.LBB0_391:
	v_readlane_b32 s10, v250, 0
	s_nop 15
	s_nop 15
	v_mbcnt_lo_u32_b32 v144, -1, 0
	v_mbcnt_hi_u32_b32 v144, -1, v144
	v_cvt_pk_bf16_f32 v90, v90, v91
	v_and_b32_e32 v0, 15, v144
	v_add_u32_e32 v143, s10, v144
	v_lshrrev_b32_e32 v145, 2, v143
	s_mov_b32 s10, 0xfffffc0
	v_ashrrev_i32_e32 v142, 4, v143
	v_and_or_b32 v145, v145, s10, v0
	s_movk_i32 s10, 0x210
	v_mul_lo_u32 v145, v145, s10
	v_lshlrev_b32_e32 v147, 3, v142
	v_add_u32_e32 v145, 16, v145
	v_and_b32_e32 v146, 0xc0, v143
	v_and_b32_e32 v147, 24, v147
	v_add3_u32 v145, v145, v146, v147
	v_cvt_pk_bf16_f32 v91, v92, v93
	v_add_u32_e32 v92, 0x6000, v145
	v_cvt_pk_bf16_f32 v58, v58, v59
	v_cvt_pk_bf16_f32 v59, v60, v61
	v_cvt_pk_bf16_f32 v50, v50, v51
	v_cvt_pk_bf16_f32 v51, v52, v53
	ds_write2_b64 v92, v[58:59], v[50:51] offset0:194 offset1:198
	v_add_u32_e32 v58, 0x10a10, v145
	v_cvt_pk_bf16_f32 v50, v78, v79
	v_cvt_pk_bf16_f32 v51, v80, v81
	v_cvt_pk_bf16_f32 v52, v74, v75
	v_cvt_pk_bf16_f32 v53, v76, v77
	ds_write2_b64 v58, v[50:51], v[52:53] offset1:4
	v_add_u32_e32 v58, 0x12b10, v145
	v_cvt_pk_bf16_f32 v50, v62, v63
	v_cvt_pk_bf16_f32 v51, v64, v65
	v_cvt_pk_bf16_f32 v52, v54, v55
	v_cvt_pk_bf16_f32 v53, v56, v57
	ds_write2_b64 v58, v[50:51], v[52:53] offset1:4
	v_add_u32_e32 v50, 0x14c10, v145
	v_cvt_pk_bf16_f32 v46, v46, v47
	v_cvt_pk_bf16_f32 v47, v48, v49
	v_cvt_pk_bf16_f32 v42, v42, v43
	v_cvt_pk_bf16_f32 v43, v44, v45
	ds_write2_b64 v50, v[46:47], v[42:43] offset1:4
	v_add_u32_e32 v42, 0x16d10, v145
	v_cvt_pk_bf16_f32 v38, v38, v39
	v_cvt_pk_bf16_f32 v39, v40, v41
	v_cvt_pk_bf16_f32 v34, v34, v35
	v_cvt_pk_bf16_f32 v35, v36, v37
	ds_write2_b64 v42, v[38:39], v[34:35] offset1:4
	v_add_u32_e32 v34, 0x10b10, v145
	v_cvt_pk_bf16_f32 v30, v30, v31
	v_cvt_pk_bf16_f32 v31, v32, v33
	v_cvt_pk_bf16_f32 v26, v26, v27
	v_cvt_pk_bf16_f32 v27, v28, v29
	v_cvt_pk_bf16_f32 v82, v82, v83
	v_cvt_pk_bf16_f32 v83, v84, v85
	ds_write2_b64 v34, v[30:31], v[26:27] offset1:4
	v_add_u32_e32 v26, 0x12c10, v145
	v_cvt_pk_bf16_f32 v22, v22, v23
	v_cvt_pk_bf16_f32 v23, v24, v25
	v_cvt_pk_bf16_f32 v18, v18, v19
	v_cvt_pk_bf16_f32 v19, v20, v21
	ds_write2_b64 v92, v[90:91], v[82:83] offset0:162 offset1:166
	v_cvt_pk_bf16_f32 v82, v106, v107
	v_cvt_pk_bf16_f32 v83, v108, v109
	v_cvt_pk_bf16_f32 v84, v98, v99
	v_cvt_pk_bf16_f32 v85, v100, v101
	ds_write2_b64 v26, v[22:23], v[18:19] offset1:4
	v_add_u32_e32 v18, 0x14d10, v145
	v_cvt_pk_bf16_f32 v14, v14, v15
	v_cvt_pk_bf16_f32 v15, v16, v17
	v_cvt_pk_bf16_f32 v10, v10, v11
	v_cvt_pk_bf16_f32 v11, v12, v13
	v_cvt_pk_bf16_f32 v126, v126, v127
	v_cvt_pk_bf16_f32 v127, v128, v129
	v_cvt_pk_bf16_f32 v122, v122, v123
	v_cvt_pk_bf16_f32 v123, v124, v125
	v_cvt_pk_bf16_f32 v118, v118, v119
	v_cvt_pk_bf16_f32 v119, v120, v121
	v_cvt_pk_bf16_f32 v114, v114, v115
	v_cvt_pk_bf16_f32 v115, v116, v117
	v_add_u32_e32 v116, 0x2000, v145
	v_cvt_pk_bf16_f32 v110, v110, v111
	v_cvt_pk_bf16_f32 v111, v112, v113
	v_cvt_pk_bf16_f32 v102, v102, v103
	v_cvt_pk_bf16_f32 v103, v104, v105
	v_add_u32_e32 v104, 0x4000, v145
	ds_write2_b64 v145, v[82:83], v[84:85] offset0:98 offset1:102
	v_cvt_pk_bf16_f32 v82, v94, v95
	v_cvt_pk_bf16_f32 v83, v96, v97
	v_cvt_pk_bf16_f32 v84, v86, v87
	v_cvt_pk_bf16_f32 v85, v88, v89
	v_cvt_pk_bf16_f32 v70, v70, v71
	v_cvt_pk_bf16_f32 v71, v72, v73
	v_cvt_pk_bf16_f32 v66, v66, v67
	v_cvt_pk_bf16_f32 v67, v68, v69
	ds_write2_b64 v18, v[14:15], v[10:11] offset1:4
	v_add_u32_e32 v10, 0x16e10, v145
	v_cvt_pk_bf16_f32 v6, v6, v7
	v_cvt_pk_bf16_f32 v7, v8, v9
	v_cvt_pk_bf16_f32 v2, v2, v3
	v_cvt_pk_bf16_f32 v3, v4, v5
	v_cmp_gt_i32_e32 vcc, 64, v143
	ds_write2_b64 v145, v[126:127], v[122:123] offset0:66 offset1:70
	ds_write2_b64 v116, v[118:119], v[114:115] offset0:98 offset1:102
	ds_write2_b64 v104, v[110:111], v[102:103] offset0:130 offset1:134
	ds_write2_b64 v116, v[82:83], v[84:85] offset0:130 offset1:134
	ds_write2_b64 v104, v[70:71], v[66:67] offset0:162 offset1:166
	ds_write2_b64 v10, v[6:7], v[2:3] offset1:4
	s_lshl_b32 s98, s24, 7
	v_lshl_or_b32 v82, v0, 3, s98
	v_ashrrev_i32_e32 v83, 31, v82
	v_lshlrev_b64 v[22:23], 2, v[82:83]
	v_lshl_add_u64 v[2:3], s[14:15], 0, v[22:23]
	v_lshl_add_u64 v[10:11], s[88:89], 0, v[22:23]
	global_load_dwordx4 v[6:9], v[2:3], off offset:16
	global_load_dwordx4 v[38:41], v[2:3], off
	s_nop 0
	global_load_dwordx4 v[2:5], v[10:11], off offset:16
	global_load_dwordx4 v[34:37], v[10:11], off
	v_lshl_add_u64 v[10:11], s[90:91], 0, v[22:23]
	v_lshl_add_u64 v[18:19], s[26:27], 0, v[22:23]
	global_load_dwordx4 v[14:17], v[10:11], off offset:16
	global_load_dwordx4 v[46:49], v[10:11], off
	s_nop 0
	global_load_dwordx4 v[10:13], v[18:19], off offset:16
	global_load_dwordx4 v[42:45], v[18:19], off
	v_lshl_add_u64 v[18:19], s[62:63], 0, v[22:23]
	v_lshl_add_u64 v[24:25], s[0:1], 0, v[22:23]
	global_load_dwordx4 v[26:29], v[18:19], off offset:16
	global_load_dwordx4 v[58:61], v[18:19], off
	s_nop 0
	global_load_dwordx4 v[18:21], v[24:25], off offset:16
	global_load_dwordx4 v[50:53], v[24:25], off
	v_lshl_add_u64 v[24:25], s[40:41], 0, v[22:23]
	v_lshl_add_u64 v[54:55], s[4:5], 0, v[22:23]
	global_load_dwordx4 v[30:33], v[24:25], off offset:16
	global_load_dwordx4 v[62:65], v[24:25], off
	s_nop 0
	global_load_dwordx4 v[22:25], v[54:55], off offset:16
	s_nop 0
	global_load_dwordx4 v[54:57], v[54:55], off
	s_and_saveexec_b64 s[42:43], vcc
	s_cbranch_execz .LBB0_400
	v_lshlrev_b32_e32 v206, 3, v144
	v_and_b32_e32 v210, 0xf8, v206
	v_mov_b32_e32 v209, 0
	s_cmpk_gt_i32 s25, 0xff
	v_cmp_gt_u32_e64 s[10:11], 32, v143
	v_mov_b32_e32 v208, 0
	v_mov_b32_e32 v207, 0
	v_mov_b32_e32 v206, 0
	s_cbranch_scc1 .LBB0_399
	s_and_b32 s28, s25, 7
	s_cmp_lg_u32 s28, 0
	s_cselect_b64 s[28:29], -1, 0
	v_cmp_lt_u32_e32 vcc, 31, v143
	s_and_b64 s[28:29], s[28:29], s[10:11]
	v_mov_b32_e32 v206, 0
	v_mov_b32_e32 v207, 0
	v_mov_b32_e32 v208, 0
	v_mov_b32_e32 v209, 0
	s_and_saveexec_b64 s[10:11], s[28:29]
	s_cbranch_execz .LBB0_395
	s_lshl_b32 s28, s25, 1
	s_add_i32 s28, s28, -1
	v_readlane_b32 s44, v252, 20
	s_mul_hi_i32 s29, s28, 0x2c00
	s_mulk_i32 s28, 0x2c00
	v_readlane_b32 s56, v252, 32
	v_readlane_b32 s57, v252, 33
	s_add_u32 s30, s56, s28
	s_addc_u32 s31, s57, s29
	s_lshl_b64 s[28:29], s[6:7], 1
	s_add_u32 s28, s30, s28
	s_addc_u32 s29, s31, s29
	v_lshlrev_b32_e32 v206, 1, v210
	global_load_dwordx4 v[206:209], v206, s[28:29]
	v_readlane_b32 s45, v252, 21
	v_readlane_b32 s46, v252, 22
	v_readlane_b32 s47, v252, 23
	v_readlane_b32 s48, v252, 24
	v_readlane_b32 s49, v252, 25
	v_readlane_b32 s50, v252, 26
	v_readlane_b32 s51, v252, 27
	v_readlane_b32 s52, v252, 28
	v_readlane_b32 s53, v252, 29
	v_readlane_b32 s54, v252, 30
	v_readlane_b32 s55, v252, 31
	v_readlane_b32 s58, v252, 34
	v_readlane_b32 s59, v252, 35
;   __device__ __forceinline__ void operator()(const f32x4 (&acc)[2][2][4][2], int pm, int pn, int wr_, int wc_, int fr_, int fq_, bf16_t* shm, int tid) const {
;     ...
;       if (pm < 256) {
;         if (!after && (pm & 7) != 0) hv = *(const u32x4*)(HU + (long)((pm - 1) * 2 + 1) * 5632 + pn * 256 + c);
;         if (after && ((pm + 1) & 7) != 0) hv = *(const u32x4*)(HU + (long)((pm + 1) * 2) * 5632 + pn * 256 + c);
;       }
;       *(u32x4*)(Us + (after ? 257 : 0) * USTR + c) = hv;
.LBB0_395:
	s_or_b64 exec, exec, s[10:11]
	s_and_saveexec_b64 s[10:11], vcc
	s_cbranch_execz .LBB0_398
	s_add_i32 s25, s25, 1
	s_and_b32 s28, s25, 7
	s_cmp_eq_u32 s28, 0
	s_cbranch_scc1 .LBB0_398
	v_readlane_b32 s44, v252, 20
	s_lshl_b32 s28, s25, 1
	s_mulk_i32 s25, 0x5800
	v_readlane_b32 s56, v252, 32
	s_mul_hi_u32 s28, s28, 0x2c00
	v_readlane_b32 s57, v252, 33
	s_add_u32 s25, s56, s25
	s_addc_u32 s28, s57, s28
	s_lshl_b64 s[6:7], s[6:7], 1
	s_add_u32 s6, s25, s6
	s_addc_u32 s7, s28, s7
	s_waitcnt vmcnt(0)
	v_lshlrev_b32_e32 v206, 1, v210
	global_load_dwordx4 v[206:209], v206, s[6:7]
	v_readlane_b32 s45, v252, 21
	v_readlane_b32 s46, v252, 22
	v_readlane_b32 s47, v252, 23
	v_readlane_b32 s48, v252, 24
	v_readlane_b32 s49, v252, 25
	v_readlane_b32 s50, v252, 26
	v_readlane_b32 s51, v252, 27
	v_readlane_b32 s52, v252, 28
	v_readlane_b32 s53, v252, 29
	v_readlane_b32 s54, v252, 30
	v_readlane_b32 s55, v252, 31
	v_readlane_b32 s58, v252, 34
	v_readlane_b32 s59, v252, 35

; __device__ __forceinline__ float bflo(unsigned w) { return __uint_as_float(w << 16); }
;   __device__ __forceinline__ void operator()(const f32x4 (&acc)[2][2][4][2], int pm, int pn, int wr_, int wc_, int fr_, int fq_, bf16_t* shm, int tid) const {
;     ...
;       *(u32x4*)(Us + (after ? 257 : 0) * USTR + c) = hv;
;     }
;     __syncthreads();
;     {
;       const int cg = tid & 15, rs = tid >> 4, f0 = pn * 128 + cg * 8;
;       float wa[3][8], wg[3][8], ba[8], bg[8];
; #pragma unroll
;       for (int t = 0; t < 3; ++t)
; #pragma unroll
;         for (int e = 0; e < 8; e += 4) {
;           const f32x4 x = *(const f32x4*)(cw + t * 5632 + f0 + e), y = *(const f32x4*)(cw + t * 5632 + 2816 + f0 + e);
;           wa[t][e] = x[0]; wa[t][e + 1] = x[1]; wa[t][e + 2] = x[2]; wa[t][e + 3] = x[3];
;           wg[t][e] = y[0]; wg[t][e + 1] = y[1]; wg[t][e + 2] = y[2]; wg[t][e + 3] = y[3];
;         }
; #pragma unroll
;       for (int e = 0; e < 8; e += 4) {
;         const f32x4 x = *(const f32x4*)(cb + f0 + e), y = *(const f32x4*)(cb + 2816 + f0 + e);
;         ba[e] = x[0]; ba[e + 1] = x[1]; ba[e + 2] = x[2]; ba[e + 3] = x[3]; bg[e] = y[0]; bg[e + 1] = y[1]; bg[e + 2] = y[2]; bg[e + 3] = y[3];
;       }
;       const bf16_t* up = Us + (rs * 8) * USTR + cg * 8;
;       u32x4 a0 = *(const u32x4*)(up), g0 = *(const u32x4*)(up + 128), a1 = *(const u32x4*)(up + USTR), g1 = *(const u32x4*)(up + USTR + 128);
;       bf16_t* outp = ACT + (long)(pm * 256 + rs * 8) * DFF + f0;
; #pragma unroll
;       for (int i = 0; i < 8; ++i) {
;         const u32x4 a2 = *(const u32x4*)(up + (i + 2) * USTR), g2 = *(const u32x4*)(up + (i + 2) * USTR + 128);
;         float res[8];
; #pragma unroll
;         for (int e = 0; e < 8; ++e) {
;           const unsigned xa0 = a0[e >> 1], xa1 = a1[e >> 1], xa2 = a2[e >> 1], xg0 = g0[e >> 1], xg1 = g1[e >> 1], xg2 = g2[e >> 1];
;           const float va0 = (e & 1) ? bfhi(xa0) : bflo(xa0), va1 = (e & 1) ? bfhi(xa1) : bflo(xa1), va2 = (e & 1) ? bfhi(xa2) : bflo(xa2);
;           const float vg0 = (e & 1) ? bfhi(xg0) : bflo(xg0), vg1 = (e & 1) ? bfhi(xg1) : bflo(xg1), vg2 = (e & 1) ? bfhi(xg2) : bflo(xg2);
;           const float av = va0 * wa[0][e] + va1 * wa[1][e] + va2 * wa[2][e] + ba[e];
;           const float gv = vg0 * wg[0][e] + vg1 * wg[1][e] + vg2 * wg[2][e] + bg[e];
;           res[e] = silu_f(av) * gv;
;         }
.LBB0_399:
	v_cmp_gt_u32_e32 vcc, 32, v143
	v_mov_b32_e32 v211, 0x21210
	v_lshlrev_b32_e32 v210, 1, v210
	v_cndmask_b32_e64 v211, v211, 0, vcc
	v_add3_u32 v210, 16, v211, v210
	s_waitcnt vmcnt(0)
	ds_write_b128 v210, v[206:209]
.LBB0_400:
	s_or_b64 exec, exec, s[42:43]
	s_waitcnt vmcnt(0) lgkmcnt(0)
	s_barrier
	s_movk_i32 s6, 0x1080
	v_mul_lo_u32 v66, v142, s6
	v_lshlrev_b32_e32 v0, 4, v0
	v_readlane_b32 s44, v252, 20
	v_add3_u32 v0, 16, v66, v0
	v_readlane_b32 s58, v252, 34
	v_readlane_b32 s59, v252, 35
	ds_read_b128 v[78:81], v0
	ds_read_b128 v[70:73], v0 offset:256
	ds_read_b128 v[74:77], v0 offset:528
	ds_read_b128 v[66:69], v0 offset:784
	v_lshl_add_u32 v86, v142, 3, s2
	v_mov_b64_e32 v[84:85], s[58:59]
	s_movk_i32 s2, 0x1600
	v_mad_i64_i32 v[84:85], s[6:7], v86, s2, v[84:85]
	v_lshl_add_u64 v[90:91], v[82:83], 1, v[84:85]
	ds_read_b128 v[86:89], v0 offset:1056
	ds_read_b128 v[82:85], v0 offset:1312
	s_waitcnt lgkmcnt(3)
	v_lshlrev_b32_e32 v96, 16, v74
	v_and_b32_e32 v97, 0xffff0000, v74
	v_lshlrev_b32_e32 v94, 16, v78
	v_and_b32_e32 v95, 0xffff0000, v78
	s_waitcnt lgkmcnt(1)
	v_lshlrev_b32_e32 v92, 16, v86
	v_and_b32_e32 v93, 0xffff0000, v86
	v_lshlrev_b32_e32 v78, 16, v79
	v_and_b32_e32 v79, 0xffff0000, v79
	v_lshlrev_b32_e32 v104, 16, v70
	v_and_b32_e32 v105, 0xffff0000, v70
	s_waitcnt lgkmcnt(0)
	v_lshlrev_b32_e32 v70, 16, v83
	v_lshlrev_b32_e32 v112, 16, v72
	v_and_b32_e32 v113, 0xffff0000, v72
	v_lshlrev_b32_e32 v72, 16, v85
	s_movk_i32 s2, 0x1000
	s_mov_b64 s[6:7], -1
	v_readlane_b32 s45, v252, 21
	v_readlane_b32 s46, v252, 22
	v_readlane_b32 s47, v252, 23
	v_readlane_b32 s48, v252, 24
	v_readlane_b32 s49, v252, 25
	v_readlane_b32 s50, v252, 26
	v_readlane_b32 s51, v252, 27
	v_readlane_b32 s52, v252, 28
	v_readlane_b32 s53, v252, 29
	v_readlane_b32 s54, v252, 30
	v_readlane_b32 s55, v252, 31
	v_readlane_b32 s56, v252, 32
	v_readlane_b32 s57, v252, 33
	s_waitcnt vmcnt(10)
	v_pk_mul_f32 v[98:99], v[46:47], v[96:97]
	s_nop 0
	v_pk_fma_f32 v[94:95], v[38:39], v[94:95], v[98:99]
	v_lshlrev_b32_e32 v98, 16, v66
	s_waitcnt vmcnt(6)
	v_pk_fma_f32 v[94:95], v[58:59], v[92:93], v[94:95]
	v_and_b32_e32 v99, 0xffff0000, v66
	v_pk_mul_f32 v[106:107], v[42:43], v[98:99]
	s_waitcnt vmcnt(2)
	v_pk_add_f32 v[100:101], v[62:63], v[94:95]
	v_lshlrev_b32_e32 v94, 16, v82
	v_mul_f32_e32 v74, 0xbfb8aa3b, v100
	v_mul_f32_e32 v66, 0xbfb8aa3b, v101
	v_exp_f32_e32 v74, v74
	v_exp_f32_e32 v66, v66
	v_and_b32_e32 v95, 0xffff0000, v82
	v_pk_fma_f32 v[104:105], v[34:35], v[104:105], v[106:107]
	v_add_f32_e32 v74, 1.0, v74
	v_add_f32_e32 v66, 1.0, v66
	v_rcp_f32_e32 v102, v74
	v_rcp_f32_e32 v103, v66
	v_lshlrev_b32_e32 v74, 16, v87
	v_pk_fma_f32 v[104:105], v[50:51], v[94:95], v[104:105]
	v_lshlrev_b32_e32 v106, 16, v68
	v_pk_mul_f32 v[100:101], v[100:101], v[102:103]
	v_lshlrev_b32_e32 v102, 16, v75
	v_and_b32_e32 v103, 0xffff0000, v75
	v_and_b32_e32 v75, 0xffff0000, v87
	v_pk_mul_f32 v[86:87], v[48:49], v[102:103]
	s_waitcnt vmcnt(0)
	v_pk_add_f32 v[104:105], v[54:55], v[104:105]
	v_pk_fma_f32 v[78:79], v[40:41], v[78:79], v[86:87]
	v_lshlrev_b32_e32 v86, 16, v67
	v_pk_fma_f32 v[78:79], v[60:61], v[74:75], v[78:79]
	v_and_b32_e32 v87, 0xffff0000, v67
	v_pk_add_f32 v[78:79], v[64:65], v[78:79]
	v_pk_mul_f32 v[100:101], v[104:105], v[100:101]
	v_mul_f32_e32 v66, 0xbfb8aa3b, v78
	v_mul_f32_e32 v67, 0xbfb8aa3b, v79
	v_exp_f32_e32 v66, v66
	v_exp_f32_e32 v67, v67
	v_lshlrev_b32_e32 v104, 16, v71
	v_and_b32_e32 v105, 0xffff0000, v71
	v_add_f32_e32 v66, 1.0, v66
	v_add_f32_e32 v67, 1.0, v67
	v_rcp_f32_e32 v66, v66
	v_rcp_f32_e32 v67, v67
	v_and_b32_e32 v71, 0xffff0000, v83
	v_pk_mul_f32 v[82:83], v[44:45], v[86:87]
	v_and_b32_e32 v107, 0xffff0000, v68
	v_pk_fma_f32 v[82:83], v[36:37], v[104:105], v[82:83]
	v_pk_mul_f32 v[66:67], v[78:79], v[66:67]
	v_pk_fma_f32 v[82:83], v[52:53], v[70:71], v[82:83]
	v_lshlrev_b32_e32 v104, 16, v76
	v_pk_add_f32 v[82:83], v[56:57], v[82:83]
	v_and_b32_e32 v105, 0xffff0000, v76
	v_pk_mul_f32 v[110:111], v[82:83], v[66:67]
	v_lshlrev_b32_e32 v66, 16, v80
	v_and_b32_e32 v67, 0xffff0000, v80
	v_pk_mul_f32 v[82:83], v[14:15], v[104:105]
	v_lshlrev_b32_e32 v78, 16, v88
	v_and_b32_e32 v79, 0xffff0000, v88
	v_pk_fma_f32 v[66:67], v[6:7], v[66:67], v[82:83]
	v_pk_mul_f32 v[114:115], v[10:11], v[106:107]
	v_pk_fma_f32 v[66:67], v[26:27], v[78:79], v[66:67]
	v_lshlrev_b32_e32 v82, 16, v84
	v_pk_add_f32 v[66:67], v[30:31], v[66:67]
	v_and_b32_e32 v83, 0xffff0000, v84
	v_mul_f32_e32 v76, 0xbfb8aa3b, v66
	v_mul_f32_e32 v68, 0xbfb8aa3b, v67
	v_exp_f32_e32 v76, v76
	v_exp_f32_e32 v68, v68
	v_pk_fma_f32 v[112:113], v[2:3], v[112:113], v[114:115]
	v_lshlrev_b32_e32 v88, 16, v69
	v_add_f32_e32 v76, 1.0, v76
	v_add_f32_e32 v68, 1.0, v68
	v_rcp_f32_e32 v108, v76
	v_rcp_f32_e32 v109, v68
	v_pk_fma_f32 v[112:113], v[18:19], v[82:83], v[112:113]
	v_lshlrev_b32_e32 v76, 16, v89
	v_pk_add_f32 v[112:113], v[22:23], v[112:113]
	v_pk_mul_f32 v[66:67], v[66:67], v[108:109]
	v_lshlrev_b32_e32 v108, 16, v77
	v_and_b32_e32 v109, 0xffff0000, v77
	v_pk_mul_f32 v[112:113], v[112:113], v[66:67]
	v_lshlrev_b32_e32 v66, 16, v81
	v_and_b32_e32 v67, 0xffff0000, v81
	v_pk_mul_f32 v[80:81], v[16:17], v[108:109]
	v_and_b32_e32 v77, 0xffff0000, v89
	v_pk_fma_f32 v[66:67], v[8:9], v[66:67], v[80:81]
	v_and_b32_e32 v89, 0xffff0000, v69
	v_pk_fma_f32 v[66:67], v[28:29], v[76:77], v[66:67]
	v_lshlrev_b32_e32 v80, 16, v73
	v_pk_add_f32 v[66:67], v[32:33], v[66:67]
	v_and_b32_e32 v81, 0xffff0000, v73
	v_mul_f32_e32 v68, 0xbfb8aa3b, v66
	v_mul_f32_e32 v69, 0xbfb8aa3b, v67
	v_exp_f32_e32 v68, v68
	v_exp_f32_e32 v69, v69
	v_and_b32_e32 v73, 0xffff0000, v85
	v_pk_mul_f32 v[84:85], v[12:13], v[88:89]
	v_add_f32_e32 v68, 1.0, v68
	v_add_f32_e32 v69, 1.0, v69
	v_rcp_f32_e32 v68, v68
	v_rcp_f32_e32 v69, v69
	v_pk_fma_f32 v[80:81], v[4:5], v[80:81], v[84:85]
	v_pk_mul_f32 v[84:85], v[46:47], v[92:93]
	v_pk_fma_f32 v[80:81], v[20:21], v[72:73], v[80:81]
	v_pk_mul_f32 v[66:67], v[66:67], v[68:69]
	v_pk_add_f32 v[80:81], v[24:25], v[80:81]
	v_cvt_pk_bf16_f32 v68, v112, v113
	v_pk_mul_f32 v[80:81], v[80:81], v[66:67]
	v_cvt_pk_bf16_f32 v66, v100, v101
	v_cvt_pk_bf16_f32 v67, v110, v111
	v_cvt_pk_bf16_f32 v69, v80, v81
	global_store_dwordx4 v[90:91], v[66:69], off
	ds_read_b128 v[110:113], v0 offset:1584
	ds_read_b128 v[66:69], v0 offset:1840
	v_pk_fma_f32 v[84:85], v[38:39], v[96:97], v[84:85]
	v_pk_mul_f32 v[100:101], v[42:43], v[94:95]
	s_waitcnt lgkmcnt(1)
; __device__ __forceinline__ unsigned pk2(float lo, float hi) { const f2_t v = {lo, hi}; return __builtin_bit_cast(unsigned, __builtin_convertvector(v, bf2_t)); }
; __device__ __forceinline__ float bflo(unsigned w) { return __uint_as_float(w << 16); }
; __device__ __forceinline__ float bfhi(unsigned w) { return __uint_as_float(w & 0xffff0000u); }
; __device__ __forceinline__ float silu_f(float v) { return v * __builtin_amdgcn_rcpf(1.f + __expf(-v)); }
;   __device__ __forceinline__ void operator()(const f32x4 (&acc)[2][2][4][2], int pm, int pn, int wr_, int wc_, int fr_, int fq_, bf16_t* shm, int tid) const {
;     ...
;       const bf16_t* up = Us + (rs * 8) * USTR + cg * 8;
;       u32x4 a0 = *(const u32x4*)(up), g0 = *(const u32x4*)(up + 128), a1 = *(const u32x4*)(up + USTR), g1 = *(const u32x4*)(up + USTR + 128);
;       bf16_t* outp = ACT + (long)(pm * 256 + rs * 8) * DFF + f0;
; #pragma unroll
;       for (int i = 0; i < 8; ++i) {
;         const u32x4 a2 = *(const u32x4*)(up + (i + 2) * USTR), g2 = *(const u32x4*)(up + (i + 2) * USTR + 128);
;         float res[8];
; #pragma unroll
;         for (int e = 0; e < 8; ++e) {
;           const unsigned xa0 = a0[e >> 1], xa1 = a1[e >> 1], xa2 = a2[e >> 1], xg0 = g0[e >> 1], xg1 = g1[e >> 1], xg2 = g2[e >> 1];
;           const float va0 = (e & 1) ? bfhi(xa0) : bflo(xa0), va1 = (e & 1) ? bfhi(xa1) : bflo(xa1), va2 = (e & 1) ? bfhi(xa2) : bflo(xa2);
;           const float vg0 = (e & 1) ? bfhi(xg0) : bflo(xg0), vg1 = (e & 1) ? bfhi(xg1) : bflo(xg1), vg2 = (e & 1) ? bfhi(xg2) : bflo(xg2);
;           const float av = va0 * wa[0][e] + va1 * wa[1][e] + va2 * wa[2][e] + ba[e];
;           const float gv = vg0 * wg[0][e] + vg1 * wg[1][e] + vg2 * wg[2][e] + bg[e];
;           res[e] = silu_f(av) * gv;
;         }
;         u32x4 w; w.x = pk2(res[0], res[1]); w.y = pk2(res[2], res[3]); w.z = pk2(res[4], res[5]); w.w = pk2(res[6], res[7]);
;         *(u32x4*)(outp + (long)i * DFF) = w;
;         a0 = a1; g0 = g1; a1 = a2; g1 = g2;
;       }
	v_lshlrev_b32_e32 v80, 16, v110
	v_and_b32_e32 v81, 0xffff0000, v110
	v_pk_fma_f32 v[84:85], v[58:59], v[80:81], v[84:85]
	s_waitcnt lgkmcnt(0)
	v_lshlrev_b32_e32 v118, 16, v66
	v_pk_add_f32 v[84:85], v[62:63], v[84:85]
	v_and_b32_e32 v119, 0xffff0000, v66
	v_mul_f32_e32 v96, 0xbfb8aa3b, v84
	v_mul_f32_e32 v66, 0xbfb8aa3b, v85
	v_exp_f32_e32 v96, v96
	v_exp_f32_e32 v66, v66
	v_pk_fma_f32 v[98:99], v[34:35], v[98:99], v[100:101]
	v_lshlrev_b32_e32 v100, 16, v111
	v_add_f32_e32 v96, 1.0, v96
	v_add_f32_e32 v66, 1.0, v66
	v_rcp_f32_e32 v96, v96
	v_rcp_f32_e32 v97, v66
	v_and_b32_e32 v101, 0xffff0000, v111
	v_lshlrev_b32_e32 v116, 16, v67
	v_and_b32_e32 v117, 0xffff0000, v67
	v_pk_mul_f32 v[84:85], v[84:85], v[96:97]
	v_pk_mul_f32 v[96:97], v[48:49], v[74:75]
	v_pk_fma_f32 v[98:99], v[50:51], v[118:119], v[98:99]
	v_pk_fma_f32 v[96:97], v[40:41], v[102:103], v[96:97]
	v_pk_add_f32 v[98:99], v[54:55], v[98:99]
	v_pk_fma_f32 v[96:97], v[60:61], v[100:101], v[96:97]
	v_pk_mul_f32 v[84:85], v[98:99], v[84:85]
	v_pk_add_f32 v[96:97], v[64:65], v[96:97]
	v_pk_mul_f32 v[98:99], v[44:45], v[70:71]
	v_mul_f32_e32 v66, 0xbfb8aa3b, v96
	v_mul_f32_e32 v67, 0xbfb8aa3b, v97
	v_exp_f32_e32 v66, v66
	v_exp_f32_e32 v67, v67
	v_pk_fma_f32 v[86:87], v[36:37], v[86:87], v[98:99]
	v_lshlrev_b32_e32 v98, 16, v112
	v_add_f32_e32 v66, 1.0, v66
	v_add_f32_e32 v67, 1.0, v67
	v_rcp_f32_e32 v66, v66
	v_rcp_f32_e32 v67, v67
	v_pk_fma_f32 v[86:87], v[52:53], v[116:117], v[86:87]
	v_and_b32_e32 v99, 0xffff0000, v112
	v_pk_add_f32 v[86:87], v[56:57], v[86:87]
	v_pk_mul_f32 v[66:67], v[96:97], v[66:67]
	v_lshlrev_b32_e32 v114, 16, v68
	v_pk_mul_f32 v[86:87], v[86:87], v[66:67]
	v_pk_mul_f32 v[66:67], v[14:15], v[78:79]
	v_and_b32_e32 v115, 0xffff0000, v68
	v_pk_fma_f32 v[66:67], v[6:7], v[104:105], v[66:67]
	v_pk_mul_f32 v[102:103], v[10:11], v[82:83]
	v_pk_fma_f32 v[66:67], v[26:27], v[98:99], v[66:67]
	v_pk_fma_f32 v[102:103], v[2:3], v[106:107], v[102:103]
	v_pk_add_f32 v[66:67], v[30:31], v[66:67]
	v_pk_fma_f32 v[102:103], v[18:19], v[114:115], v[102:103]
	v_mul_f32_e32 v96, 0xbfb8aa3b, v66
	v_mul_f32_e32 v68, 0xbfb8aa3b, v67
	v_exp_f32_e32 v96, v96
	v_exp_f32_e32 v68, v68
	v_pk_add_f32 v[102:103], v[22:23], v[102:103]
	v_lshlrev_b32_e32 v112, 16, v69
	v_add_f32_e32 v96, 1.0, v96
	v_add_f32_e32 v68, 1.0, v68
	v_rcp_f32_e32 v96, v96
	v_rcp_f32_e32 v97, v68
	v_pk_mul_f32 v[104:105], v[12:13], v[72:73]
	v_pk_mul_f32 v[66:67], v[66:67], v[96:97]
	s_nop 0
	v_pk_mul_f32 v[102:103], v[102:103], v[66:67]
	v_pk_mul_f32 v[66:67], v[16:17], v[76:77]
	v_lshlrev_b32_e32 v96, 16, v113
	v_and_b32_e32 v97, 0xffff0000, v113
	v_pk_fma_f32 v[66:67], v[8:9], v[108:109], v[66:67]
	v_and_b32_e32 v113, 0xffff0000, v69
	v_pk_fma_f32 v[66:67], v[28:29], v[96:97], v[66:67]
	v_pk_fma_f32 v[88:89], v[4:5], v[88:89], v[104:105]
	v_pk_add_f32 v[66:67], v[32:33], v[66:67]
	v_pk_fma_f32 v[88:89], v[20:21], v[112:113], v[88:89]
	v_mul_f32_e32 v68, 0xbfb8aa3b, v66
	v_mul_f32_e32 v69, 0xbfb8aa3b, v67
	v_exp_f32_e32 v68, v68
	v_exp_f32_e32 v69, v69
	v_pk_add_f32 v[88:89], v[24:25], v[88:89]
	v_add_f32_e32 v68, 1.0, v68
	v_add_f32_e32 v69, 1.0, v69
	v_rcp_f32_e32 v68, v68
	v_rcp_f32_e32 v69, v69
	s_nop 0
	v_pk_mul_f32 v[66:67], v[66:67], v[68:69]
	s_nop 0
	v_pk_mul_f32 v[88:89], v[88:89], v[66:67]
	v_cvt_pk_bf16_f32 v66, v84, v85
	v_add_co_u32_e32 v84, vcc, s2, v90
	v_cvt_pk_bf16_f32 v67, v86, v87
	v_cvt_pk_bf16_f32 v68, v102, v103
	v_cvt_pk_bf16_f32 v69, v88, v89
	v_addc_co_u32_e32 v85, vcc, 0, v91, vcc
	global_store_dwordx4 v[84:85], v[66:69], off offset:1536
	ds_read_b128 v[102:105], v0 offset:2112
	ds_read_b128 v[66:69], v0 offset:2368
	v_pk_mul_f32 v[84:85], v[46:47], v[80:81]
	s_movk_i32 s2, 0x2000
	v_pk_fma_f32 v[84:85], v[38:39], v[92:93], v[84:85]
	s_waitcnt lgkmcnt(1)
	v_lshlrev_b32_e32 v88, 16, v102
	v_and_b32_e32 v89, 0xffff0000, v102
	v_pk_fma_f32 v[84:85], v[58:59], v[88:89], v[84:85]
	s_waitcnt lgkmcnt(0)
	v_lshlrev_b32_e32 v110, 16, v66
	v_pk_add_f32 v[84:85], v[62:63], v[84:85]
	v_and_b32_e32 v111, 0xffff0000, v66
	v_mul_f32_e32 v86, 0xbfb8aa3b, v84
	v_mul_f32_e32 v66, 0xbfb8aa3b, v85
	v_exp_f32_e32 v86, v86
	v_exp_f32_e32 v66, v66
	v_pk_mul_f32 v[92:93], v[42:43], v[118:119]
	v_lshlrev_b32_e32 v108, 16, v67
	v_add_f32_e32 v86, 1.0, v86
	v_add_f32_e32 v66, 1.0, v66
	v_rcp_f32_e32 v86, v86
	v_rcp_f32_e32 v87, v66
	v_pk_fma_f32 v[92:93], v[34:35], v[94:95], v[92:93]
	v_and_b32_e32 v109, 0xffff0000, v67
	v_pk_fma_f32 v[92:93], v[50:51], v[110:111], v[92:93]
	v_pk_mul_f32 v[84:85], v[84:85], v[86:87]
	v_pk_add_f32 v[92:93], v[54:55], v[92:93]
	v_lshlrev_b32_e32 v86, 16, v103
	v_pk_mul_f32 v[92:93], v[92:93], v[84:85]
	v_pk_mul_f32 v[84:85], v[48:49], v[100:101]
	v_and_b32_e32 v87, 0xffff0000, v103
	v_pk_fma_f32 v[74:75], v[40:41], v[74:75], v[84:85]
	v_pk_mul_f32 v[84:85], v[44:45], v[116:117]
	v_pk_fma_f32 v[74:75], v[60:61], v[86:87], v[74:75]
	v_pk_fma_f32 v[70:71], v[36:37], v[70:71], v[84:85]
	v_pk_add_f32 v[74:75], v[64:65], v[74:75]
	v_pk_fma_f32 v[70:71], v[52:53], v[108:109], v[70:71]
	v_mul_f32_e32 v66, 0xbfb8aa3b, v74
	v_mul_f32_e32 v67, 0xbfb8aa3b, v75
	v_exp_f32_e32 v66, v66
	v_exp_f32_e32 v67, v67
	v_pk_add_f32 v[70:71], v[56:57], v[70:71]
	v_lshlrev_b32_e32 v84, 16, v104
	v_add_f32_e32 v66, 1.0, v66
	v_add_f32_e32 v67, 1.0, v67
	v_rcp_f32_e32 v66, v66
	v_rcp_f32_e32 v67, v67
	v_and_b32_e32 v85, 0xffff0000, v104
	v_lshlrev_b32_e32 v106, 16, v68
	v_and_b32_e32 v107, 0xffff0000, v68
	v_pk_mul_f32 v[66:67], v[74:75], v[66:67]
	v_lshlrev_b32_e32 v104, 16, v69
	v_pk_mul_f32 v[70:71], v[70:71], v[66:67]
	v_pk_mul_f32 v[66:67], v[14:15], v[98:99]
	s_nop 0
	v_pk_fma_f32 v[66:67], v[6:7], v[78:79], v[66:67]
; __device__ __forceinline__ unsigned pk2(float lo, float hi) { const f2_t v = {lo, hi}; return __builtin_bit_cast(unsigned, __builtin_convertvector(v, bf2_t)); }
; __device__ __forceinline__ float bflo(unsigned w) { return __uint_as_float(w << 16); }
; __device__ __forceinline__ float bfhi(unsigned w) { return __uint_as_float(w & 0xffff0000u); }
; __device__ __forceinline__ float silu_f(float v) { return v * __builtin_amdgcn_rcpf(1.f + __expf(-v)); }
;   __device__ __forceinline__ void operator()(const f32x4 (&acc)[2][2][4][2], int pm, int pn, int wr_, int wc_, int fr_, int fq_, bf16_t* shm, int tid) const {
;     ...
;       const bf16_t* up = Us + (rs * 8) * USTR + cg * 8;
;       u32x4 a0 = *(const u32x4*)(up), g0 = *(const u32x4*)(up + 128), a1 = *(const u32x4*)(up + USTR), g1 = *(const u32x4*)(up + USTR + 128);
;       bf16_t* outp = ACT + (long)(pm * 256 + rs * 8) * DFF + f0;
; #pragma unroll
;       for (int i = 0; i < 8; ++i) {
;         const u32x4 a2 = *(const u32x4*)(up + (i + 2) * USTR), g2 = *(const u32x4*)(up + (i + 2) * USTR + 128);
;         float res[8];
; #pragma unroll
;         for (int e = 0; e < 8; ++e) {
;           const unsigned xa0 = a0[e >> 1], xa1 = a1[e >> 1], xa2 = a2[e >> 1], xg0 = g0[e >> 1], xg1 = g1[e >> 1], xg2 = g2[e >> 1];
;           const float va0 = (e & 1) ? bfhi(xa0) : bflo(xa0), va1 = (e & 1) ? bfhi(xa1) : bflo(xa1), va2 = (e & 1) ? bfhi(xa2) : bflo(xa2);
;           const float vg0 = (e & 1) ? bfhi(xg0) : bflo(xg0), vg1 = (e & 1) ? bfhi(xg1) : bflo(xg1), vg2 = (e & 1) ? bfhi(xg2) : bflo(xg2);
;           const float av = va0 * wa[0][e] + va1 * wa[1][e] + va2 * wa[2][e] + ba[e];
;           const float gv = vg0 * wg[0][e] + vg1 * wg[1][e] + vg2 * wg[2][e] + bg[e];
;           res[e] = silu_f(av) * gv;
;         }
;         u32x4 w; w.x = pk2(res[0], res[1]); w.y = pk2(res[2], res[3]); w.z = pk2(res[4], res[5]); w.w = pk2(res[6], res[7]);
;         *(u32x4*)(outp + (long)i * DFF) = w;
;         a0 = a1; g0 = g1; a1 = a2; g1 = g2;
;       }
	v_pk_mul_f32 v[78:79], v[10:11], v[114:115]
	v_pk_fma_f32 v[66:67], v[26:27], v[84:85], v[66:67]
	v_pk_fma_f32 v[78:79], v[2:3], v[82:83], v[78:79]
	v_pk_add_f32 v[66:67], v[30:31], v[66:67]
	v_pk_fma_f32 v[78:79], v[18:19], v[106:107], v[78:79]
	v_mul_f32_e32 v74, 0xbfb8aa3b, v66
	v_mul_f32_e32 v68, 0xbfb8aa3b, v67
	v_exp_f32_e32 v74, v74
	v_exp_f32_e32 v68, v68
	v_pk_add_f32 v[78:79], v[22:23], v[78:79]
	v_add_f32_e32 v74, 1.0, v74
	v_add_f32_e32 v68, 1.0, v68
	v_rcp_f32_e32 v74, v74
	v_rcp_f32_e32 v75, v68
	s_nop 0
	v_pk_mul_f32 v[66:67], v[66:67], v[74:75]
	s_nop 0
	v_pk_mul_f32 v[74:75], v[78:79], v[66:67]
	v_pk_mul_f32 v[66:67], v[16:17], v[96:97]
	v_lshlrev_b32_e32 v78, 16, v105
	v_and_b32_e32 v79, 0xffff0000, v105
	v_pk_fma_f32 v[66:67], v[8:9], v[76:77], v[66:67]
	v_and_b32_e32 v105, 0xffff0000, v69
	v_pk_fma_f32 v[66:67], v[28:29], v[78:79], v[66:67]
	v_pk_mul_f32 v[76:77], v[12:13], v[112:113]
	v_pk_add_f32 v[66:67], v[32:33], v[66:67]
	v_pk_fma_f32 v[72:73], v[4:5], v[72:73], v[76:77]
	v_mul_f32_e32 v68, 0xbfb8aa3b, v66
	v_mul_f32_e32 v69, 0xbfb8aa3b, v67
	v_exp_f32_e32 v68, v68
	v_exp_f32_e32 v69, v69
	v_pk_fma_f32 v[72:73], v[20:21], v[104:105], v[72:73]
	v_add_f32_e32 v68, 1.0, v68
	v_add_f32_e32 v69, 1.0, v69
	v_rcp_f32_e32 v68, v68
	v_rcp_f32_e32 v69, v69
	v_pk_add_f32 v[72:73], v[24:25], v[72:73]
	v_pk_mul_f32 v[66:67], v[66:67], v[68:69]
	s_nop 0
	v_pk_mul_f32 v[72:73], v[72:73], v[66:67]
	v_cvt_pk_bf16_f32 v67, v70, v71
	v_add_co_u32_e32 v70, vcc, s2, v90
	v_cvt_pk_bf16_f32 v66, v92, v93
	v_cvt_pk_bf16_f32 v68, v74, v75
	v_cvt_pk_bf16_f32 v69, v72, v73
	v_addc_co_u32_e32 v71, vcc, 0, v91, vcc
	global_store_dwordx4 v[70:71], v[66:69], off offset:3072
	ds_read_b128 v[92:95], v0 offset:2640
	ds_read_b128 v[66:69], v0 offset:2896
	v_pk_mul_f32 v[70:71], v[46:47], v[88:89]
	v_pk_mul_f32 v[74:75], v[42:43], v[110:111]
	v_pk_fma_f32 v[70:71], v[38:39], v[80:81], v[70:71]
	s_waitcnt lgkmcnt(1)
	v_lshlrev_b32_e32 v76, 16, v92
	v_and_b32_e32 v77, 0xffff0000, v92
	v_pk_fma_f32 v[70:71], v[58:59], v[76:77], v[70:71]
	s_waitcnt lgkmcnt(0)
	v_lshlrev_b32_e32 v102, 16, v66
	v_pk_add_f32 v[70:71], v[62:63], v[70:71]
	v_and_b32_e32 v103, 0xffff0000, v66
	v_mul_f32_e32 v72, 0xbfb8aa3b, v70
	v_mul_f32_e32 v66, 0xbfb8aa3b, v71
	v_exp_f32_e32 v72, v72
	v_exp_f32_e32 v66, v66
	v_pk_fma_f32 v[74:75], v[34:35], v[118:119], v[74:75]
	s_movk_i32 s2, 0x4000
	v_add_f32_e32 v72, 1.0, v72
	v_add_f32_e32 v66, 1.0, v66
	v_rcp_f32_e32 v72, v72
	v_rcp_f32_e32 v73, v66
	v_pk_fma_f32 v[74:75], v[50:51], v[102:103], v[74:75]
	v_pk_mul_f32 v[70:71], v[70:71], v[72:73]
	v_pk_add_f32 v[74:75], v[54:55], v[74:75]
	v_pk_mul_f32 v[72:73], v[44:45], v[108:109]
	v_pk_mul_f32 v[80:81], v[74:75], v[70:71]
	v_pk_mul_f32 v[70:71], v[48:49], v[86:87]
	v_lshlrev_b32_e32 v74, 16, v93
	v_and_b32_e32 v75, 0xffff0000, v93
	v_pk_fma_f32 v[70:71], v[40:41], v[100:101], v[70:71]
	v_lshlrev_b32_e32 v100, 16, v67
	v_pk_fma_f32 v[70:71], v[60:61], v[74:75], v[70:71]
	v_and_b32_e32 v101, 0xffff0000, v67
	v_pk_add_f32 v[70:71], v[64:65], v[70:71]
	v_pk_fma_f32 v[72:73], v[36:37], v[116:117], v[72:73]
	v_mul_f32_e32 v66, 0xbfb8aa3b, v70
	v_mul_f32_e32 v67, 0xbfb8aa3b, v71
	v_exp_f32_e32 v66, v66
	v_exp_f32_e32 v67, v67
	v_pk_fma_f32 v[72:73], v[52:53], v[100:101], v[72:73]
	v_pk_mul_f32 v[92:93], v[10:11], v[106:107]
	v_add_f32_e32 v66, 1.0, v66
	v_add_f32_e32 v67, 1.0, v67
	v_rcp_f32_e32 v66, v66
	v_rcp_f32_e32 v67, v67
	v_pk_add_f32 v[72:73], v[56:57], v[72:73]
	v_pk_fma_f32 v[92:93], v[2:3], v[114:115], v[92:93]
	v_pk_mul_f32 v[66:67], v[70:71], v[66:67]
	s_nop 0
	v_pk_mul_f32 v[82:83], v[72:73], v[66:67]
	v_pk_mul_f32 v[66:67], v[14:15], v[84:85]
	v_lshlrev_b32_e32 v72, 16, v94
	v_and_b32_e32 v73, 0xffff0000, v94
	v_pk_fma_f32 v[66:67], v[6:7], v[98:99], v[66:67]
	v_lshlrev_b32_e32 v98, 16, v68
	v_pk_fma_f32 v[66:67], v[26:27], v[72:73], v[66:67]
	v_and_b32_e32 v99, 0xffff0000, v68
	v_pk_add_f32 v[66:67], v[30:31], v[66:67]
	v_pk_fma_f32 v[92:93], v[18:19], v[98:99], v[92:93]
	v_mul_f32_e32 v70, 0xbfb8aa3b, v66
	v_mul_f32_e32 v68, 0xbfb8aa3b, v67
	v_exp_f32_e32 v70, v70
	v_exp_f32_e32 v68, v68
	v_pk_add_f32 v[92:93], v[22:23], v[92:93]
	v_lshlrev_b32_e32 v94, 16, v69
	v_add_f32_e32 v70, 1.0, v70
	v_add_f32_e32 v68, 1.0, v68
	v_rcp_f32_e32 v70, v70
	v_rcp_f32_e32 v71, v68
	s_nop 0
	v_pk_mul_f32 v[66:67], v[66:67], v[70:71]
	s_nop 0
	v_pk_mul_f32 v[92:93], v[92:93], v[66:67]
	v_pk_mul_f32 v[66:67], v[16:17], v[78:79]
	v_lshlrev_b32_e32 v70, 16, v95
	v_and_b32_e32 v71, 0xffff0000, v95
	v_pk_fma_f32 v[66:67], v[8:9], v[96:97], v[66:67]
	v_and_b32_e32 v95, 0xffff0000, v69
	v_pk_fma_f32 v[66:67], v[28:29], v[70:71], v[66:67]
	v_pk_mul_f32 v[96:97], v[12:13], v[104:105]
	v_pk_add_f32 v[66:67], v[32:33], v[66:67]
	v_pk_fma_f32 v[96:97], v[4:5], v[112:113], v[96:97]
	v_mul_f32_e32 v68, 0xbfb8aa3b, v66
	v_mul_f32_e32 v69, 0xbfb8aa3b, v67
	v_exp_f32_e32 v68, v68
	v_exp_f32_e32 v69, v69
	v_pk_fma_f32 v[96:97], v[20:21], v[94:95], v[96:97]
	v_add_f32_e32 v68, 1.0, v68
	v_add_f32_e32 v69, 1.0, v69
	v_rcp_f32_e32 v68, v68
	v_rcp_f32_e32 v69, v69
	v_pk_add_f32 v[96:97], v[24:25], v[96:97]
	v_pk_mul_f32 v[66:67], v[66:67], v[68:69]
	s_nop 0
	v_pk_mul_f32 v[96:97], v[96:97], v[66:67]
	v_cvt_pk_bf16_f32 v66, v80, v81
	v_add_co_u32_e32 v80, vcc, s2, v90
	v_cvt_pk_bf16_f32 v67, v82, v83
	v_cvt_pk_bf16_f32 v68, v92, v93
	v_cvt_pk_bf16_f32 v69, v96, v97
	v_addc_co_u32_e32 v81, vcc, 0, v91, vcc
	global_store_dwordx4 v[80:81], v[66:69], off offset:512
	ds_read_b128 v[114:117], v0 offset:3168
	ds_read_b128 v[66:69], v0 offset:3424
	v_pk_mul_f32 v[80:81], v[46:47], v[76:77]
	s_movk_i32 s2, 0x5000
	v_pk_fma_f32 v[80:81], v[38:39], v[88:89], v[80:81]
	s_waitcnt lgkmcnt(1)
; __device__ __forceinline__ unsigned pk2(float lo, float hi) { const f2_t v = {lo, hi}; return __builtin_bit_cast(unsigned, __builtin_convertvector(v, bf2_t)); }
; __device__ __forceinline__ float bflo(unsigned w) { return __uint_as_float(w << 16); }
; __device__ __forceinline__ float bfhi(unsigned w) { return __uint_as_float(w & 0xffff0000u); }
; __device__ __forceinline__ float silu_f(float v) { return v * __builtin_amdgcn_rcpf(1.f + __expf(-v)); }
;   __device__ __forceinline__ void operator()(const f32x4 (&acc)[2][2][4][2], int pm, int pn, int wr_, int wc_, int fr_, int fq_, bf16_t* shm, int tid) const {
;     ...
;       const bf16_t* up = Us + (rs * 8) * USTR + cg * 8;
;       u32x4 a0 = *(const u32x4*)(up), g0 = *(const u32x4*)(up + 128), a1 = *(const u32x4*)(up + USTR), g1 = *(const u32x4*)(up + USTR + 128);
;       bf16_t* outp = ACT + (long)(pm * 256 + rs * 8) * DFF + f0;
; #pragma unroll
;       for (int i = 0; i < 8; ++i) {
;         const u32x4 a2 = *(const u32x4*)(up + (i + 2) * USTR), g2 = *(const u32x4*)(up + (i + 2) * USTR + 128);
;         float res[8];
; #pragma unroll
;         for (int e = 0; e < 8; ++e) {
;           const unsigned xa0 = a0[e >> 1], xa1 = a1[e >> 1], xa2 = a2[e >> 1], xg0 = g0[e >> 1], xg1 = g1[e >> 1], xg2 = g2[e >> 1];
;           const float va0 = (e & 1) ? bfhi(xa0) : bflo(xa0), va1 = (e & 1) ? bfhi(xa1) : bflo(xa1), va2 = (e & 1) ? bfhi(xa2) : bflo(xa2);
;           const float vg0 = (e & 1) ? bfhi(xg0) : bflo(xg0), vg1 = (e & 1) ? bfhi(xg1) : bflo(xg1), vg2 = (e & 1) ? bfhi(xg2) : bflo(xg2);
;           const float av = va0 * wa[0][e] + va1 * wa[1][e] + va2 * wa[2][e] + ba[e];
;           const float gv = vg0 * wg[0][e] + vg1 * wg[1][e] + vg2 * wg[2][e] + bg[e];
;           res[e] = silu_f(av) * gv;
;         }
;         u32x4 w; w.x = pk2(res[0], res[1]); w.y = pk2(res[2], res[3]); w.z = pk2(res[4], res[5]); w.w = pk2(res[6], res[7]);
;         *(u32x4*)(outp + (long)i * DFF) = w;
;         a0 = a1; g0 = g1; a1 = a2; g1 = g2;
;       }
	v_lshlrev_b32_e32 v92, 16, v114
	v_and_b32_e32 v93, 0xffff0000, v114
	v_pk_fma_f32 v[80:81], v[58:59], v[92:93], v[80:81]
	s_waitcnt lgkmcnt(0)
	v_lshlrev_b32_e32 v112, 16, v66
	v_pk_add_f32 v[80:81], v[62:63], v[80:81]
	v_and_b32_e32 v113, 0xffff0000, v66
	v_mul_f32_e32 v82, 0xbfb8aa3b, v80
	v_mul_f32_e32 v66, 0xbfb8aa3b, v81
	v_exp_f32_e32 v82, v82
	v_exp_f32_e32 v66, v66
	v_pk_mul_f32 v[88:89], v[42:43], v[102:103]
	v_lshlrev_b32_e32 v96, 16, v67
	v_add_f32_e32 v82, 1.0, v82
	v_add_f32_e32 v66, 1.0, v66
	v_rcp_f32_e32 v82, v82
	v_rcp_f32_e32 v83, v66
	v_pk_fma_f32 v[88:89], v[34:35], v[110:111], v[88:89]
	v_and_b32_e32 v97, 0xffff0000, v67
	v_pk_fma_f32 v[88:89], v[50:51], v[112:113], v[88:89]
	v_pk_mul_f32 v[80:81], v[80:81], v[82:83]
	v_pk_add_f32 v[88:89], v[54:55], v[88:89]
	v_pk_mul_f32 v[82:83], v[44:45], v[100:101]
	v_pk_mul_f32 v[110:111], v[88:89], v[80:81]
	v_pk_mul_f32 v[80:81], v[48:49], v[74:75]
	v_lshlrev_b32_e32 v88, 16, v115
	v_and_b32_e32 v89, 0xffff0000, v115
	v_pk_fma_f32 v[80:81], v[40:41], v[86:87], v[80:81]
	v_pk_fma_f32 v[82:83], v[36:37], v[108:109], v[82:83]
	v_pk_fma_f32 v[80:81], v[60:61], v[88:89], v[80:81]
	v_pk_fma_f32 v[82:83], v[52:53], v[96:97], v[82:83]
	v_pk_add_f32 v[80:81], v[64:65], v[80:81]
	v_pk_add_f32 v[82:83], v[56:57], v[82:83]
	v_mul_f32_e32 v66, 0xbfb8aa3b, v80
	v_mul_f32_e32 v67, 0xbfb8aa3b, v81
	v_exp_f32_e32 v66, v66
	v_exp_f32_e32 v67, v67
	v_lshlrev_b32_e32 v86, 16, v68
	v_and_b32_e32 v87, 0xffff0000, v68
	v_add_f32_e32 v66, 1.0, v66
	v_add_f32_e32 v67, 1.0, v67
	v_rcp_f32_e32 v66, v66
	v_rcp_f32_e32 v67, v67
	v_pk_mul_f32 v[114:115], v[42:43], v[112:113]
	v_pk_mul_f32 v[66:67], v[80:81], v[66:67]
	s_nop 0
	v_pk_mul_f32 v[108:109], v[82:83], v[66:67]
	v_pk_mul_f32 v[66:67], v[14:15], v[72:73]
	v_lshlrev_b32_e32 v82, 16, v116
	v_and_b32_e32 v83, 0xffff0000, v116
	v_pk_fma_f32 v[66:67], v[6:7], v[84:85], v[66:67]
	v_pk_mul_f32 v[84:85], v[10:11], v[98:99]
	v_pk_fma_f32 v[66:67], v[26:27], v[82:83], v[66:67]
	v_pk_fma_f32 v[84:85], v[2:3], v[106:107], v[84:85]
	v_pk_add_f32 v[66:67], v[30:31], v[66:67]
	v_pk_fma_f32 v[84:85], v[18:19], v[86:87], v[84:85]
	v_mul_f32_e32 v80, 0xbfb8aa3b, v66
	v_mul_f32_e32 v68, 0xbfb8aa3b, v67
	v_exp_f32_e32 v80, v80
	v_exp_f32_e32 v68, v68
	v_pk_add_f32 v[84:85], v[22:23], v[84:85]
	v_pk_fma_f32 v[102:103], v[34:35], v[102:103], v[114:115]
	v_add_f32_e32 v80, 1.0, v80
	v_add_f32_e32 v68, 1.0, v68
	v_rcp_f32_e32 v80, v80
	v_rcp_f32_e32 v81, v68
	v_pk_mul_f32 v[114:115], v[10:11], v[86:87]
	v_pk_mul_f32 v[66:67], v[66:67], v[80:81]
	s_nop 0
	v_pk_mul_f32 v[106:107], v[84:85], v[66:67]
	v_pk_mul_f32 v[66:67], v[16:17], v[70:71]
	v_lshlrev_b32_e32 v80, 16, v117
	v_and_b32_e32 v81, 0xffff0000, v117
	v_pk_fma_f32 v[66:67], v[8:9], v[78:79], v[66:67]
	v_lshlrev_b32_e32 v84, 16, v69
	v_pk_fma_f32 v[66:67], v[28:29], v[80:81], v[66:67]
	v_and_b32_e32 v85, 0xffff0000, v69
	v_pk_add_f32 v[66:67], v[32:33], v[66:67]
	v_pk_mul_f32 v[78:79], v[12:13], v[94:95]
	v_mul_f32_e32 v68, 0xbfb8aa3b, v66
	v_mul_f32_e32 v69, 0xbfb8aa3b, v67
	v_exp_f32_e32 v68, v68
	v_exp_f32_e32 v69, v69
	v_pk_fma_f32 v[78:79], v[4:5], v[104:105], v[78:79]
	v_pk_mul_f32 v[104:105], v[46:47], v[92:93]
	v_add_f32_e32 v68, 1.0, v68
	v_add_f32_e32 v69, 1.0, v69
	v_rcp_f32_e32 v68, v68
	v_rcp_f32_e32 v69, v69
	v_pk_fma_f32 v[78:79], v[20:21], v[84:85], v[78:79]
	v_pk_fma_f32 v[76:77], v[38:39], v[76:77], v[104:105]
	v_pk_add_f32 v[78:79], v[24:25], v[78:79]
	v_pk_mul_f32 v[66:67], v[66:67], v[68:69]
	v_cvt_pk_bf16_f32 v68, v106, v107
	v_pk_mul_f32 v[78:79], v[78:79], v[66:67]
	v_cvt_pk_bf16_f32 v66, v110, v111
	v_cvt_pk_bf16_f32 v69, v78, v79
	v_add_co_u32_e32 v78, vcc, s2, v90
	v_cvt_pk_bf16_f32 v67, v108, v109
	s_nop 0
	v_addc_co_u32_e32 v79, vcc, 0, v91, vcc
	global_store_dwordx4 v[78:79], v[66:69], off offset:2048
	ds_read_b128 v[108:111], v0 offset:3696
	ds_read_b128 v[66:69], v0 offset:3952
	v_pk_fma_f32 v[98:99], v[2:3], v[98:99], v[114:115]
	s_waitcnt lgkmcnt(1)
	v_lshlrev_b32_e32 v78, 16, v108
	v_and_b32_e32 v79, 0xffff0000, v108
	v_pk_fma_f32 v[76:77], v[58:59], v[78:79], v[76:77]
	s_waitcnt lgkmcnt(0)
	v_and_b32_e32 v105, 0xffff0000, v66
	v_pk_add_f32 v[76:77], v[62:63], v[76:77]
	s_nop 0
	v_mul_f32_e32 v104, 0xbfb8aa3b, v76
	v_exp_f32_e32 v104, v104
	s_nop 0
	v_add_f32_e32 v104, 1.0, v104
	v_rcp_f32_e32 v106, v104
	v_lshlrev_b32_e32 v104, 16, v66
	v_mul_f32_e32 v66, 0xbfb8aa3b, v77
	v_exp_f32_e32 v66, v66
	v_pk_fma_f32 v[102:103], v[50:51], v[104:105], v[102:103]
	v_add_f32_e32 v66, 1.0, v66
	v_rcp_f32_e32 v107, v66
	v_pk_add_f32 v[102:103], v[54:55], v[102:103]
	v_pk_mul_f32 v[76:77], v[76:77], v[106:107]
	s_nop 0
	v_pk_mul_f32 v[106:107], v[102:103], v[76:77]
	v_pk_mul_f32 v[102:103], v[48:49], v[88:89]
	v_lshlrev_b32_e32 v76, 16, v109
	v_and_b32_e32 v77, 0xffff0000, v109
	v_pk_fma_f32 v[74:75], v[40:41], v[74:75], v[102:103]
	v_lshlrev_b32_e32 v102, 16, v67
	v_pk_fma_f32 v[74:75], v[60:61], v[76:77], v[74:75]
	v_and_b32_e32 v103, 0xffff0000, v67
	v_pk_add_f32 v[74:75], v[64:65], v[74:75]
	v_pk_mul_f32 v[108:109], v[44:45], v[96:97]
	v_mul_f32_e32 v66, 0xbfb8aa3b, v74
	v_mul_f32_e32 v67, 0xbfb8aa3b, v75
	v_exp_f32_e32 v66, v66
	v_exp_f32_e32 v67, v67
	v_pk_fma_f32 v[100:101], v[36:37], v[100:101], v[108:109]
	v_add_f32_e32 v66, 1.0, v66
	v_add_f32_e32 v67, 1.0, v67
	v_rcp_f32_e32 v66, v66
	v_rcp_f32_e32 v67, v67
	v_pk_fma_f32 v[100:101], v[52:53], v[102:103], v[100:101]
	v_pk_mul_f32 v[66:67], v[74:75], v[66:67]
	v_pk_add_f32 v[100:101], v[56:57], v[100:101]
	v_lshlrev_b32_e32 v74, 16, v110
	v_pk_mul_f32 v[108:109], v[100:101], v[66:67]
	v_pk_mul_f32 v[66:67], v[14:15], v[82:83]
; __device__ __forceinline__ unsigned pk2(float lo, float hi) { const f2_t v = {lo, hi}; return __builtin_bit_cast(unsigned, __builtin_convertvector(v, bf2_t)); }
; __device__ __forceinline__ float bflo(unsigned w) { return __uint_as_float(w << 16); }
; __device__ __forceinline__ float bfhi(unsigned w) { return __uint_as_float(w & 0xffff0000u); }
; __device__ __forceinline__ float silu_f(float v) { return v * __builtin_amdgcn_rcpf(1.f + __expf(-v)); }
;   __device__ __forceinline__ void operator()(const f32x4 (&acc)[2][2][4][2], int pm, int pn, int wr_, int wc_, int fr_, int fq_, bf16_t* shm, int tid) const {
;     ...
;       const bf16_t* up = Us + (rs * 8) * USTR + cg * 8;
;       u32x4 a0 = *(const u32x4*)(up), g0 = *(const u32x4*)(up + 128), a1 = *(const u32x4*)(up + USTR), g1 = *(const u32x4*)(up + USTR + 128);
;       bf16_t* outp = ACT + (long)(pm * 256 + rs * 8) * DFF + f0;
; #pragma unroll
;       for (int i = 0; i < 8; ++i) {
;         const u32x4 a2 = *(const u32x4*)(up + (i + 2) * USTR), g2 = *(const u32x4*)(up + (i + 2) * USTR + 128);
;         float res[8];
; #pragma unroll
;         for (int e = 0; e < 8; ++e) {
;           const unsigned xa0 = a0[e >> 1], xa1 = a1[e >> 1], xa2 = a2[e >> 1], xg0 = g0[e >> 1], xg1 = g1[e >> 1], xg2 = g2[e >> 1];
;           const float va0 = (e & 1) ? bfhi(xa0) : bflo(xa0), va1 = (e & 1) ? bfhi(xa1) : bflo(xa1), va2 = (e & 1) ? bfhi(xa2) : bflo(xa2);
;           const float vg0 = (e & 1) ? bfhi(xg0) : bflo(xg0), vg1 = (e & 1) ? bfhi(xg1) : bflo(xg1), vg2 = (e & 1) ? bfhi(xg2) : bflo(xg2);
;           const float av = va0 * wa[0][e] + va1 * wa[1][e] + va2 * wa[2][e] + ba[e];
;           const float gv = vg0 * wg[0][e] + vg1 * wg[1][e] + vg2 * wg[2][e] + bg[e];
;           res[e] = silu_f(av) * gv;
;         }
;         u32x4 w; w.x = pk2(res[0], res[1]); w.y = pk2(res[2], res[3]); w.z = pk2(res[4], res[5]); w.w = pk2(res[6], res[7]);
;         *(u32x4*)(outp + (long)i * DFF) = w;
;         a0 = a1; g0 = g1; a1 = a2; g1 = g2;
;       }
	v_and_b32_e32 v75, 0xffff0000, v110
	v_pk_fma_f32 v[66:67], v[6:7], v[72:73], v[66:67]
	v_lshlrev_b32_e32 v100, 16, v68
	v_pk_fma_f32 v[66:67], v[26:27], v[74:75], v[66:67]
	v_and_b32_e32 v101, 0xffff0000, v68
	v_pk_add_f32 v[66:67], v[30:31], v[66:67]
	v_pk_fma_f32 v[98:99], v[18:19], v[100:101], v[98:99]
	v_mul_f32_e32 v72, 0xbfb8aa3b, v66
	v_mul_f32_e32 v68, 0xbfb8aa3b, v67
	v_exp_f32_e32 v72, v72
	v_exp_f32_e32 v68, v68
	v_pk_add_f32 v[98:99], v[22:23], v[98:99]
	v_add_f32_e32 v72, 1.0, v72
	v_add_f32_e32 v68, 1.0, v68
	v_rcp_f32_e32 v72, v72
	v_rcp_f32_e32 v73, v68
	s_nop 0
	v_pk_mul_f32 v[66:67], v[66:67], v[72:73]
	s_nop 0
	v_pk_mul_f32 v[98:99], v[98:99], v[66:67]
	v_pk_mul_f32 v[66:67], v[16:17], v[80:81]
	v_lshlrev_b32_e32 v72, 16, v111
	v_and_b32_e32 v73, 0xffff0000, v111
	v_pk_fma_f32 v[66:67], v[8:9], v[70:71], v[66:67]
	v_lshlrev_b32_e32 v70, 16, v69
	v_pk_fma_f32 v[66:67], v[28:29], v[72:73], v[66:67]
	v_and_b32_e32 v71, 0xffff0000, v69
	v_pk_add_f32 v[66:67], v[32:33], v[66:67]
	v_pk_mul_f32 v[110:111], v[12:13], v[84:85]
	v_mul_f32_e32 v68, 0xbfb8aa3b, v66
	v_mul_f32_e32 v69, 0xbfb8aa3b, v67
	v_exp_f32_e32 v68, v68
	v_exp_f32_e32 v69, v69
	v_pk_fma_f32 v[94:95], v[4:5], v[94:95], v[110:111]
	v_pk_mul_f32 v[110:111], v[44:45], v[102:103]
	v_add_f32_e32 v68, 1.0, v68
	v_add_f32_e32 v69, 1.0, v69
	v_rcp_f32_e32 v68, v68
	v_rcp_f32_e32 v69, v69
	v_pk_fma_f32 v[94:95], v[20:21], v[70:71], v[94:95]
	v_pk_fma_f32 v[96:97], v[36:37], v[96:97], v[110:111]
	v_pk_add_f32 v[94:95], v[24:25], v[94:95]
	v_pk_mul_f32 v[66:67], v[66:67], v[68:69]
	v_cvt_pk_bf16_f32 v68, v98, v99
	v_pk_mul_f32 v[94:95], v[94:95], v[66:67]
	v_cvt_pk_bf16_f32 v66, v106, v107
	v_cvt_pk_bf16_f32 v69, v94, v95
	v_add_co_u32_e32 v94, vcc, s93, v90
	v_cvt_pk_bf16_f32 v67, v108, v109
	s_nop 0
	v_addc_co_u32_e32 v95, vcc, 0, v91, vcc
	global_store_dwordx4 v[94:95], v[66:69], off offset:3584
	ds_read_b128 v[114:117], v0 offset:4224
	ds_read_b128 v[66:69], v0 offset:4480
	v_pk_mul_f32 v[98:99], v[46:47], v[78:79]
	v_pk_mul_f32 v[108:109], v[42:43], v[104:105]
	v_pk_fma_f32 v[92:93], v[38:39], v[92:93], v[98:99]
	s_waitcnt lgkmcnt(1)
	v_lshlrev_b32_e32 v94, 16, v114
	v_and_b32_e32 v95, 0xffff0000, v114
	v_pk_fma_f32 v[92:93], v[58:59], v[94:95], v[92:93]
	s_waitcnt lgkmcnt(0)
	v_lshlrev_b32_e32 v106, 16, v66
	v_pk_add_f32 v[92:93], v[62:63], v[92:93]
	v_and_b32_e32 v107, 0xffff0000, v66
	v_mul_f32_e32 v98, 0xbfb8aa3b, v92
	v_mul_f32_e32 v66, 0xbfb8aa3b, v93
	v_exp_f32_e32 v98, v98
	v_exp_f32_e32 v66, v66
	v_pk_fma_f32 v[108:109], v[34:35], v[112:113], v[108:109]
	v_pk_mul_f32 v[112:113], v[10:11], v[100:101]
	v_add_f32_e32 v98, 1.0, v98
	v_add_f32_e32 v66, 1.0, v66
	v_rcp_f32_e32 v98, v98
	v_rcp_f32_e32 v99, v66
	v_pk_fma_f32 v[108:109], v[50:51], v[106:107], v[108:109]
	v_pk_fma_f32 v[86:87], v[2:3], v[86:87], v[112:113]
	v_pk_add_f32 v[108:109], v[54:55], v[108:109]
	v_pk_mul_f32 v[92:93], v[92:93], v[98:99]
	v_pk_mul_f32 v[98:99], v[48:49], v[76:77]
	v_pk_mul_f32 v[108:109], v[108:109], v[92:93]
	v_lshlrev_b32_e32 v92, 16, v115
	v_and_b32_e32 v93, 0xffff0000, v115
	v_pk_fma_f32 v[88:89], v[40:41], v[88:89], v[98:99]
	v_lshlrev_b32_e32 v98, 16, v67
	v_pk_fma_f32 v[88:89], v[60:61], v[92:93], v[88:89]
	v_and_b32_e32 v99, 0xffff0000, v67
	v_pk_add_f32 v[88:89], v[64:65], v[88:89]
	v_pk_fma_f32 v[96:97], v[52:53], v[98:99], v[96:97]
	v_mul_f32_e32 v66, 0xbfb8aa3b, v88
	v_mul_f32_e32 v67, 0xbfb8aa3b, v89
	v_exp_f32_e32 v66, v66
	v_exp_f32_e32 v67, v67
	v_pk_add_f32 v[96:97], v[56:57], v[96:97]
	v_pk_mul_f32 v[112:113], v[12:13], v[70:71]
	v_add_f32_e32 v66, 1.0, v66
	v_add_f32_e32 v67, 1.0, v67
	v_rcp_f32_e32 v66, v66
	v_rcp_f32_e32 v67, v67
	v_pk_fma_f32 v[84:85], v[4:5], v[84:85], v[112:113]
	v_pk_mul_f32 v[46:47], v[46:47], v[94:95]
	v_pk_mul_f32 v[42:43], v[42:43], v[106:107]
	v_pk_mul_f32 v[66:67], v[88:89], v[66:67]
	v_lshlrev_b32_e32 v88, 16, v116
	v_pk_mul_f32 v[110:111], v[96:97], v[66:67]
	v_pk_mul_f32 v[66:67], v[14:15], v[74:75]
	v_and_b32_e32 v89, 0xffff0000, v116
	v_pk_fma_f32 v[66:67], v[6:7], v[82:83], v[66:67]
	v_lshlrev_b32_e32 v96, 16, v68
	v_pk_fma_f32 v[66:67], v[26:27], v[88:89], v[66:67]
	v_and_b32_e32 v97, 0xffff0000, v68
	v_pk_add_f32 v[66:67], v[30:31], v[66:67]
	v_pk_fma_f32 v[86:87], v[18:19], v[96:97], v[86:87]
	v_mul_f32_e32 v82, 0xbfb8aa3b, v66
	v_mul_f32_e32 v68, 0xbfb8aa3b, v67
	v_exp_f32_e32 v82, v82
	v_exp_f32_e32 v68, v68
	v_pk_add_f32 v[86:87], v[22:23], v[86:87]
	v_pk_fma_f32 v[38:39], v[38:39], v[78:79], v[46:47]
	v_add_f32_e32 v82, 1.0, v82
	v_add_f32_e32 v68, 1.0, v68
	v_rcp_f32_e32 v82, v82
	v_rcp_f32_e32 v83, v68
	v_pk_fma_f32 v[34:35], v[34:35], v[104:105], v[42:43]
	v_pk_mul_f32 v[42:43], v[48:49], v[92:93]
	v_pk_mul_f32 v[44:45], v[44:45], v[98:99]
	v_pk_mul_f32 v[66:67], v[66:67], v[82:83]
	v_lshlrev_b32_e32 v82, 16, v117
	v_pk_mul_f32 v[86:87], v[86:87], v[66:67]
	v_pk_mul_f32 v[66:67], v[16:17], v[72:73]
	v_and_b32_e32 v83, 0xffff0000, v117
	v_pk_fma_f32 v[66:67], v[8:9], v[80:81], v[66:67]
	v_lshlrev_b32_e32 v80, 16, v69
	v_pk_fma_f32 v[66:67], v[28:29], v[82:83], v[66:67]
	v_and_b32_e32 v81, 0xffff0000, v69
	v_pk_add_f32 v[66:67], v[32:33], v[66:67]
	v_pk_fma_f32 v[84:85], v[20:21], v[80:81], v[84:85]
	v_mul_f32_e32 v68, 0xbfb8aa3b, v66
	v_mul_f32_e32 v69, 0xbfb8aa3b, v67
	v_exp_f32_e32 v68, v68
	v_exp_f32_e32 v69, v69
	v_pk_add_f32 v[84:85], v[24:25], v[84:85]
	v_pk_fma_f32 v[40:41], v[40:41], v[76:77], v[42:43]
	v_add_f32_e32 v68, 1.0, v68
	v_add_f32_e32 v69, 1.0, v69
	v_rcp_f32_e32 v68, v68
	v_rcp_f32_e32 v69, v69
	v_pk_fma_f32 v[36:37], v[36:37], v[102:103], v[44:45]
	v_pk_mul_f32 v[14:15], v[14:15], v[88:89]
	v_pk_mul_f32 v[10:11], v[10:11], v[96:97]
	v_pk_mul_f32 v[66:67], v[66:67], v[68:69]
	v_cvt_pk_bf16_f32 v68, v86, v87
	v_pk_mul_f32 v[84:85], v[84:85], v[66:67]
	v_cvt_pk_bf16_f32 v66, v108, v109
	v_cvt_pk_bf16_f32 v69, v84, v85
	v_add_co_u32_e32 v84, vcc, s74, v90
	v_cvt_pk_bf16_f32 v67, v110, v111
	s_nop 0
	v_addc_co_u32_e32 v85, vcc, 0, v91, vcc
	global_store_dwordx4 v[84:85], v[66:69], off offset:1024
	ds_read_b128 v[84:87], v0 offset:4752
	ds_read_b128 v[66:69], v0 offset:5008
	v_pk_fma_f32 v[6:7], v[6:7], v[74:75], v[14:15]
	v_pk_fma_f32 v[2:3], v[2:3], v[100:101], v[10:11]
	v_pk_mul_f32 v[10:11], v[16:17], v[82:83]
	s_waitcnt lgkmcnt(1)
; __device__ __forceinline__ unsigned pk2(float lo, float hi) { const f2_t v = {lo, hi}; return __builtin_bit_cast(unsigned, __builtin_convertvector(v, bf2_t)); }
; __device__ __forceinline__ float bflo(unsigned w) { return __uint_as_float(w << 16); }
; __device__ __forceinline__ float bfhi(unsigned w) { return __uint_as_float(w & 0xffff0000u); }
; __device__ __forceinline__ float silu_f(float v) { return v * __builtin_amdgcn_rcpf(1.f + __expf(-v)); }
; template <bool OVL, bool PANEL = false, class Epi>
; __device__ __forceinline__ void gemm_phase(const bf16_t* __restrict__ A, long lda, const bf16_t* __restrict__ Bt, long ldb, int nM, int nN, int K,
;                                            const Epi& epi, bf16_t* shm, int w0) {
;     ...
;     else if (have) { const int nbrow = pm * BM, nbcol = pn * BM;
;       STAGE(SB(0, 0), Bt, ldb, boff, nbcol, 0); STAGE(SA(0, 0), A, lda, aoff, nbrow, 0);
;       STAGE(SB(0, 1), Bt, ldb, boff, nbcol + HALF, 0); STAGE(SA(0, 1), A, lda, aoff, nbrow + HALF, 0); }
;   __device__ __forceinline__ void operator()(const f32x4 (&acc)[2][2][4][2], int pm, int pn, int wr_, int wc_, int fr_, int fq_, bf16_t* shm, int tid) const {
;     ...
;       for (int i = 0; i < 8; ++i) {
;         const u32x4 a2 = *(const u32x4*)(up + (i + 2) * USTR), g2 = *(const u32x4*)(up + (i + 2) * USTR + 128);
;         float res[8];
; #pragma unroll
;         for (int e = 0; e < 8; ++e) {
;           const unsigned xa0 = a0[e >> 1], xa1 = a1[e >> 1], xa2 = a2[e >> 1], xg0 = g0[e >> 1], xg1 = g1[e >> 1], xg2 = g2[e >> 1];
;           const float va0 = (e & 1) ? bfhi(xa0) : bflo(xa0), va1 = (e & 1) ? bfhi(xa1) : bflo(xa1), va2 = (e & 1) ? bfhi(xa2) : bflo(xa2);
;           const float vg0 = (e & 1) ? bfhi(xg0) : bflo(xg0), vg1 = (e & 1) ? bfhi(xg1) : bflo(xg1), vg2 = (e & 1) ? bfhi(xg2) : bflo(xg2);
;           const float av = va0 * wa[0][e] + va1 * wa[1][e] + va2 * wa[2][e] + ba[e];
;           const float gv = vg0 * wg[0][e] + vg1 * wg[1][e] + vg2 * wg[2][e] + bg[e];
;           res[e] = silu_f(av) * gv;
;         }
;         u32x4 w; w.x = pk2(res[0], res[1]); w.y = pk2(res[2], res[3]); w.z = pk2(res[4], res[5]); w.w = pk2(res[6], res[7]);
;         *(u32x4*)(outp + (long)i * DFF) = w;
;         a0 = a1; g0 = g1; a1 = a2; g1 = g2;
;       }
;     }
;     __syncthreads();
	v_lshlrev_b32_e32 v108, 16, v84
	v_and_b32_e32 v109, 0xffff0000, v84
	v_pk_fma_f32 v[38:39], v[58:59], v[108:109], v[38:39]
	s_waitcnt lgkmcnt(0)
	v_lshlrev_b32_e32 v58, 16, v66
	v_pk_add_f32 v[38:39], v[62:63], v[38:39]
	v_and_b32_e32 v59, 0xffff0000, v66
	v_mul_f32_e32 v0, 0xbfb8aa3b, v38
	v_exp_f32_e32 v0, v0
	v_pk_fma_f32 v[34:35], v[50:51], v[58:59], v[34:35]
	v_lshlrev_b32_e32 v42, 16, v67
	v_pk_add_f32 v[34:35], v[54:55], v[34:35]
	v_add_f32_e32 v0, 1.0, v0
	v_rcp_f32_e32 v46, v0
	v_mul_f32_e32 v0, 0xbfb8aa3b, v39
	v_exp_f32_e32 v0, v0
	v_and_b32_e32 v43, 0xffff0000, v67
	v_pk_fma_f32 v[36:37], v[52:53], v[42:43], v[36:37]
	v_pk_fma_f32 v[8:9], v[8:9], v[72:73], v[10:11]
	v_add_f32_e32 v0, 1.0, v0
	v_rcp_f32_e32 v47, v0
	v_pk_add_f32 v[36:37], v[56:57], v[36:37]
	v_pk_mul_f32 v[12:13], v[12:13], v[80:81]
	v_lshlrev_b32_e32 v10, 16, v69
	v_pk_mul_f32 v[38:39], v[38:39], v[46:47]
	v_and_b32_e32 v11, 0xffff0000, v69
	v_pk_mul_f32 v[34:35], v[34:35], v[38:39]
	v_lshlrev_b32_e32 v38, 16, v85
	v_and_b32_e32 v39, 0xffff0000, v85
	v_pk_fma_f32 v[38:39], v[60:61], v[38:39], v[40:41]
	v_pk_fma_f32 v[4:5], v[4:5], v[70:71], v[12:13]
	v_pk_add_f32 v[38:39], v[64:65], v[38:39]
	v_pk_fma_f32 v[4:5], v[20:21], v[10:11], v[4:5]
	v_mul_f32_e32 v0, 0xbfb8aa3b, v38
	v_exp_f32_e32 v0, v0
	v_pk_add_f32 v[4:5], v[24:25], v[4:5]
	v_add_f32_e32 v0, 1.0, v0
	v_rcp_f32_e32 v40, v0
	v_mul_f32_e32 v0, 0xbfb8aa3b, v39
	v_exp_f32_e32 v0, v0
	s_nop 0
	v_add_f32_e32 v0, 1.0, v0
	v_rcp_f32_e32 v41, v0
	s_nop 0
	v_pk_mul_f32 v[38:39], v[38:39], v[40:41]
	s_nop 0
	v_pk_mul_f32 v[36:37], v[36:37], v[38:39]
	v_lshlrev_b32_e32 v38, 16, v86
	v_and_b32_e32 v39, 0xffff0000, v86
	v_pk_fma_f32 v[6:7], v[26:27], v[38:39], v[6:7]
	v_lshlrev_b32_e32 v26, 16, v68
	v_pk_add_f32 v[6:7], v[30:31], v[6:7]
	v_and_b32_e32 v27, 0xffff0000, v68
	v_mul_f32_e32 v0, 0xbfb8aa3b, v6
	v_exp_f32_e32 v0, v0
	v_pk_fma_f32 v[2:3], v[18:19], v[26:27], v[2:3]
	v_add_f32_e32 v0, 1.0, v0
	v_rcp_f32_e32 v14, v0
	v_mul_f32_e32 v0, 0xbfb8aa3b, v7
	v_exp_f32_e32 v0, v0
	v_pk_add_f32 v[2:3], v[22:23], v[2:3]
	v_add_f32_e32 v0, 1.0, v0
	v_rcp_f32_e32 v15, v0
	s_nop 0
	v_pk_mul_f32 v[6:7], v[6:7], v[14:15]
	s_nop 0
	v_pk_mul_f32 v[6:7], v[2:3], v[6:7]
	v_lshlrev_b32_e32 v2, 16, v87
	v_and_b32_e32 v3, 0xffff0000, v87
	v_pk_fma_f32 v[2:3], v[28:29], v[2:3], v[8:9]
	s_nop 0
	v_pk_add_f32 v[2:3], v[32:33], v[2:3]
	s_nop 0
	v_mul_f32_e32 v0, 0xbfb8aa3b, v2
	v_exp_f32_e32 v0, v0
	s_nop 0
	v_add_f32_e32 v0, 1.0, v0
	v_rcp_f32_e32 v8, v0
	v_mul_f32_e32 v0, 0xbfb8aa3b, v3
	v_exp_f32_e32 v0, v0
	s_nop 0
	v_add_f32_e32 v0, 1.0, v0
	v_rcp_f32_e32 v9, v0
	s_nop 0
	v_pk_mul_f32 v[2:3], v[2:3], v[8:9]
	s_nop 0
	v_pk_mul_f32 v[8:9], v[4:5], v[2:3]
	v_cvt_pk_bf16_f32 v4, v6, v7
	v_add_co_u32_e32 v6, vcc, 0x9000, v90
	v_cvt_pk_bf16_f32 v2, v34, v35
	s_nop 0
	v_addc_co_u32_e32 v7, vcc, 0, v91, vcc
	v_cvt_pk_bf16_f32 v3, v36, v37
	v_cvt_pk_bf16_f32 v5, v8, v9
	s_andn2_b64 vcc, exec, s[8:9]
	global_store_dwordx4 v[6:7], v[2:5], off offset:2560
	s_barrier
	s_cbranch_vccnz .LBB0_382
	s_lshl_b32 s6, s18, 8
	s_ashr_i32 s7, s6, 31
	s_lshl_b64 s[8:9], s[6:7], 11
	v_readlane_b32 s80, v251, 49
	v_readlane_b32 s81, v251, 50
	s_add_u32 s8, s80, s8
	v_readfirstlane_b32 s2, v132
	s_addc_u32 s9, s81, s9
	v_mov_b32_e32 v0, v131
	s_mov_b32 m0, s2
	v_readfirstlane_b32 s2, v133
	v_readlane_b32 s44, v252, 20
	global_load_lds_dwordx4 v0, s[8:9]
	s_mov_b32 m0, s2
	s_lshl_b32 s2, s23, 8
	v_lshl_add_u64 v[2:3], s[8:9], 0, v[0:1]
	s_mov_b64 s[10:11], 0x20000
	s_lshl_b64 s[8:9], s[2:3], 11
	v_readlane_b32 s50, v252, 26
	v_lshl_add_u64 v[2:3], v[2:3], 0, s[10:11]
	v_readlane_b32 s51, v252, 27
	s_add_u32 s8, s50, s8
	v_readfirstlane_b32 s7, v134
	global_load_lds_dwordx4 v[2:3], off
	s_addc_u32 s9, s51, s9
	v_mov_b32_e32 v0, v131
	s_mov_b32 m0, s7
	v_readfirstlane_b32 s7, v135
	s_bitset1_b32 s6, 7
	v_readlane_b32 s82, v251, 51
	global_load_lds_dwordx4 v0, s[8:9]
	s_mov_b32 m0, s7
	s_ashr_i32 s7, s6, 31
	v_lshl_add_u64 v[2:3], s[8:9], 0, v[0:1]
	s_lshl_b64 s[6:7], s[6:7], 11
	v_lshl_add_u64 v[2:3], v[2:3], 0, s[10:11]
	s_add_u32 s6, s80, s6
	v_readfirstlane_b32 s8, v136
	global_load_lds_dwordx4 v[2:3], off
	s_addc_u32 s7, s81, s7
	v_mov_b32_e32 v0, v131
	s_mov_b32 m0, s8
	s_bitset1_b32 s2, 7
	v_lshl_add_u64 v[2:3], s[6:7], 0, v[0:1]
	global_load_lds_dwordx4 v0, s[6:7]
	v_readfirstlane_b32 s6, v137
	s_mov_b32 m0, s6
	s_lshl_b64 s[6:7], s[2:3], 11
	s_add_u32 s6, s50, s6
	v_lshl_add_u64 v[2:3], v[2:3], 0, s[10:11]
	s_addc_u32 s7, s51, s7
	v_mov_b32_e32 v0, v131
	v_readfirstlane_b32 s2, v138
	global_load_lds_dwordx4 v[2:3], off
	s_mov_b32 m0, s2
	v_lshl_add_u64 v[2:3], s[6:7], 0, v[0:1]
	v_readfirstlane_b32 s2, v139
	global_load_lds_dwordx4 v0, s[6:7]
	v_lshl_add_u64 v[2:3], v[2:3], 0, s[10:11]
	s_mov_b32 m0, s2
	s_mov_b64 s[6:7], 0
	global_load_lds_dwordx4 v[2:3], off
	v_readlane_b32 s83, v251, 52
	v_readlane_b32 s84, v251, 53
	v_readlane_b32 s85, v251, 54
	v_readlane_b32 s86, v251, 55
	v_readlane_b32 s87, v251, 56
	v_readlane_b32 s45, v252, 21
	v_readlane_b32 s46, v252, 22
	v_readlane_b32 s47, v252, 23
	v_readlane_b32 s48, v252, 24
	v_readlane_b32 s49, v252, 25
	v_readlane_b32 s52, v252, 28
	v_readlane_b32 s53, v252, 29
	v_readlane_b32 s54, v252, 30
	v_readlane_b32 s55, v252, 31
	v_readlane_b32 s56, v252, 32
	v_readlane_b32 s57, v252, 33
	v_readlane_b32 s58, v252, 34
	v_readlane_b32 s59, v252, 35
	s_branch .LBB0_382

; #define LDA(dst, b, h) for (int m = 0; m < 4; ++m) for (int k = 0; k < 2; ++k) \
;     dst[m][k] = *reinterpret_cast<const bf16x8*>((char*)SA(b, h) + a_thr + (m * 2 + k) * 1024)
; #define LDB(dst, b, h) for (int n = 0; n < 2; ++n) for (int k = 0; k < 2; ++k) \
;     dst[n][k] = *reinterpret_cast<const bf16x8*>((char*)SB(b, h) + b_thr + (n * 2 + k) * 1024)
; #define MMA(ai, bj, At, Btf) do { __builtin_amdgcn_s_setprio(1); \
;     for (int m = 0; m < 4; ++m) for (int n = 0; n < 2; ++n) for (int k = 0; k < 2; ++k) \
;       acc[ai][bj][m][n] = __builtin_amdgcn_mfma_f32_16x16x32_bf16(Btf[n][k], At[m][k], acc[ai][bj][m][n], 0, 0, 0); \
;     __builtin_amdgcn_s_setprio(0); } while (0)
; #define WAIT_V(n) asm volatile("s_waitcnt vmcnt(" #n ")" ::: "memory")
; #define WAIT_L(n) asm volatile("s_waitcnt lgkmcnt(" #n ")" ::: "memory")
; #define BAR __builtin_amdgcn_s_barrier()
; #define SCHED __builtin_amdgcn_sched_barrier(0)
; template <bool OVL, bool PANEL = false, class Epi>
; __device__ __forceinline__ void gemm_phase(const bf16_t* __restrict__ A, long lda, const bf16_t* __restrict__ Bt, long ldb, int nM, int nN, int K,
;                                            const Epi& epi, bf16_t* shm, int w0) {
;     ...
;     for (int t = 0; t < nt - 2; t += 2) {
;       LDB(B0, 0, 0); SCHED; LDA(At, 0, 0); STAGE(SA(1, 1), A, lda, aoff, brow + HALF, t + 1);
;       WAIT_L(8); BAR; WAIT_L(0); MMA(0, 0, At, B0); BAR; SCHED;
;       LDB(B1, 0, 1); STAGE(SB(0, 0), Bt, ldb, boff, bcol, t + 2);
;       BAR; WAIT_L(0); MMA(0, 1, At, B1); BAR;
;       LDA(At, 0, 1); STAGE(SA(0, 0), A, lda, aoff, brow, t + 2);
;       BAR; WAIT_L(0); MMA(1, 0, At, B0); BAR; SCHED;
;       STAGE(SB(0, 1), Bt, ldb, boff, bcol + HALF, t + 2);
;       WAIT_V(6); BAR; MMA(1, 1, At, B1); BAR;
;       LDB(B0, 1, 0); SCHED; LDA(At, 1, 0); STAGE(SA(0, 1), A, lda, aoff, brow + HALF, t + 2);
;       WAIT_L(8); BAR; WAIT_L(0); MMA(0, 0, At, B0); BAR; SCHED;
;       LDB(B1, 1, 1); STAGE(SB(1, 0), Bt, ldb, boff, bcol, t + 3);
;       BAR; WAIT_L(0); MMA(0, 1, At, B1); BAR;
;       LDA(At, 1, 1); STAGE(SA(1, 0), A, lda, aoff, brow, t + 3);
;       BAR; WAIT_L(0); MMA(1, 0, At, B0); BAR; SCHED;
;       STAGE(SB(1, 1), Bt, ldb, boff, bcol + HALF, t + 3);
;       WAIT_V(6); BAR; MMA(1, 1, At, B1); BAR;
;     }
.LBB0_410:
	ds_read_b128 v[152:155], v220
	ds_read_b128 v[156:159], v220 offset:1024
	ds_read_b128 v[160:163], v220 offset:2048
	ds_read_b128 v[164:167], v220 offset:3072
	s_add_u32 s12, s8, s10
	s_addc_u32 s13, s9, s11
	ds_read_b128 v[168:171], v143
	ds_read_b128 v[172:175], v143 offset:1024
	ds_read_b128 v[176:179], v143 offset:2048
	ds_read_b128 v[180:183], v143 offset:3072
	ds_read_b128 v[184:187], v143 offset:4096
	ds_read_b128 v[188:191], v143 offset:5120
	ds_read_b128 v[192:195], v143 offset:6144
	ds_read_b128 v[196:199], v143 offset:7168
	s_mov_b32 m0, s16
	s_add_u32 s98, s12, s24
	s_addc_u32 s99, s13, s25
	global_load_lds_dwordx4 v131, s[98:99]
	s_mov_b32 m0, s23
	s_add_u32 s98, s12, s36
	s_addc_u32 s99, s13, s37
	global_load_lds_dwordx4 v131, s[98:99]
	s_waitcnt lgkmcnt(8)
	s_waitcnt vmcnt(10)
	s_barrier
	s_waitcnt lgkmcnt(0)
	s_waitcnt lgkmcnt(0)
	v_mfma_f32_16x16x32_bf16 v[126:129], v[152:155], v[168:171], v[126:129]
	v_mfma_f32_16x16x32_bf16 v[122:125], v[160:163], v[168:171], v[122:125]
	v_mfma_f32_16x16x32_bf16 v[118:121], v[152:155], v[176:179], v[118:121]
	v_mfma_f32_16x16x32_bf16 v[114:117], v[160:163], v[176:179], v[114:117]
	v_mfma_f32_16x16x32_bf16 v[110:113], v[152:155], v[184:187], v[110:113]
	v_mfma_f32_16x16x32_bf16 v[106:109], v[160:163], v[184:187], v[106:109]
	v_mfma_f32_16x16x32_bf16 v[102:105], v[152:155], v[192:195], v[102:105]
	v_mfma_f32_16x16x32_bf16 v[98:101], v[160:163], v[192:195], v[98:101]
	v_mfma_f32_16x16x32_bf16 v[126:129], v[156:159], v[172:175], v[126:129]
	v_mfma_f32_16x16x32_bf16 v[122:125], v[164:167], v[172:175], v[122:125]
	v_mfma_f32_16x16x32_bf16 v[118:121], v[156:159], v[180:183], v[118:121]
	v_mfma_f32_16x16x32_bf16 v[114:117], v[164:167], v[180:183], v[114:117]
	v_mfma_f32_16x16x32_bf16 v[110:113], v[156:159], v[188:191], v[110:113]
	v_mfma_f32_16x16x32_bf16 v[106:109], v[164:167], v[188:191], v[106:109]
	v_mfma_f32_16x16x32_bf16 v[102:105], v[156:159], v[196:199], v[102:105]
	v_mfma_f32_16x16x32_bf16 v[98:101], v[164:167], v[196:199], v[98:101]
	s_barrier
	s_add_u32 s14, s0, s10
	ds_read_b128 v[200:203], v221
	ds_read_b128 v[204:207], v221 offset:1024
	ds_read_b128 v[208:211], v221 offset:2048
	ds_read_b128 v[212:215], v221 offset:3072
	s_addc_u32 s15, s1, s11
	s_mov_b32 m0, s30
	s_add_u32 s98, s14, s34
	s_addc_u32 s99, s15, s35
	global_load_lds_dwordx4 v131, s[98:99]
	s_mov_b32 m0, s31
	s_add_u32 s98, s14, s64
	s_addc_u32 s99, s15, s65
	global_load_lds_dwordx4 v131, s[98:99]
	s_waitcnt vmcnt(10)
	s_barrier
	s_waitcnt lgkmcnt(0)
	s_waitcnt lgkmcnt(0)
	v_mfma_f32_16x16x32_bf16 v[94:97], v[200:203], v[168:171], v[94:97]
	v_mfma_f32_16x16x32_bf16 v[90:93], v[208:211], v[168:171], v[90:93]
	v_mfma_f32_16x16x32_bf16 v[86:89], v[200:203], v[176:179], v[86:89]
	v_mfma_f32_16x16x32_bf16 v[82:85], v[208:211], v[176:179], v[82:85]
	v_mfma_f32_16x16x32_bf16 v[78:81], v[200:203], v[184:187], v[78:81]
	v_mfma_f32_16x16x32_bf16 v[74:77], v[208:211], v[184:187], v[74:77]
	v_mfma_f32_16x16x32_bf16 v[70:73], v[200:203], v[192:195], v[70:73]
	v_mfma_f32_16x16x32_bf16 v[66:69], v[208:211], v[192:195], v[66:69]
	v_mfma_f32_16x16x32_bf16 v[94:97], v[204:207], v[172:175], v[94:97]
	v_mfma_f32_16x16x32_bf16 v[90:93], v[212:215], v[172:175], v[90:93]
	v_mfma_f32_16x16x32_bf16 v[86:89], v[204:207], v[180:183], v[86:89]
	v_mfma_f32_16x16x32_bf16 v[82:85], v[212:215], v[180:183], v[82:85]
	v_mfma_f32_16x16x32_bf16 v[78:81], v[204:207], v[188:191], v[78:81]
	v_mfma_f32_16x16x32_bf16 v[74:77], v[212:215], v[188:191], v[74:77]
	v_mfma_f32_16x16x32_bf16 v[70:73], v[204:207], v[196:199], v[70:73]
	v_mfma_f32_16x16x32_bf16 v[66:69], v[212:215], v[196:199], v[66:69]
	s_barrier
	ds_read_b128 v[168:171], v143 offset:16384
	ds_read_b128 v[172:175], v143 offset:17408
	ds_read_b128 v[176:179], v143 offset:18432
	ds_read_b128 v[180:183], v143 offset:19456
	ds_read_b128 v[184:187], v143 offset:20480
	ds_read_b128 v[188:191], v143 offset:21504
	ds_read_b128 v[192:195], v143 offset:22528
	ds_read_b128 v[196:199], v143 offset:23552
	s_mov_b32 m0, s32
	s_add_u32 s98, s12, s34
	s_addc_u32 s99, s13, s35
	global_load_lds_dwordx4 v131, s[98:99]
	s_mov_b32 m0, s40
	s_add_u32 s98, s12, s64
	s_addc_u32 s99, s13, s65
	global_load_lds_dwordx4 v131, s[98:99]
	s_barrier
	s_waitcnt lgkmcnt(0)
	s_waitcnt lgkmcnt(0)
	v_mfma_f32_16x16x32_bf16 v[62:65], v[152:155], v[168:171], v[62:65]
	v_mfma_f32_16x16x32_bf16 v[58:61], v[160:163], v[168:171], v[58:61]
	v_mfma_f32_16x16x32_bf16 v[54:57], v[152:155], v[176:179], v[54:57]
	v_mfma_f32_16x16x32_bf16 v[50:53], v[160:163], v[176:179], v[50:53]
	v_mfma_f32_16x16x32_bf16 v[46:49], v[152:155], v[184:187], v[46:49]
	v_mfma_f32_16x16x32_bf16 v[42:45], v[160:163], v[184:187], v[42:45]
	v_mfma_f32_16x16x32_bf16 v[38:41], v[152:155], v[192:195], v[38:41]
	v_mfma_f32_16x16x32_bf16 v[34:37], v[160:163], v[192:195], v[34:37]
	v_mfma_f32_16x16x32_bf16 v[62:65], v[156:159], v[172:175], v[62:65]
	v_mfma_f32_16x16x32_bf16 v[58:61], v[164:167], v[172:175], v[58:61]
	v_mfma_f32_16x16x32_bf16 v[54:57], v[156:159], v[180:183], v[54:57]
	v_mfma_f32_16x16x32_bf16 v[50:53], v[164:167], v[180:183], v[50:53]
	v_mfma_f32_16x16x32_bf16 v[46:49], v[156:159], v[188:191], v[46:49]
	v_mfma_f32_16x16x32_bf16 v[42:45], v[164:167], v[188:191], v[42:45]
	v_mfma_f32_16x16x32_bf16 v[38:41], v[156:159], v[196:199], v[38:41]
	v_mfma_f32_16x16x32_bf16 v[34:37], v[164:167], v[196:199], v[34:37]
	s_barrier
	s_mov_b32 m0, s41
	s_add_u32 s98, s14, s68
	s_addc_u32 s99, s15, s69
	global_load_lds_dwordx4 v131, s[98:99]
	s_mov_b32 m0, s42
	s_add_u32 s98, s14, s70
	s_addc_u32 s99, s15, s71
	global_load_lds_dwordx4 v131, s[98:99]
	s_waitcnt vmcnt(10)
	s_barrier
; #define LDA(dst, b, h) for (int m = 0; m < 4; ++m) for (int k = 0; k < 2; ++k) \
;     dst[m][k] = *reinterpret_cast<const bf16x8*>((char*)SA(b, h) + a_thr + (m * 2 + k) * 1024)
; #define LDB(dst, b, h) for (int n = 0; n < 2; ++n) for (int k = 0; k < 2; ++k) \
;     dst[n][k] = *reinterpret_cast<const bf16x8*>((char*)SB(b, h) + b_thr + (n * 2 + k) * 1024)
; #define MMA(ai, bj, At, Btf) do { __builtin_amdgcn_s_setprio(1); \
;     for (int m = 0; m < 4; ++m) for (int n = 0; n < 2; ++n) for (int k = 0; k < 2; ++k) \
;       acc[ai][bj][m][n] = __builtin_amdgcn_mfma_f32_16x16x32_bf16(Btf[n][k], At[m][k], acc[ai][bj][m][n], 0, 0, 0); \
;     __builtin_amdgcn_s_setprio(0); } while (0)
; #define WAIT_V(n) asm volatile("s_waitcnt vmcnt(" #n ")" ::: "memory")
; #define WAIT_L(n) asm volatile("s_waitcnt lgkmcnt(" #n ")" ::: "memory")
; #define BAR __builtin_amdgcn_s_barrier()
; #define SCHED __builtin_amdgcn_sched_barrier(0)
; template <bool OVL, bool PANEL = false, class Epi>
; __device__ __forceinline__ void gemm_phase(const bf16_t* __restrict__ A, long lda, const bf16_t* __restrict__ Bt, long ldb, int nM, int nN, int K,
;                                            const Epi& epi, bf16_t* shm, int w0) {
;     ...
;     for (int t = 0; t < nt - 2; t += 2) {
;       LDB(B0, 0, 0); SCHED; LDA(At, 0, 0); STAGE(SA(1, 1), A, lda, aoff, brow + HALF, t + 1);
;       WAIT_L(8); BAR; WAIT_L(0); MMA(0, 0, At, B0); BAR; SCHED;
;       LDB(B1, 0, 1); STAGE(SB(0, 0), Bt, ldb, boff, bcol, t + 2);
;       BAR; WAIT_L(0); MMA(0, 1, At, B1); BAR;
;       LDA(At, 0, 1); STAGE(SA(0, 0), A, lda, aoff, brow, t + 2);
;       BAR; WAIT_L(0); MMA(1, 0, At, B0); BAR; SCHED;
;       STAGE(SB(0, 1), Bt, ldb, boff, bcol + HALF, t + 2);
;       WAIT_V(6); BAR; MMA(1, 1, At, B1); BAR;
;       LDB(B0, 1, 0); SCHED; LDA(At, 1, 0); STAGE(SA(0, 1), A, lda, aoff, brow + HALF, t + 2);
;       WAIT_L(8); BAR; WAIT_L(0); MMA(0, 0, At, B0); BAR; SCHED;
;       LDB(B1, 1, 1); STAGE(SB(1, 0), Bt, ldb, boff, bcol, t + 3);
;       BAR; WAIT_L(0); MMA(0, 1, At, B1); BAR;
;       LDA(At, 1, 1); STAGE(SA(1, 0), A, lda, aoff, brow, t + 3);
;       BAR; WAIT_L(0); MMA(1, 0, At, B0); BAR; SCHED;
;       STAGE(SB(1, 1), Bt, ldb, boff, bcol + HALF, t + 3);
;       WAIT_V(6); BAR; MMA(1, 1, At, B1); BAR;
;     }
	v_mfma_f32_16x16x32_bf16 v[30:33], v[200:203], v[168:171], v[30:33]
	v_mfma_f32_16x16x32_bf16 v[26:29], v[208:211], v[168:171], v[26:29]
	v_mfma_f32_16x16x32_bf16 v[22:25], v[200:203], v[176:179], v[22:25]
	v_mfma_f32_16x16x32_bf16 v[18:21], v[208:211], v[176:179], v[18:21]
	v_mfma_f32_16x16x32_bf16 v[14:17], v[200:203], v[184:187], v[14:17]
	v_mfma_f32_16x16x32_bf16 v[10:13], v[208:211], v[184:187], v[10:13]
	v_mfma_f32_16x16x32_bf16 v[6:9], v[200:203], v[192:195], v[6:9]
	v_mfma_f32_16x16x32_bf16 v[2:5], v[208:211], v[192:195], v[2:5]
	v_mfma_f32_16x16x32_bf16 v[30:33], v[204:207], v[172:175], v[30:33]
	v_mfma_f32_16x16x32_bf16 v[26:29], v[212:215], v[172:175], v[26:29]
	v_mfma_f32_16x16x32_bf16 v[22:25], v[204:207], v[180:183], v[22:25]
	v_mfma_f32_16x16x32_bf16 v[18:21], v[212:215], v[180:183], v[18:21]
	v_mfma_f32_16x16x32_bf16 v[14:17], v[204:207], v[188:191], v[14:17]
	v_mfma_f32_16x16x32_bf16 v[10:13], v[212:215], v[188:191], v[10:13]
	v_mfma_f32_16x16x32_bf16 v[6:9], v[204:207], v[196:199], v[6:9]
	v_mfma_f32_16x16x32_bf16 v[2:5], v[212:215], v[196:199], v[2:5]
	s_barrier
	ds_read_b128 v[152:155], v222
	ds_read_b128 v[156:159], v222 offset:1024
	ds_read_b128 v[160:163], v222 offset:2048
	ds_read_b128 v[164:167], v222 offset:3072
	ds_read_b128 v[168:171], v143 offset:32768
	ds_read_b128 v[172:175], v143 offset:33792
	ds_read_b128 v[176:179], v143 offset:34816
	ds_read_b128 v[180:183], v143 offset:35840
	ds_read_b128 v[184:187], v143 offset:36864
	ds_read_b128 v[188:191], v143 offset:37888
	ds_read_b128 v[192:195], v143 offset:38912
	ds_read_b128 v[196:199], v143 offset:39936
	s_mov_b32 m0, s43
	s_add_u32 s98, s12, s68
	s_addc_u32 s99, s13, s69
	global_load_lds_dwordx4 v131, s[98:99]
	s_mov_b32 m0, s44
	s_add_u32 s98, s12, s70
	s_addc_u32 s99, s13, s71
	global_load_lds_dwordx4 v131, s[98:99]
	s_waitcnt lgkmcnt(8)
	s_waitcnt vmcnt(10)
	s_barrier
	s_waitcnt lgkmcnt(0)
	s_waitcnt lgkmcnt(0)
	v_mfma_f32_16x16x32_bf16 v[126:129], v[152:155], v[168:171], v[126:129]
	v_mfma_f32_16x16x32_bf16 v[122:125], v[160:163], v[168:171], v[122:125]
	v_mfma_f32_16x16x32_bf16 v[118:121], v[152:155], v[176:179], v[118:121]
	v_mfma_f32_16x16x32_bf16 v[114:117], v[160:163], v[176:179], v[114:117]
	v_mfma_f32_16x16x32_bf16 v[110:113], v[152:155], v[184:187], v[110:113]
	v_mfma_f32_16x16x32_bf16 v[106:109], v[160:163], v[184:187], v[106:109]
	v_mfma_f32_16x16x32_bf16 v[102:105], v[152:155], v[192:195], v[102:105]
	v_mfma_f32_16x16x32_bf16 v[98:101], v[160:163], v[192:195], v[98:101]
	v_mfma_f32_16x16x32_bf16 v[126:129], v[156:159], v[172:175], v[126:129]
	v_mfma_f32_16x16x32_bf16 v[122:125], v[164:167], v[172:175], v[122:125]
	v_mfma_f32_16x16x32_bf16 v[118:121], v[156:159], v[180:183], v[118:121]
	v_mfma_f32_16x16x32_bf16 v[114:117], v[164:167], v[180:183], v[114:117]
	v_mfma_f32_16x16x32_bf16 v[110:113], v[156:159], v[188:191], v[110:113]
	v_mfma_f32_16x16x32_bf16 v[106:109], v[164:167], v[188:191], v[106:109]
	v_mfma_f32_16x16x32_bf16 v[102:105], v[156:159], v[196:199], v[102:105]
	v_mfma_f32_16x16x32_bf16 v[98:101], v[164:167], v[196:199], v[98:101]
	s_barrier
	ds_read_b128 v[200:203], v223
	ds_read_b128 v[204:207], v223 offset:1024
	ds_read_b128 v[208:211], v223 offset:2048
	ds_read_b128 v[212:215], v223 offset:3072
	s_mov_b32 m0, s45
	s_add_u32 s98, s14, s94
	s_addc_u32 s99, s15, s95
	global_load_lds_dwordx4 v131, s[98:99]
	s_mov_b32 m0, s46
	s_add_u32 s98, s14, s72
	s_addc_u32 s99, s15, s73
	global_load_lds_dwordx4 v131, s[98:99]
	s_waitcnt vmcnt(10)
	s_barrier
	s_waitcnt lgkmcnt(0)
	s_waitcnt lgkmcnt(0)
	v_mfma_f32_16x16x32_bf16 v[94:97], v[200:203], v[168:171], v[94:97]
	v_mfma_f32_16x16x32_bf16 v[90:93], v[208:211], v[168:171], v[90:93]
	v_mfma_f32_16x16x32_bf16 v[86:89], v[200:203], v[176:179], v[86:89]
	v_mfma_f32_16x16x32_bf16 v[82:85], v[208:211], v[176:179], v[82:85]
	v_mfma_f32_16x16x32_bf16 v[78:81], v[200:203], v[184:187], v[78:81]
	v_mfma_f32_16x16x32_bf16 v[74:77], v[208:211], v[184:187], v[74:77]
	v_mfma_f32_16x16x32_bf16 v[70:73], v[200:203], v[192:195], v[70:73]
	v_mfma_f32_16x16x32_bf16 v[66:69], v[208:211], v[192:195], v[66:69]
	v_mfma_f32_16x16x32_bf16 v[94:97], v[204:207], v[172:175], v[94:97]
	v_mfma_f32_16x16x32_bf16 v[90:93], v[212:215], v[172:175], v[90:93]
	v_mfma_f32_16x16x32_bf16 v[86:89], v[204:207], v[180:183], v[86:89]
	v_mfma_f32_16x16x32_bf16 v[82:85], v[212:215], v[180:183], v[82:85]
	v_mfma_f32_16x16x32_bf16 v[78:81], v[204:207], v[188:191], v[78:81]
	v_mfma_f32_16x16x32_bf16 v[74:77], v[212:215], v[188:191], v[74:77]
	v_mfma_f32_16x16x32_bf16 v[70:73], v[204:207], v[196:199], v[70:73]
	v_mfma_f32_16x16x32_bf16 v[66:69], v[212:215], v[196:199], v[66:69]
	s_barrier
; #define LDA(dst, b, h) for (int m = 0; m < 4; ++m) for (int k = 0; k < 2; ++k) \
;     dst[m][k] = *reinterpret_cast<const bf16x8*>((char*)SA(b, h) + a_thr + (m * 2 + k) * 1024)
; #define LDB(dst, b, h) for (int n = 0; n < 2; ++n) for (int k = 0; k < 2; ++k) \
;     dst[n][k] = *reinterpret_cast<const bf16x8*>((char*)SB(b, h) + b_thr + (n * 2 + k) * 1024)
; #define MMA(ai, bj, At, Btf) do { __builtin_amdgcn_s_setprio(1); \
;     for (int m = 0; m < 4; ++m) for (int n = 0; n < 2; ++n) for (int k = 0; k < 2; ++k) \
;       acc[ai][bj][m][n] = __builtin_amdgcn_mfma_f32_16x16x32_bf16(Btf[n][k], At[m][k], acc[ai][bj][m][n], 0, 0, 0); \
;     __builtin_amdgcn_s_setprio(0); } while (0)
; #define WAIT_V(n) asm volatile("s_waitcnt vmcnt(" #n ")" ::: "memory")
; #define WAIT_L(n) asm volatile("s_waitcnt lgkmcnt(" #n ")" ::: "memory")
; #define BAR __builtin_amdgcn_s_barrier()
; template <bool OVL, bool PANEL = false, class Epi>
; __device__ __forceinline__ void gemm_phase(const bf16_t* __restrict__ A, long lda, const bf16_t* __restrict__ Bt, long ldb, int nM, int nN, int K,
;                                            const Epi& epi, bf16_t* shm, int w0) {
;     ...
;     for (int t = 0; t < nt - 2; t += 2) {
;       LDB(B0, 0, 0); SCHED; LDA(At, 0, 0); STAGE(SA(1, 1), A, lda, aoff, brow + HALF, t + 1);
;       WAIT_L(8); BAR; WAIT_L(0); MMA(0, 0, At, B0); BAR; SCHED;
;       LDB(B1, 0, 1); STAGE(SB(0, 0), Bt, ldb, boff, bcol, t + 2);
;       BAR; WAIT_L(0); MMA(0, 1, At, B1); BAR;
;       LDA(At, 0, 1); STAGE(SA(0, 0), A, lda, aoff, brow, t + 2);
;       BAR; WAIT_L(0); MMA(1, 0, At, B0); BAR; SCHED;
;       STAGE(SB(0, 1), Bt, ldb, boff, bcol + HALF, t + 2);
;       WAIT_V(6); BAR; MMA(1, 1, At, B1); BAR;
;       LDB(B0, 1, 0); SCHED; LDA(At, 1, 0); STAGE(SA(0, 1), A, lda, aoff, brow + HALF, t + 2);
;       WAIT_L(8); BAR; WAIT_L(0); MMA(0, 0, At, B0); BAR; SCHED;
;       LDB(B1, 1, 1); STAGE(SB(1, 0), Bt, ldb, boff, bcol, t + 3);
;       BAR; WAIT_L(0); MMA(0, 1, At, B1); BAR;
;       LDA(At, 1, 1); STAGE(SA(1, 0), A, lda, aoff, brow, t + 3);
;       BAR; WAIT_L(0); MMA(1, 0, At, B0); BAR; SCHED;
;       STAGE(SB(1, 1), Bt, ldb, boff, bcol + HALF, t + 3);
;       WAIT_V(6); BAR; MMA(1, 1, At, B1); BAR;
;     }
;     { LDB(B0, 0, 0); LDA(At, 0, 0); STAGE(SA(1, 1), A, lda, aoff, brow + HALF, nt - 1);
;       BAR; WAIT_L(0); MMA(0, 0, At, B0); BAR;
	ds_read_b128 v[168:171], v143 offset:49152
	ds_read_b128 v[172:175], v143 offset:50176
	ds_read_b128 v[176:179], v143 offset:51200
	ds_read_b128 v[180:183], v143 offset:52224
	ds_read_b128 v[184:187], v143 offset:53248
	ds_read_b128 v[188:191], v143 offset:54272
	ds_read_b128 v[192:195], v143 offset:55296
	ds_read_b128 v[196:199], v143 offset:56320
	s_mov_b32 m0, s47
	s_add_u32 s98, s12, s94
	s_addc_u32 s99, s13, s95
	global_load_lds_dwordx4 v131, s[98:99]
	s_mov_b32 m0, s48
	s_add_u32 s98, s12, s72
	s_addc_u32 s99, s13, s73
	global_load_lds_dwordx4 v131, s[98:99]
	s_barrier
	s_waitcnt lgkmcnt(0)
	s_waitcnt lgkmcnt(0)
	v_mfma_f32_16x16x32_bf16 v[62:65], v[152:155], v[168:171], v[62:65]
	v_mfma_f32_16x16x32_bf16 v[58:61], v[160:163], v[168:171], v[58:61]
	v_mfma_f32_16x16x32_bf16 v[54:57], v[152:155], v[176:179], v[54:57]
	v_mfma_f32_16x16x32_bf16 v[50:53], v[160:163], v[176:179], v[50:53]
	v_mfma_f32_16x16x32_bf16 v[46:49], v[152:155], v[184:187], v[46:49]
	v_mfma_f32_16x16x32_bf16 v[42:45], v[160:163], v[184:187], v[42:45]
	v_mfma_f32_16x16x32_bf16 v[38:41], v[152:155], v[192:195], v[38:41]
	v_mfma_f32_16x16x32_bf16 v[34:37], v[160:163], v[192:195], v[34:37]
	v_mfma_f32_16x16x32_bf16 v[62:65], v[156:159], v[172:175], v[62:65]
	v_mfma_f32_16x16x32_bf16 v[58:61], v[164:167], v[172:175], v[58:61]
	v_mfma_f32_16x16x32_bf16 v[54:57], v[156:159], v[180:183], v[54:57]
	v_mfma_f32_16x16x32_bf16 v[50:53], v[164:167], v[180:183], v[50:53]
	v_mfma_f32_16x16x32_bf16 v[46:49], v[156:159], v[188:191], v[46:49]
	v_mfma_f32_16x16x32_bf16 v[42:45], v[164:167], v[188:191], v[42:45]
	v_mfma_f32_16x16x32_bf16 v[38:41], v[156:159], v[196:199], v[38:41]
	v_mfma_f32_16x16x32_bf16 v[34:37], v[164:167], v[196:199], v[34:37]
	s_barrier
	s_mov_b32 m0, s49
	s_add_u32 s98, s14, s26
	s_addc_u32 s99, s15, s27
	global_load_lds_dwordx4 v131, s[98:99]
	s_mov_b32 m0, s50
	s_add_u32 s98, s14, s28
	s_addc_u32 s99, s15, s29
	global_load_lds_dwordx4 v131, s[98:99]
	s_waitcnt vmcnt(10)
	s_barrier
	v_mfma_f32_16x16x32_bf16 v[30:33], v[200:203], v[168:171], v[30:33]
	v_mfma_f32_16x16x32_bf16 v[26:29], v[208:211], v[168:171], v[26:29]
	v_mfma_f32_16x16x32_bf16 v[22:25], v[200:203], v[176:179], v[22:25]
	v_mfma_f32_16x16x32_bf16 v[18:21], v[208:211], v[176:179], v[18:21]
	v_mfma_f32_16x16x32_bf16 v[14:17], v[200:203], v[184:187], v[14:17]
	v_mfma_f32_16x16x32_bf16 v[10:13], v[208:211], v[184:187], v[10:13]
	v_mfma_f32_16x16x32_bf16 v[6:9], v[200:203], v[192:195], v[6:9]
	v_mfma_f32_16x16x32_bf16 v[2:5], v[208:211], v[192:195], v[2:5]
	v_mfma_f32_16x16x32_bf16 v[30:33], v[204:207], v[172:175], v[30:33]
	v_mfma_f32_16x16x32_bf16 v[26:29], v[212:215], v[172:175], v[26:29]
	v_mfma_f32_16x16x32_bf16 v[22:25], v[204:207], v[180:183], v[22:25]
	v_mfma_f32_16x16x32_bf16 v[18:21], v[212:215], v[180:183], v[18:21]
	v_mfma_f32_16x16x32_bf16 v[14:17], v[204:207], v[188:191], v[14:17]
	v_mfma_f32_16x16x32_bf16 v[10:13], v[212:215], v[188:191], v[10:13]
	v_mfma_f32_16x16x32_bf16 v[6:9], v[204:207], v[196:199], v[6:9]
	v_mfma_f32_16x16x32_bf16 v[2:5], v[212:215], v[196:199], v[2:5]
	s_add_i32 s21, s21, 2
	s_add_u32 s10, s10, 0x100
	s_addc_u32 s11, s11, 0
	s_cmp_lt_u32 s21, 12
	s_barrier
	s_cbranch_scc1 .LBB0_410
	s_waitcnt vmcnt(6)
	v_add_u32_e32 v212, 16, v140
	v_add_u32_e32 v0, 0x10000, v212
	ds_read_b128 v[144:147], v0
	ds_read_b128 v[152:155], v0 offset:1024
	ds_read_b128 v[156:159], v0 offset:2048
	ds_read_b128 v[160:163], v0 offset:3072
	ds_read_b128 v[164:167], v143
	ds_read_b128 v[168:171], v143 offset:1024
	ds_read_b128 v[172:175], v143 offset:2048
	ds_read_b128 v[176:179], v143 offset:3072
	ds_read_b128 v[180:183], v143 offset:4096
	ds_read_b128 v[184:187], v143 offset:5120
	ds_read_b128 v[188:191], v143 offset:6144
	ds_read_b128 v[192:195], v143 offset:7168
	v_mov_b32_e32 v0, v131
	s_mov_b64 s[0:1], 0x40780
	v_lshl_add_u64 v[148:149], s[8:9], 0, v[0:1]
	v_lshl_add_u64 v[196:197], v[148:149], 0, s[0:1]
	v_readfirstlane_b32 s0, v150
	s_mov_b32 m0, s0
	s_mov_b64 s[0:1], 0x60780
	v_lshl_add_u64 v[148:149], v[148:149], 0, s[0:1]
	v_readfirstlane_b32 s0, v151
	global_load_lds_dwordx4 v[196:197], off
	s_mov_b32 m0, s0
	s_nop 0
	global_load_lds_dwordx4 v[148:149], off
	s_barrier
	s_waitcnt lgkmcnt(0)

; #define LDA(dst, b, h) for (int m = 0; m < 4; ++m) for (int k = 0; k < 2; ++k) \
;     dst[m][k] = *reinterpret_cast<const bf16x8*>((char*)SA(b, h) + a_thr + (m * 2 + k) * 1024)
; #define LDB(dst, b, h) for (int n = 0; n < 2; ++n) for (int k = 0; k < 2; ++k) \
;     dst[n][k] = *reinterpret_cast<const bf16x8*>((char*)SB(b, h) + b_thr + (n * 2 + k) * 1024)
; #define MMA(ai, bj, At, Btf) do { __builtin_amdgcn_s_setprio(1); \
;     for (int m = 0; m < 4; ++m) for (int n = 0; n < 2; ++n) for (int k = 0; k < 2; ++k) \
;       acc[ai][bj][m][n] = __builtin_amdgcn_mfma_f32_16x16x32_bf16(Btf[n][k], At[m][k], acc[ai][bj][m][n], 0, 0, 0); \
;     __builtin_amdgcn_s_setprio(0); } while (0)
; #define WAIT_L(n) asm volatile("s_waitcnt lgkmcnt(" #n ")" ::: "memory")
; #define BAR __builtin_amdgcn_s_barrier()
; template <bool OVL, bool PANEL = false, class Epi>
; __device__ __forceinline__ void gemm_phase(const bf16_t* __restrict__ A, long lda, const bf16_t* __restrict__ Bt, long ldb, int nM, int nN, int K,
;                                            const Epi& epi, bf16_t* shm, int w0) {
;     ...
;     { LDB(B0, 0, 0); LDA(At, 0, 0); STAGE(SA(1, 1), A, lda, aoff, brow + HALF, nt - 1);
;       BAR; WAIT_L(0); MMA(0, 0, At, B0); BAR;
	s_waitcnt lgkmcnt(0)
	v_mfma_f32_16x16x32_bf16 v[126:129], v[144:147], v[164:167], v[126:129]
	v_mfma_f32_16x16x32_bf16 v[122:125], v[156:159], v[164:167], v[122:125]
	v_mfma_f32_16x16x32_bf16 v[118:121], v[144:147], v[172:175], v[118:121]
	v_mfma_f32_16x16x32_bf16 v[114:117], v[156:159], v[172:175], v[114:117]
	v_mfma_f32_16x16x32_bf16 v[110:113], v[144:147], v[180:183], v[110:113]
	v_mfma_f32_16x16x32_bf16 v[106:109], v[156:159], v[180:183], v[106:109]
	v_mfma_f32_16x16x32_bf16 v[102:105], v[144:147], v[188:191], v[102:105]
	v_mfma_f32_16x16x32_bf16 v[126:129], v[152:155], v[168:171], v[126:129]
	v_mfma_f32_16x16x32_bf16 v[122:125], v[160:163], v[168:171], v[122:125]
	v_mfma_f32_16x16x32_bf16 v[118:121], v[152:155], v[176:179], v[118:121]
	v_mfma_f32_16x16x32_bf16 v[114:117], v[160:163], v[176:179], v[114:117]
	v_mfma_f32_16x16x32_bf16 v[110:113], v[152:155], v[184:187], v[110:113]
	v_mfma_f32_16x16x32_bf16 v[106:109], v[160:163], v[184:187], v[106:109]
	v_mfma_f32_16x16x32_bf16 v[102:105], v[152:155], v[192:195], v[102:105]
	v_mfma_f32_16x16x32_bf16 v[98:101], v[156:159], v[188:191], v[98:101]
	v_mfma_f32_16x16x32_bf16 v[148:151], v[160:163], v[192:195], v[98:101]

; #define LDB(dst, b, h) for (int n = 0; n < 2; ++n) for (int k = 0; k < 2; ++k) \
;     dst[n][k] = *reinterpret_cast<const bf16x8*>((char*)SB(b, h) + b_thr + (n * 2 + k) * 1024)
; #define MMA(ai, bj, At, Btf) do { __builtin_amdgcn_s_setprio(1); \
;     for (int m = 0; m < 4; ++m) for (int n = 0; n < 2; ++n) for (int k = 0; k < 2; ++k) \
;       acc[ai][bj][m][n] = __builtin_amdgcn_mfma_f32_16x16x32_bf16(Btf[n][k], At[m][k], acc[ai][bj][m][n], 0, 0, 0); \
;     __builtin_amdgcn_s_setprio(0); } while (0)
; #define WAIT_L(n) asm volatile("s_waitcnt lgkmcnt(" #n ")" ::: "memory")
; #define BAR __builtin_amdgcn_s_barrier()
; template <bool OVL, bool PANEL = false, class Epi>
; __device__ __forceinline__ void gemm_phase(const bf16_t* __restrict__ A, long lda, const bf16_t* __restrict__ Bt, long ldb, int nM, int nN, int K,
;                                            const Epi& epi, bf16_t* shm, int w0) {
;     ...
;       LDB(B1, 0, 1); BAR; WAIT_L(0); MMA(0, 1, At, B1); BAR;
	v_add_u32_e32 v0, 0x14000, v212
	s_barrier
	s_nop 3
	ds_read_b128 v[98:101], v0
	ds_read_b128 v[196:199], v0 offset:1024
	ds_read_b128 v[200:203], v0 offset:2048
	ds_read_b128 v[204:207], v0 offset:3072
	s_barrier
	s_waitcnt lgkmcnt(0)

; #define LDB(dst, b, h) for (int n = 0; n < 2; ++n) for (int k = 0; k < 2; ++k) \
;     dst[n][k] = *reinterpret_cast<const bf16x8*>((char*)SB(b, h) + b_thr + (n * 2 + k) * 1024)
; #define MMA(ai, bj, At, Btf) do { __builtin_amdgcn_s_setprio(1); \
;     for (int m = 0; m < 4; ++m) for (int n = 0; n < 2; ++n) for (int k = 0; k < 2; ++k) \
;       acc[ai][bj][m][n] = __builtin_amdgcn_mfma_f32_16x16x32_bf16(Btf[n][k], At[m][k], acc[ai][bj][m][n], 0, 0, 0); \
;     __builtin_amdgcn_s_setprio(0); } while (0)
; #define WAIT_L(n) asm volatile("s_waitcnt lgkmcnt(" #n ")" ::: "memory")
; #define BAR __builtin_amdgcn_s_barrier()
; template <bool OVL, bool PANEL = false, class Epi>
; __device__ __forceinline__ void gemm_phase(const bf16_t* __restrict__ A, long lda, const bf16_t* __restrict__ Bt, long ldb, int nM, int nN, int K,
;                                            const Epi& epi, bf16_t* shm, int w0) {
;     ...
;       LDB(B1, 0, 1); BAR; WAIT_L(0); MMA(0, 1, At, B1); BAR;
	s_waitcnt lgkmcnt(0)
	v_mfma_f32_16x16x32_bf16 v[94:97], v[98:101], v[164:167], v[94:97]
	v_mfma_f32_16x16x32_bf16 v[86:89], v[98:101], v[172:175], v[86:89]
	v_mfma_f32_16x16x32_bf16 v[82:85], v[200:203], v[172:175], v[82:85]
	v_mfma_f32_16x16x32_bf16 v[78:81], v[98:101], v[180:183], v[78:81]
	v_mfma_f32_16x16x32_bf16 v[74:77], v[200:203], v[180:183], v[74:77]
	v_mfma_f32_16x16x32_bf16 v[94:97], v[196:199], v[168:171], v[94:97]
	v_mfma_f32_16x16x32_bf16 v[90:93], v[200:203], v[164:167], v[90:93]
	v_mfma_f32_16x16x32_bf16 v[86:89], v[196:199], v[176:179], v[86:89]
	v_mfma_f32_16x16x32_bf16 v[82:85], v[204:207], v[176:179], v[82:85]
	v_mfma_f32_16x16x32_bf16 v[78:81], v[196:199], v[184:187], v[78:81]
	v_mfma_f32_16x16x32_bf16 v[74:77], v[204:207], v[184:187], v[74:77]
	v_mfma_f32_16x16x32_bf16 v[70:73], v[98:101], v[188:191], v[70:73]
	v_mfma_f32_16x16x32_bf16 v[66:69], v[200:203], v[188:191], v[66:69]
	v_mfma_f32_16x16x32_bf16 v[164:167], v[204:207], v[168:171], v[90:93]
	v_mfma_f32_16x16x32_bf16 v[168:171], v[196:199], v[192:195], v[70:73]
	v_mfma_f32_16x16x32_bf16 v[172:175], v[204:207], v[192:195], v[66:69]

; #define LDA(dst, b, h) for (int m = 0; m < 4; ++m) for (int k = 0; k < 2; ++k) \
;     dst[m][k] = *reinterpret_cast<const bf16x8*>((char*)SA(b, h) + a_thr + (m * 2 + k) * 1024)
; #define MMA(ai, bj, At, Btf) do { __builtin_amdgcn_s_setprio(1); \
;     for (int m = 0; m < 4; ++m) for (int n = 0; n < 2; ++n) for (int k = 0; k < 2; ++k) \
;       acc[ai][bj][m][n] = __builtin_amdgcn_mfma_f32_16x16x32_bf16(Btf[n][k], At[m][k], acc[ai][bj][m][n], 0, 0, 0); \
;     __builtin_amdgcn_s_setprio(0); } while (0)
; #define WAIT_V(n) asm volatile("s_waitcnt vmcnt(" #n ")" ::: "memory")
; #define WAIT_L(n) asm volatile("s_waitcnt lgkmcnt(" #n ")" ::: "memory")
; #define BAR __builtin_amdgcn_s_barrier()
; template <bool OVL, bool PANEL = false, class Epi>
; __device__ __forceinline__ void gemm_phase(const bf16_t* __restrict__ A, long lda, const bf16_t* __restrict__ Bt, long ldb, int nM, int nN, int K,
;                                            const Epi& epi, bf16_t* shm, int w0) {
;     ...
;       LDA(At, 0, 1); WAIT_V(4); BAR; WAIT_L(0); MMA(1, 0, At, B0); MMA(1, 1, At, B1); BAR; }
	s_barrier
	s_nop 2
	ds_read_b128 v[66:69], v143 offset:16384
	ds_read_b128 v[70:73], v143 offset:17408
	ds_read_b128 v[90:93], v143 offset:18432
	ds_read_b128 v[176:179], v143 offset:19456
	ds_read_b128 v[180:183], v143 offset:20480
	ds_read_b128 v[184:187], v143 offset:21504
	ds_read_b128 v[188:191], v143 offset:22528
	ds_read_b128 v[192:195], v143 offset:23552
	s_waitcnt vmcnt(4)
	s_barrier
	s_waitcnt lgkmcnt(0)

; #define LDA(dst, b, h) for (int m = 0; m < 4; ++m) for (int k = 0; k < 2; ++k) \
;     dst[m][k] = *reinterpret_cast<const bf16x8*>((char*)SA(b, h) + a_thr + (m * 2 + k) * 1024)
; #define MMA(ai, bj, At, Btf) do { __builtin_amdgcn_s_setprio(1); \
;     for (int m = 0; m < 4; ++m) for (int n = 0; n < 2; ++n) for (int k = 0; k < 2; ++k) \
;       acc[ai][bj][m][n] = __builtin_amdgcn_mfma_f32_16x16x32_bf16(Btf[n][k], At[m][k], acc[ai][bj][m][n], 0, 0, 0); \
;     __builtin_amdgcn_s_setprio(0); } while (0)
; #define WAIT_V(n) asm volatile("s_waitcnt vmcnt(" #n ")" ::: "memory")
; #define WAIT_L(n) asm volatile("s_waitcnt lgkmcnt(" #n ")" ::: "memory")
; #define BAR __builtin_amdgcn_s_barrier()
; template <bool OVL, bool PANEL = false, class Epi>
; __device__ __forceinline__ void gemm_phase(const bf16_t* __restrict__ A, long lda, const bf16_t* __restrict__ Bt, long ldb, int nM, int nN, int K,
;                                            const Epi& epi, bf16_t* shm, int w0) {
;     ...
;       LDA(At, 0, 1); WAIT_V(4); BAR; WAIT_L(0); MMA(1, 0, At, B0); MMA(1, 1, At, B1); BAR; }
	s_waitcnt lgkmcnt(0)
	v_mfma_f32_16x16x32_bf16 v[62:65], v[144:147], v[66:69], v[62:65]
	v_mfma_f32_16x16x32_bf16 v[54:57], v[144:147], v[90:93], v[54:57]
	v_mfma_f32_16x16x32_bf16 v[50:53], v[156:159], v[90:93], v[50:53]
	v_mfma_f32_16x16x32_bf16 v[46:49], v[144:147], v[180:183], v[46:49]
	v_mfma_f32_16x16x32_bf16 v[42:45], v[156:159], v[180:183], v[42:45]
	v_mfma_f32_16x16x32_bf16 v[38:41], v[144:147], v[188:191], v[38:41]
	v_mfma_f32_16x16x32_bf16 v[34:37], v[156:159], v[188:191], v[34:37]
	v_mfma_f32_16x16x32_bf16 v[62:65], v[152:155], v[70:73], v[62:65]
	v_mfma_f32_16x16x32_bf16 v[58:61], v[156:159], v[66:69], v[58:61]
	v_mfma_f32_16x16x32_bf16 v[54:57], v[152:155], v[176:179], v[54:57]
	v_mfma_f32_16x16x32_bf16 v[50:53], v[160:163], v[176:179], v[50:53]
	v_mfma_f32_16x16x32_bf16 v[46:49], v[152:155], v[184:187], v[46:49]
	v_mfma_f32_16x16x32_bf16 v[42:45], v[160:163], v[184:187], v[42:45]
	v_mfma_f32_16x16x32_bf16 v[38:41], v[152:155], v[192:195], v[38:41]
	v_mfma_f32_16x16x32_bf16 v[34:37], v[160:163], v[192:195], v[34:37]
	v_mfma_f32_16x16x32_bf16 v[208:211], v[160:163], v[70:73], v[58:61]


; #define LDA(dst, b, h) for (int m = 0; m < 4; ++m) for (int k = 0; k < 2; ++k) \
;     dst[m][k] = *reinterpret_cast<const bf16x8*>((char*)SA(b, h) + a_thr + (m * 2 + k) * 1024)
; #define MMA(ai, bj, At, Btf) do { __builtin_amdgcn_s_setprio(1); \
;     for (int m = 0; m < 4; ++m) for (int n = 0; n < 2; ++n) for (int k = 0; k < 2; ++k) \
;       acc[ai][bj][m][n] = __builtin_amdgcn_mfma_f32_16x16x32_bf16(Btf[n][k], At[m][k], acc[ai][bj][m][n], 0, 0, 0); \
;     __builtin_amdgcn_s_setprio(0); } while (0)
; #define WAIT_V(n) asm volatile("s_waitcnt vmcnt(" #n ")" ::: "memory")
; #define WAIT_L(n) asm volatile("s_waitcnt lgkmcnt(" #n ")" ::: "memory")
; #define BAR __builtin_amdgcn_s_barrier()
; template <bool OVL, bool PANEL = false, class Epi>
; __device__ __forceinline__ void gemm_phase(const bf16_t* __restrict__ A, long lda, const bf16_t* __restrict__ Bt, long ldb, int nM, int nN, int K,
;                                            const Epi& epi, bf16_t* shm, int w0) {
;     ...
;       LDA(At, 0, 1); WAIT_V(4); BAR; WAIT_L(0); MMA(1, 0, At, B0); MMA(1, 1, At, B1); BAR; }
	v_mfma_f32_16x16x32_bf16 v[30:33], v[98:101], v[66:69], v[30:33]
	v_mfma_f32_16x16x32_bf16 v[26:29], v[200:203], v[66:69], v[26:29]
	v_mfma_f32_16x16x32_bf16 v[22:25], v[98:101], v[90:93], v[22:25]
	v_mfma_f32_16x16x32_bf16 v[18:21], v[200:203], v[90:93], v[18:21]
	v_mfma_f32_16x16x32_bf16 v[14:17], v[98:101], v[180:183], v[14:17]
	v_mfma_f32_16x16x32_bf16 v[10:13], v[200:203], v[180:183], v[10:13]
	v_mfma_f32_16x16x32_bf16 v[6:9], v[98:101], v[188:191], v[6:9]
	v_mfma_f32_16x16x32_bf16 v[2:5], v[200:203], v[188:191], v[2:5]
	v_mfma_f32_16x16x32_bf16 v[30:33], v[196:199], v[70:73], v[30:33]
	v_mfma_f32_16x16x32_bf16 v[26:29], v[204:207], v[70:73], v[26:29]
	v_mfma_f32_16x16x32_bf16 v[22:25], v[196:199], v[176:179], v[22:25]
	v_mfma_f32_16x16x32_bf16 v[18:21], v[204:207], v[176:179], v[18:21]
	v_mfma_f32_16x16x32_bf16 v[14:17], v[196:199], v[184:187], v[14:17]
	v_mfma_f32_16x16x32_bf16 v[10:13], v[204:207], v[184:187], v[10:13]
	v_mfma_f32_16x16x32_bf16 v[6:9], v[196:199], v[192:195], v[6:9]
	v_mfma_f32_16x16x32_bf16 v[2:5], v[204:207], v[192:195], v[2:5]

; #define LDA(dst, b, h) for (int m = 0; m < 4; ++m) for (int k = 0; k < 2; ++k) \
;     dst[m][k] = *reinterpret_cast<const bf16x8*>((char*)SA(b, h) + a_thr + (m * 2 + k) * 1024)
; #define LDB(dst, b, h) for (int n = 0; n < 2; ++n) for (int k = 0; k < 2; ++k) \
;     dst[n][k] = *reinterpret_cast<const bf16x8*>((char*)SB(b, h) + b_thr + (n * 2 + k) * 1024)
; #define MMA(ai, bj, At, Btf) do { __builtin_amdgcn_s_setprio(1); \
;     for (int m = 0; m < 4; ++m) for (int n = 0; n < 2; ++n) for (int k = 0; k < 2; ++k) \
;       acc[ai][bj][m][n] = __builtin_amdgcn_mfma_f32_16x16x32_bf16(Btf[n][k], At[m][k], acc[ai][bj][m][n], 0, 0, 0); \
;     __builtin_amdgcn_s_setprio(0); } while (0)
; #define WAIT_V(n) asm volatile("s_waitcnt vmcnt(" #n ")" ::: "memory")
; #define WAIT_L(n) asm volatile("s_waitcnt lgkmcnt(" #n ")" ::: "memory")
; #define BAR __builtin_amdgcn_s_barrier()
; template <bool OVL, bool PANEL = false, class Epi>
; __device__ __forceinline__ void gemm_phase(const bf16_t* __restrict__ A, long lda, const bf16_t* __restrict__ Bt, long ldb, int nM, int nN, int K,
;                                            const Epi& epi, bf16_t* shm, int w0) {
;     ...
;     { LDB(B0, 1, 0); LDA(At, 1, 0); WAIT_V(2); BAR; WAIT_L(0); MMA(0, 0, At, B0); BAR;
	v_add_u32_e32 v0, 0x18000, v212
	s_barrier
	ds_read_b128 v[144:147], v0
	ds_read_b128 v[152:155], v0 offset:1024
	ds_read_b128 v[156:159], v0 offset:2048
	ds_read_b128 v[160:163], v0 offset:3072
	ds_read_b128 v[58:61], v143 offset:32768
	ds_read_b128 v[66:69], v143 offset:33792
	ds_read_b128 v[70:73], v143 offset:34816
	ds_read_b128 v[176:179], v143 offset:35840
	ds_read_b128 v[180:183], v143 offset:36864
	ds_read_b128 v[184:187], v143 offset:37888
	ds_read_b128 v[188:191], v143 offset:38912
	ds_read_b128 v[192:195], v143 offset:39936
	s_waitcnt vmcnt(2)
	s_barrier
	s_waitcnt lgkmcnt(0)

; #define LDA(dst, b, h) for (int m = 0; m < 4; ++m) for (int k = 0; k < 2; ++k) \
;     dst[m][k] = *reinterpret_cast<const bf16x8*>((char*)SA(b, h) + a_thr + (m * 2 + k) * 1024)
; #define LDB(dst, b, h) for (int n = 0; n < 2; ++n) for (int k = 0; k < 2; ++k) \
;     dst[n][k] = *reinterpret_cast<const bf16x8*>((char*)SB(b, h) + b_thr + (n * 2 + k) * 1024)
; #define MMA(ai, bj, At, Btf) do { __builtin_amdgcn_s_setprio(1); \
;     for (int m = 0; m < 4; ++m) for (int n = 0; n < 2; ++n) for (int k = 0; k < 2; ++k) \
;       acc[ai][bj][m][n] = __builtin_amdgcn_mfma_f32_16x16x32_bf16(Btf[n][k], At[m][k], acc[ai][bj][m][n], 0, 0, 0); \
;     __builtin_amdgcn_s_setprio(0); } while (0)
; #define WAIT_V(n) asm volatile("s_waitcnt vmcnt(" #n ")" ::: "memory")
; #define WAIT_L(n) asm volatile("s_waitcnt lgkmcnt(" #n ")" ::: "memory")
; #define BAR __builtin_amdgcn_s_barrier()
; template <bool OVL, bool PANEL = false, class Epi>
; __device__ __forceinline__ void gemm_phase(const bf16_t* __restrict__ A, long lda, const bf16_t* __restrict__ Bt, long ldb, int nM, int nN, int K,
;                                            const Epi& epi, bf16_t* shm, int w0) {
;     ...
;     { LDB(B0, 1, 0); LDA(At, 1, 0); WAIT_V(2); BAR; WAIT_L(0); MMA(0, 0, At, B0); BAR;
	s_waitcnt lgkmcnt(0)
	v_mfma_f32_16x16x32_bf16 v[90:93], v[144:147], v[58:61], v[126:129]
	v_mfma_f32_16x16x32_bf16 v[126:129], v[152:155], v[66:69], v[90:93]
	v_mfma_f32_16x16x32_bf16 v[90:93], v[156:159], v[58:61], v[122:125]
	v_mfma_f32_16x16x32_bf16 v[122:125], v[160:163], v[66:69], v[90:93]
	v_mfma_f32_16x16x32_bf16 v[90:93], v[144:147], v[70:73], v[118:121]
	v_mfma_f32_16x16x32_bf16 v[118:121], v[152:155], v[176:179], v[90:93]
	v_mfma_f32_16x16x32_bf16 v[90:93], v[156:159], v[70:73], v[114:117]
	v_mfma_f32_16x16x32_bf16 v[114:117], v[160:163], v[176:179], v[90:93]
	v_mfma_f32_16x16x32_bf16 v[90:93], v[144:147], v[180:183], v[110:113]
	v_mfma_f32_16x16x32_bf16 v[110:113], v[152:155], v[184:187], v[90:93]
	v_mfma_f32_16x16x32_bf16 v[90:93], v[156:159], v[180:183], v[106:109]
	v_mfma_f32_16x16x32_bf16 v[106:109], v[160:163], v[184:187], v[90:93]
	v_mfma_f32_16x16x32_bf16 v[90:93], v[144:147], v[188:191], v[102:105]
	v_mfma_f32_16x16x32_bf16 v[98:101], v[152:155], v[192:195], v[90:93]
	v_mfma_f32_16x16x32_bf16 v[90:93], v[156:159], v[188:191], v[148:151]
	v_mfma_f32_16x16x32_bf16 v[90:93], v[160:163], v[192:195], v[90:93]

; #define LDB(dst, b, h) for (int n = 0; n < 2; ++n) for (int k = 0; k < 2; ++k) \
;     dst[n][k] = *reinterpret_cast<const bf16x8*>((char*)SB(b, h) + b_thr + (n * 2 + k) * 1024)
; #define MMA(ai, bj, At, Btf) do { __builtin_amdgcn_s_setprio(1); \
;     for (int m = 0; m < 4; ++m) for (int n = 0; n < 2; ++n) for (int k = 0; k < 2; ++k) \
;       acc[ai][bj][m][n] = __builtin_amdgcn_mfma_f32_16x16x32_bf16(Btf[n][k], At[m][k], acc[ai][bj][m][n], 0, 0, 0); \
;     __builtin_amdgcn_s_setprio(0); } while (0)
; #define WAIT_V(n) asm volatile("s_waitcnt vmcnt(" #n ")" ::: "memory")
; #define WAIT_L(n) asm volatile("s_waitcnt lgkmcnt(" #n ")" ::: "memory")
; #define BAR __builtin_amdgcn_s_barrier()
; template <bool OVL, bool PANEL = false, class Epi>
; __device__ __forceinline__ void gemm_phase(const bf16_t* __restrict__ A, long lda, const bf16_t* __restrict__ Bt, long ldb, int nM, int nN, int K,
;                                            const Epi& epi, bf16_t* shm, int w0) {
;     ...
;       LDB(B1, 1, 1); WAIT_V(0); BAR; WAIT_L(0); MMA(0, 1, At, B1); BAR;
	v_add_u32_e32 v0, 0x1c000, v212
	s_barrier
	ds_read_b128 v[148:151], v0
	ds_read_b128 v[196:199], v0 offset:1024
	ds_read_b128 v[200:203], v0 offset:2048
	ds_read_b128 v[204:207], v0 offset:3072
	s_waitcnt vmcnt(0)
	s_barrier
	s_waitcnt lgkmcnt(0)

; #define LDB(dst, b, h) for (int n = 0; n < 2; ++n) for (int k = 0; k < 2; ++k) \
;     dst[n][k] = *reinterpret_cast<const bf16x8*>((char*)SB(b, h) + b_thr + (n * 2 + k) * 1024)
; #define MMA(ai, bj, At, Btf) do { __builtin_amdgcn_s_setprio(1); \
;     for (int m = 0; m < 4; ++m) for (int n = 0; n < 2; ++n) for (int k = 0; k < 2; ++k) \
;       acc[ai][bj][m][n] = __builtin_amdgcn_mfma_f32_16x16x32_bf16(Btf[n][k], At[m][k], acc[ai][bj][m][n], 0, 0, 0); \
;     __builtin_amdgcn_s_setprio(0); } while (0)
; #define WAIT_V(n) asm volatile("s_waitcnt vmcnt(" #n ")" ::: "memory")
; #define WAIT_L(n) asm volatile("s_waitcnt lgkmcnt(" #n ")" ::: "memory")
; #define BAR __builtin_amdgcn_s_barrier()
; template <bool OVL, bool PANEL = false, class Epi>
; __device__ __forceinline__ void gemm_phase(const bf16_t* __restrict__ A, long lda, const bf16_t* __restrict__ Bt, long ldb, int nM, int nN, int K,
;                                            const Epi& epi, bf16_t* shm, int w0) {
;     ...
;       LDB(B1, 1, 1); WAIT_V(0); BAR; WAIT_L(0); MMA(0, 1, At, B1); BAR;
	s_waitcnt lgkmcnt(0)
	v_mfma_f32_16x16x32_bf16 v[94:97], v[148:151], v[58:61], v[94:97]
	v_mfma_f32_16x16x32_bf16 v[58:61], v[200:203], v[58:61], v[164:167]
	v_mfma_f32_16x16x32_bf16 v[102:105], v[196:199], v[66:69], v[94:97]
	v_mfma_f32_16x16x32_bf16 v[94:97], v[204:207], v[66:69], v[58:61]
	v_mfma_f32_16x16x32_bf16 v[58:61], v[148:151], v[70:73], v[86:89]
	v_mfma_f32_16x16x32_bf16 v[86:89], v[196:199], v[176:179], v[58:61]
	v_mfma_f32_16x16x32_bf16 v[58:61], v[200:203], v[70:73], v[82:85]
	v_mfma_f32_16x16x32_bf16 v[82:85], v[204:207], v[176:179], v[58:61]
	v_mfma_f32_16x16x32_bf16 v[58:61], v[148:151], v[180:183], v[78:81]
	v_mfma_f32_16x16x32_bf16 v[78:81], v[196:199], v[184:187], v[58:61]
	v_mfma_f32_16x16x32_bf16 v[58:61], v[200:203], v[180:183], v[74:77]
	v_mfma_f32_16x16x32_bf16 v[70:73], v[204:207], v[184:187], v[58:61]
	v_mfma_f32_16x16x32_bf16 v[58:61], v[148:151], v[188:191], v[168:171]
	v_mfma_f32_16x16x32_bf16 v[66:69], v[196:199], v[192:195], v[58:61]
	v_mfma_f32_16x16x32_bf16 v[58:61], v[200:203], v[188:191], v[172:175]
	v_mfma_f32_16x16x32_bf16 v[58:61], v[204:207], v[192:195], v[58:61]

; #define LDA(dst, b, h) for (int m = 0; m < 4; ++m) for (int k = 0; k < 2; ++k) \
;     dst[m][k] = *reinterpret_cast<const bf16x8*>((char*)SA(b, h) + a_thr + (m * 2 + k) * 1024)
; #define MMA(ai, bj, At, Btf) do { __builtin_amdgcn_s_setprio(1); \
;     for (int m = 0; m < 4; ++m) for (int n = 0; n < 2; ++n) for (int k = 0; k < 2; ++k) \
;       acc[ai][bj][m][n] = __builtin_amdgcn_mfma_f32_16x16x32_bf16(Btf[n][k], At[m][k], acc[ai][bj][m][n], 0, 0, 0); \
;     __builtin_amdgcn_s_setprio(0); } while (0)
; #define WAIT_L(n) asm volatile("s_waitcnt lgkmcnt(" #n ")" ::: "memory")
; #define BAR __builtin_amdgcn_s_barrier()
; template <bool OVL, bool PANEL = false, class Epi>
; __device__ __forceinline__ void gemm_phase(const bf16_t* __restrict__ A, long lda, const bf16_t* __restrict__ Bt, long ldb, int nM, int nN, int K,
;                                            const Epi& epi, bf16_t* shm, int w0) {
;     ...
;       LDA(At, 1, 1); BAR; WAIT_L(0); MMA(1, 0, At, B0); MMA(1, 1, At, B1); BAR; }
	s_barrier
	ds_read_b128 v[164:167], v143 offset:49152
	ds_read_b128 v[168:171], v143 offset:50176
	ds_read_b128 v[172:175], v143 offset:51200
	ds_read_b128 v[176:179], v143 offset:52224
	ds_read_b128 v[180:183], v143 offset:53248
	ds_read_b128 v[184:187], v143 offset:54272
	ds_read_b128 v[188:191], v143 offset:55296
	ds_read_b128 v[192:195], v143 offset:56320
	s_barrier
	s_waitcnt lgkmcnt(0)

; #define LDA(dst, b, h) for (int m = 0; m < 4; ++m) for (int k = 0; k < 2; ++k) \
;     dst[m][k] = *reinterpret_cast<const bf16x8*>((char*)SA(b, h) + a_thr + (m * 2 + k) * 1024)
; #define MMA(ai, bj, At, Btf) do { __builtin_amdgcn_s_setprio(1); \
;     for (int m = 0; m < 4; ++m) for (int n = 0; n < 2; ++n) for (int k = 0; k < 2; ++k) \
;       acc[ai][bj][m][n] = __builtin_amdgcn_mfma_f32_16x16x32_bf16(Btf[n][k], At[m][k], acc[ai][bj][m][n], 0, 0, 0); \
;     __builtin_amdgcn_s_setprio(0); } while (0)
; #define WAIT_L(n) asm volatile("s_waitcnt lgkmcnt(" #n ")" ::: "memory")
; #define BAR __builtin_amdgcn_s_barrier()
; template <bool OVL, bool PANEL = false, class Epi>
; __device__ __forceinline__ void gemm_phase(const bf16_t* __restrict__ A, long lda, const bf16_t* __restrict__ Bt, long ldb, int nM, int nN, int K,
;                                            const Epi& epi, bf16_t* shm, int w0) {
;     ...
;       LDA(At, 1, 1); BAR; WAIT_L(0); MMA(1, 0, At, B0); MMA(1, 1, At, B1); BAR; }
	s_waitcnt lgkmcnt(0)
	v_mfma_f32_16x16x32_bf16 v[62:65], v[144:147], v[164:167], v[62:65]
	v_mfma_f32_16x16x32_bf16 v[74:77], v[152:155], v[168:171], v[62:65]
	v_mfma_f32_16x16x32_bf16 v[62:65], v[156:159], v[164:167], v[208:211]
	v_mfma_f32_16x16x32_bf16 v[54:57], v[144:147], v[172:175], v[54:57]
	v_mfma_f32_16x16x32_bf16 v[50:53], v[156:159], v[172:175], v[50:53]
	v_mfma_f32_16x16x32_bf16 v[46:49], v[144:147], v[180:183], v[46:49]
	v_mfma_f32_16x16x32_bf16 v[42:45], v[156:159], v[180:183], v[42:45]
	v_mfma_f32_16x16x32_bf16 v[38:41], v[144:147], v[188:191], v[38:41]
	v_mfma_f32_16x16x32_bf16 v[34:37], v[156:159], v[188:191], v[34:37]
	v_mfma_f32_16x16x32_bf16 v[62:65], v[160:163], v[168:171], v[62:65]
	v_mfma_f32_16x16x32_bf16 v[54:57], v[152:155], v[176:179], v[54:57]
	v_mfma_f32_16x16x32_bf16 v[50:53], v[160:163], v[176:179], v[50:53]
	v_mfma_f32_16x16x32_bf16 v[46:49], v[152:155], v[184:187], v[46:49]
	v_mfma_f32_16x16x32_bf16 v[42:45], v[160:163], v[184:187], v[42:45]
	v_mfma_f32_16x16x32_bf16 v[38:41], v[152:155], v[192:195], v[38:41]
	v_mfma_f32_16x16x32_bf16 v[34:37], v[160:163], v[192:195], v[34:37]


; #define LDA(dst, b, h) for (int m = 0; m < 4; ++m) for (int k = 0; k < 2; ++k) \
;     dst[m][k] = *reinterpret_cast<const bf16x8*>((char*)SA(b, h) + a_thr + (m * 2 + k) * 1024)
; #define MMA(ai, bj, At, Btf) do { __builtin_amdgcn_s_setprio(1); \
;     for (int m = 0; m < 4; ++m) for (int n = 0; n < 2; ++n) for (int k = 0; k < 2; ++k) \
;       acc[ai][bj][m][n] = __builtin_amdgcn_mfma_f32_16x16x32_bf16(Btf[n][k], At[m][k], acc[ai][bj][m][n], 0, 0, 0); \
;     __builtin_amdgcn_s_setprio(0); } while (0)
; #define WAIT_L(n) asm volatile("s_waitcnt lgkmcnt(" #n ")" ::: "memory")
; #define BAR __builtin_amdgcn_s_barrier()
; template <bool OVL, bool PANEL = false, class Epi>
; __device__ __forceinline__ void gemm_phase(const bf16_t* __restrict__ A, long lda, const bf16_t* __restrict__ Bt, long ldb, int nM, int nN, int K,
;                                            const Epi& epi, bf16_t* shm, int w0) {
;     ...
;       LDA(At, 1, 1); BAR; WAIT_L(0); MMA(1, 0, At, B0); MMA(1, 1, At, B1); BAR; }
	v_mfma_f32_16x16x32_bf16 v[30:33], v[148:151], v[164:167], v[30:33]
	v_mfma_f32_16x16x32_bf16 v[26:29], v[200:203], v[164:167], v[26:29]
	v_mfma_f32_16x16x32_bf16 v[22:25], v[148:151], v[172:175], v[22:25]
	v_mfma_f32_16x16x32_bf16 v[18:21], v[200:203], v[172:175], v[18:21]
	v_mfma_f32_16x16x32_bf16 v[14:17], v[148:151], v[180:183], v[14:17]
	v_mfma_f32_16x16x32_bf16 v[10:13], v[200:203], v[180:183], v[10:13]
	v_mfma_f32_16x16x32_bf16 v[6:9], v[148:151], v[188:191], v[6:9]
	v_mfma_f32_16x16x32_bf16 v[2:5], v[200:203], v[188:191], v[2:5]
	v_mfma_f32_16x16x32_bf16 v[30:33], v[196:199], v[168:171], v[30:33]
	v_mfma_f32_16x16x32_bf16 v[26:29], v[204:207], v[168:171], v[26:29]
	v_mfma_f32_16x16x32_bf16 v[22:25], v[196:199], v[176:179], v[22:25]
	v_mfma_f32_16x16x32_bf16 v[18:21], v[204:207], v[176:179], v[18:21]
	v_mfma_f32_16x16x32_bf16 v[14:17], v[196:199], v[184:187], v[14:17]
	v_mfma_f32_16x16x32_bf16 v[10:13], v[204:207], v[184:187], v[10:13]
	v_mfma_f32_16x16x32_bf16 v[6:9], v[196:199], v[192:195], v[6:9]
	v_mfma_f32_16x16x32_bf16 v[2:5], v[204:207], v[192:195], v[2:5]

; #define LDA(dst, b, h) for (int m = 0; m < 4; ++m) for (int k = 0; k < 2; ++k) \
;     dst[m][k] = *reinterpret_cast<const bf16x8*>((char*)SA(b, h) + a_thr + (m * 2 + k) * 1024)
; #define MMA(ai, bj, At, Btf) do { __builtin_amdgcn_s_setprio(1); \
;     for (int m = 0; m < 4; ++m) for (int n = 0; n < 2; ++n) for (int k = 0; k < 2; ++k) \
;       acc[ai][bj][m][n] = __builtin_amdgcn_mfma_f32_16x16x32_bf16(Btf[n][k], At[m][k], acc[ai][bj][m][n], 0, 0, 0); \
;     __builtin_amdgcn_s_setprio(0); } while (0)
; #define WAIT_L(n) asm volatile("s_waitcnt lgkmcnt(" #n ")" ::: "memory")
; #define BAR __builtin_amdgcn_s_barrier()
; template <bool OVL, bool PANEL = false, class Epi>
; __device__ __forceinline__ void gemm_phase(const bf16_t* __restrict__ A, long lda, const bf16_t* __restrict__ Bt, long ldb, int nM, int nN, int K,
;                                            const Epi& epi, bf16_t* shm, int w0) {
;     ...
;       LDA(At, 1, 1); BAR; WAIT_L(0); MMA(1, 0, At, B0); MMA(1, 1, At, B1); BAR; }
;     if (wr == 0) BAR;
	s_barrier
	s_and_saveexec_b64 s[0:1], s[6:7]
	s_cbranch_execz .LBB0_413
	s_barrier

; #define LDA(dst, b, h) for (int m = 0; m < 4; ++m) for (int k = 0; k < 2; ++k) \
;     dst[m][k] = *reinterpret_cast<const bf16x8*>((char*)SA(b, h) + a_thr + (m * 2 + k) * 1024)
; #define LDB(dst, b, h) for (int n = 0; n < 2; ++n) for (int k = 0; k < 2; ++k) \
;     dst[n][k] = *reinterpret_cast<const bf16x8*>((char*)SB(b, h) + b_thr + (n * 2 + k) * 1024)
; #define MMA(ai, bj, At, Btf) do { __builtin_amdgcn_s_setprio(1); \
;     for (int m = 0; m < 4; ++m) for (int n = 0; n < 2; ++n) for (int k = 0; k < 2; ++k) \
;       acc[ai][bj][m][n] = __builtin_amdgcn_mfma_f32_16x16x32_bf16(Btf[n][k], At[m][k], acc[ai][bj][m][n], 0, 0, 0); \
;     __builtin_amdgcn_s_setprio(0); } while (0)
; #define WAIT_V(n) asm volatile("s_waitcnt vmcnt(" #n ")" ::: "memory")
; #define WAIT_L(n) asm volatile("s_waitcnt lgkmcnt(" #n ")" ::: "memory")
; #define BAR __builtin_amdgcn_s_barrier()
; #define SCHED __builtin_amdgcn_sched_barrier(0)
; template <bool OVL, bool PANEL = false, class Epi>
; __device__ __forceinline__ void gemm_phase(const bf16_t* __restrict__ A, long lda, const bf16_t* __restrict__ Bt, long ldb, int nM, int nN, int K,
;                                            const Epi& epi, bf16_t* shm, int w0) {
;     ...
;     for (int t = 0; t < nt - 2; t += 2) {
;       LDB(B0, 0, 0); SCHED; LDA(At, 0, 0); STAGE(SA(1, 1), A, lda, aoff, brow + HALF, t + 1);
;       WAIT_L(8); BAR; WAIT_L(0); MMA(0, 0, At, B0); BAR; SCHED;
;       LDB(B1, 0, 1); STAGE(SB(0, 0), Bt, ldb, boff, bcol, t + 2);
;       BAR; WAIT_L(0); MMA(0, 1, At, B1); BAR;
;       LDA(At, 0, 1); STAGE(SA(0, 0), A, lda, aoff, brow, t + 2);
;       BAR; WAIT_L(0); MMA(1, 0, At, B0); BAR; SCHED;
;       STAGE(SB(0, 1), Bt, ldb, boff, bcol + HALF, t + 2);
;       WAIT_V(6); BAR; MMA(1, 1, At, B1); BAR;
;       LDB(B0, 1, 0); SCHED; LDA(At, 1, 0); STAGE(SA(0, 1), A, lda, aoff, brow + HALF, t + 2);
;       WAIT_L(8); BAR; WAIT_L(0); MMA(0, 0, At, B0); BAR; SCHED;
;       LDB(B1, 1, 1); STAGE(SB(1, 0), Bt, ldb, boff, bcol, t + 3);
;       BAR; WAIT_L(0); MMA(0, 1, At, B1); BAR;
;       LDA(At, 1, 1); STAGE(SA(1, 0), A, lda, aoff, brow, t + 3);
;       BAR; WAIT_L(0); MMA(1, 0, At, B0); BAR; SCHED;
;       STAGE(SB(1, 1), Bt, ldb, boff, bcol + HALF, t + 3);
;       WAIT_V(6); BAR; MMA(1, 1, At, B1); BAR;
;     }
.LBB0_472:
	ds_read_b128 v[138:141], v206
	ds_read_b128 v[142:145], v206 offset:1024
	ds_read_b128 v[146:149], v206 offset:2048
	ds_read_b128 v[150:153], v206 offset:3072
	s_add_u32 vcc_lo, s8, s80
	s_addc_u32 vcc_hi, s9, s81
	ds_read_b128 v[154:157], v241
	ds_read_b128 v[158:161], v241 offset:1024
	ds_read_b128 v[162:165], v241 offset:2048
	ds_read_b128 v[166:169], v241 offset:3072
	ds_read_b128 v[170:173], v241 offset:4096
	ds_read_b128 v[174:177], v241 offset:5120
	ds_read_b128 v[178:181], v241 offset:6144
	ds_read_b128 v[182:185], v241 offset:7168
	s_mov_b32 m0, s16
	s_add_u32 s98, vcc_lo, s12
	s_addc_u32 s99, vcc_hi, s13
	global_load_lds_dwordx4 v221, s[98:99]
	s_mov_b32 m0, s32
	s_add_u32 s98, vcc_lo, s36
	s_addc_u32 s99, vcc_hi, s37
	global_load_lds_dwordx4 v221, s[98:99]
	s_waitcnt lgkmcnt(8)
	s_waitcnt vmcnt(10)
	s_barrier
	s_waitcnt lgkmcnt(0)
	s_waitcnt lgkmcnt(0)
	v_mfma_f32_16x16x32_bf16 v[126:129], v[138:141], v[154:157], v[126:129]
	v_mfma_f32_16x16x32_bf16 v[122:125], v[146:149], v[154:157], v[122:125]
	v_mfma_f32_16x16x32_bf16 v[118:121], v[138:141], v[162:165], v[118:121]
	v_mfma_f32_16x16x32_bf16 v[114:117], v[146:149], v[162:165], v[114:117]
	v_mfma_f32_16x16x32_bf16 v[110:113], v[138:141], v[170:173], v[110:113]
	v_mfma_f32_16x16x32_bf16 v[106:109], v[146:149], v[170:173], v[106:109]
	v_mfma_f32_16x16x32_bf16 v[102:105], v[138:141], v[178:181], v[102:105]
	v_mfma_f32_16x16x32_bf16 v[98:101], v[146:149], v[178:181], v[98:101]
	v_mfma_f32_16x16x32_bf16 v[126:129], v[142:145], v[158:161], v[126:129]
	v_mfma_f32_16x16x32_bf16 v[122:125], v[150:153], v[158:161], v[122:125]
	v_mfma_f32_16x16x32_bf16 v[118:121], v[142:145], v[166:169], v[118:121]
	v_mfma_f32_16x16x32_bf16 v[114:117], v[150:153], v[166:169], v[114:117]
	v_mfma_f32_16x16x32_bf16 v[110:113], v[142:145], v[174:177], v[110:113]
	v_mfma_f32_16x16x32_bf16 v[106:109], v[150:153], v[174:177], v[106:109]
	v_mfma_f32_16x16x32_bf16 v[102:105], v[142:145], v[182:185], v[102:105]
	v_mfma_f32_16x16x32_bf16 v[98:101], v[150:153], v[182:185], v[98:101]
	s_barrier
	s_add_u32 s0, s6, s80
	ds_read_b128 v[186:189], v207
	ds_read_b128 v[190:193], v207 offset:1024
	ds_read_b128 v[194:197], v207 offset:2048
	ds_read_b128 v[198:201], v207 offset:3072
	s_addc_u32 s1, s7, s81
	s_mov_b32 m0, s44
	s_add_u32 s98, s0, s34
	s_addc_u32 s99, s1, s35
	global_load_lds_dwordx4 v221, s[98:99]
	s_mov_b32 m0, s45
	s_add_u32 s98, s0, s64
	s_addc_u32 s99, s1, s65
	global_load_lds_dwordx4 v221, s[98:99]
	s_waitcnt vmcnt(10)
	s_barrier
	s_waitcnt lgkmcnt(0)
	s_waitcnt lgkmcnt(0)
	v_mfma_f32_16x16x32_bf16 v[94:97], v[186:189], v[154:157], v[94:97]
	v_mfma_f32_16x16x32_bf16 v[90:93], v[194:197], v[154:157], v[90:93]
	v_mfma_f32_16x16x32_bf16 v[86:89], v[186:189], v[162:165], v[86:89]
	v_mfma_f32_16x16x32_bf16 v[82:85], v[194:197], v[162:165], v[82:85]
	v_mfma_f32_16x16x32_bf16 v[78:81], v[186:189], v[170:173], v[78:81]
	v_mfma_f32_16x16x32_bf16 v[74:77], v[194:197], v[170:173], v[74:77]
	v_mfma_f32_16x16x32_bf16 v[70:73], v[186:189], v[178:181], v[70:73]
	v_mfma_f32_16x16x32_bf16 v[66:69], v[194:197], v[178:181], v[66:69]
	v_mfma_f32_16x16x32_bf16 v[94:97], v[190:193], v[158:161], v[94:97]
	v_mfma_f32_16x16x32_bf16 v[90:93], v[198:201], v[158:161], v[90:93]
	v_mfma_f32_16x16x32_bf16 v[86:89], v[190:193], v[166:169], v[86:89]
	v_mfma_f32_16x16x32_bf16 v[82:85], v[198:201], v[166:169], v[82:85]
	v_mfma_f32_16x16x32_bf16 v[78:81], v[190:193], v[174:177], v[78:81]
	v_mfma_f32_16x16x32_bf16 v[74:77], v[198:201], v[174:177], v[74:77]
	v_mfma_f32_16x16x32_bf16 v[70:73], v[190:193], v[182:185], v[70:73]
	v_mfma_f32_16x16x32_bf16 v[66:69], v[198:201], v[182:185], v[66:69]
	s_barrier
	ds_read_b128 v[154:157], v241 offset:16384
	ds_read_b128 v[158:161], v241 offset:17408
	ds_read_b128 v[162:165], v241 offset:18432
	ds_read_b128 v[166:169], v241 offset:19456
	ds_read_b128 v[170:173], v241 offset:20480
	ds_read_b128 v[174:177], v241 offset:21504
	ds_read_b128 v[178:181], v241 offset:22528
	ds_read_b128 v[182:185], v241 offset:23552
	s_mov_b32 m0, s46
	s_add_u32 s98, vcc_lo, s34
	s_addc_u32 s99, vcc_hi, s35
	global_load_lds_dwordx4 v221, s[98:99]
	s_mov_b32 m0, s47
	s_add_u32 s98, vcc_lo, s64
	s_addc_u32 s99, vcc_hi, s65
	global_load_lds_dwordx4 v221, s[98:99]
	s_barrier
	s_waitcnt lgkmcnt(0)
	s_waitcnt lgkmcnt(0)
	v_mfma_f32_16x16x32_bf16 v[62:65], v[138:141], v[154:157], v[62:65]
	v_mfma_f32_16x16x32_bf16 v[58:61], v[146:149], v[154:157], v[58:61]
	v_mfma_f32_16x16x32_bf16 v[54:57], v[138:141], v[162:165], v[54:57]
	v_mfma_f32_16x16x32_bf16 v[50:53], v[146:149], v[162:165], v[50:53]
	v_mfma_f32_16x16x32_bf16 v[46:49], v[138:141], v[170:173], v[46:49]
	v_mfma_f32_16x16x32_bf16 v[42:45], v[146:149], v[170:173], v[42:45]
	v_mfma_f32_16x16x32_bf16 v[38:41], v[138:141], v[178:181], v[38:41]
	v_mfma_f32_16x16x32_bf16 v[34:37], v[146:149], v[178:181], v[34:37]
	v_mfma_f32_16x16x32_bf16 v[62:65], v[142:145], v[158:161], v[62:65]
	v_mfma_f32_16x16x32_bf16 v[58:61], v[150:153], v[158:161], v[58:61]
	v_mfma_f32_16x16x32_bf16 v[54:57], v[142:145], v[166:169], v[54:57]
	v_mfma_f32_16x16x32_bf16 v[50:53], v[150:153], v[166:169], v[50:53]
	v_mfma_f32_16x16x32_bf16 v[46:49], v[142:145], v[174:177], v[46:49]
	v_mfma_f32_16x16x32_bf16 v[42:45], v[150:153], v[174:177], v[42:45]
	v_mfma_f32_16x16x32_bf16 v[38:41], v[142:145], v[182:185], v[38:41]
	v_mfma_f32_16x16x32_bf16 v[34:37], v[150:153], v[182:185], v[34:37]
	s_barrier
	s_mov_b32 m0, s48
	s_add_u32 s98, s0, s68
	s_addc_u32 s99, s1, s69
	global_load_lds_dwordx4 v221, s[98:99]
	s_mov_b32 m0, s49
	s_add_u32 s98, s0, s70
	s_addc_u32 s99, s1, s71
	global_load_lds_dwordx4 v221, s[98:99]
	s_waitcnt vmcnt(10)
	s_barrier
; #define LDA(dst, b, h) for (int m = 0; m < 4; ++m) for (int k = 0; k < 2; ++k) \
;     dst[m][k] = *reinterpret_cast<const bf16x8*>((char*)SA(b, h) + a_thr + (m * 2 + k) * 1024)
; #define LDB(dst, b, h) for (int n = 0; n < 2; ++n) for (int k = 0; k < 2; ++k) \
;     dst[n][k] = *reinterpret_cast<const bf16x8*>((char*)SB(b, h) + b_thr + (n * 2 + k) * 1024)
; #define MMA(ai, bj, At, Btf) do { __builtin_amdgcn_s_setprio(1); \
;     for (int m = 0; m < 4; ++m) for (int n = 0; n < 2; ++n) for (int k = 0; k < 2; ++k) \
;       acc[ai][bj][m][n] = __builtin_amdgcn_mfma_f32_16x16x32_bf16(Btf[n][k], At[m][k], acc[ai][bj][m][n], 0, 0, 0); \
;     __builtin_amdgcn_s_setprio(0); } while (0)
; #define WAIT_V(n) asm volatile("s_waitcnt vmcnt(" #n ")" ::: "memory")
; #define WAIT_L(n) asm volatile("s_waitcnt lgkmcnt(" #n ")" ::: "memory")
; #define BAR __builtin_amdgcn_s_barrier()
; #define SCHED __builtin_amdgcn_sched_barrier(0)
; template <bool OVL, bool PANEL = false, class Epi>
; __device__ __forceinline__ void gemm_phase(const bf16_t* __restrict__ A, long lda, const bf16_t* __restrict__ Bt, long ldb, int nM, int nN, int K,
;                                            const Epi& epi, bf16_t* shm, int w0) {
;     ...
;     for (int t = 0; t < nt - 2; t += 2) {
;       LDB(B0, 0, 0); SCHED; LDA(At, 0, 0); STAGE(SA(1, 1), A, lda, aoff, brow + HALF, t + 1);
;       WAIT_L(8); BAR; WAIT_L(0); MMA(0, 0, At, B0); BAR; SCHED;
;       LDB(B1, 0, 1); STAGE(SB(0, 0), Bt, ldb, boff, bcol, t + 2);
;       BAR; WAIT_L(0); MMA(0, 1, At, B1); BAR;
;       LDA(At, 0, 1); STAGE(SA(0, 0), A, lda, aoff, brow, t + 2);
;       BAR; WAIT_L(0); MMA(1, 0, At, B0); BAR; SCHED;
;       STAGE(SB(0, 1), Bt, ldb, boff, bcol + HALF, t + 2);
;       WAIT_V(6); BAR; MMA(1, 1, At, B1); BAR;
;       LDB(B0, 1, 0); SCHED; LDA(At, 1, 0); STAGE(SA(0, 1), A, lda, aoff, brow + HALF, t + 2);
;       WAIT_L(8); BAR; WAIT_L(0); MMA(0, 0, At, B0); BAR; SCHED;
;       LDB(B1, 1, 1); STAGE(SB(1, 0), Bt, ldb, boff, bcol, t + 3);
;       BAR; WAIT_L(0); MMA(0, 1, At, B1); BAR;
;       LDA(At, 1, 1); STAGE(SA(1, 0), A, lda, aoff, brow, t + 3);
;       BAR; WAIT_L(0); MMA(1, 0, At, B0); BAR; SCHED;
;       STAGE(SB(1, 1), Bt, ldb, boff, bcol + HALF, t + 3);
;       WAIT_V(6); BAR; MMA(1, 1, At, B1); BAR;
;     }
	v_mfma_f32_16x16x32_bf16 v[30:33], v[186:189], v[154:157], v[30:33]
	v_mfma_f32_16x16x32_bf16 v[26:29], v[194:197], v[154:157], v[26:29]
	v_mfma_f32_16x16x32_bf16 v[22:25], v[186:189], v[162:165], v[22:25]
	v_mfma_f32_16x16x32_bf16 v[18:21], v[194:197], v[162:165], v[18:21]
	v_mfma_f32_16x16x32_bf16 v[14:17], v[186:189], v[170:173], v[14:17]
	v_mfma_f32_16x16x32_bf16 v[10:13], v[194:197], v[170:173], v[10:13]
	v_mfma_f32_16x16x32_bf16 v[6:9], v[186:189], v[178:181], v[6:9]
	v_mfma_f32_16x16x32_bf16 v[2:5], v[194:197], v[178:181], v[2:5]
	v_mfma_f32_16x16x32_bf16 v[30:33], v[190:193], v[158:161], v[30:33]
	v_mfma_f32_16x16x32_bf16 v[26:29], v[198:201], v[158:161], v[26:29]
	v_mfma_f32_16x16x32_bf16 v[22:25], v[190:193], v[166:169], v[22:25]
	v_mfma_f32_16x16x32_bf16 v[18:21], v[198:201], v[166:169], v[18:21]
	v_mfma_f32_16x16x32_bf16 v[14:17], v[190:193], v[174:177], v[14:17]
	v_mfma_f32_16x16x32_bf16 v[10:13], v[198:201], v[174:177], v[10:13]
	v_mfma_f32_16x16x32_bf16 v[6:9], v[190:193], v[182:185], v[6:9]
	v_mfma_f32_16x16x32_bf16 v[2:5], v[198:201], v[182:185], v[2:5]
	s_barrier
	ds_read_b128 v[138:141], v208
	ds_read_b128 v[142:145], v208 offset:1024
	ds_read_b128 v[146:149], v208 offset:2048
	ds_read_b128 v[150:153], v208 offset:3072
	ds_read_b128 v[154:157], v241 offset:32768
	ds_read_b128 v[158:161], v241 offset:33792
	ds_read_b128 v[162:165], v241 offset:34816
	ds_read_b128 v[166:169], v241 offset:35840
	ds_read_b128 v[170:173], v241 offset:36864
	ds_read_b128 v[174:177], v241 offset:37888
	ds_read_b128 v[178:181], v241 offset:38912
	ds_read_b128 v[182:185], v241 offset:39936
	s_mov_b32 m0, s50
	s_add_u32 s98, vcc_lo, s68
	s_addc_u32 s99, vcc_hi, s69
	global_load_lds_dwordx4 v221, s[98:99]
	s_mov_b32 m0, s51
	s_add_u32 s98, vcc_lo, s70
	s_addc_u32 s99, vcc_hi, s71
	global_load_lds_dwordx4 v221, s[98:99]
	s_waitcnt lgkmcnt(8)
	s_waitcnt vmcnt(10)
	s_barrier
	s_waitcnt lgkmcnt(0)
	s_waitcnt lgkmcnt(0)
	v_mfma_f32_16x16x32_bf16 v[126:129], v[138:141], v[154:157], v[126:129]
	v_mfma_f32_16x16x32_bf16 v[122:125], v[146:149], v[154:157], v[122:125]
	v_mfma_f32_16x16x32_bf16 v[118:121], v[138:141], v[162:165], v[118:121]
	v_mfma_f32_16x16x32_bf16 v[114:117], v[146:149], v[162:165], v[114:117]
	v_mfma_f32_16x16x32_bf16 v[110:113], v[138:141], v[170:173], v[110:113]
	v_mfma_f32_16x16x32_bf16 v[106:109], v[146:149], v[170:173], v[106:109]
	v_mfma_f32_16x16x32_bf16 v[102:105], v[138:141], v[178:181], v[102:105]
	v_mfma_f32_16x16x32_bf16 v[98:101], v[146:149], v[178:181], v[98:101]
	v_mfma_f32_16x16x32_bf16 v[126:129], v[142:145], v[158:161], v[126:129]
	v_mfma_f32_16x16x32_bf16 v[122:125], v[150:153], v[158:161], v[122:125]
	v_mfma_f32_16x16x32_bf16 v[118:121], v[142:145], v[166:169], v[118:121]
	v_mfma_f32_16x16x32_bf16 v[114:117], v[150:153], v[166:169], v[114:117]
	v_mfma_f32_16x16x32_bf16 v[110:113], v[142:145], v[174:177], v[110:113]
	v_mfma_f32_16x16x32_bf16 v[106:109], v[150:153], v[174:177], v[106:109]
	v_mfma_f32_16x16x32_bf16 v[102:105], v[142:145], v[182:185], v[102:105]
	v_mfma_f32_16x16x32_bf16 v[98:101], v[150:153], v[182:185], v[98:101]
	s_barrier
	ds_read_b128 v[186:189], v209
	ds_read_b128 v[190:193], v209 offset:1024
	ds_read_b128 v[194:197], v209 offset:2048
	ds_read_b128 v[198:201], v209 offset:3072
	s_mov_b32 m0, s52
	s_add_u32 s98, s0, s94
	s_addc_u32 s99, s1, s95
	global_load_lds_dwordx4 v221, s[98:99]
	s_mov_b32 m0, s53
	s_add_u32 s98, s0, s72
	s_addc_u32 s99, s1, s73
	global_load_lds_dwordx4 v221, s[98:99]
	s_waitcnt vmcnt(10)
	s_barrier
	s_waitcnt lgkmcnt(0)
	s_waitcnt lgkmcnt(0)
	v_mfma_f32_16x16x32_bf16 v[94:97], v[186:189], v[154:157], v[94:97]
	v_mfma_f32_16x16x32_bf16 v[90:93], v[194:197], v[154:157], v[90:93]
	v_mfma_f32_16x16x32_bf16 v[86:89], v[186:189], v[162:165], v[86:89]
	v_mfma_f32_16x16x32_bf16 v[82:85], v[194:197], v[162:165], v[82:85]
	v_mfma_f32_16x16x32_bf16 v[78:81], v[186:189], v[170:173], v[78:81]
	v_mfma_f32_16x16x32_bf16 v[74:77], v[194:197], v[170:173], v[74:77]
	v_mfma_f32_16x16x32_bf16 v[70:73], v[186:189], v[178:181], v[70:73]
	v_mfma_f32_16x16x32_bf16 v[66:69], v[194:197], v[178:181], v[66:69]
	v_mfma_f32_16x16x32_bf16 v[94:97], v[190:193], v[158:161], v[94:97]
	v_mfma_f32_16x16x32_bf16 v[90:93], v[198:201], v[158:161], v[90:93]
	v_mfma_f32_16x16x32_bf16 v[86:89], v[190:193], v[166:169], v[86:89]
	v_mfma_f32_16x16x32_bf16 v[82:85], v[198:201], v[166:169], v[82:85]
	v_mfma_f32_16x16x32_bf16 v[78:81], v[190:193], v[174:177], v[78:81]
	v_mfma_f32_16x16x32_bf16 v[74:77], v[198:201], v[174:177], v[74:77]
	v_mfma_f32_16x16x32_bf16 v[70:73], v[190:193], v[182:185], v[70:73]
	v_mfma_f32_16x16x32_bf16 v[66:69], v[198:201], v[182:185], v[66:69]
	s_barrier
; #define LDA(dst, b, h) for (int m = 0; m < 4; ++m) for (int k = 0; k < 2; ++k) \
;     dst[m][k] = *reinterpret_cast<const bf16x8*>((char*)SA(b, h) + a_thr + (m * 2 + k) * 1024)
; #define LDB(dst, b, h) for (int n = 0; n < 2; ++n) for (int k = 0; k < 2; ++k) \
;     dst[n][k] = *reinterpret_cast<const bf16x8*>((char*)SB(b, h) + b_thr + (n * 2 + k) * 1024)
; #define MMA(ai, bj, At, Btf) do { __builtin_amdgcn_s_setprio(1); \
;     for (int m = 0; m < 4; ++m) for (int n = 0; n < 2; ++n) for (int k = 0; k < 2; ++k) \
;       acc[ai][bj][m][n] = __builtin_amdgcn_mfma_f32_16x16x32_bf16(Btf[n][k], At[m][k], acc[ai][bj][m][n], 0, 0, 0); \
;     __builtin_amdgcn_s_setprio(0); } while (0)
; #define WAIT_V(n) asm volatile("s_waitcnt vmcnt(" #n ")" ::: "memory")
; #define WAIT_L(n) asm volatile("s_waitcnt lgkmcnt(" #n ")" ::: "memory")
; #define BAR __builtin_amdgcn_s_barrier()
; template <bool OVL, bool PANEL = false, class Epi>
; __device__ __forceinline__ void gemm_phase(const bf16_t* __restrict__ A, long lda, const bf16_t* __restrict__ Bt, long ldb, int nM, int nN, int K,
;                                            const Epi& epi, bf16_t* shm, int w0) {
;     ...
;     for (int t = 0; t < nt - 2; t += 2) {
;       LDB(B0, 0, 0); SCHED; LDA(At, 0, 0); STAGE(SA(1, 1), A, lda, aoff, brow + HALF, t + 1);
;       WAIT_L(8); BAR; WAIT_L(0); MMA(0, 0, At, B0); BAR; SCHED;
;       LDB(B1, 0, 1); STAGE(SB(0, 0), Bt, ldb, boff, bcol, t + 2);
;       BAR; WAIT_L(0); MMA(0, 1, At, B1); BAR;
;       LDA(At, 0, 1); STAGE(SA(0, 0), A, lda, aoff, brow, t + 2);
;       BAR; WAIT_L(0); MMA(1, 0, At, B0); BAR; SCHED;
;       STAGE(SB(0, 1), Bt, ldb, boff, bcol + HALF, t + 2);
;       WAIT_V(6); BAR; MMA(1, 1, At, B1); BAR;
;       LDB(B0, 1, 0); SCHED; LDA(At, 1, 0); STAGE(SA(0, 1), A, lda, aoff, brow + HALF, t + 2);
;       WAIT_L(8); BAR; WAIT_L(0); MMA(0, 0, At, B0); BAR; SCHED;
;       LDB(B1, 1, 1); STAGE(SB(1, 0), Bt, ldb, boff, bcol, t + 3);
;       BAR; WAIT_L(0); MMA(0, 1, At, B1); BAR;
;       LDA(At, 1, 1); STAGE(SA(1, 0), A, lda, aoff, brow, t + 3);
;       BAR; WAIT_L(0); MMA(1, 0, At, B0); BAR; SCHED;
;       STAGE(SB(1, 1), Bt, ldb, boff, bcol + HALF, t + 3);
;       WAIT_V(6); BAR; MMA(1, 1, At, B1); BAR;
;     }
;     { LDB(B0, 0, 0); LDA(At, 0, 0); STAGE(SA(1, 1), A, lda, aoff, brow + HALF, nt - 1);
;       BAR; WAIT_L(0); MMA(0, 0, At, B0); BAR;
	ds_read_b128 v[154:157], v241 offset:49152
	ds_read_b128 v[158:161], v241 offset:50176
	ds_read_b128 v[162:165], v241 offset:51200
	ds_read_b128 v[166:169], v241 offset:52224
	ds_read_b128 v[170:173], v241 offset:53248
	ds_read_b128 v[174:177], v241 offset:54272
	ds_read_b128 v[178:181], v241 offset:55296
	ds_read_b128 v[182:185], v241 offset:56320
	s_mov_b32 m0, s54
	s_add_u32 s98, vcc_lo, s94
	s_addc_u32 s99, vcc_hi, s95
	global_load_lds_dwordx4 v221, s[98:99]
	s_mov_b32 m0, s55
	s_add_u32 s98, vcc_lo, s72
	s_addc_u32 s99, vcc_hi, s73
	global_load_lds_dwordx4 v221, s[98:99]
	s_barrier
	s_waitcnt lgkmcnt(0)
	s_waitcnt lgkmcnt(0)
	v_mfma_f32_16x16x32_bf16 v[62:65], v[138:141], v[154:157], v[62:65]
	v_mfma_f32_16x16x32_bf16 v[58:61], v[146:149], v[154:157], v[58:61]
	v_mfma_f32_16x16x32_bf16 v[54:57], v[138:141], v[162:165], v[54:57]
	v_mfma_f32_16x16x32_bf16 v[50:53], v[146:149], v[162:165], v[50:53]
	v_mfma_f32_16x16x32_bf16 v[46:49], v[138:141], v[170:173], v[46:49]
	v_mfma_f32_16x16x32_bf16 v[42:45], v[146:149], v[170:173], v[42:45]
	v_mfma_f32_16x16x32_bf16 v[38:41], v[138:141], v[178:181], v[38:41]
	v_mfma_f32_16x16x32_bf16 v[34:37], v[146:149], v[178:181], v[34:37]
	v_mfma_f32_16x16x32_bf16 v[62:65], v[142:145], v[158:161], v[62:65]
	v_mfma_f32_16x16x32_bf16 v[58:61], v[150:153], v[158:161], v[58:61]
	v_mfma_f32_16x16x32_bf16 v[54:57], v[142:145], v[166:169], v[54:57]
	v_mfma_f32_16x16x32_bf16 v[50:53], v[150:153], v[166:169], v[50:53]
	v_mfma_f32_16x16x32_bf16 v[46:49], v[142:145], v[174:177], v[46:49]
	v_mfma_f32_16x16x32_bf16 v[42:45], v[150:153], v[174:177], v[42:45]
	v_mfma_f32_16x16x32_bf16 v[38:41], v[142:145], v[182:185], v[38:41]
	v_mfma_f32_16x16x32_bf16 v[34:37], v[150:153], v[182:185], v[34:37]
	s_barrier
	s_mov_b32 m0, s56
	s_add_u32 s98, s0, s14
	s_addc_u32 s99, s1, s15
	global_load_lds_dwordx4 v221, s[98:99]
	s_mov_b32 m0, s57
	s_add_u32 s98, s0, s18
	s_addc_u32 s99, s1, s19
	global_load_lds_dwordx4 v221, s[98:99]
	s_waitcnt vmcnt(10)
	s_barrier
	v_mfma_f32_16x16x32_bf16 v[30:33], v[186:189], v[154:157], v[30:33]
	v_mfma_f32_16x16x32_bf16 v[26:29], v[194:197], v[154:157], v[26:29]
	v_mfma_f32_16x16x32_bf16 v[22:25], v[186:189], v[162:165], v[22:25]
	v_mfma_f32_16x16x32_bf16 v[18:21], v[194:197], v[162:165], v[18:21]
	v_mfma_f32_16x16x32_bf16 v[14:17], v[186:189], v[170:173], v[14:17]
	v_mfma_f32_16x16x32_bf16 v[10:13], v[194:197], v[170:173], v[10:13]
	v_mfma_f32_16x16x32_bf16 v[6:9], v[186:189], v[178:181], v[6:9]
	v_mfma_f32_16x16x32_bf16 v[2:5], v[194:197], v[178:181], v[2:5]
	v_mfma_f32_16x16x32_bf16 v[30:33], v[190:193], v[158:161], v[30:33]
	v_mfma_f32_16x16x32_bf16 v[26:29], v[198:201], v[158:161], v[26:29]
	v_mfma_f32_16x16x32_bf16 v[22:25], v[190:193], v[166:169], v[22:25]
	v_mfma_f32_16x16x32_bf16 v[18:21], v[198:201], v[166:169], v[18:21]
	v_mfma_f32_16x16x32_bf16 v[14:17], v[190:193], v[174:177], v[14:17]
	v_mfma_f32_16x16x32_bf16 v[10:13], v[198:201], v[174:177], v[10:13]
	v_mfma_f32_16x16x32_bf16 v[6:9], v[190:193], v[182:185], v[6:9]
	v_mfma_f32_16x16x32_bf16 v[2:5], v[198:201], v[182:185], v[2:5]
	s_add_i32 s2, s2, 2
	s_add_u32 s80, s80, 0x100
	s_addc_u32 s81, s81, 0
	s_cmp_gt_u32 s2, 11
	s_barrier
	s_cbranch_scc0 .LBB0_472
	s_waitcnt vmcnt(6)
	s_or_b32 s0, s82, 0x80
	s_ashr_i32 s1, s0, 31
	v_readlane_b32 s44, v252, 20
	s_lshl_b64 s[0:1], s[0:1], 11
	v_readlane_b32 s50, v252, 26
	v_add_u32_e32 v206, 16, v240
	v_readlane_b32 s51, v252, 27
	s_add_u32 s0, s50, s0
	v_add_u32_e32 v0, 0x10000, v206
	s_addc_u32 s1, s51, s1
	ds_read_b128 v[130:133], v0
	ds_read_b128 v[138:141], v0 offset:1024
	ds_read_b128 v[142:145], v0 offset:2048
	ds_read_b128 v[146:149], v0 offset:3072
	ds_read_b128 v[150:153], v241
	ds_read_b128 v[154:157], v241 offset:1024
	ds_read_b128 v[158:161], v241 offset:2048
	ds_read_b128 v[162:165], v241 offset:3072
	ds_read_b128 v[166:169], v241 offset:4096
	ds_read_b128 v[170:173], v241 offset:5120
	ds_read_b128 v[174:177], v241 offset:6144
	ds_read_b128 v[178:181], v241 offset:7168
	v_mov_b32_e32 v0, v221
	v_readlane_b32 s45, v252, 21
	v_lshl_add_u64 v[134:135], s[0:1], 0, v[0:1]
	s_mov_b64 s[0:1], 0x780
	v_lshl_add_u64 v[182:183], v[134:135], 0, s[0:1]
	v_readfirstlane_b32 s0, v136
	s_mov_b32 m0, s0
	s_mov_b64 s[0:1], 0x20780
	v_lshl_add_u64 v[134:135], v[134:135], 0, s[0:1]
	v_readfirstlane_b32 s0, v137
	global_load_lds_dwordx4 v[182:183], off
	s_mov_b32 m0, s0
	v_readlane_b32 s46, v252, 22
	global_load_lds_dwordx4 v[134:135], off
	s_barrier
	s_waitcnt lgkmcnt(0)
	v_readlane_b32 s47, v252, 23
	v_readlane_b32 s48, v252, 24
	v_readlane_b32 s49, v252, 25
	v_readlane_b32 s52, v252, 28
	v_readlane_b32 s53, v252, 29
	v_readlane_b32 s54, v252, 30
	v_readlane_b32 s55, v252, 31
	v_readlane_b32 s56, v252, 32
	v_readlane_b32 s57, v252, 33
	v_readlane_b32 s58, v252, 34
	v_readlane_b32 s59, v252, 35

; #define LDA(dst, b, h) for (int m = 0; m < 4; ++m) for (int k = 0; k < 2; ++k) \
;     dst[m][k] = *reinterpret_cast<const bf16x8*>((char*)SA(b, h) + a_thr + (m * 2 + k) * 1024)
; #define LDB(dst, b, h) for (int n = 0; n < 2; ++n) for (int k = 0; k < 2; ++k) \
;     dst[n][k] = *reinterpret_cast<const bf16x8*>((char*)SB(b, h) + b_thr + (n * 2 + k) * 1024)
; #define MMA(ai, bj, At, Btf) do { __builtin_amdgcn_s_setprio(1); \
;     for (int m = 0; m < 4; ++m) for (int n = 0; n < 2; ++n) for (int k = 0; k < 2; ++k) \
;       acc[ai][bj][m][n] = __builtin_amdgcn_mfma_f32_16x16x32_bf16(Btf[n][k], At[m][k], acc[ai][bj][m][n], 0, 0, 0); \
;     __builtin_amdgcn_s_setprio(0); } while (0)
; #define WAIT_L(n) asm volatile("s_waitcnt lgkmcnt(" #n ")" ::: "memory")
; #define BAR __builtin_amdgcn_s_barrier()
; template <bool OVL, bool PANEL = false, class Epi>
; __device__ __forceinline__ void gemm_phase(const bf16_t* __restrict__ A, long lda, const bf16_t* __restrict__ Bt, long ldb, int nM, int nN, int K,
;                                            const Epi& epi, bf16_t* shm, int w0) {
;     ...
;     { LDB(B0, 0, 0); LDA(At, 0, 0); STAGE(SA(1, 1), A, lda, aoff, brow + HALF, nt - 1);
;       BAR; WAIT_L(0); MMA(0, 0, At, B0); BAR;
	s_waitcnt lgkmcnt(0)
	v_mfma_f32_16x16x32_bf16 v[126:129], v[130:133], v[150:153], v[126:129]
	v_mfma_f32_16x16x32_bf16 v[122:125], v[142:145], v[150:153], v[122:125]
	v_mfma_f32_16x16x32_bf16 v[118:121], v[130:133], v[158:161], v[118:121]
	v_mfma_f32_16x16x32_bf16 v[114:117], v[142:145], v[158:161], v[114:117]
	v_mfma_f32_16x16x32_bf16 v[106:109], v[142:145], v[166:169], v[106:109]
	v_mfma_f32_16x16x32_bf16 v[102:105], v[130:133], v[174:177], v[102:105]
	v_mfma_f32_16x16x32_bf16 v[98:101], v[142:145], v[174:177], v[98:101]
	v_mfma_f32_16x16x32_bf16 v[126:129], v[138:141], v[154:157], v[126:129]
	v_mfma_f32_16x16x32_bf16 v[122:125], v[146:149], v[154:157], v[122:125]
	v_mfma_f32_16x16x32_bf16 v[118:121], v[138:141], v[162:165], v[118:121]
	v_mfma_f32_16x16x32_bf16 v[114:117], v[146:149], v[162:165], v[114:117]
	v_mfma_f32_16x16x32_bf16 v[110:113], v[130:133], v[166:169], v[110:113]
	v_mfma_f32_16x16x32_bf16 v[106:109], v[146:149], v[170:173], v[106:109]
	v_mfma_f32_16x16x32_bf16 v[102:105], v[138:141], v[178:181], v[102:105]
	v_mfma_f32_16x16x32_bf16 v[98:101], v[146:149], v[178:181], v[98:101]
	v_mfma_f32_16x16x32_bf16 v[134:137], v[138:141], v[170:173], v[110:113]

; #define LDB(dst, b, h) for (int n = 0; n < 2; ++n) for (int k = 0; k < 2; ++k) \
;     dst[n][k] = *reinterpret_cast<const bf16x8*>((char*)SB(b, h) + b_thr + (n * 2 + k) * 1024)
; #define MMA(ai, bj, At, Btf) do { __builtin_amdgcn_s_setprio(1); \
;     for (int m = 0; m < 4; ++m) for (int n = 0; n < 2; ++n) for (int k = 0; k < 2; ++k) \
;       acc[ai][bj][m][n] = __builtin_amdgcn_mfma_f32_16x16x32_bf16(Btf[n][k], At[m][k], acc[ai][bj][m][n], 0, 0, 0); \
;     __builtin_amdgcn_s_setprio(0); } while (0)
; #define WAIT_L(n) asm volatile("s_waitcnt lgkmcnt(" #n ")" ::: "memory")
; #define BAR __builtin_amdgcn_s_barrier()
; template <bool OVL, bool PANEL = false, class Epi>
; __device__ __forceinline__ void gemm_phase(const bf16_t* __restrict__ A, long lda, const bf16_t* __restrict__ Bt, long ldb, int nM, int nN, int K,
;                                            const Epi& epi, bf16_t* shm, int w0) {
;     ...
;       LDB(B1, 0, 1); BAR; WAIT_L(0); MMA(0, 1, At, B1); BAR;
	v_add_u32_e32 v0, 0x14000, v206
	s_barrier
	s_nop 0
	ds_read_b128 v[110:113], v0
	ds_read_b128 v[182:185], v0 offset:1024
	ds_read_b128 v[186:189], v0 offset:2048
	ds_read_b128 v[190:193], v0 offset:3072
	s_barrier
	s_waitcnt lgkmcnt(0)

; #define LDB(dst, b, h) for (int n = 0; n < 2; ++n) for (int k = 0; k < 2; ++k) \
;     dst[n][k] = *reinterpret_cast<const bf16x8*>((char*)SB(b, h) + b_thr + (n * 2 + k) * 1024)
; #define MMA(ai, bj, At, Btf) do { __builtin_amdgcn_s_setprio(1); \
;     for (int m = 0; m < 4; ++m) for (int n = 0; n < 2; ++n) for (int k = 0; k < 2; ++k) \
;       acc[ai][bj][m][n] = __builtin_amdgcn_mfma_f32_16x16x32_bf16(Btf[n][k], At[m][k], acc[ai][bj][m][n], 0, 0, 0); \
;     __builtin_amdgcn_s_setprio(0); } while (0)
; #define WAIT_L(n) asm volatile("s_waitcnt lgkmcnt(" #n ")" ::: "memory")
; #define BAR __builtin_amdgcn_s_barrier()
; template <bool OVL, bool PANEL = false, class Epi>
; __device__ __forceinline__ void gemm_phase(const bf16_t* __restrict__ A, long lda, const bf16_t* __restrict__ Bt, long ldb, int nM, int nN, int K,
;                                            const Epi& epi, bf16_t* shm, int w0) {
;     ...
;       LDB(B1, 0, 1); BAR; WAIT_L(0); MMA(0, 1, At, B1); BAR;
	s_waitcnt lgkmcnt(0)
	v_mfma_f32_16x16x32_bf16 v[90:93], v[186:189], v[150:153], v[90:93]
	v_mfma_f32_16x16x32_bf16 v[74:77], v[186:189], v[166:169], v[74:77]
	v_mfma_f32_16x16x32_bf16 v[70:73], v[110:113], v[174:177], v[70:73]
	v_mfma_f32_16x16x32_bf16 v[66:69], v[186:189], v[174:177], v[66:69]
	v_mfma_f32_16x16x32_bf16 v[94:97], v[110:113], v[150:153], v[94:97]
	v_mfma_f32_16x16x32_bf16 v[90:93], v[190:193], v[154:157], v[90:93]
	v_mfma_f32_16x16x32_bf16 v[86:89], v[110:113], v[158:161], v[86:89]
	v_mfma_f32_16x16x32_bf16 v[82:85], v[186:189], v[158:161], v[82:85]
	v_mfma_f32_16x16x32_bf16 v[78:81], v[110:113], v[166:169], v[78:81]
	v_mfma_f32_16x16x32_bf16 v[74:77], v[190:193], v[170:173], v[74:77]
	v_mfma_f32_16x16x32_bf16 v[70:73], v[182:185], v[178:181], v[70:73]
	v_mfma_f32_16x16x32_bf16 v[66:69], v[190:193], v[178:181], v[66:69]
	v_mfma_f32_16x16x32_bf16 v[194:197], v[182:185], v[154:157], v[94:97]
	v_mfma_f32_16x16x32_bf16 v[150:153], v[182:185], v[162:165], v[86:89]
	v_mfma_f32_16x16x32_bf16 v[154:157], v[190:193], v[162:165], v[82:85]
	v_mfma_f32_16x16x32_bf16 v[158:161], v[182:185], v[170:173], v[78:81]

; #define LDA(dst, b, h) for (int m = 0; m < 4; ++m) for (int k = 0; k < 2; ++k) \
;     dst[m][k] = *reinterpret_cast<const bf16x8*>((char*)SA(b, h) + a_thr + (m * 2 + k) * 1024)
; #define MMA(ai, bj, At, Btf) do { __builtin_amdgcn_s_setprio(1); \
;     for (int m = 0; m < 4; ++m) for (int n = 0; n < 2; ++n) for (int k = 0; k < 2; ++k) \
;       acc[ai][bj][m][n] = __builtin_amdgcn_mfma_f32_16x16x32_bf16(Btf[n][k], At[m][k], acc[ai][bj][m][n], 0, 0, 0); \
;     __builtin_amdgcn_s_setprio(0); } while (0)
; #define WAIT_V(n) asm volatile("s_waitcnt vmcnt(" #n ")" ::: "memory")
; #define WAIT_L(n) asm volatile("s_waitcnt lgkmcnt(" #n ")" ::: "memory")
; #define BAR __builtin_amdgcn_s_barrier()
; template <bool OVL, bool PANEL = false, class Epi>
; __device__ __forceinline__ void gemm_phase(const bf16_t* __restrict__ A, long lda, const bf16_t* __restrict__ Bt, long ldb, int nM, int nN, int K,
;                                            const Epi& epi, bf16_t* shm, int w0) {
;     ...
;       LDA(At, 0, 1); WAIT_V(4); BAR; WAIT_L(0); MMA(1, 0, At, B0); MMA(1, 1, At, B1); BAR; }
	s_barrier
	s_nop 0
	ds_read_b128 v[78:81], v241 offset:16384
	ds_read_b128 v[82:85], v241 offset:17408
	ds_read_b128 v[86:89], v241 offset:18432
	ds_read_b128 v[94:97], v241 offset:19456
	ds_read_b128 v[162:165], v241 offset:20480
	ds_read_b128 v[166:169], v241 offset:21504
	ds_read_b128 v[170:173], v241 offset:22528
	ds_read_b128 v[174:177], v241 offset:23552
	s_waitcnt vmcnt(4)
	s_barrier
	s_waitcnt lgkmcnt(0)

; #define LDA(dst, b, h) for (int m = 0; m < 4; ++m) for (int k = 0; k < 2; ++k) \
;     dst[m][k] = *reinterpret_cast<const bf16x8*>((char*)SA(b, h) + a_thr + (m * 2 + k) * 1024)
; #define MMA(ai, bj, At, Btf) do { __builtin_amdgcn_s_setprio(1); \
;     for (int m = 0; m < 4; ++m) for (int n = 0; n < 2; ++n) for (int k = 0; k < 2; ++k) \
;       acc[ai][bj][m][n] = __builtin_amdgcn_mfma_f32_16x16x32_bf16(Btf[n][k], At[m][k], acc[ai][bj][m][n], 0, 0, 0); \
;     __builtin_amdgcn_s_setprio(0); } while (0)
; #define WAIT_V(n) asm volatile("s_waitcnt vmcnt(" #n ")" ::: "memory")
; #define WAIT_L(n) asm volatile("s_waitcnt lgkmcnt(" #n ")" ::: "memory")
; #define BAR __builtin_amdgcn_s_barrier()
; template <bool OVL, bool PANEL = false, class Epi>
; __device__ __forceinline__ void gemm_phase(const bf16_t* __restrict__ A, long lda, const bf16_t* __restrict__ Bt, long ldb, int nM, int nN, int K,
;                                            const Epi& epi, bf16_t* shm, int w0) {
;     ...
;       LDA(At, 0, 1); WAIT_V(4); BAR; WAIT_L(0); MMA(1, 0, At, B0); MMA(1, 1, At, B1); BAR; }
	s_waitcnt lgkmcnt(0)
	v_mfma_f32_16x16x32_bf16 v[62:65], v[130:133], v[78:81], v[62:65]
	v_mfma_f32_16x16x32_bf16 v[58:61], v[142:145], v[78:81], v[58:61]
	v_mfma_f32_16x16x32_bf16 v[54:57], v[130:133], v[86:89], v[54:57]
	v_mfma_f32_16x16x32_bf16 v[50:53], v[142:145], v[86:89], v[50:53]
	v_mfma_f32_16x16x32_bf16 v[46:49], v[130:133], v[162:165], v[46:49]
	v_mfma_f32_16x16x32_bf16 v[42:45], v[142:145], v[162:165], v[42:45]
	v_mfma_f32_16x16x32_bf16 v[34:37], v[142:145], v[170:173], v[34:37]
	v_mfma_f32_16x16x32_bf16 v[62:65], v[138:141], v[82:85], v[62:65]
	v_mfma_f32_16x16x32_bf16 v[58:61], v[146:149], v[82:85], v[58:61]
	v_mfma_f32_16x16x32_bf16 v[54:57], v[138:141], v[94:97], v[54:57]
	v_mfma_f32_16x16x32_bf16 v[50:53], v[146:149], v[94:97], v[50:53]
	v_mfma_f32_16x16x32_bf16 v[46:49], v[138:141], v[166:169], v[46:49]
	v_mfma_f32_16x16x32_bf16 v[42:45], v[146:149], v[166:169], v[42:45]
	v_mfma_f32_16x16x32_bf16 v[38:41], v[130:133], v[170:173], v[38:41]
	v_mfma_f32_16x16x32_bf16 v[34:37], v[146:149], v[174:177], v[34:37]
	v_mfma_f32_16x16x32_bf16 v[130:133], v[138:141], v[174:177], v[38:41]


; #define LDA(dst, b, h) for (int m = 0; m < 4; ++m) for (int k = 0; k < 2; ++k) \
;     dst[m][k] = *reinterpret_cast<const bf16x8*>((char*)SA(b, h) + a_thr + (m * 2 + k) * 1024)
; #define MMA(ai, bj, At, Btf) do { __builtin_amdgcn_s_setprio(1); \
;     for (int m = 0; m < 4; ++m) for (int n = 0; n < 2; ++n) for (int k = 0; k < 2; ++k) \
;       acc[ai][bj][m][n] = __builtin_amdgcn_mfma_f32_16x16x32_bf16(Btf[n][k], At[m][k], acc[ai][bj][m][n], 0, 0, 0); \
;     __builtin_amdgcn_s_setprio(0); } while (0)
; #define WAIT_V(n) asm volatile("s_waitcnt vmcnt(" #n ")" ::: "memory")
; #define WAIT_L(n) asm volatile("s_waitcnt lgkmcnt(" #n ")" ::: "memory")
; #define BAR __builtin_amdgcn_s_barrier()
; template <bool OVL, bool PANEL = false, class Epi>
; __device__ __forceinline__ void gemm_phase(const bf16_t* __restrict__ A, long lda, const bf16_t* __restrict__ Bt, long ldb, int nM, int nN, int K,
;                                            const Epi& epi, bf16_t* shm, int w0) {
;     ...
;       LDA(At, 0, 1); WAIT_V(4); BAR; WAIT_L(0); MMA(1, 0, At, B0); MMA(1, 1, At, B1); BAR; }
	v_mfma_f32_16x16x32_bf16 v[30:33], v[110:113], v[78:81], v[30:33]
	v_mfma_f32_16x16x32_bf16 v[26:29], v[186:189], v[78:81], v[26:29]
	v_mfma_f32_16x16x32_bf16 v[22:25], v[110:113], v[86:89], v[22:25]
	v_mfma_f32_16x16x32_bf16 v[18:21], v[186:189], v[86:89], v[18:21]
	v_mfma_f32_16x16x32_bf16 v[14:17], v[110:113], v[162:165], v[14:17]
	v_mfma_f32_16x16x32_bf16 v[10:13], v[186:189], v[162:165], v[10:13]
	v_mfma_f32_16x16x32_bf16 v[6:9], v[110:113], v[170:173], v[6:9]
	v_mfma_f32_16x16x32_bf16 v[2:5], v[186:189], v[170:173], v[2:5]
	v_mfma_f32_16x16x32_bf16 v[138:141], v[182:185], v[82:85], v[30:33]
	v_mfma_f32_16x16x32_bf16 v[142:145], v[190:193], v[82:85], v[26:29]
	v_mfma_f32_16x16x32_bf16 v[146:149], v[182:185], v[94:97], v[22:25]
	v_mfma_f32_16x16x32_bf16 v[178:181], v[190:193], v[94:97], v[18:21]
	v_mfma_f32_16x16x32_bf16 v[198:201], v[182:185], v[166:169], v[14:17]
	v_mfma_f32_16x16x32_bf16 v[162:165], v[190:193], v[166:169], v[10:13]
	v_mfma_f32_16x16x32_bf16 v[166:169], v[182:185], v[174:177], v[6:9]
	v_mfma_f32_16x16x32_bf16 v[170:173], v[190:193], v[174:177], v[2:5]

; #define LDA(dst, b, h) for (int m = 0; m < 4; ++m) for (int k = 0; k < 2; ++k) \
;     dst[m][k] = *reinterpret_cast<const bf16x8*>((char*)SA(b, h) + a_thr + (m * 2 + k) * 1024)
; #define LDB(dst, b, h) for (int n = 0; n < 2; ++n) for (int k = 0; k < 2; ++k) \
;     dst[n][k] = *reinterpret_cast<const bf16x8*>((char*)SB(b, h) + b_thr + (n * 2 + k) * 1024)
; #define MMA(ai, bj, At, Btf) do { __builtin_amdgcn_s_setprio(1); \
;     for (int m = 0; m < 4; ++m) for (int n = 0; n < 2; ++n) for (int k = 0; k < 2; ++k) \
;       acc[ai][bj][m][n] = __builtin_amdgcn_mfma_f32_16x16x32_bf16(Btf[n][k], At[m][k], acc[ai][bj][m][n], 0, 0, 0); \
;     __builtin_amdgcn_s_setprio(0); } while (0)
; #define WAIT_V(n) asm volatile("s_waitcnt vmcnt(" #n ")" ::: "memory")
; #define WAIT_L(n) asm volatile("s_waitcnt lgkmcnt(" #n ")" ::: "memory")
; #define BAR __builtin_amdgcn_s_barrier()
; template <bool OVL, bool PANEL = false, class Epi>
; __device__ __forceinline__ void gemm_phase(const bf16_t* __restrict__ A, long lda, const bf16_t* __restrict__ Bt, long ldb, int nM, int nN, int K,
;                                            const Epi& epi, bf16_t* shm, int w0) {
;     ...
;     { LDB(B0, 1, 0); LDA(At, 1, 0); WAIT_V(2); BAR; WAIT_L(0); MMA(0, 0, At, B0); BAR;
	v_add_u32_e32 v0, 0x18000, v206
	s_barrier
	ds_read_b128 v[174:177], v0
	ds_read_b128 v[182:185], v0 offset:1024
	ds_read_b128 v[186:189], v0 offset:2048
	ds_read_b128 v[190:193], v0 offset:3072
	ds_read_b128 v[6:9], v241 offset:32768
	ds_read_b128 v[14:17], v241 offset:33792
	ds_read_b128 v[18:21], v241 offset:34816
	ds_read_b128 v[22:25], v241 offset:35840
	ds_read_b128 v[26:29], v241 offset:36864
	ds_read_b128 v[30:33], v241 offset:37888
	ds_read_b128 v[38:41], v241 offset:38912
	ds_read_b128 v[202:205], v241 offset:39936
	s_waitcnt vmcnt(2)
	s_barrier
	s_waitcnt lgkmcnt(0)

; #define LDA(dst, b, h) for (int m = 0; m < 4; ++m) for (int k = 0; k < 2; ++k) \
;     dst[m][k] = *reinterpret_cast<const bf16x8*>((char*)SA(b, h) + a_thr + (m * 2 + k) * 1024)
; #define LDB(dst, b, h) for (int n = 0; n < 2; ++n) for (int k = 0; k < 2; ++k) \
;     dst[n][k] = *reinterpret_cast<const bf16x8*>((char*)SB(b, h) + b_thr + (n * 2 + k) * 1024)
; #define MMA(ai, bj, At, Btf) do { __builtin_amdgcn_s_setprio(1); \
;     for (int m = 0; m < 4; ++m) for (int n = 0; n < 2; ++n) for (int k = 0; k < 2; ++k) \
;       acc[ai][bj][m][n] = __builtin_amdgcn_mfma_f32_16x16x32_bf16(Btf[n][k], At[m][k], acc[ai][bj][m][n], 0, 0, 0); \
;     __builtin_amdgcn_s_setprio(0); } while (0)
; #define WAIT_V(n) asm volatile("s_waitcnt vmcnt(" #n ")" ::: "memory")
; #define WAIT_L(n) asm volatile("s_waitcnt lgkmcnt(" #n ")" ::: "memory")
; #define BAR __builtin_amdgcn_s_barrier()
; template <bool OVL, bool PANEL = false, class Epi>
; __device__ __forceinline__ void gemm_phase(const bf16_t* __restrict__ A, long lda, const bf16_t* __restrict__ Bt, long ldb, int nM, int nN, int K,
;                                            const Epi& epi, bf16_t* shm, int w0) {
;     ...
;     { LDB(B0, 1, 0); LDA(At, 1, 0); WAIT_V(2); BAR; WAIT_L(0); MMA(0, 0, At, B0); BAR;
	s_waitcnt lgkmcnt(0)
	v_mfma_f32_16x16x32_bf16 v[2:5], v[174:177], v[6:9], v[126:129]
	v_mfma_f32_16x16x32_bf16 v[126:129], v[182:185], v[14:17], v[2:5]
	v_mfma_f32_16x16x32_bf16 v[2:5], v[186:189], v[6:9], v[122:125]
	v_mfma_f32_16x16x32_bf16 v[82:85], v[190:193], v[14:17], v[2:5]
	v_mfma_f32_16x16x32_bf16 v[2:5], v[174:177], v[18:21], v[118:121]
	v_mfma_f32_16x16x32_bf16 v[110:113], v[182:185], v[22:25], v[2:5]
	v_mfma_f32_16x16x32_bf16 v[2:5], v[186:189], v[18:21], v[114:117]
	v_mfma_f32_16x16x32_bf16 v[86:89], v[190:193], v[22:25], v[2:5]
	v_mfma_f32_16x16x32_bf16 v[2:5], v[174:177], v[26:29], v[134:137]
	v_mfma_f32_16x16x32_bf16 v[94:97], v[182:185], v[30:33], v[2:5]
	v_mfma_f32_16x16x32_bf16 v[2:5], v[186:189], v[26:29], v[106:109]
	v_mfma_f32_16x16x32_bf16 v[78:81], v[190:193], v[30:33], v[2:5]
	v_mfma_f32_16x16x32_bf16 v[2:5], v[174:177], v[38:41], v[102:105]
	v_mfma_f32_16x16x32_bf16 v[10:13], v[186:189], v[38:41], v[98:101]
	v_mfma_f32_16x16x32_bf16 v[2:5], v[182:185], v[202:205], v[2:5]
	v_mfma_f32_16x16x32_bf16 v[10:13], v[190:193], v[202:205], v[10:13]

; #define LDB(dst, b, h) for (int n = 0; n < 2; ++n) for (int k = 0; k < 2; ++k) \
;     dst[n][k] = *reinterpret_cast<const bf16x8*>((char*)SB(b, h) + b_thr + (n * 2 + k) * 1024)
; #define MMA(ai, bj, At, Btf) do { __builtin_amdgcn_s_setprio(1); \
;     for (int m = 0; m < 4; ++m) for (int n = 0; n < 2; ++n) for (int k = 0; k < 2; ++k) \
;       acc[ai][bj][m][n] = __builtin_amdgcn_mfma_f32_16x16x32_bf16(Btf[n][k], At[m][k], acc[ai][bj][m][n], 0, 0, 0); \
;     __builtin_amdgcn_s_setprio(0); } while (0)
; #define WAIT_V(n) asm volatile("s_waitcnt vmcnt(" #n ")" ::: "memory")
; #define WAIT_L(n) asm volatile("s_waitcnt lgkmcnt(" #n ")" ::: "memory")
; #define BAR __builtin_amdgcn_s_barrier()
; template <bool OVL, bool PANEL = false, class Epi>
; __device__ __forceinline__ void gemm_phase(const bf16_t* __restrict__ A, long lda, const bf16_t* __restrict__ Bt, long ldb, int nM, int nN, int K,
;                                            const Epi& epi, bf16_t* shm, int w0) {
;     ...
;       LDB(B1, 1, 1); WAIT_V(0); BAR; WAIT_L(0); MMA(0, 1, At, B1); BAR;
	v_add_u32_e32 v0, 0x1c000, v206
	s_barrier
	ds_read_b128 v[122:125], v0
	ds_read_b128 v[134:137], v0 offset:1024
	ds_read_b128 v[206:209], v0 offset:2048
	ds_read_b128 v[210:213], v0 offset:3072
	s_waitcnt vmcnt(0)
	s_barrier
	s_waitcnt lgkmcnt(0)

; #define LDB(dst, b, h) for (int n = 0; n < 2; ++n) for (int k = 0; k < 2; ++k) \
;     dst[n][k] = *reinterpret_cast<const bf16x8*>((char*)SB(b, h) + b_thr + (n * 2 + k) * 1024)
; #define MMA(ai, bj, At, Btf) do { __builtin_amdgcn_s_setprio(1); \
;     for (int m = 0; m < 4; ++m) for (int n = 0; n < 2; ++n) for (int k = 0; k < 2; ++k) \
;       acc[ai][bj][m][n] = __builtin_amdgcn_mfma_f32_16x16x32_bf16(Btf[n][k], At[m][k], acc[ai][bj][m][n], 0, 0, 0); \
;     __builtin_amdgcn_s_setprio(0); } while (0)
; #define WAIT_V(n) asm volatile("s_waitcnt vmcnt(" #n ")" ::: "memory")
; #define WAIT_L(n) asm volatile("s_waitcnt lgkmcnt(" #n ")" ::: "memory")
; #define BAR __builtin_amdgcn_s_barrier()
; template <bool OVL, bool PANEL = false, class Epi>
; __device__ __forceinline__ void gemm_phase(const bf16_t* __restrict__ A, long lda, const bf16_t* __restrict__ Bt, long ldb, int nM, int nN, int K,
;                                            const Epi& epi, bf16_t* shm, int w0) {
;     ...
;       LDB(B1, 1, 1); WAIT_V(0); BAR; WAIT_L(0); MMA(0, 1, At, B1); BAR;
	s_waitcnt lgkmcnt(0)
	v_mfma_f32_16x16x32_bf16 v[98:101], v[122:125], v[6:9], v[194:197]
	v_mfma_f32_16x16x32_bf16 v[6:9], v[206:209], v[6:9], v[90:93]
	v_mfma_f32_16x16x32_bf16 v[114:117], v[210:213], v[14:17], v[6:9]
	v_mfma_f32_16x16x32_bf16 v[6:9], v[122:125], v[18:21], v[150:153]
	v_mfma_f32_16x16x32_bf16 v[102:105], v[134:137], v[22:25], v[6:9]
	v_mfma_f32_16x16x32_bf16 v[6:9], v[206:209], v[18:21], v[154:157]
	v_mfma_f32_16x16x32_bf16 v[118:121], v[210:213], v[22:25], v[6:9]
	v_mfma_f32_16x16x32_bf16 v[6:9], v[122:125], v[26:29], v[158:161]
	v_mfma_f32_16x16x32_bf16 v[90:93], v[134:137], v[30:33], v[6:9]
	v_mfma_f32_16x16x32_bf16 v[6:9], v[206:209], v[26:29], v[74:77]
	v_mfma_f32_16x16x32_bf16 v[106:109], v[210:213], v[30:33], v[6:9]
	v_mfma_f32_16x16x32_bf16 v[6:9], v[122:125], v[38:41], v[70:73]
	v_mfma_f32_16x16x32_bf16 v[22:25], v[134:137], v[202:205], v[6:9]
	v_mfma_f32_16x16x32_bf16 v[6:9], v[206:209], v[38:41], v[66:69]
	v_mfma_f32_16x16x32_bf16 v[98:101], v[134:137], v[14:17], v[98:101]
	v_mfma_f32_16x16x32_bf16 v[38:41], v[210:213], v[202:205], v[6:9]

; #define LDA(dst, b, h) for (int m = 0; m < 4; ++m) for (int k = 0; k < 2; ++k) \
;     dst[m][k] = *reinterpret_cast<const bf16x8*>((char*)SA(b, h) + a_thr + (m * 2 + k) * 1024)
; #define MMA(ai, bj, At, Btf) do { __builtin_amdgcn_s_setprio(1); \
;     for (int m = 0; m < 4; ++m) for (int n = 0; n < 2; ++n) for (int k = 0; k < 2; ++k) \
;       acc[ai][bj][m][n] = __builtin_amdgcn_mfma_f32_16x16x32_bf16(Btf[n][k], At[m][k], acc[ai][bj][m][n], 0, 0, 0); \
;     __builtin_amdgcn_s_setprio(0); } while (0)
; #define WAIT_L(n) asm volatile("s_waitcnt lgkmcnt(" #n ")" ::: "memory")
; #define BAR __builtin_amdgcn_s_barrier()
; template <bool OVL, bool PANEL = false, class Epi>
; __device__ __forceinline__ void gemm_phase(const bf16_t* __restrict__ A, long lda, const bf16_t* __restrict__ Bt, long ldb, int nM, int nN, int K,
;                                            const Epi& epi, bf16_t* shm, int w0) {
;     ...
;       LDA(At, 1, 1); BAR; WAIT_L(0); MMA(1, 0, At, B0); MMA(1, 1, At, B1); BAR; }
	s_barrier
	ds_read_b128 v[70:73], v241 offset:49152
	ds_read_b128 v[74:77], v241 offset:50176
	ds_read_b128 v[150:153], v241 offset:51200
	ds_read_b128 v[154:157], v241 offset:52224
	ds_read_b128 v[158:161], v241 offset:53248
	ds_read_b128 v[194:197], v241 offset:54272
	ds_read_b128 v[202:205], v241 offset:55296
	ds_read_b128 v[214:217], v241 offset:56320
	s_barrier
	s_waitcnt lgkmcnt(0)

; #define LDA(dst, b, h) for (int m = 0; m < 4; ++m) for (int k = 0; k < 2; ++k) \
;     dst[m][k] = *reinterpret_cast<const bf16x8*>((char*)SA(b, h) + a_thr + (m * 2 + k) * 1024)
; #define MMA(ai, bj, At, Btf) do { __builtin_amdgcn_s_setprio(1); \
;     for (int m = 0; m < 4; ++m) for (int n = 0; n < 2; ++n) for (int k = 0; k < 2; ++k) \
;       acc[ai][bj][m][n] = __builtin_amdgcn_mfma_f32_16x16x32_bf16(Btf[n][k], At[m][k], acc[ai][bj][m][n], 0, 0, 0); \
;     __builtin_amdgcn_s_setprio(0); } while (0)
; #define WAIT_L(n) asm volatile("s_waitcnt lgkmcnt(" #n ")" ::: "memory")
; #define BAR __builtin_amdgcn_s_barrier()
; template <bool OVL, bool PANEL = false, class Epi>
; __device__ __forceinline__ void gemm_phase(const bf16_t* __restrict__ A, long lda, const bf16_t* __restrict__ Bt, long ldb, int nM, int nN, int K,
;                                            const Epi& epi, bf16_t* shm, int w0) {
;     ...
;       LDA(At, 1, 1); BAR; WAIT_L(0); MMA(1, 0, At, B0); MMA(1, 1, At, B1); BAR; }
	s_waitcnt lgkmcnt(0)
	v_mfma_f32_16x16x32_bf16 v[14:17], v[186:189], v[70:73], v[58:61]
	v_mfma_f32_16x16x32_bf16 v[42:45], v[186:189], v[158:161], v[42:45]
	v_mfma_f32_16x16x32_bf16 v[6:9], v[174:177], v[70:73], v[62:65]
	v_mfma_f32_16x16x32_bf16 v[18:21], v[190:193], v[74:77], v[14:17]
	v_mfma_f32_16x16x32_bf16 v[14:17], v[174:177], v[150:153], v[54:57]
	v_mfma_f32_16x16x32_bf16 v[26:29], v[186:189], v[150:153], v[50:53]
	v_mfma_f32_16x16x32_bf16 v[30:33], v[174:177], v[158:161], v[46:49]
	v_mfma_f32_16x16x32_bf16 v[46:49], v[190:193], v[194:197], v[42:45]
	v_mfma_f32_16x16x32_bf16 v[42:45], v[174:177], v[202:205], v[130:133]
	v_mfma_f32_16x16x32_bf16 v[34:37], v[186:189], v[202:205], v[34:37]
	v_mfma_f32_16x16x32_bf16 v[6:9], v[182:185], v[74:77], v[6:9]
	v_mfma_f32_16x16x32_bf16 v[14:17], v[182:185], v[154:157], v[14:17]
	v_mfma_f32_16x16x32_bf16 v[26:29], v[190:193], v[154:157], v[26:29]
	v_mfma_f32_16x16x32_bf16 v[30:33], v[182:185], v[194:197], v[30:33]
	v_mfma_f32_16x16x32_bf16 v[54:57], v[182:185], v[214:217], v[42:45]
	v_mfma_f32_16x16x32_bf16 v[66:69], v[190:193], v[214:217], v[34:37]


; #define LDA(dst, b, h) for (int m = 0; m < 4; ++m) for (int k = 0; k < 2; ++k) \
;     dst[m][k] = *reinterpret_cast<const bf16x8*>((char*)SA(b, h) + a_thr + (m * 2 + k) * 1024)
; #define MMA(ai, bj, At, Btf) do { __builtin_amdgcn_s_setprio(1); \
;     for (int m = 0; m < 4; ++m) for (int n = 0; n < 2; ++n) for (int k = 0; k < 2; ++k) \
;       acc[ai][bj][m][n] = __builtin_amdgcn_mfma_f32_16x16x32_bf16(Btf[n][k], At[m][k], acc[ai][bj][m][n], 0, 0, 0); \
;     __builtin_amdgcn_s_setprio(0); } while (0)
; #define WAIT_L(n) asm volatile("s_waitcnt lgkmcnt(" #n ")" ::: "memory")
; #define BAR __builtin_amdgcn_s_barrier()
; template <bool OVL, bool PANEL = false, class Epi>
; __device__ __forceinline__ void gemm_phase(const bf16_t* __restrict__ A, long lda, const bf16_t* __restrict__ Bt, long ldb, int nM, int nN, int K,
;                                            const Epi& epi, bf16_t* shm, int w0) {
;     ...
;       LDA(At, 1, 1); BAR; WAIT_L(0); MMA(1, 0, At, B0); MMA(1, 1, At, B1); BAR; }
	v_mfma_f32_16x16x32_bf16 v[34:37], v[122:125], v[70:73], v[138:141]
	v_mfma_f32_16x16x32_bf16 v[42:45], v[206:209], v[70:73], v[142:145]
	v_mfma_f32_16x16x32_bf16 v[34:37], v[134:137], v[74:77], v[34:37]
	v_mfma_f32_16x16x32_bf16 v[50:53], v[210:213], v[74:77], v[42:45]
	v_mfma_f32_16x16x32_bf16 v[42:45], v[122:125], v[150:153], v[146:149]
	v_mfma_f32_16x16x32_bf16 v[58:61], v[206:209], v[150:153], v[178:181]
	v_mfma_f32_16x16x32_bf16 v[62:65], v[122:125], v[158:161], v[198:201]
	v_mfma_f32_16x16x32_bf16 v[70:73], v[206:209], v[158:161], v[162:165]
	v_mfma_f32_16x16x32_bf16 v[74:77], v[122:125], v[202:205], v[166:169]
	v_mfma_f32_16x16x32_bf16 v[122:125], v[206:209], v[202:205], v[170:173]
	v_mfma_f32_16x16x32_bf16 v[42:45], v[134:137], v[154:157], v[42:45]
	v_mfma_f32_16x16x32_bf16 v[58:61], v[210:213], v[154:157], v[58:61]
	v_mfma_f32_16x16x32_bf16 v[62:65], v[134:137], v[194:197], v[62:65]
	v_mfma_f32_16x16x32_bf16 v[70:73], v[210:213], v[194:197], v[70:73]
	v_mfma_f32_16x16x32_bf16 v[74:77], v[134:137], v[214:217], v[74:77]
	v_mfma_f32_16x16x32_bf16 v[122:125], v[210:213], v[214:217], v[122:125]

; #define LDA(dst, b, h) for (int m = 0; m < 4; ++m) for (int k = 0; k < 2; ++k) \
;     dst[m][k] = *reinterpret_cast<const bf16x8*>((char*)SA(b, h) + a_thr + (m * 2 + k) * 1024)
; #define MMA(ai, bj, At, Btf) do { __builtin_amdgcn_s_setprio(1); \
;     for (int m = 0; m < 4; ++m) for (int n = 0; n < 2; ++n) for (int k = 0; k < 2; ++k) \
;       acc[ai][bj][m][n] = __builtin_amdgcn_mfma_f32_16x16x32_bf16(Btf[n][k], At[m][k], acc[ai][bj][m][n], 0, 0, 0); \
;     __builtin_amdgcn_s_setprio(0); } while (0)
; #define WAIT_L(n) asm volatile("s_waitcnt lgkmcnt(" #n ")" ::: "memory")
; #define BAR __builtin_amdgcn_s_barrier()
; template <bool OVL, bool PANEL = false, class Epi>
; __device__ __forceinline__ void gemm_phase(const bf16_t* __restrict__ A, long lda, const bf16_t* __restrict__ Bt, long ldb, int nM, int nN, int K,
;                                            const Epi& epi, bf16_t* shm, int w0) {
;     ...
;       LDA(At, 1, 1); BAR; WAIT_L(0); MMA(1, 0, At, B0); MMA(1, 1, At, B1); BAR; }
;     if (wr == 0) BAR;
	s_barrier
	s_and_saveexec_b64 s[0:1], s[90:91]
	s_cbranch_execz .LBB0_475
	s_barrier

; #define LDA(dst, b, h) for (int m = 0; m < 4; ++m) for (int k = 0; k < 2; ++k) \
;     dst[m][k] = *reinterpret_cast<const bf16x8*>((char*)SA(b, h) + a_thr + (m * 2 + k) * 1024)
; #define LDB(dst, b, h) for (int n = 0; n < 2; ++n) for (int k = 0; k < 2; ++k) \
;     dst[n][k] = *reinterpret_cast<const bf16x8*>((char*)SB(b, h) + b_thr + (n * 2 + k) * 1024)
; #define MMA(ai, bj, At, Btf) do { __builtin_amdgcn_s_setprio(1); \
;     for (int m = 0; m < 4; ++m) for (int n = 0; n < 2; ++n) for (int k = 0; k < 2; ++k) \
;       acc[ai][bj][m][n] = __builtin_amdgcn_mfma_f32_16x16x32_bf16(Btf[n][k], At[m][k], acc[ai][bj][m][n], 0, 0, 0); \
;     __builtin_amdgcn_s_setprio(0); } while (0)
; #define WAIT_V(n) asm volatile("s_waitcnt vmcnt(" #n ")" ::: "memory")
; #define WAIT_L(n) asm volatile("s_waitcnt lgkmcnt(" #n ")" ::: "memory")
; #define BAR __builtin_amdgcn_s_barrier()
; #define SCHED __builtin_amdgcn_sched_barrier(0)
; template <bool OVL, bool PANEL = false, class Epi>
; __device__ __forceinline__ void gemm_phase(const bf16_t* __restrict__ A, long lda, const bf16_t* __restrict__ Bt, long ldb, int nM, int nN, int K,
;                                            const Epi& epi, bf16_t* shm, int w0) {
;     ...
;     if (wr == 1) BAR;
;     WAIT_V(4); BAR;
;     STAGE(SB(1, 0), Bt, ldb, boff, bcol, 1); STAGE(SA(1, 0), A, lda, aoff, brow, 1); STAGE(SB(1, 1), Bt, ldb, boff, bcol + HALF, 1);
;     WAIT_V(6); BAR;
;     for (int t = 0; t < nt - 2; t += 2) {
;       LDB(B0, 0, 0); SCHED; LDA(At, 0, 0); STAGE(SA(1, 1), A, lda, aoff, brow + HALF, t + 1);
;       WAIT_L(8); BAR; WAIT_L(0); MMA(0, 0, At, B0); BAR; SCHED;
.LBB0_685:
	s_or_b64 exec, exec, s[8:9]
	s_lshl_b32 s12, s21, 8
	s_ashr_i32 s13, s12, 31
	v_readlane_b32 s76, v252, 3
	s_lshl_b32 s23, s22, 8
	s_lshl_b64 s[8:9], s[12:13], 9
	v_readlane_b32 s84, v252, 11
	v_readlane_b32 s85, v252, 12
	s_add_u32 s40, s84, s8
	v_mov_b32_e32 v0, v136
	s_waitcnt vmcnt(4)
	s_barrier
	s_addc_u32 s41, s85, s9
	s_mov_b64 s[24:25], 0x80
	v_lshl_add_u64 v[2:3], s[40:41], 0, v[0:1]
	v_add_u32_e32 v0, s96, v134
	v_readlane_b32 s44, v252, 20
	v_readfirstlane_b32 s42, v0
	v_add_u32_e32 v0, 0x2000, v0
	v_lshl_add_u64 v[4:5], v[2:3], 0, s[24:25]
	s_mov_b32 m0, s42
	s_mov_b64 s[26:27], 0x8080
	v_readfirstlane_b32 s31, v0
	s_mul_i32 s8, s22, 0xf8000
	v_readlane_b32 s52, v252, 28
	global_load_lds_dwordx4 v[4:5], off
	v_lshl_add_u64 v[2:3], v[2:3], 0, s[26:27]
	s_mov_b32 m0, s31
	s_mul_hi_u32 s9, s23, 0xf80
	v_readlane_b32 s53, v252, 29
	s_add_u32 s14, s52, s8
	v_mov_b32_e32 v0, v135
	global_load_lds_dwordx4 v[2:3], off
	s_addc_u32 s15, s53, s9
	v_readlane_b32 s45, v252, 21
	v_lshl_add_u64 v[2:3], s[14:15], 0, v[0:1]
	v_add_u32_e32 v0, 0x8000, v139
	s_or_b32 s8, s12, 0x80
	v_readlane_b32 s46, v252, 22
	v_readlane_b32 s47, v252, 23
	s_mov_b64 s[44:45], 0xcc0
	v_readfirstlane_b32 s30, v0
	v_add_u32_e32 v0, 0xa000, v139
	s_ashr_i32 s9, s8, 31
	v_lshl_add_u64 v[4:5], v[2:3], 0, s[44:45]
	s_mov_b32 m0, s30
	s_mov_b64 s[46:47], 0x3ecc0
	v_readfirstlane_b32 s28, v0
	s_lshl_b64 s[8:9], s[8:9], 9
	global_load_lds_dwordx4 v[4:5], off
	v_lshl_add_u64 v[2:3], v[2:3], 0, s[46:47]
	s_mov_b32 m0, s28
	s_add_u32 s10, s84, s8
	v_mov_b32_e32 v0, v136
	global_load_lds_dwordx4 v[2:3], off
	s_addc_u32 s11, s85, s9
	v_add_u32_e32 v144, s20, v149
	v_lshl_add_u64 v[2:3], s[10:11], 0, v[0:1]
	v_add_u32_e32 v0, s75, v134
	v_lshl_add_u64 v[4:5], v[2:3], 0, s[24:25]
	v_readfirstlane_b32 s25, v0
	v_add_u32_e32 v0, 0x2000, v0
	s_mov_b32 m0, s25
	v_readfirstlane_b32 s24, v0
	global_load_lds_dwordx4 v[4:5], off
	v_lshl_add_u64 v[2:3], v[2:3], 0, s[26:27]
	s_mov_b32 m0, s24
	s_or_b32 s8, s23, 0x80
	global_load_lds_dwordx4 v[2:3], off
	s_waitcnt vmcnt(6)
	s_barrier
	ds_read_b128 v[2:5], v144
	ds_read_b128 v[6:9], v144 offset:1024
	s_waitcnt vmcnt(0)
	ds_read_b128 v[10:13], v144 offset:2048
	s_waitcnt lgkmcnt(0)
	ds_read_b128 v[14:17], v144 offset:3072
	s_mul_hi_u32 s9, s8, 0xf80
	s_mulk_i32 s8, 0xf80
	s_add_u32 s8, s52, s8
	s_addc_u32 s9, s53, s9
	v_readlane_b32 s77, v252, 4
	v_readlane_b32 s78, v252, 5
	v_readlane_b32 s79, v252, 6
	v_readlane_b32 s80, v252, 7
	v_readlane_b32 s81, v252, 8
	v_readlane_b32 s82, v252, 9
	v_readlane_b32 s83, v252, 10
	v_readlane_b32 s86, v252, 13
	v_readlane_b32 s87, v252, 14
	v_readlane_b32 s88, v252, 15
	v_readlane_b32 s89, v252, 16
	v_readlane_b32 s90, v252, 17
	v_readlane_b32 s91, v252, 18
	v_readlane_b32 s48, v252, 24
	v_readlane_b32 s49, v252, 25
	v_readlane_b32 s50, v252, 26
	v_readlane_b32 s51, v252, 27
	v_readlane_b32 s54, v252, 30
	v_readlane_b32 s55, v252, 31
	v_readlane_b32 s56, v252, 32
	v_readlane_b32 s57, v252, 33
	v_readlane_b32 s58, v252, 34
	v_readlane_b32 s59, v252, 35
	v_mov_b32_e32 v0, v135
	ds_read_b128 v[18:21], v148
	ds_read_b128 v[22:25], v148 offset:1024
	ds_read_b128 v[26:29], v148 offset:2048
	ds_read_b128 v[30:33], v148 offset:3072
	ds_read_b128 v[34:37], v148 offset:4096
	ds_read_b128 v[38:41], v148 offset:5120
	ds_read_b128 v[42:45], v148 offset:6144
	ds_read_b128 v[46:49], v148 offset:7168
	s_nop 0
	v_lshl_add_u64 v[50:51], s[8:9], 0, v[0:1]
	v_add_u32_e32 v0, 0xc000, v139
	v_lshl_add_u64 v[52:53], v[50:51], 0, s[44:45]
	v_readfirstlane_b32 s29, v0
	v_add_u32_e32 v0, 0xe000, v139
	s_mov_b32 m0, s29
	v_readfirstlane_b32 s13, v0
	global_load_lds_dwordx4 v[52:53], off
	v_lshl_add_u64 v[50:51], v[50:51], 0, s[46:47]
	s_mov_b32 m0, s13
	s_nop 0
	global_load_lds_dwordx4 v[50:51], off
	s_waitcnt lgkmcnt(8)
	s_barrier
	s_waitcnt lgkmcnt(0)

; #define MMA(ai, bj, At, Btf) do { __builtin_amdgcn_s_setprio(1); \
;     for (int m = 0; m < 4; ++m) for (int n = 0; n < 2; ++n) for (int k = 0; k < 2; ++k) \
;       acc[ai][bj][m][n] = __builtin_amdgcn_mfma_f32_16x16x32_bf16(Btf[n][k], At[m][k], acc[ai][bj][m][n], 0, 0, 0); \
;     __builtin_amdgcn_s_setprio(0); } while (0)
; #define WAIT_L(n) asm volatile("s_waitcnt lgkmcnt(" #n ")" ::: "memory")
; #define BAR __builtin_amdgcn_s_barrier()
; #define SCHED __builtin_amdgcn_sched_barrier(0)
; template <bool OVL, bool PANEL = false, class Epi>
; __device__ __forceinline__ void gemm_phase(const bf16_t* __restrict__ A, long lda, const bf16_t* __restrict__ Bt, long ldb, int nM, int nN, int K,
;                                            const Epi& epi, bf16_t* shm, int w0) {
;     ...
;       WAIT_L(8); BAR; WAIT_L(0); MMA(0, 0, At, B0); BAR; SCHED;
	s_waitcnt lgkmcnt(0)
	v_mfma_f32_16x16x32_bf16 v[50:53], v[2:5], v[18:21], 0
	v_mfma_f32_16x16x32_bf16 v[54:57], v[10:13], v[18:21], 0
	v_mfma_f32_16x16x32_bf16 v[58:61], v[2:5], v[26:29], 0
	v_mfma_f32_16x16x32_bf16 v[62:65], v[10:13], v[26:29], 0
	v_mfma_f32_16x16x32_bf16 v[66:69], v[2:5], v[34:37], 0
	v_mfma_f32_16x16x32_bf16 v[70:73], v[10:13], v[34:37], 0
	v_mfma_f32_16x16x32_bf16 v[74:77], v[2:5], v[42:45], 0
	v_mfma_f32_16x16x32_bf16 v[78:81], v[10:13], v[42:45], 0
	v_mfma_f32_16x16x32_bf16 v[50:53], v[6:9], v[22:25], v[50:53]
	v_mfma_f32_16x16x32_bf16 v[54:57], v[14:17], v[22:25], v[54:57]
	v_mfma_f32_16x16x32_bf16 v[58:61], v[6:9], v[30:33], v[58:61]
	v_mfma_f32_16x16x32_bf16 v[62:65], v[14:17], v[30:33], v[62:65]
	v_mfma_f32_16x16x32_bf16 v[66:69], v[6:9], v[38:41], v[66:69]
	v_mfma_f32_16x16x32_bf16 v[70:73], v[14:17], v[38:41], v[70:73]
	v_mfma_f32_16x16x32_bf16 v[74:77], v[6:9], v[46:49], v[74:77]
	v_mfma_f32_16x16x32_bf16 v[78:81], v[14:17], v[46:49], v[78:81]

; #define LDB(dst, b, h) for (int n = 0; n < 2; ++n) for (int k = 0; k < 2; ++k) \
;     dst[n][k] = *reinterpret_cast<const bf16x8*>((char*)SB(b, h) + b_thr + (n * 2 + k) * 1024)
; #define MMA(ai, bj, At, Btf) do { __builtin_amdgcn_s_setprio(1); \
;     for (int m = 0; m < 4; ++m) for (int n = 0; n < 2; ++n) for (int k = 0; k < 2; ++k) \
;       acc[ai][bj][m][n] = __builtin_amdgcn_mfma_f32_16x16x32_bf16(Btf[n][k], At[m][k], acc[ai][bj][m][n], 0, 0, 0); \
;     __builtin_amdgcn_s_setprio(0); } while (0)
; #define WAIT_L(n) asm volatile("s_waitcnt lgkmcnt(" #n ")" ::: "memory")
; #define BAR __builtin_amdgcn_s_barrier()
; template <bool OVL, bool PANEL = false, class Epi>
; __device__ __forceinline__ void gemm_phase(const bf16_t* __restrict__ A, long lda, const bf16_t* __restrict__ Bt, long ldb, int nM, int nN, int K,
;                                            const Epi& epi, bf16_t* shm, int w0) {
;     ...
;       LDB(B1, 0, 1); STAGE(SB(0, 0), Bt, ldb, boff, bcol, t + 2);
;       BAR; WAIT_L(0); MMA(0, 1, At, B1); BAR;
	s_barrier
	v_add_u32_e32 v145, s33, v149
	v_mov_b32_e32 v0, v136
	ds_read_b128 v[82:85], v145
	ds_read_b128 v[86:89], v145 offset:1024
	ds_read_b128 v[90:93], v145 offset:2048
	ds_read_b128 v[94:97], v145 offset:3072
	v_readfirstlane_b32 s43, v137
	v_lshl_add_u64 v[98:99], s[40:41], 0, v[0:1]
	v_add_u32_e32 v0, 0x2000, v137
	v_lshl_add_u64 v[100:101], v[98:99], 0, s[34:35]
	s_mov_b32 m0, s43
	s_mov_b64 s[26:27], 0x8100
	v_readfirstlane_b32 s43, v0
	global_load_lds_dwordx4 v[100:101], off
	v_lshl_add_u64 v[98:99], v[98:99], 0, s[26:27]
	s_mov_b32 m0, s43
	s_nop 0
	global_load_lds_dwordx4 v[98:99], off
	s_barrier
	s_waitcnt lgkmcnt(0)

; #define MMA(ai, bj, At, Btf) do { __builtin_amdgcn_s_setprio(1); \
;     for (int m = 0; m < 4; ++m) for (int n = 0; n < 2; ++n) for (int k = 0; k < 2; ++k) \
;       acc[ai][bj][m][n] = __builtin_amdgcn_mfma_f32_16x16x32_bf16(Btf[n][k], At[m][k], acc[ai][bj][m][n], 0, 0, 0); \
;     __builtin_amdgcn_s_setprio(0); } while (0)
; #define WAIT_L(n) asm volatile("s_waitcnt lgkmcnt(" #n ")" ::: "memory")
; #define BAR __builtin_amdgcn_s_barrier()
; template <bool OVL, bool PANEL = false, class Epi>
; __device__ __forceinline__ void gemm_phase(const bf16_t* __restrict__ A, long lda, const bf16_t* __restrict__ Bt, long ldb, int nM, int nN, int K,
;                                            const Epi& epi, bf16_t* shm, int w0) {
;     ...
;       BAR; WAIT_L(0); MMA(0, 1, At, B1); BAR;
	s_waitcnt lgkmcnt(0)
	v_mfma_f32_16x16x32_bf16 v[98:101], v[82:85], v[18:21], 0
	v_mfma_f32_16x16x32_bf16 v[18:21], v[90:93], v[18:21], 0
	v_mfma_f32_16x16x32_bf16 v[98:101], v[86:89], v[22:25], v[98:101]
	v_mfma_f32_16x16x32_bf16 v[18:21], v[94:97], v[22:25], v[18:21]
	v_mfma_f32_16x16x32_bf16 v[22:25], v[82:85], v[26:29], 0
	v_mfma_f32_16x16x32_bf16 v[26:29], v[90:93], v[26:29], 0
	v_mfma_f32_16x16x32_bf16 v[22:25], v[86:89], v[30:33], v[22:25]
	v_mfma_f32_16x16x32_bf16 v[26:29], v[94:97], v[30:33], v[26:29]
	v_mfma_f32_16x16x32_bf16 v[30:33], v[82:85], v[34:37], 0
	v_mfma_f32_16x16x32_bf16 v[34:37], v[90:93], v[34:37], 0
	v_mfma_f32_16x16x32_bf16 v[30:33], v[86:89], v[38:41], v[30:33]
	v_mfma_f32_16x16x32_bf16 v[34:37], v[94:97], v[38:41], v[34:37]
	v_mfma_f32_16x16x32_bf16 v[38:41], v[82:85], v[42:45], 0
	v_mfma_f32_16x16x32_bf16 v[42:45], v[90:93], v[42:45], 0
	v_mfma_f32_16x16x32_bf16 v[38:41], v[86:89], v[46:49], v[38:41]
	v_mfma_f32_16x16x32_bf16 v[42:45], v[94:97], v[46:49], v[42:45]

; #define LDA(dst, b, h) for (int m = 0; m < 4; ++m) for (int k = 0; k < 2; ++k) \
;     dst[m][k] = *reinterpret_cast<const bf16x8*>((char*)SA(b, h) + a_thr + (m * 2 + k) * 1024)
; #define MMA(ai, bj, At, Btf) do { __builtin_amdgcn_s_setprio(1); \
;     for (int m = 0; m < 4; ++m) for (int n = 0; n < 2; ++n) for (int k = 0; k < 2; ++k) \
;       acc[ai][bj][m][n] = __builtin_amdgcn_mfma_f32_16x16x32_bf16(Btf[n][k], At[m][k], acc[ai][bj][m][n], 0, 0, 0); \
;     __builtin_amdgcn_s_setprio(0); } while (0)
; #define WAIT_L(n) asm volatile("s_waitcnt lgkmcnt(" #n ")" ::: "memory")
; #define BAR __builtin_amdgcn_s_barrier()
; #define SCHED __builtin_amdgcn_sched_barrier(0)
; template <bool OVL, bool PANEL = false, class Epi>
; __device__ __forceinline__ void gemm_phase(const bf16_t* __restrict__ A, long lda, const bf16_t* __restrict__ Bt, long ldb, int nM, int nN, int K,
;                                            const Epi& epi, bf16_t* shm, int w0) {
;     ...
;       LDA(At, 0, 1); STAGE(SA(0, 0), A, lda, aoff, brow, t + 2);
;       BAR; WAIT_L(0); MMA(1, 0, At, B0); BAR; SCHED;
	v_mov_b32_e32 v0, v135
	s_barrier
	ds_read_b128 v[46:49], v148 offset:16384
	ds_read_b128 v[102:105], v148 offset:17408
	ds_read_b128 v[106:109], v148 offset:18432
	ds_read_b128 v[110:113], v148 offset:19456
	ds_read_b128 v[114:117], v148 offset:20480
	ds_read_b128 v[118:121], v148 offset:21504
	ds_read_b128 v[122:125], v148 offset:22528
	ds_read_b128 v[126:129], v148 offset:23552
	s_mov_b64 s[44:45], 0xd40
	v_lshl_add_u64 v[130:131], s[14:15], 0, v[0:1]
	v_readfirstlane_b32 s43, v139
	v_add_u32_e32 v0, 0x2000, v139
	v_lshl_add_u64 v[132:133], v[130:131], 0, s[44:45]
	s_mov_b32 m0, s43
	s_mov_b64 s[46:47], 0x3ed40
	v_readfirstlane_b32 s43, v0
	global_load_lds_dwordx4 v[132:133], off
	v_lshl_add_u64 v[130:131], v[130:131], 0, s[46:47]
	s_mov_b32 m0, s43
	s_nop 0
	global_load_lds_dwordx4 v[130:131], off
	s_barrier
	s_waitcnt lgkmcnt(0)

; #define MMA(ai, bj, At, Btf) do { __builtin_amdgcn_s_setprio(1); \
;     for (int m = 0; m < 4; ++m) for (int n = 0; n < 2; ++n) for (int k = 0; k < 2; ++k) \
;       acc[ai][bj][m][n] = __builtin_amdgcn_mfma_f32_16x16x32_bf16(Btf[n][k], At[m][k], acc[ai][bj][m][n], 0, 0, 0); \
;     __builtin_amdgcn_s_setprio(0); } while (0)
; #define WAIT_L(n) asm volatile("s_waitcnt lgkmcnt(" #n ")" ::: "memory")
; #define BAR __builtin_amdgcn_s_barrier()
; #define SCHED __builtin_amdgcn_sched_barrier(0)
; template <bool OVL, bool PANEL = false, class Epi>
; __device__ __forceinline__ void gemm_phase(const bf16_t* __restrict__ A, long lda, const bf16_t* __restrict__ Bt, long ldb, int nM, int nN, int K,
;                                            const Epi& epi, bf16_t* shm, int w0) {
;     ...
;       BAR; WAIT_L(0); MMA(1, 0, At, B0); BAR; SCHED;
	s_waitcnt lgkmcnt(0)
	v_mfma_f32_16x16x32_bf16 v[130:133], v[2:5], v[46:49], 0
	v_mfma_f32_16x16x32_bf16 v[154:157], v[2:5], v[106:109], 0
	v_mfma_f32_16x16x32_bf16 v[162:165], v[2:5], v[114:117], 0
	v_mfma_f32_16x16x32_bf16 v[2:5], v[2:5], v[122:125], 0
	v_mfma_f32_16x16x32_bf16 v[130:133], v[6:9], v[102:105], v[130:133]
	v_mfma_f32_16x16x32_bf16 v[154:157], v[6:9], v[110:113], v[154:157]
	v_mfma_f32_16x16x32_bf16 v[162:165], v[6:9], v[118:121], v[162:165]
	v_mfma_f32_16x16x32_bf16 v[2:5], v[6:9], v[126:129], v[2:5]
	v_mfma_f32_16x16x32_bf16 v[6:9], v[10:13], v[122:125], 0
	v_mfma_f32_16x16x32_bf16 v[150:153], v[10:13], v[46:49], 0
	v_mfma_f32_16x16x32_bf16 v[158:161], v[10:13], v[106:109], 0
	v_mfma_f32_16x16x32_bf16 v[166:169], v[10:13], v[114:117], 0
	v_mfma_f32_16x16x32_bf16 v[6:9], v[14:17], v[126:129], v[6:9]
	v_mfma_f32_16x16x32_bf16 v[150:153], v[14:17], v[102:105], v[150:153]
	v_mfma_f32_16x16x32_bf16 v[158:161], v[14:17], v[110:113], v[158:161]
	v_mfma_f32_16x16x32_bf16 v[166:169], v[14:17], v[118:121], v[166:169]

; #define MMA(ai, bj, At, Btf) do { __builtin_amdgcn_s_setprio(1); \
;     for (int m = 0; m < 4; ++m) for (int n = 0; n < 2; ++n) for (int k = 0; k < 2; ++k) \
;       acc[ai][bj][m][n] = __builtin_amdgcn_mfma_f32_16x16x32_bf16(Btf[n][k], At[m][k], acc[ai][bj][m][n], 0, 0, 0); \
;     __builtin_amdgcn_s_setprio(0); } while (0)
; #define WAIT_V(n) asm volatile("s_waitcnt vmcnt(" #n ")" ::: "memory")
; #define BAR __builtin_amdgcn_s_barrier()
; template <bool OVL, bool PANEL = false, class Epi>
; __device__ __forceinline__ void gemm_phase(const bf16_t* __restrict__ A, long lda, const bf16_t* __restrict__ Bt, long ldb, int nM, int nN, int K,
;                                            const Epi& epi, bf16_t* shm, int w0) {
;     ...
;       STAGE(SB(0, 1), Bt, ldb, boff, bcol + HALF, t + 2);
;       WAIT_V(6); BAR; MMA(1, 1, At, B1); BAR;
	s_barrier
	v_mov_b32_e32 v0, v136
	v_readfirstlane_b32 s43, v227
	v_lshl_add_u64 v[10:11], s[10:11], 0, v[0:1]
	v_add_u32_e32 v0, 0x2000, v227
	v_lshl_add_u64 v[12:13], v[10:11], 0, s[34:35]
	s_mov_b32 m0, s43
	v_readfirstlane_b32 s43, v0
	global_load_lds_dwordx4 v[12:13], off
	v_lshl_add_u64 v[10:11], v[10:11], 0, s[26:27]
	s_mov_b32 m0, s43
	s_nop 0
	global_load_lds_dwordx4 v[10:11], off
	s_waitcnt vmcnt(6)
	s_barrier

; #define MMA(ai, bj, At, Btf) do { __builtin_amdgcn_s_setprio(1); \
;     for (int m = 0; m < 4; ++m) for (int n = 0; n < 2; ++n) for (int k = 0; k < 2; ++k) \
;       acc[ai][bj][m][n] = __builtin_amdgcn_mfma_f32_16x16x32_bf16(Btf[n][k], At[m][k], acc[ai][bj][m][n], 0, 0, 0); \
;     __builtin_amdgcn_s_setprio(0); } while (0)
; #define WAIT_V(n) asm volatile("s_waitcnt vmcnt(" #n ")" ::: "memory")
; #define BAR __builtin_amdgcn_s_barrier()
; template <bool OVL, bool PANEL = false, class Epi>
; __device__ __forceinline__ void gemm_phase(const bf16_t* __restrict__ A, long lda, const bf16_t* __restrict__ Bt, long ldb, int nM, int nN, int K,
;                                            const Epi& epi, bf16_t* shm, int w0) {
;     ...
;       WAIT_V(6); BAR; MMA(1, 1, At, B1); BAR;
	v_mfma_f32_16x16x32_bf16 v[10:13], v[82:85], v[46:49], 0
	v_mfma_f32_16x16x32_bf16 v[14:17], v[90:93], v[46:49], 0
	v_mfma_f32_16x16x32_bf16 v[10:13], v[86:89], v[102:105], v[10:13]
	v_mfma_f32_16x16x32_bf16 v[14:17], v[94:97], v[102:105], v[14:17]
	v_mfma_f32_16x16x32_bf16 v[46:49], v[82:85], v[106:109], 0
	v_mfma_f32_16x16x32_bf16 v[102:105], v[90:93], v[106:109], 0
	v_mfma_f32_16x16x32_bf16 v[106:109], v[82:85], v[114:117], 0
	v_mfma_f32_16x16x32_bf16 v[82:85], v[82:85], v[122:125], 0
	v_mfma_f32_16x16x32_bf16 v[46:49], v[86:89], v[110:113], v[46:49]
	v_mfma_f32_16x16x32_bf16 v[102:105], v[94:97], v[110:113], v[102:105]
	v_mfma_f32_16x16x32_bf16 v[106:109], v[86:89], v[118:121], v[106:109]
	v_mfma_f32_16x16x32_bf16 v[110:113], v[90:93], v[114:117], 0
	v_mfma_f32_16x16x32_bf16 v[82:85], v[86:89], v[126:129], v[82:85]
	v_mfma_f32_16x16x32_bf16 v[86:89], v[90:93], v[122:125], 0
	v_mfma_f32_16x16x32_bf16 v[110:113], v[94:97], v[118:121], v[110:113]
	v_mfma_f32_16x16x32_bf16 v[86:89], v[94:97], v[126:129], v[86:89]

; #define LDA(dst, b, h) for (int m = 0; m < 4; ++m) for (int k = 0; k < 2; ++k) \
;     dst[m][k] = *reinterpret_cast<const bf16x8*>((char*)SA(b, h) + a_thr + (m * 2 + k) * 1024)
; #define LDB(dst, b, h) for (int n = 0; n < 2; ++n) for (int k = 0; k < 2; ++k) \
;     dst[n][k] = *reinterpret_cast<const bf16x8*>((char*)SB(b, h) + b_thr + (n * 2 + k) * 1024)
; #define MMA(ai, bj, At, Btf) do { __builtin_amdgcn_s_setprio(1); \
;     for (int m = 0; m < 4; ++m) for (int n = 0; n < 2; ++n) for (int k = 0; k < 2; ++k) \
;       acc[ai][bj][m][n] = __builtin_amdgcn_mfma_f32_16x16x32_bf16(Btf[n][k], At[m][k], acc[ai][bj][m][n], 0, 0, 0); \
;     __builtin_amdgcn_s_setprio(0); } while (0)
; #define WAIT_L(n) asm volatile("s_waitcnt lgkmcnt(" #n ")" ::: "memory")
; #define BAR __builtin_amdgcn_s_barrier()
; #define SCHED __builtin_amdgcn_sched_barrier(0)
; template <bool OVL, bool PANEL = false, class Epi>
; __device__ __forceinline__ void gemm_phase(const bf16_t* __restrict__ A, long lda, const bf16_t* __restrict__ Bt, long ldb, int nM, int nN, int K,
;                                            const Epi& epi, bf16_t* shm, int w0) {
;     ...
;       LDB(B0, 1, 0); SCHED; LDA(At, 1, 0); STAGE(SA(0, 1), A, lda, aoff, brow + HALF, t + 2);
;       WAIT_L(8); BAR; WAIT_L(0); MMA(0, 0, At, B0); BAR; SCHED;
	v_add_u32_e32 v146, s96, v149
	s_barrier
	ds_read_b128 v[90:93], v146
	ds_read_b128 v[94:97], v146 offset:1024
	ds_read_b128 v[114:117], v146 offset:2048
	ds_read_b128 v[118:121], v146 offset:3072
	v_mov_b32_e32 v0, v135
	ds_read_b128 v[122:125], v148 offset:32768
	ds_read_b128 v[126:129], v148 offset:33792
	ds_read_b128 v[170:173], v148 offset:34816
	ds_read_b128 v[174:177], v148 offset:35840
	ds_read_b128 v[178:181], v148 offset:36864
	ds_read_b128 v[182:185], v148 offset:37888
	ds_read_b128 v[186:189], v148 offset:38912
	ds_read_b128 v[190:193], v148 offset:39936
	s_nop 0
	v_lshl_add_u64 v[140:141], s[8:9], 0, v[0:1]
	v_add_u32_e32 v0, 0x4000, v139
	v_lshl_add_u64 v[142:143], v[140:141], 0, s[44:45]
	v_readfirstlane_b32 s43, v0
	s_mov_b32 m0, s43
	v_readfirstlane_b32 s43, v138
	global_load_lds_dwordx4 v[142:143], off
	v_lshl_add_u64 v[140:141], v[140:141], 0, s[46:47]
	s_mov_b32 m0, s43
	s_nop 0
	global_load_lds_dwordx4 v[140:141], off
	s_waitcnt lgkmcnt(8)
	s_barrier
	s_waitcnt lgkmcnt(0)

; #define MMA(ai, bj, At, Btf) do { __builtin_amdgcn_s_setprio(1); \
;     for (int m = 0; m < 4; ++m) for (int n = 0; n < 2; ++n) for (int k = 0; k < 2; ++k) \
;       acc[ai][bj][m][n] = __builtin_amdgcn_mfma_f32_16x16x32_bf16(Btf[n][k], At[m][k], acc[ai][bj][m][n], 0, 0, 0); \
;     __builtin_amdgcn_s_setprio(0); } while (0)
; #define WAIT_L(n) asm volatile("s_waitcnt lgkmcnt(" #n ")" ::: "memory")
; #define BAR __builtin_amdgcn_s_barrier()
; #define SCHED __builtin_amdgcn_sched_barrier(0)
; template <bool OVL, bool PANEL = false, class Epi>
; __device__ __forceinline__ void gemm_phase(const bf16_t* __restrict__ A, long lda, const bf16_t* __restrict__ Bt, long ldb, int nM, int nN, int K,
;                                            const Epi& epi, bf16_t* shm, int w0) {
;     ...
;       WAIT_L(8); BAR; WAIT_L(0); MMA(0, 0, At, B0); BAR; SCHED;
	s_waitcnt lgkmcnt(0)
	v_mfma_f32_16x16x32_bf16 v[50:53], v[90:93], v[122:125], v[50:53]
	v_mfma_f32_16x16x32_bf16 v[54:57], v[114:117], v[122:125], v[54:57]
	v_mfma_f32_16x16x32_bf16 v[58:61], v[90:93], v[170:173], v[58:61]
	v_mfma_f32_16x16x32_bf16 v[62:65], v[114:117], v[170:173], v[62:65]
	v_mfma_f32_16x16x32_bf16 v[66:69], v[90:93], v[178:181], v[66:69]
	v_mfma_f32_16x16x32_bf16 v[70:73], v[114:117], v[178:181], v[70:73]
	v_mfma_f32_16x16x32_bf16 v[74:77], v[90:93], v[186:189], v[74:77]
	v_mfma_f32_16x16x32_bf16 v[78:81], v[114:117], v[186:189], v[78:81]
	v_mfma_f32_16x16x32_bf16 v[50:53], v[94:97], v[126:129], v[50:53]
	v_mfma_f32_16x16x32_bf16 v[54:57], v[118:121], v[126:129], v[54:57]
	v_mfma_f32_16x16x32_bf16 v[58:61], v[94:97], v[174:177], v[58:61]
	v_mfma_f32_16x16x32_bf16 v[62:65], v[118:121], v[174:177], v[62:65]
	v_mfma_f32_16x16x32_bf16 v[66:69], v[94:97], v[182:185], v[66:69]
	v_mfma_f32_16x16x32_bf16 v[70:73], v[118:121], v[182:185], v[70:73]
	v_mfma_f32_16x16x32_bf16 v[74:77], v[94:97], v[190:193], v[74:77]
	v_mfma_f32_16x16x32_bf16 v[78:81], v[118:121], v[190:193], v[78:81]

; #define LDB(dst, b, h) for (int n = 0; n < 2; ++n) for (int k = 0; k < 2; ++k) \
;     dst[n][k] = *reinterpret_cast<const bf16x8*>((char*)SB(b, h) + b_thr + (n * 2 + k) * 1024)
; #define MMA(ai, bj, At, Btf) do { __builtin_amdgcn_s_setprio(1); \
;     for (int m = 0; m < 4; ++m) for (int n = 0; n < 2; ++n) for (int k = 0; k < 2; ++k) \
;       acc[ai][bj][m][n] = __builtin_amdgcn_mfma_f32_16x16x32_bf16(Btf[n][k], At[m][k], acc[ai][bj][m][n], 0, 0, 0); \
;     __builtin_amdgcn_s_setprio(0); } while (0)
; #define WAIT_L(n) asm volatile("s_waitcnt lgkmcnt(" #n ")" ::: "memory")
; #define BAR __builtin_amdgcn_s_barrier()
; template <bool OVL, bool PANEL = false, class Epi>
; __device__ __forceinline__ void gemm_phase(const bf16_t* __restrict__ A, long lda, const bf16_t* __restrict__ Bt, long ldb, int nM, int nN, int K,
;                                            const Epi& epi, bf16_t* shm, int w0) {
;     ...
;       LDB(B1, 1, 1); STAGE(SB(1, 0), Bt, ldb, boff, bcol, t + 3);
;       BAR; WAIT_L(0); MMA(0, 1, At, B1); BAR;
	s_barrier
	v_add_u32_e32 v147, s75, v149
	v_mov_b32_e32 v0, v136
	ds_read_b128 v[194:197], v147
	ds_read_b128 v[198:201], v147 offset:1024
	ds_read_b128 v[202:205], v147 offset:2048
	ds_read_b128 v[206:209], v147 offset:3072
	s_mov_b32 m0, s42
	v_lshl_add_u64 v[140:141], s[40:41], 0, v[0:1]
	v_lshl_add_u64 v[142:143], v[140:141], 0, s[94:95]
	s_mov_b64 s[26:27], 0x8180
	global_load_lds_dwordx4 v[142:143], off
	v_lshl_add_u64 v[140:141], v[140:141], 0, s[26:27]
	s_mov_b32 m0, s31
	s_nop 0
	global_load_lds_dwordx4 v[140:141], off
	s_barrier
	s_waitcnt lgkmcnt(0)

; #define MMA(ai, bj, At, Btf) do { __builtin_amdgcn_s_setprio(1); \
;     for (int m = 0; m < 4; ++m) for (int n = 0; n < 2; ++n) for (int k = 0; k < 2; ++k) \
;       acc[ai][bj][m][n] = __builtin_amdgcn_mfma_f32_16x16x32_bf16(Btf[n][k], At[m][k], acc[ai][bj][m][n], 0, 0, 0); \
;     __builtin_amdgcn_s_setprio(0); } while (0)
; #define WAIT_L(n) asm volatile("s_waitcnt lgkmcnt(" #n ")" ::: "memory")
; #define BAR __builtin_amdgcn_s_barrier()
; template <bool OVL, bool PANEL = false, class Epi>
; __device__ __forceinline__ void gemm_phase(const bf16_t* __restrict__ A, long lda, const bf16_t* __restrict__ Bt, long ldb, int nM, int nN, int K,
;                                            const Epi& epi, bf16_t* shm, int w0) {
;     ...
;       BAR; WAIT_L(0); MMA(0, 1, At, B1); BAR;
	s_waitcnt lgkmcnt(0)
	v_mfma_f32_16x16x32_bf16 v[98:101], v[194:197], v[122:125], v[98:101]
	v_mfma_f32_16x16x32_bf16 v[18:21], v[202:205], v[122:125], v[18:21]
	v_mfma_f32_16x16x32_bf16 v[22:25], v[194:197], v[170:173], v[22:25]
	v_mfma_f32_16x16x32_bf16 v[26:29], v[202:205], v[170:173], v[26:29]
	v_mfma_f32_16x16x32_bf16 v[30:33], v[194:197], v[178:181], v[30:33]
	v_mfma_f32_16x16x32_bf16 v[34:37], v[202:205], v[178:181], v[34:37]
	v_mfma_f32_16x16x32_bf16 v[38:41], v[194:197], v[186:189], v[38:41]
	v_mfma_f32_16x16x32_bf16 v[42:45], v[202:205], v[186:189], v[42:45]
	v_mfma_f32_16x16x32_bf16 v[98:101], v[198:201], v[126:129], v[98:101]
	v_mfma_f32_16x16x32_bf16 v[18:21], v[206:209], v[126:129], v[18:21]
	v_mfma_f32_16x16x32_bf16 v[22:25], v[198:201], v[174:177], v[22:25]
	v_mfma_f32_16x16x32_bf16 v[26:29], v[206:209], v[174:177], v[26:29]
	v_mfma_f32_16x16x32_bf16 v[30:33], v[198:201], v[182:185], v[30:33]
	v_mfma_f32_16x16x32_bf16 v[34:37], v[206:209], v[182:185], v[34:37]
	v_mfma_f32_16x16x32_bf16 v[38:41], v[198:201], v[190:193], v[38:41]
	v_mfma_f32_16x16x32_bf16 v[42:45], v[206:209], v[190:193], v[42:45]

; #define LDA(dst, b, h) for (int m = 0; m < 4; ++m) for (int k = 0; k < 2; ++k) \
;     dst[m][k] = *reinterpret_cast<const bf16x8*>((char*)SA(b, h) + a_thr + (m * 2 + k) * 1024)
; #define MMA(ai, bj, At, Btf) do { __builtin_amdgcn_s_setprio(1); \
;     for (int m = 0; m < 4; ++m) for (int n = 0; n < 2; ++n) for (int k = 0; k < 2; ++k) \
;       acc[ai][bj][m][n] = __builtin_amdgcn_mfma_f32_16x16x32_bf16(Btf[n][k], At[m][k], acc[ai][bj][m][n], 0, 0, 0); \
;     __builtin_amdgcn_s_setprio(0); } while (0)
; #define WAIT_L(n) asm volatile("s_waitcnt lgkmcnt(" #n ")" ::: "memory")
; #define BAR __builtin_amdgcn_s_barrier()
; #define SCHED __builtin_amdgcn_sched_barrier(0)
; template <bool OVL, bool PANEL = false, class Epi>
; __device__ __forceinline__ void gemm_phase(const bf16_t* __restrict__ A, long lda, const bf16_t* __restrict__ Bt, long ldb, int nM, int nN, int K,
;                                            const Epi& epi, bf16_t* shm, int w0) {
;     ...
;       LDA(At, 1, 1); STAGE(SA(1, 0), A, lda, aoff, brow, t + 3);
;       BAR; WAIT_L(0); MMA(1, 0, At, B0); BAR; SCHED;
	v_mov_b32_e32 v0, v135
	s_barrier
	ds_read_b128 v[122:125], v148 offset:49152
	ds_read_b128 v[126:129], v148 offset:50176
	ds_read_b128 v[170:173], v148 offset:51200
	ds_read_b128 v[174:177], v148 offset:52224
	ds_read_b128 v[178:181], v148 offset:53248
	ds_read_b128 v[182:185], v148 offset:54272
	ds_read_b128 v[186:189], v148 offset:55296
	ds_read_b128 v[190:193], v148 offset:56320
	s_mov_b32 m0, s30
	v_lshl_add_u64 v[140:141], s[14:15], 0, v[0:1]
	s_mov_b64 s[14:15], 0xdc0
	v_lshl_add_u64 v[142:143], v[140:141], 0, s[14:15]
	s_mov_b64 s[30:31], 0x3edc0
	global_load_lds_dwordx4 v[142:143], off
	v_lshl_add_u64 v[140:141], v[140:141], 0, s[30:31]
	s_mov_b32 m0, s28
	s_nop 0
	global_load_lds_dwordx4 v[140:141], off
	s_barrier
	s_waitcnt lgkmcnt(0)

; #define MMA(ai, bj, At, Btf) do { __builtin_amdgcn_s_setprio(1); \
;     for (int m = 0; m < 4; ++m) for (int n = 0; n < 2; ++n) for (int k = 0; k < 2; ++k) \
;       acc[ai][bj][m][n] = __builtin_amdgcn_mfma_f32_16x16x32_bf16(Btf[n][k], At[m][k], acc[ai][bj][m][n], 0, 0, 0); \
;     __builtin_amdgcn_s_setprio(0); } while (0)
; #define WAIT_L(n) asm volatile("s_waitcnt lgkmcnt(" #n ")" ::: "memory")
; #define BAR __builtin_amdgcn_s_barrier()
; #define SCHED __builtin_amdgcn_sched_barrier(0)
; template <bool OVL, bool PANEL = false, class Epi>
; __device__ __forceinline__ void gemm_phase(const bf16_t* __restrict__ A, long lda, const bf16_t* __restrict__ Bt, long ldb, int nM, int nN, int K,
;                                            const Epi& epi, bf16_t* shm, int w0) {
;     ...
;       BAR; WAIT_L(0); MMA(1, 0, At, B0); BAR; SCHED;
	s_waitcnt lgkmcnt(0)
	v_mfma_f32_16x16x32_bf16 v[2:5], v[90:93], v[186:189], v[2:5]
	v_mfma_f32_16x16x32_bf16 v[6:9], v[114:117], v[186:189], v[6:9]
	v_mfma_f32_16x16x32_bf16 v[130:133], v[90:93], v[122:125], v[130:133]
	v_mfma_f32_16x16x32_bf16 v[150:153], v[114:117], v[122:125], v[150:153]
	v_mfma_f32_16x16x32_bf16 v[154:157], v[90:93], v[170:173], v[154:157]
	v_mfma_f32_16x16x32_bf16 v[158:161], v[114:117], v[170:173], v[158:161]
	v_mfma_f32_16x16x32_bf16 v[162:165], v[90:93], v[178:181], v[162:165]
	v_mfma_f32_16x16x32_bf16 v[166:169], v[114:117], v[178:181], v[166:169]
	v_mfma_f32_16x16x32_bf16 v[2:5], v[94:97], v[190:193], v[2:5]
	v_mfma_f32_16x16x32_bf16 v[6:9], v[118:121], v[190:193], v[6:9]
	v_mfma_f32_16x16x32_bf16 v[130:133], v[94:97], v[126:129], v[130:133]
	v_mfma_f32_16x16x32_bf16 v[150:153], v[118:121], v[126:129], v[150:153]
	v_mfma_f32_16x16x32_bf16 v[154:157], v[94:97], v[174:177], v[154:157]
	v_mfma_f32_16x16x32_bf16 v[158:161], v[118:121], v[174:177], v[158:161]
	v_mfma_f32_16x16x32_bf16 v[162:165], v[94:97], v[182:185], v[162:165]
	v_mfma_f32_16x16x32_bf16 v[166:169], v[118:121], v[182:185], v[166:169]

; #define MMA(ai, bj, At, Btf) do { __builtin_amdgcn_s_setprio(1); \
;     for (int m = 0; m < 4; ++m) for (int n = 0; n < 2; ++n) for (int k = 0; k < 2; ++k) \
;       acc[ai][bj][m][n] = __builtin_amdgcn_mfma_f32_16x16x32_bf16(Btf[n][k], At[m][k], acc[ai][bj][m][n], 0, 0, 0); \
;     __builtin_amdgcn_s_setprio(0); } while (0)
; #define WAIT_V(n) asm volatile("s_waitcnt vmcnt(" #n ")" ::: "memory")
; #define BAR __builtin_amdgcn_s_barrier()
; template <bool OVL, bool PANEL = false, class Epi>
; __device__ __forceinline__ void gemm_phase(const bf16_t* __restrict__ A, long lda, const bf16_t* __restrict__ Bt, long ldb, int nM, int nN, int K,
;                                            const Epi& epi, bf16_t* shm, int w0) {
;     ...
;       STAGE(SB(1, 1), Bt, ldb, boff, bcol + HALF, t + 3);
;       WAIT_V(6); BAR; MMA(1, 1, At, B1); BAR;
	s_barrier
	v_mov_b32_e32 v0, v136
	s_mov_b32 m0, s25
	v_lshl_add_u64 v[90:91], s[10:11], 0, v[0:1]
	v_lshl_add_u64 v[92:93], v[90:91], 0, s[94:95]
	global_load_lds_dwordx4 v[92:93], off
	v_lshl_add_u64 v[90:91], v[90:91], 0, s[26:27]
	s_mov_b32 m0, s24
	s_nop 0
	global_load_lds_dwordx4 v[90:91], off
	s_waitcnt vmcnt(6)
	s_barrier

; #define MMA(ai, bj, At, Btf) do { __builtin_amdgcn_s_setprio(1); \
;     for (int m = 0; m < 4; ++m) for (int n = 0; n < 2; ++n) for (int k = 0; k < 2; ++k) \
;       acc[ai][bj][m][n] = __builtin_amdgcn_mfma_f32_16x16x32_bf16(Btf[n][k], At[m][k], acc[ai][bj][m][n], 0, 0, 0); \
;     __builtin_amdgcn_s_setprio(0); } while (0)
; #define WAIT_V(n) asm volatile("s_waitcnt vmcnt(" #n ")" ::: "memory")
; #define BAR __builtin_amdgcn_s_barrier()
; template <bool OVL, bool PANEL = false, class Epi>
; __device__ __forceinline__ void gemm_phase(const bf16_t* __restrict__ A, long lda, const bf16_t* __restrict__ Bt, long ldb, int nM, int nN, int K,
;                                            const Epi& epi, bf16_t* shm, int w0) {
;     ...
;       WAIT_V(6); BAR; MMA(1, 1, At, B1); BAR;
	v_mfma_f32_16x16x32_bf16 v[10:13], v[194:197], v[122:125], v[10:13]
	v_mfma_f32_16x16x32_bf16 v[14:17], v[202:205], v[122:125], v[14:17]
	v_mfma_f32_16x16x32_bf16 v[46:49], v[194:197], v[170:173], v[46:49]
	v_mfma_f32_16x16x32_bf16 v[90:93], v[202:205], v[170:173], v[102:105]
	v_mfma_f32_16x16x32_bf16 v[94:97], v[194:197], v[178:181], v[106:109]
	v_mfma_f32_16x16x32_bf16 v[102:105], v[202:205], v[178:181], v[110:113]
	v_mfma_f32_16x16x32_bf16 v[82:85], v[194:197], v[186:189], v[82:85]
	v_mfma_f32_16x16x32_bf16 v[86:89], v[202:205], v[186:189], v[86:89]
	v_mfma_f32_16x16x32_bf16 v[10:13], v[198:201], v[126:129], v[10:13]
	v_mfma_f32_16x16x32_bf16 v[14:17], v[206:209], v[126:129], v[14:17]
	v_mfma_f32_16x16x32_bf16 v[46:49], v[198:201], v[174:177], v[46:49]
	v_mfma_f32_16x16x32_bf16 v[90:93], v[206:209], v[174:177], v[90:93]
	v_mfma_f32_16x16x32_bf16 v[94:97], v[198:201], v[182:185], v[94:97]
	v_mfma_f32_16x16x32_bf16 v[102:105], v[206:209], v[182:185], v[102:105]
	v_mfma_f32_16x16x32_bf16 v[82:85], v[198:201], v[190:193], v[82:85]
	v_mfma_f32_16x16x32_bf16 v[86:89], v[206:209], v[190:193], v[86:89]

; #define LDA(dst, b, h) for (int m = 0; m < 4; ++m) for (int k = 0; k < 2; ++k) \
;     dst[m][k] = *reinterpret_cast<const bf16x8*>((char*)SA(b, h) + a_thr + (m * 2 + k) * 1024)
; #define LDB(dst, b, h) for (int n = 0; n < 2; ++n) for (int k = 0; k < 2; ++k) \
;     dst[n][k] = *reinterpret_cast<const bf16x8*>((char*)SB(b, h) + b_thr + (n * 2 + k) * 1024)
; #define MMA(ai, bj, At, Btf) do { __builtin_amdgcn_s_setprio(1); \
;     for (int m = 0; m < 4; ++m) for (int n = 0; n < 2; ++n) for (int k = 0; k < 2; ++k) \
;       acc[ai][bj][m][n] = __builtin_amdgcn_mfma_f32_16x16x32_bf16(Btf[n][k], At[m][k], acc[ai][bj][m][n], 0, 0, 0); \
;     __builtin_amdgcn_s_setprio(0); } while (0)
; #define WAIT_L(n) asm volatile("s_waitcnt lgkmcnt(" #n ")" ::: "memory")
; #define BAR __builtin_amdgcn_s_barrier()
; template <bool OVL, bool PANEL = false, class Epi>
; __device__ __forceinline__ void gemm_phase(const bf16_t* __restrict__ A, long lda, const bf16_t* __restrict__ Bt, long ldb, int nM, int nN, int K,
;                                            const Epi& epi, bf16_t* shm, int w0) {
;     ...
;     { LDB(B0, 0, 0); LDA(At, 0, 0); STAGE(SA(1, 1), A, lda, aoff, brow + HALF, nt - 1);
;       BAR; WAIT_L(0); MMA(0, 0, At, B0); BAR;
	v_mov_b32_e32 v0, v135
	s_barrier
	ds_read_b128 v[106:109], v144
	ds_read_b128 v[110:113], v144 offset:1024
	ds_read_b128 v[114:117], v144 offset:2048
	ds_read_b128 v[118:121], v144 offset:3072
	ds_read_b128 v[122:125], v148
	ds_read_b128 v[126:129], v148 offset:1024
	ds_read_b128 v[170:173], v148 offset:2048
	ds_read_b128 v[174:177], v148 offset:3072
	ds_read_b128 v[178:181], v148 offset:4096
	ds_read_b128 v[182:185], v148 offset:5120
	ds_read_b128 v[186:189], v148 offset:6144
	ds_read_b128 v[190:193], v148 offset:7168
	s_mov_b32 m0, s29
	v_lshl_add_u64 v[140:141], s[8:9], 0, v[0:1]
	v_lshl_add_u64 v[142:143], v[140:141], 0, s[14:15]
	global_load_lds_dwordx4 v[142:143], off
	v_lshl_add_u64 v[140:141], v[140:141], 0, s[30:31]
	s_mov_b32 m0, s13
	s_nop 0
	global_load_lds_dwordx4 v[140:141], off
	s_barrier
	s_waitcnt lgkmcnt(0)

; #define MMA(ai, bj, At, Btf) do { __builtin_amdgcn_s_setprio(1); \
;     for (int m = 0; m < 4; ++m) for (int n = 0; n < 2; ++n) for (int k = 0; k < 2; ++k) \
;       acc[ai][bj][m][n] = __builtin_amdgcn_mfma_f32_16x16x32_bf16(Btf[n][k], At[m][k], acc[ai][bj][m][n], 0, 0, 0); \
;     __builtin_amdgcn_s_setprio(0); } while (0)
; #define WAIT_L(n) asm volatile("s_waitcnt lgkmcnt(" #n ")" ::: "memory")
; #define BAR __builtin_amdgcn_s_barrier()
; template <bool OVL, bool PANEL = false, class Epi>
; __device__ __forceinline__ void gemm_phase(const bf16_t* __restrict__ A, long lda, const bf16_t* __restrict__ Bt, long ldb, int nM, int nN, int K,
;                                            const Epi& epi, bf16_t* shm, int w0) {
;     ...
;       BAR; WAIT_L(0); MMA(0, 0, At, B0); BAR;
	s_waitcnt lgkmcnt(0)
	v_mfma_f32_16x16x32_bf16 v[50:53], v[106:109], v[122:125], v[50:53]
	v_mfma_f32_16x16x32_bf16 v[54:57], v[114:117], v[122:125], v[54:57]
	v_mfma_f32_16x16x32_bf16 v[58:61], v[106:109], v[170:173], v[58:61]
	v_mfma_f32_16x16x32_bf16 v[62:65], v[114:117], v[170:173], v[62:65]
	v_mfma_f32_16x16x32_bf16 v[66:69], v[106:109], v[178:181], v[66:69]
	v_mfma_f32_16x16x32_bf16 v[70:73], v[114:117], v[178:181], v[70:73]
	v_mfma_f32_16x16x32_bf16 v[74:77], v[106:109], v[186:189], v[74:77]
	v_mfma_f32_16x16x32_bf16 v[78:81], v[114:117], v[186:189], v[78:81]
	v_mfma_f32_16x16x32_bf16 v[50:53], v[110:113], v[126:129], v[50:53]
	v_mfma_f32_16x16x32_bf16 v[54:57], v[118:121], v[126:129], v[54:57]
	v_mfma_f32_16x16x32_bf16 v[58:61], v[110:113], v[174:177], v[58:61]
	v_mfma_f32_16x16x32_bf16 v[62:65], v[118:121], v[174:177], v[62:65]
	v_mfma_f32_16x16x32_bf16 v[66:69], v[110:113], v[182:185], v[66:69]
	v_mfma_f32_16x16x32_bf16 v[70:73], v[118:121], v[182:185], v[70:73]
	v_mfma_f32_16x16x32_bf16 v[74:77], v[110:113], v[190:193], v[74:77]
	v_mfma_f32_16x16x32_bf16 v[78:81], v[118:121], v[190:193], v[78:81]

; #define LDB(dst, b, h) for (int n = 0; n < 2; ++n) for (int k = 0; k < 2; ++k) \
;     dst[n][k] = *reinterpret_cast<const bf16x8*>((char*)SB(b, h) + b_thr + (n * 2 + k) * 1024)
; #define MMA(ai, bj, At, Btf) do { __builtin_amdgcn_s_setprio(1); \
;     for (int m = 0; m < 4; ++m) for (int n = 0; n < 2; ++n) for (int k = 0; k < 2; ++k) \
;       acc[ai][bj][m][n] = __builtin_amdgcn_mfma_f32_16x16x32_bf16(Btf[n][k], At[m][k], acc[ai][bj][m][n], 0, 0, 0); \
;     __builtin_amdgcn_s_setprio(0); } while (0)
; #define WAIT_L(n) asm volatile("s_waitcnt lgkmcnt(" #n ")" ::: "memory")
; #define BAR __builtin_amdgcn_s_barrier()
; template <bool OVL, bool PANEL = false, class Epi>
; __device__ __forceinline__ void gemm_phase(const bf16_t* __restrict__ A, long lda, const bf16_t* __restrict__ Bt, long ldb, int nM, int nN, int K,
;                                            const Epi& epi, bf16_t* shm, int w0) {
;     ...
;       LDB(B1, 0, 1); BAR; WAIT_L(0); MMA(0, 1, At, B1); BAR;
	s_barrier
	ds_read_b128 v[194:197], v145
	ds_read_b128 v[198:201], v145 offset:1024
	ds_read_b128 v[202:205], v145 offset:2048
	ds_read_b128 v[206:209], v145 offset:3072
	s_barrier
	s_waitcnt lgkmcnt(0)

; #define LDB(dst, b, h) for (int n = 0; n < 2; ++n) for (int k = 0; k < 2; ++k) \
;     dst[n][k] = *reinterpret_cast<const bf16x8*>((char*)SB(b, h) + b_thr + (n * 2 + k) * 1024)
; #define MMA(ai, bj, At, Btf) do { __builtin_amdgcn_s_setprio(1); \
;     for (int m = 0; m < 4; ++m) for (int n = 0; n < 2; ++n) for (int k = 0; k < 2; ++k) \
;       acc[ai][bj][m][n] = __builtin_amdgcn_mfma_f32_16x16x32_bf16(Btf[n][k], At[m][k], acc[ai][bj][m][n], 0, 0, 0); \
;     __builtin_amdgcn_s_setprio(0); } while (0)
; #define WAIT_L(n) asm volatile("s_waitcnt lgkmcnt(" #n ")" ::: "memory")
; #define BAR __builtin_amdgcn_s_barrier()
; template <bool OVL, bool PANEL = false, class Epi>
; __device__ __forceinline__ void gemm_phase(const bf16_t* __restrict__ A, long lda, const bf16_t* __restrict__ Bt, long ldb, int nM, int nN, int K,
;                                            const Epi& epi, bf16_t* shm, int w0) {
;     ...
;       LDB(B1, 0, 1); BAR; WAIT_L(0); MMA(0, 1, At, B1); BAR;
	s_waitcnt lgkmcnt(0)
	v_mfma_f32_16x16x32_bf16 v[18:21], v[202:205], v[122:125], v[18:21]
	v_mfma_f32_16x16x32_bf16 v[22:25], v[194:197], v[170:173], v[22:25]
	v_mfma_f32_16x16x32_bf16 v[26:29], v[202:205], v[170:173], v[26:29]
	v_mfma_f32_16x16x32_bf16 v[30:33], v[194:197], v[178:181], v[30:33]
	v_mfma_f32_16x16x32_bf16 v[34:37], v[202:205], v[178:181], v[34:37]
	v_mfma_f32_16x16x32_bf16 v[38:41], v[194:197], v[186:189], v[38:41]
	v_mfma_f32_16x16x32_bf16 v[42:45], v[202:205], v[186:189], v[42:45]
	v_mfma_f32_16x16x32_bf16 v[98:101], v[194:197], v[122:125], v[98:101]
	v_mfma_f32_16x16x32_bf16 v[18:21], v[206:209], v[126:129], v[18:21]
	v_mfma_f32_16x16x32_bf16 v[22:25], v[198:201], v[174:177], v[22:25]
	v_mfma_f32_16x16x32_bf16 v[26:29], v[206:209], v[174:177], v[26:29]
	v_mfma_f32_16x16x32_bf16 v[30:33], v[198:201], v[182:185], v[30:33]
	v_mfma_f32_16x16x32_bf16 v[34:37], v[206:209], v[182:185], v[34:37]
	v_mfma_f32_16x16x32_bf16 v[38:41], v[198:201], v[190:193], v[38:41]
	v_mfma_f32_16x16x32_bf16 v[42:45], v[206:209], v[190:193], v[42:45]
	v_mfma_f32_16x16x32_bf16 v[210:213], v[198:201], v[126:129], v[98:101]

; #define LDA(dst, b, h) for (int m = 0; m < 4; ++m) for (int k = 0; k < 2; ++k) \
;     dst[m][k] = *reinterpret_cast<const bf16x8*>((char*)SA(b, h) + a_thr + (m * 2 + k) * 1024)
; #define MMA(ai, bj, At, Btf) do { __builtin_amdgcn_s_setprio(1); \
;     for (int m = 0; m < 4; ++m) for (int n = 0; n < 2; ++n) for (int k = 0; k < 2; ++k) \
;       acc[ai][bj][m][n] = __builtin_amdgcn_mfma_f32_16x16x32_bf16(Btf[n][k], At[m][k], acc[ai][bj][m][n], 0, 0, 0); \
;     __builtin_amdgcn_s_setprio(0); } while (0)
; #define WAIT_V(n) asm volatile("s_waitcnt vmcnt(" #n ")" ::: "memory")
; #define WAIT_L(n) asm volatile("s_waitcnt lgkmcnt(" #n ")" ::: "memory")
; #define BAR __builtin_amdgcn_s_barrier()
; template <bool OVL, bool PANEL = false, class Epi>
; __device__ __forceinline__ void gemm_phase(const bf16_t* __restrict__ A, long lda, const bf16_t* __restrict__ Bt, long ldb, int nM, int nN, int K,
;                                            const Epi& epi, bf16_t* shm, int w0) {
;     ...
;       LDA(At, 0, 1); WAIT_V(4); BAR; WAIT_L(0); MMA(1, 0, At, B0); MMA(1, 1, At, B1); BAR; }
	s_barrier
	s_nop 0
	ds_read_b128 v[98:101], v148 offset:16384
	ds_read_b128 v[122:125], v148 offset:17408
	ds_read_b128 v[126:129], v148 offset:18432
	ds_read_b128 v[170:173], v148 offset:19456
	ds_read_b128 v[174:177], v148 offset:20480
	ds_read_b128 v[178:181], v148 offset:21504
	ds_read_b128 v[182:185], v148 offset:22528
	ds_read_b128 v[186:189], v148 offset:23552
	s_waitcnt vmcnt(4)
	s_barrier
	s_waitcnt lgkmcnt(0)

; #define LDA(dst, b, h) for (int m = 0; m < 4; ++m) for (int k = 0; k < 2; ++k) \
;     dst[m][k] = *reinterpret_cast<const bf16x8*>((char*)SA(b, h) + a_thr + (m * 2 + k) * 1024)
; #define MMA(ai, bj, At, Btf) do { __builtin_amdgcn_s_setprio(1); \
;     for (int m = 0; m < 4; ++m) for (int n = 0; n < 2; ++n) for (int k = 0; k < 2; ++k) \
;       acc[ai][bj][m][n] = __builtin_amdgcn_mfma_f32_16x16x32_bf16(Btf[n][k], At[m][k], acc[ai][bj][m][n], 0, 0, 0); \
;     __builtin_amdgcn_s_setprio(0); } while (0)
; #define WAIT_V(n) asm volatile("s_waitcnt vmcnt(" #n ")" ::: "memory")
; #define WAIT_L(n) asm volatile("s_waitcnt lgkmcnt(" #n ")" ::: "memory")
; #define BAR __builtin_amdgcn_s_barrier()
; template <bool OVL, bool PANEL = false, class Epi>
; __device__ __forceinline__ void gemm_phase(const bf16_t* __restrict__ A, long lda, const bf16_t* __restrict__ Bt, long ldb, int nM, int nN, int K,
;                                            const Epi& epi, bf16_t* shm, int w0) {
;     ...
;       LDA(At, 0, 1); WAIT_V(4); BAR; WAIT_L(0); MMA(1, 0, At, B0); MMA(1, 1, At, B1); BAR; }
	s_waitcnt lgkmcnt(0)
	v_mfma_f32_16x16x32_bf16 v[2:5], v[106:109], v[182:185], v[2:5]
	v_mfma_f32_16x16x32_bf16 v[6:9], v[114:117], v[182:185], v[6:9]
	v_mfma_f32_16x16x32_bf16 v[130:133], v[106:109], v[98:101], v[130:133]
	v_mfma_f32_16x16x32_bf16 v[150:153], v[114:117], v[98:101], v[150:153]
	v_mfma_f32_16x16x32_bf16 v[154:157], v[106:109], v[126:129], v[154:157]
	v_mfma_f32_16x16x32_bf16 v[158:161], v[114:117], v[126:129], v[158:161]
	v_mfma_f32_16x16x32_bf16 v[162:165], v[106:109], v[174:177], v[162:165]
	v_mfma_f32_16x16x32_bf16 v[166:169], v[114:117], v[174:177], v[166:169]
	v_mfma_f32_16x16x32_bf16 v[2:5], v[110:113], v[186:189], v[2:5]
	v_mfma_f32_16x16x32_bf16 v[6:9], v[118:121], v[186:189], v[6:9]
	v_mfma_f32_16x16x32_bf16 v[130:133], v[110:113], v[122:125], v[130:133]
	v_mfma_f32_16x16x32_bf16 v[150:153], v[118:121], v[122:125], v[150:153]
	v_mfma_f32_16x16x32_bf16 v[154:157], v[110:113], v[170:173], v[154:157]
	v_mfma_f32_16x16x32_bf16 v[158:161], v[118:121], v[170:173], v[158:161]
	v_mfma_f32_16x16x32_bf16 v[162:165], v[110:113], v[178:181], v[162:165]
	v_mfma_f32_16x16x32_bf16 v[166:169], v[118:121], v[178:181], v[166:169]


; #define LDA(dst, b, h) for (int m = 0; m < 4; ++m) for (int k = 0; k < 2; ++k) \
;     dst[m][k] = *reinterpret_cast<const bf16x8*>((char*)SA(b, h) + a_thr + (m * 2 + k) * 1024)
; #define MMA(ai, bj, At, Btf) do { __builtin_amdgcn_s_setprio(1); \
;     for (int m = 0; m < 4; ++m) for (int n = 0; n < 2; ++n) for (int k = 0; k < 2; ++k) \
;       acc[ai][bj][m][n] = __builtin_amdgcn_mfma_f32_16x16x32_bf16(Btf[n][k], At[m][k], acc[ai][bj][m][n], 0, 0, 0); \
;     __builtin_amdgcn_s_setprio(0); } while (0)
; #define WAIT_V(n) asm volatile("s_waitcnt vmcnt(" #n ")" ::: "memory")
; #define WAIT_L(n) asm volatile("s_waitcnt lgkmcnt(" #n ")" ::: "memory")
; #define BAR __builtin_amdgcn_s_barrier()
; template <bool OVL, bool PANEL = false, class Epi>
; __device__ __forceinline__ void gemm_phase(const bf16_t* __restrict__ A, long lda, const bf16_t* __restrict__ Bt, long ldb, int nM, int nN, int K,
;                                            const Epi& epi, bf16_t* shm, int w0) {
;     ...
;       LDA(At, 0, 1); WAIT_V(4); BAR; WAIT_L(0); MMA(1, 0, At, B0); MMA(1, 1, At, B1); BAR; }
	v_mfma_f32_16x16x32_bf16 v[46:49], v[194:197], v[126:129], v[46:49]
	v_mfma_f32_16x16x32_bf16 v[190:193], v[198:201], v[170:173], v[46:49]
	v_mfma_f32_16x16x32_bf16 v[46:49], v[202:205], v[126:129], v[90:93]
	v_mfma_f32_16x16x32_bf16 v[170:173], v[206:209], v[170:173], v[46:49]
	v_mfma_f32_16x16x32_bf16 v[46:49], v[194:197], v[174:177], v[94:97]
	v_mfma_f32_16x16x32_bf16 v[214:217], v[198:201], v[178:181], v[46:49]
	v_mfma_f32_16x16x32_bf16 v[46:49], v[202:205], v[174:177], v[102:105]
	v_mfma_f32_16x16x32_bf16 v[10:13], v[194:197], v[98:101], v[10:13]
	v_mfma_f32_16x16x32_bf16 v[14:17], v[202:205], v[98:101], v[14:17]
	v_mfma_f32_16x16x32_bf16 v[174:177], v[206:209], v[178:181], v[46:49]
	v_mfma_f32_16x16x32_bf16 v[46:49], v[194:197], v[182:185], v[82:85]
	v_mfma_f32_16x16x32_bf16 v[10:13], v[198:201], v[122:125], v[10:13]
	v_mfma_f32_16x16x32_bf16 v[14:17], v[206:209], v[122:125], v[14:17]
	v_mfma_f32_16x16x32_bf16 v[178:181], v[198:201], v[186:189], v[46:49]
	v_mfma_f32_16x16x32_bf16 v[46:49], v[202:205], v[182:185], v[86:89]
	v_mfma_f32_16x16x32_bf16 v[182:185], v[206:209], v[186:189], v[46:49]

; #define LDA(dst, b, h) for (int m = 0; m < 4; ++m) for (int k = 0; k < 2; ++k) \
;     dst[m][k] = *reinterpret_cast<const bf16x8*>((char*)SA(b, h) + a_thr + (m * 2 + k) * 1024)
; #define LDB(dst, b, h) for (int n = 0; n < 2; ++n) for (int k = 0; k < 2; ++k) \
;     dst[n][k] = *reinterpret_cast<const bf16x8*>((char*)SB(b, h) + b_thr + (n * 2 + k) * 1024)
; #define MMA(ai, bj, At, Btf) do { __builtin_amdgcn_s_setprio(1); \
;     for (int m = 0; m < 4; ++m) for (int n = 0; n < 2; ++n) for (int k = 0; k < 2; ++k) \
;       acc[ai][bj][m][n] = __builtin_amdgcn_mfma_f32_16x16x32_bf16(Btf[n][k], At[m][k], acc[ai][bj][m][n], 0, 0, 0); \
;     __builtin_amdgcn_s_setprio(0); } while (0)
; #define WAIT_V(n) asm volatile("s_waitcnt vmcnt(" #n ")" ::: "memory")
; #define WAIT_L(n) asm volatile("s_waitcnt lgkmcnt(" #n ")" ::: "memory")
; #define BAR __builtin_amdgcn_s_barrier()
; template <bool OVL, bool PANEL = false, class Epi>
; __device__ __forceinline__ void gemm_phase(const bf16_t* __restrict__ A, long lda, const bf16_t* __restrict__ Bt, long ldb, int nM, int nN, int K,
;                                            const Epi& epi, bf16_t* shm, int w0) {
;     ...
;     { LDB(B0, 1, 0); LDA(At, 1, 0); WAIT_V(2); BAR; WAIT_L(0); MMA(0, 0, At, B0); BAR;
	s_barrier
	ds_read_b128 v[186:189], v146
	ds_read_b128 v[194:197], v146 offset:1024
	ds_read_b128 v[198:201], v146 offset:2048
	ds_read_b128 v[202:205], v146 offset:3072
	s_nop 0
	ds_read_b128 v[46:49], v148 offset:32768
	ds_read_b128 v[82:85], v148 offset:33792
	ds_read_b128 v[206:209], v148 offset:34816
	ds_read_b128 v[218:221], v148 offset:35840
	ds_read_b128 v[222:225], v148 offset:36864
	ds_read_b128 v[228:231], v148 offset:37888
	ds_read_b128 v[232:235], v148 offset:38912
	ds_read_b128 v[236:239], v148 offset:39936
	s_waitcnt vmcnt(2)
	s_barrier
	s_waitcnt lgkmcnt(0)

; #define LDA(dst, b, h) for (int m = 0; m < 4; ++m) for (int k = 0; k < 2; ++k) \
;     dst[m][k] = *reinterpret_cast<const bf16x8*>((char*)SA(b, h) + a_thr + (m * 2 + k) * 1024)
; #define LDB(dst, b, h) for (int n = 0; n < 2; ++n) for (int k = 0; k < 2; ++k) \
;     dst[n][k] = *reinterpret_cast<const bf16x8*>((char*)SB(b, h) + b_thr + (n * 2 + k) * 1024)
; #define MMA(ai, bj, At, Btf) do { __builtin_amdgcn_s_setprio(1); \
;     for (int m = 0; m < 4; ++m) for (int n = 0; n < 2; ++n) for (int k = 0; k < 2; ++k) \
;       acc[ai][bj][m][n] = __builtin_amdgcn_mfma_f32_16x16x32_bf16(Btf[n][k], At[m][k], acc[ai][bj][m][n], 0, 0, 0); \
;     __builtin_amdgcn_s_setprio(0); } while (0)
; #define WAIT_V(n) asm volatile("s_waitcnt vmcnt(" #n ")" ::: "memory")
; #define WAIT_L(n) asm volatile("s_waitcnt lgkmcnt(" #n ")" ::: "memory")
; #define BAR __builtin_amdgcn_s_barrier()
; template <bool OVL, bool PANEL = false, class Epi>
; __device__ __forceinline__ void gemm_phase(const bf16_t* __restrict__ A, long lda, const bf16_t* __restrict__ Bt, long ldb, int nM, int nN, int K,
;                                            const Epi& epi, bf16_t* shm, int w0) {
;     ...
;     { LDB(B0, 1, 0); LDA(At, 1, 0); WAIT_V(2); BAR; WAIT_L(0); MMA(0, 0, At, B0); BAR;
	s_waitcnt lgkmcnt(0)
	v_mfma_f32_16x16x32_bf16 v[50:53], v[186:189], v[46:49], v[50:53]
	v_mfma_f32_16x16x32_bf16 v[126:129], v[194:197], v[82:85], v[50:53]
	v_mfma_f32_16x16x32_bf16 v[50:53], v[198:201], v[46:49], v[54:57]
	v_mfma_f32_16x16x32_bf16 v[122:125], v[202:205], v[82:85], v[50:53]
	v_mfma_f32_16x16x32_bf16 v[50:53], v[186:189], v[206:209], v[58:61]
	v_mfma_f32_16x16x32_bf16 v[118:121], v[194:197], v[218:221], v[50:53]
	v_mfma_f32_16x16x32_bf16 v[50:53], v[198:201], v[206:209], v[62:65]
	v_mfma_f32_16x16x32_bf16 v[114:117], v[202:205], v[218:221], v[50:53]
	v_mfma_f32_16x16x32_bf16 v[50:53], v[186:189], v[222:225], v[66:69]
	v_mfma_f32_16x16x32_bf16 v[110:113], v[194:197], v[228:231], v[50:53]
	v_mfma_f32_16x16x32_bf16 v[50:53], v[198:201], v[222:225], v[70:73]
	v_mfma_f32_16x16x32_bf16 v[106:109], v[202:205], v[228:231], v[50:53]
	v_mfma_f32_16x16x32_bf16 v[50:53], v[186:189], v[232:235], v[74:77]
	v_mfma_f32_16x16x32_bf16 v[102:105], v[194:197], v[236:239], v[50:53]
	v_mfma_f32_16x16x32_bf16 v[50:53], v[198:201], v[232:235], v[78:81]
	v_mfma_f32_16x16x32_bf16 v[98:101], v[202:205], v[236:239], v[50:53]

; #define LDB(dst, b, h) for (int n = 0; n < 2; ++n) for (int k = 0; k < 2; ++k) \
;     dst[n][k] = *reinterpret_cast<const bf16x8*>((char*)SB(b, h) + b_thr + (n * 2 + k) * 1024)
; #define MMA(ai, bj, At, Btf) do { __builtin_amdgcn_s_setprio(1); \
;     for (int m = 0; m < 4; ++m) for (int n = 0; n < 2; ++n) for (int k = 0; k < 2; ++k) \
;       acc[ai][bj][m][n] = __builtin_amdgcn_mfma_f32_16x16x32_bf16(Btf[n][k], At[m][k], acc[ai][bj][m][n], 0, 0, 0); \
;     __builtin_amdgcn_s_setprio(0); } while (0)
; #define WAIT_V(n) asm volatile("s_waitcnt vmcnt(" #n ")" ::: "memory")
; #define WAIT_L(n) asm volatile("s_waitcnt lgkmcnt(" #n ")" ::: "memory")
; #define BAR __builtin_amdgcn_s_barrier()
; template <bool OVL, bool PANEL = false, class Epi>
; __device__ __forceinline__ void gemm_phase(const bf16_t* __restrict__ A, long lda, const bf16_t* __restrict__ Bt, long ldb, int nM, int nN, int K,
;                                            const Epi& epi, bf16_t* shm, int w0) {
;     ...
;       LDB(B1, 1, 1); WAIT_V(0); BAR; WAIT_L(0); MMA(0, 1, At, B1); BAR;
	s_barrier
	ds_read_b128 v[240:243], v147
	ds_read_b128 v[244:247], v147 offset:1024
	ds_read_b128 v[140:143], v147 offset:2048
	ds_read_b128 v[144:147], v147 offset:3072
	s_waitcnt vmcnt(0)
	s_barrier
	s_waitcnt lgkmcnt(0)

; #define LDB(dst, b, h) for (int n = 0; n < 2; ++n) for (int k = 0; k < 2; ++k) \
;     dst[n][k] = *reinterpret_cast<const bf16x8*>((char*)SB(b, h) + b_thr + (n * 2 + k) * 1024)
; #define MMA(ai, bj, At, Btf) do { __builtin_amdgcn_s_setprio(1); \
;     for (int m = 0; m < 4; ++m) for (int n = 0; n < 2; ++n) for (int k = 0; k < 2; ++k) \
;       acc[ai][bj][m][n] = __builtin_amdgcn_mfma_f32_16x16x32_bf16(Btf[n][k], At[m][k], acc[ai][bj][m][n], 0, 0, 0); \
;     __builtin_amdgcn_s_setprio(0); } while (0)
; #define WAIT_V(n) asm volatile("s_waitcnt vmcnt(" #n ")" ::: "memory")
; #define WAIT_L(n) asm volatile("s_waitcnt lgkmcnt(" #n ")" ::: "memory")
; #define BAR __builtin_amdgcn_s_barrier()
; template <bool OVL, bool PANEL = false, class Epi>
; __device__ __forceinline__ void gemm_phase(const bf16_t* __restrict__ A, long lda, const bf16_t* __restrict__ Bt, long ldb, int nM, int nN, int K,
;                                            const Epi& epi, bf16_t* shm, int w0) {
;     ...
;       LDB(B1, 1, 1); WAIT_V(0); BAR; WAIT_L(0); MMA(0, 1, At, B1); BAR;
	s_waitcnt lgkmcnt(0)
	v_mfma_f32_16x16x32_bf16 v[18:21], v[140:143], v[46:49], v[18:21]
	v_mfma_f32_16x16x32_bf16 v[90:93], v[144:147], v[82:85], v[18:21]
	v_mfma_f32_16x16x32_bf16 v[18:21], v[240:243], v[206:209], v[22:25]
	v_mfma_f32_16x16x32_bf16 v[50:53], v[240:243], v[46:49], v[210:213]
	v_mfma_f32_16x16x32_bf16 v[86:89], v[244:247], v[218:221], v[18:21]
	v_mfma_f32_16x16x32_bf16 v[18:21], v[140:143], v[206:209], v[26:29]
	v_mfma_f32_16x16x32_bf16 v[94:97], v[244:247], v[82:85], v[50:53]
	v_mfma_f32_16x16x32_bf16 v[82:85], v[144:147], v[218:221], v[18:21]
	v_mfma_f32_16x16x32_bf16 v[18:21], v[240:243], v[222:225], v[30:33]
	v_mfma_f32_16x16x32_bf16 v[78:81], v[244:247], v[228:231], v[18:21]
	v_mfma_f32_16x16x32_bf16 v[18:21], v[140:143], v[222:225], v[34:37]
	v_mfma_f32_16x16x32_bf16 v[74:77], v[144:147], v[228:231], v[18:21]
	v_mfma_f32_16x16x32_bf16 v[18:21], v[240:243], v[232:235], v[38:41]
	v_mfma_f32_16x16x32_bf16 v[70:73], v[244:247], v[236:239], v[18:21]
	v_mfma_f32_16x16x32_bf16 v[18:21], v[140:143], v[232:235], v[42:45]
	v_mfma_f32_16x16x32_bf16 v[66:69], v[144:147], v[236:239], v[18:21]

; #define LDA(dst, b, h) for (int m = 0; m < 4; ++m) for (int k = 0; k < 2; ++k) \
;     dst[m][k] = *reinterpret_cast<const bf16x8*>((char*)SA(b, h) + a_thr + (m * 2 + k) * 1024)
; #define MMA(ai, bj, At, Btf) do { __builtin_amdgcn_s_setprio(1); \
;     for (int m = 0; m < 4; ++m) for (int n = 0; n < 2; ++n) for (int k = 0; k < 2; ++k) \
;       acc[ai][bj][m][n] = __builtin_amdgcn_mfma_f32_16x16x32_bf16(Btf[n][k], At[m][k], acc[ai][bj][m][n], 0, 0, 0); \
;     __builtin_amdgcn_s_setprio(0); } while (0)
; #define WAIT_L(n) asm volatile("s_waitcnt lgkmcnt(" #n ")" ::: "memory")
; #define BAR __builtin_amdgcn_s_barrier()
; template <bool OVL, bool PANEL = false, class Epi>
; __device__ __forceinline__ void gemm_phase(const bf16_t* __restrict__ A, long lda, const bf16_t* __restrict__ Bt, long ldb, int nM, int nN, int K,
;                                            const Epi& epi, bf16_t* shm, int w0) {
;     ...
;       LDA(At, 1, 1); BAR; WAIT_L(0); MMA(1, 0, At, B0); MMA(1, 1, At, B1); BAR; }
	s_barrier
	s_nop 4
	ds_read_b128 v[18:21], v148 offset:49152
	ds_read_b128 v[22:25], v148 offset:50176
	ds_read_b128 v[206:209], v148 offset:51200
	ds_read_b128 v[210:213], v148 offset:52224
	ds_read_b128 v[218:221], v148 offset:53248
	ds_read_b128 v[222:225], v148 offset:54272
	ds_read_b128 v[228:231], v148 offset:55296
	ds_read_b128 v[232:235], v148 offset:56320
	s_barrier
	s_waitcnt lgkmcnt(0)

; #define LDA(dst, b, h) for (int m = 0; m < 4; ++m) for (int k = 0; k < 2; ++k) \
;     dst[m][k] = *reinterpret_cast<const bf16x8*>((char*)SA(b, h) + a_thr + (m * 2 + k) * 1024)
; #define MMA(ai, bj, At, Btf) do { __builtin_amdgcn_s_setprio(1); \
;     for (int m = 0; m < 4; ++m) for (int n = 0; n < 2; ++n) for (int k = 0; k < 2; ++k) \
;       acc[ai][bj][m][n] = __builtin_amdgcn_mfma_f32_16x16x32_bf16(Btf[n][k], At[m][k], acc[ai][bj][m][n], 0, 0, 0); \
;     __builtin_amdgcn_s_setprio(0); } while (0)
; #define WAIT_L(n) asm volatile("s_waitcnt lgkmcnt(" #n ")" ::: "memory")
; #define BAR __builtin_amdgcn_s_barrier()
; template <bool OVL, bool PANEL = false, class Epi>
; __device__ __forceinline__ void gemm_phase(const bf16_t* __restrict__ A, long lda, const bf16_t* __restrict__ Bt, long ldb, int nM, int nN, int K,
;                                            const Epi& epi, bf16_t* shm, int w0) {
;     ...
;       LDA(At, 1, 1); BAR; WAIT_L(0); MMA(1, 0, At, B0); MMA(1, 1, At, B1); BAR; }
	s_waitcnt lgkmcnt(0)
	v_mfma_f32_16x16x32_bf16 v[26:29], v[186:189], v[18:21], v[130:133]
	v_mfma_f32_16x16x32_bf16 v[62:65], v[194:197], v[22:25], v[26:29]
	v_mfma_f32_16x16x32_bf16 v[26:29], v[198:201], v[18:21], v[150:153]
	v_mfma_f32_16x16x32_bf16 v[58:61], v[202:205], v[22:25], v[26:29]
	v_mfma_f32_16x16x32_bf16 v[26:29], v[186:189], v[206:209], v[154:157]
	v_mfma_f32_16x16x32_bf16 v[54:57], v[194:197], v[210:213], v[26:29]
	v_mfma_f32_16x16x32_bf16 v[26:29], v[198:201], v[206:209], v[158:161]
	v_mfma_f32_16x16x32_bf16 v[50:53], v[202:205], v[210:213], v[26:29]
	v_mfma_f32_16x16x32_bf16 v[26:29], v[186:189], v[218:221], v[162:165]
	v_mfma_f32_16x16x32_bf16 v[2:5], v[186:189], v[228:231], v[2:5]
	v_mfma_f32_16x16x32_bf16 v[46:49], v[194:197], v[222:225], v[26:29]
	v_mfma_f32_16x16x32_bf16 v[26:29], v[198:201], v[218:221], v[166:169]
	v_mfma_f32_16x16x32_bf16 v[38:41], v[194:197], v[232:235], v[2:5]
	v_mfma_f32_16x16x32_bf16 v[2:5], v[198:201], v[228:231], v[6:9]
	v_mfma_f32_16x16x32_bf16 v[42:45], v[202:205], v[222:225], v[26:29]
	v_mfma_f32_16x16x32_bf16 v[34:37], v[202:205], v[232:235], v[2:5]


; #define LDA(dst, b, h) for (int m = 0; m < 4; ++m) for (int k = 0; k < 2; ++k) \
;     dst[m][k] = *reinterpret_cast<const bf16x8*>((char*)SA(b, h) + a_thr + (m * 2 + k) * 1024)
; #define MMA(ai, bj, At, Btf) do { __builtin_amdgcn_s_setprio(1); \
;     for (int m = 0; m < 4; ++m) for (int n = 0; n < 2; ++n) for (int k = 0; k < 2; ++k) \
;       acc[ai][bj][m][n] = __builtin_amdgcn_mfma_f32_16x16x32_bf16(Btf[n][k], At[m][k], acc[ai][bj][m][n], 0, 0, 0); \
;     __builtin_amdgcn_s_setprio(0); } while (0)
; #define WAIT_L(n) asm volatile("s_waitcnt lgkmcnt(" #n ")" ::: "memory")
; #define BAR __builtin_amdgcn_s_barrier()
; template <bool OVL, bool PANEL = false, class Epi>
; __device__ __forceinline__ void gemm_phase(const bf16_t* __restrict__ A, long lda, const bf16_t* __restrict__ Bt, long ldb, int nM, int nN, int K,
;                                            const Epi& epi, bf16_t* shm, int w0) {
;     ...
;       LDA(At, 1, 1); BAR; WAIT_L(0); MMA(1, 0, At, B0); MMA(1, 1, At, B1); BAR; }
	v_mfma_f32_16x16x32_bf16 v[2:5], v[240:243], v[18:21], v[10:13]
	v_mfma_f32_16x16x32_bf16 v[30:33], v[244:247], v[22:25], v[2:5]
	v_mfma_f32_16x16x32_bf16 v[2:5], v[140:143], v[18:21], v[14:17]
	v_mfma_f32_16x16x32_bf16 v[26:29], v[144:147], v[22:25], v[2:5]
	v_mfma_f32_16x16x32_bf16 v[2:5], v[240:243], v[206:209], v[190:193]
	v_mfma_f32_16x16x32_bf16 v[22:25], v[244:247], v[210:213], v[2:5]
	v_mfma_f32_16x16x32_bf16 v[2:5], v[140:143], v[206:209], v[170:173]
	v_mfma_f32_16x16x32_bf16 v[18:21], v[144:147], v[210:213], v[2:5]
	v_mfma_f32_16x16x32_bf16 v[2:5], v[240:243], v[218:221], v[214:217]
	v_mfma_f32_16x16x32_bf16 v[14:17], v[244:247], v[222:225], v[2:5]
	v_mfma_f32_16x16x32_bf16 v[2:5], v[140:143], v[218:221], v[174:177]
	v_mfma_f32_16x16x32_bf16 v[10:13], v[144:147], v[222:225], v[2:5]
	v_mfma_f32_16x16x32_bf16 v[2:5], v[240:243], v[228:231], v[178:181]
	v_mfma_f32_16x16x32_bf16 v[6:9], v[244:247], v[232:235], v[2:5]
	v_mfma_f32_16x16x32_bf16 v[2:5], v[140:143], v[228:231], v[182:185]
	v_mfma_f32_16x16x32_bf16 v[2:5], v[144:147], v[232:235], v[2:5]

; #define LDA(dst, b, h) for (int m = 0; m < 4; ++m) for (int k = 0; k < 2; ++k) \
;     dst[m][k] = *reinterpret_cast<const bf16x8*>((char*)SA(b, h) + a_thr + (m * 2 + k) * 1024)
; #define MMA(ai, bj, At, Btf) do { __builtin_amdgcn_s_setprio(1); \
;     for (int m = 0; m < 4; ++m) for (int n = 0; n < 2; ++n) for (int k = 0; k < 2; ++k) \
;       acc[ai][bj][m][n] = __builtin_amdgcn_mfma_f32_16x16x32_bf16(Btf[n][k], At[m][k], acc[ai][bj][m][n], 0, 0, 0); \
;     __builtin_amdgcn_s_setprio(0); } while (0)
; #define WAIT_L(n) asm volatile("s_waitcnt lgkmcnt(" #n ")" ::: "memory")
; #define BAR __builtin_amdgcn_s_barrier()
; template <bool OVL, bool PANEL = false, class Epi>
; __device__ __forceinline__ void gemm_phase(const bf16_t* __restrict__ A, long lda, const bf16_t* __restrict__ Bt, long ldb, int nM, int nN, int K,
;                                            const Epi& epi, bf16_t* shm, int w0) {
;     ...
;       LDA(At, 1, 1); BAR; WAIT_L(0); MMA(1, 0, At, B0); MMA(1, 1, At, B1); BAR; }
;     if (wr == 0) BAR;
	s_barrier
	s_and_saveexec_b64 s[8:9], s[6:7]
	s_cbranch_execz .LBB0_687
	s_barrier

; #define LDA(dst, b, h) for (int m = 0; m < 4; ++m) for (int k = 0; k < 2; ++k) \
;     dst[m][k] = *reinterpret_cast<const bf16x8*>((char*)SA(b, h) + a_thr + (m * 2 + k) * 1024)
; #define LDB(dst, b, h) for (int n = 0; n < 2; ++n) for (int k = 0; k < 2; ++k) \
;     dst[n][k] = *reinterpret_cast<const bf16x8*>((char*)SB(b, h) + b_thr + (n * 2 + k) * 1024)
; #define MMA(ai, bj, At, Btf) do { __builtin_amdgcn_s_setprio(1); \
;     for (int m = 0; m < 4; ++m) for (int n = 0; n < 2; ++n) for (int k = 0; k < 2; ++k) \
;       acc[ai][bj][m][n] = __builtin_amdgcn_mfma_f32_16x16x32_bf16(Btf[n][k], At[m][k], acc[ai][bj][m][n], 0, 0, 0); \
;     __builtin_amdgcn_s_setprio(0); } while (0)
; template <bool OVL, bool PANEL = false, class Epi>
; __device__ __forceinline__ void gemm_phase(const bf16_t* __restrict__ A, long lda, const bf16_t* __restrict__ Bt, long ldb, int nM, int nN, int K,
;                                            const Epi& epi, bf16_t* shm, int w0) {
;     ...
;     if (wr == 1) BAR;
;     WAIT_V(4); BAR;
;     STAGE(SB(1, 0), Bt, ldb, boff, bcol, 1); STAGE(SA(1, 0), A, lda, aoff, brow, 1); STAGE(SB(1, 1), Bt, ldb, boff, bcol + HALF, 1);
;     WAIT_V(6); BAR;
;     for (int t = 0; t < nt - 2; t += 2) {
;       LDB(B0, 0, 0); SCHED; LDA(At, 0, 0); STAGE(SA(1, 1), A, lda, aoff, brow + HALF, t + 1);
;       WAIT_L(8); BAR; WAIT_L(0); MMA(0, 0, At, B0); BAR; SCHED;
;       LDB(B1, 0, 1); STAGE(SB(0, 0), Bt, ldb, boff, bcol, t + 2);
;       BAR; WAIT_L(0); MMA(0, 1, At, B1); BAR;
;       LDA(At, 0, 1); STAGE(SA(0, 0), A, lda, aoff, brow, t + 2);
;       BAR; WAIT_L(0); MMA(1, 0, At, B0); BAR; SCHED;
;       STAGE(SB(0, 1), Bt, ldb, boff, bcol + HALF, t + 2);
;       WAIT_V(6); BAR; MMA(1, 1, At, B1); BAR;
;       LDB(B0, 1, 0); SCHED; LDA(At, 1, 0); STAGE(SA(0, 1), A, lda, aoff, brow + HALF, t + 2);
;       WAIT_L(8); BAR; WAIT_L(0); MMA(0, 0, At, B0); BAR; SCHED;
;       LDB(B1, 1, 1); STAGE(SB(1, 0), Bt, ldb, boff, bcol, t + 3);
;       BAR; WAIT_L(0); MMA(0, 1, At, B1); BAR;
;       LDA(At, 1, 1); STAGE(SA(1, 0), A, lda, aoff, brow, t + 3);
;       BAR; WAIT_L(0); MMA(1, 0, At, B0); BAR; SCHED;
;       STAGE(SB(1, 1), Bt, ldb, boff, bcol + HALF, t + 3);
;       WAIT_V(6); BAR; MMA(1, 1, At, B1); BAR;
;     }
;     { LDB(B0, 0, 0); LDA(At, 0, 0); STAGE(SA(1, 1), A, lda, aoff, brow + HALF, nt - 1);
;       BAR; WAIT_L(0); MMA(0, 0, At, B0); BAR;
.LBB0_696:
	s_or_b64 exec, exec, s[8:9]
	v_readlane_b32 s16, v252, 3
	s_lshl_b32 s14, s2, 8
	s_lshl_b32 s8, s13, 17
	v_readlane_b32 s26, v252, 13
	v_readlane_b32 s27, v252, 14
	s_add_u32 s8, s26, s8
	v_mov_b32_e32 v0, v134
	s_waitcnt vmcnt(4)
	s_barrier
	s_addc_u32 s9, s27, 0
	s_mov_b64 s[10:11], 0x80
	v_lshl_add_u64 v[2:3], s[8:9], 0, v[0:1]
	v_add_u32_e32 v0, s96, v227
	v_lshl_add_u64 v[4:5], v[2:3], 0, s[10:11]
	v_readfirstlane_b32 s10, v0
	v_readlane_b32 s17, v252, 4
	v_readlane_b32 s18, v252, 5
	v_readlane_b32 s19, v252, 6
	v_readlane_b32 s20, v252, 7
	v_readlane_b32 s21, v252, 8
	v_readlane_b32 s22, v252, 9
	v_readlane_b32 s23, v252, 10
	v_readlane_b32 s24, v252, 11
	v_readlane_b32 s25, v252, 12
	v_readlane_b32 s28, v252, 15
	v_readlane_b32 s29, v252, 16
	v_readlane_b32 s30, v252, 17
	v_readlane_b32 s31, v252, 18
	s_mov_b32 m0, s10
	s_mov_b64 s[10:11], 0x8080
	v_add_u32_e32 v0, 0x2000, v0
	v_lshl_add_u64 v[2:3], v[2:3], 0, s[10:11]
	v_readfirstlane_b32 s10, v0
	v_readlane_b32 s16, v252, 20
	global_load_lds_dwordx4 v[4:5], off
	s_mov_b32 m0, s10
	s_mul_i32 s10, s2, 0xf8000
	v_readlane_b32 s24, v252, 28
	s_mul_hi_u32 s11, s14, 0xf80
	v_readlane_b32 s25, v252, 29
	s_add_u32 s10, s24, s10
	v_mov_b32_e32 v0, v249
	global_load_lds_dwordx4 v[2:3], off
	s_addc_u32 s11, s25, s11
	v_readlane_b32 s17, v252, 21
	v_lshl_add_u64 v[2:3], s[10:11], 0, v[0:1]
	v_add_u32_e32 v0, 0x8000, v137
	v_readlane_b32 s18, v252, 22
	v_readlane_b32 s19, v252, 23
	s_mov_b64 s[16:17], 0xec0
	v_readfirstlane_b32 s10, v0
	v_add_u32_e32 v0, 0xa000, v137
	v_lshl_add_u64 v[4:5], v[2:3], 0, s[16:17]
	s_mov_b32 m0, s10
	s_mov_b64 s[18:19], 0x3eec0
	v_readfirstlane_b32 s10, v0
	global_load_lds_dwordx4 v[4:5], off
	v_lshl_add_u64 v[2:3], v[2:3], 0, s[18:19]
	s_mov_b32 m0, s10
	v_mov_b32_e32 v0, v134
	global_load_lds_dwordx4 v[2:3], off
	v_add_u32_e32 v82, 16, v143
	v_lshl_add_u64 v[2:3], s[8:9], 0, v[0:1]
	s_mov_b64 s[8:9], 0x10080
	v_add_u32_e32 v0, s75, v227
	v_lshl_add_u64 v[4:5], v[2:3], 0, s[8:9]
	v_readfirstlane_b32 s8, v0
	s_mov_b32 m0, s8
	s_mov_b64 s[8:9], 0x18080
	v_add_u32_e32 v0, 0x2000, v0
	v_lshl_add_u64 v[2:3], v[2:3], 0, s[8:9]
	v_readfirstlane_b32 s8, v0
	global_load_lds_dwordx4 v[4:5], off
	s_mov_b32 m0, s8
	s_or_b32 s8, s14, 0x80
	global_load_lds_dwordx4 v[2:3], off
	v_add_u32_e32 v0, 0x10000, v82
	s_mul_hi_u32 s9, s8, 0xf80
	s_mulk_i32 s8, 0xf80
	s_waitcnt vmcnt(6)
	s_barrier
	ds_read_b128 v[2:5], v0
	ds_read_b128 v[6:9], v0 offset:1024
	s_waitcnt vmcnt(0)
	ds_read_b128 v[10:13], v0 offset:2048
	ds_read_b128 v[14:17], v0 offset:3072
	ds_read_b128 v[18:21], v144
	ds_read_b128 v[22:25], v144 offset:1024
	ds_read_b128 v[26:29], v144 offset:2048
	ds_read_b128 v[30:33], v144 offset:3072
	ds_read_b128 v[34:37], v144 offset:4096
	ds_read_b128 v[38:41], v144 offset:5120
	ds_read_b128 v[42:45], v144 offset:6144
	ds_read_b128 v[46:49], v144 offset:7168
	s_add_u32 s8, s24, s8
	v_mov_b32_e32 v0, v249
	s_addc_u32 s9, s25, s9
	v_readlane_b32 s20, v252, 24
	v_lshl_add_u64 v[50:51], s[8:9], 0, v[0:1]
	v_add_u32_e32 v0, 0xc000, v137
	v_lshl_add_u64 v[52:53], v[50:51], 0, s[16:17]
	v_readfirstlane_b32 s8, v0
	v_add_u32_e32 v0, 0xe000, v137
	s_mov_b32 m0, s8
	v_readfirstlane_b32 s8, v0
	global_load_lds_dwordx4 v[52:53], off
	v_lshl_add_u64 v[50:51], v[50:51], 0, s[18:19]
	s_mov_b32 m0, s8
	v_readlane_b32 s21, v252, 25
	global_load_lds_dwordx4 v[50:51], off
	s_barrier
	s_waitcnt lgkmcnt(0)
	v_readlane_b32 s22, v252, 26
	v_readlane_b32 s23, v252, 27
	v_readlane_b32 s26, v252, 30
	v_readlane_b32 s27, v252, 31
	v_readlane_b32 s28, v252, 32
	v_readlane_b32 s29, v252, 33
	v_readlane_b32 s30, v252, 34
	v_readlane_b32 s31, v252, 35

; #define MMA(ai, bj, At, Btf) do { __builtin_amdgcn_s_setprio(1); \
;     for (int m = 0; m < 4; ++m) for (int n = 0; n < 2; ++n) for (int k = 0; k < 2; ++k) \
;       acc[ai][bj][m][n] = __builtin_amdgcn_mfma_f32_16x16x32_bf16(Btf[n][k], At[m][k], acc[ai][bj][m][n], 0, 0, 0); \
;     __builtin_amdgcn_s_setprio(0); } while (0)
; #define WAIT_L(n) asm volatile("s_waitcnt lgkmcnt(" #n ")" ::: "memory")
; #define BAR __builtin_amdgcn_s_barrier()
; template <bool OVL, bool PANEL = false, class Epi>
; __device__ __forceinline__ void gemm_phase(const bf16_t* __restrict__ A, long lda, const bf16_t* __restrict__ Bt, long ldb, int nM, int nN, int K,
;                                            const Epi& epi, bf16_t* shm, int w0) {
;     ...
;       BAR; WAIT_L(0); MMA(0, 0, At, B0); BAR;
	s_waitcnt lgkmcnt(0)
	v_mfma_f32_16x16x32_bf16 v[50:53], v[2:5], v[18:21], 0
	v_mfma_f32_16x16x32_bf16 v[54:57], v[10:13], v[18:21], 0
	v_mfma_f32_16x16x32_bf16 v[58:61], v[2:5], v[26:29], 0
	v_mfma_f32_16x16x32_bf16 v[62:65], v[10:13], v[26:29], 0
	v_mfma_f32_16x16x32_bf16 v[66:69], v[2:5], v[34:37], 0
	v_mfma_f32_16x16x32_bf16 v[70:73], v[10:13], v[34:37], 0
	v_mfma_f32_16x16x32_bf16 v[74:77], v[2:5], v[42:45], 0
	v_mfma_f32_16x16x32_bf16 v[78:81], v[10:13], v[42:45], 0
	v_mfma_f32_16x16x32_bf16 v[50:53], v[6:9], v[22:25], v[50:53]
	v_mfma_f32_16x16x32_bf16 v[54:57], v[14:17], v[22:25], v[54:57]
	v_mfma_f32_16x16x32_bf16 v[58:61], v[6:9], v[30:33], v[58:61]
	v_mfma_f32_16x16x32_bf16 v[62:65], v[14:17], v[30:33], v[62:65]
	v_mfma_f32_16x16x32_bf16 v[66:69], v[6:9], v[38:41], v[66:69]
	v_mfma_f32_16x16x32_bf16 v[70:73], v[14:17], v[38:41], v[70:73]
	v_mfma_f32_16x16x32_bf16 v[74:77], v[6:9], v[46:49], v[74:77]
	v_mfma_f32_16x16x32_bf16 v[78:81], v[14:17], v[46:49], v[78:81]

; #define LDB(dst, b, h) for (int n = 0; n < 2; ++n) for (int k = 0; k < 2; ++k) \
;     dst[n][k] = *reinterpret_cast<const bf16x8*>((char*)SB(b, h) + b_thr + (n * 2 + k) * 1024)
; #define MMA(ai, bj, At, Btf) do { __builtin_amdgcn_s_setprio(1); \
;     for (int m = 0; m < 4; ++m) for (int n = 0; n < 2; ++n) for (int k = 0; k < 2; ++k) \
;       acc[ai][bj][m][n] = __builtin_amdgcn_mfma_f32_16x16x32_bf16(Btf[n][k], At[m][k], acc[ai][bj][m][n], 0, 0, 0); \
;     __builtin_amdgcn_s_setprio(0); } while (0)
; #define WAIT_L(n) asm volatile("s_waitcnt lgkmcnt(" #n ")" ::: "memory")
; #define BAR __builtin_amdgcn_s_barrier()
; template <bool OVL, bool PANEL = false, class Epi>
; __device__ __forceinline__ void gemm_phase(const bf16_t* __restrict__ A, long lda, const bf16_t* __restrict__ Bt, long ldb, int nM, int nN, int K,
;                                            const Epi& epi, bf16_t* shm, int w0) {
;     ...
;       LDB(B1, 0, 1); BAR; WAIT_L(0); MMA(0, 1, At, B1); BAR;
	v_add_u32_e32 v0, 0x14000, v82
	s_barrier
	ds_read_b128 v[82:85], v0
	ds_read_b128 v[86:89], v0 offset:1024
	ds_read_b128 v[90:93], v0 offset:2048
	ds_read_b128 v[94:97], v0 offset:3072
	s_barrier
	s_waitcnt lgkmcnt(0)

; #define LDB(dst, b, h) for (int n = 0; n < 2; ++n) for (int k = 0; k < 2; ++k) \
;     dst[n][k] = *reinterpret_cast<const bf16x8*>((char*)SB(b, h) + b_thr + (n * 2 + k) * 1024)
; #define MMA(ai, bj, At, Btf) do { __builtin_amdgcn_s_setprio(1); \
;     for (int m = 0; m < 4; ++m) for (int n = 0; n < 2; ++n) for (int k = 0; k < 2; ++k) \
;       acc[ai][bj][m][n] = __builtin_amdgcn_mfma_f32_16x16x32_bf16(Btf[n][k], At[m][k], acc[ai][bj][m][n], 0, 0, 0); \
;     __builtin_amdgcn_s_setprio(0); } while (0)
; #define WAIT_L(n) asm volatile("s_waitcnt lgkmcnt(" #n ")" ::: "memory")
; #define BAR __builtin_amdgcn_s_barrier()
; template <bool OVL, bool PANEL = false, class Epi>
; __device__ __forceinline__ void gemm_phase(const bf16_t* __restrict__ A, long lda, const bf16_t* __restrict__ Bt, long ldb, int nM, int nN, int K,
;                                            const Epi& epi, bf16_t* shm, int w0) {
;     ...
;       LDB(B1, 0, 1); BAR; WAIT_L(0); MMA(0, 1, At, B1); BAR;
	s_waitcnt lgkmcnt(0)
	v_mfma_f32_16x16x32_bf16 v[98:101], v[82:85], v[18:21], 0
	v_mfma_f32_16x16x32_bf16 v[18:21], v[90:93], v[18:21], 0
	v_mfma_f32_16x16x32_bf16 v[146:149], v[86:89], v[22:25], v[98:101]
	v_mfma_f32_16x16x32_bf16 v[18:21], v[94:97], v[22:25], v[18:21]
	v_mfma_f32_16x16x32_bf16 v[22:25], v[82:85], v[26:29], 0
	v_mfma_f32_16x16x32_bf16 v[26:29], v[90:93], v[26:29], 0
	v_mfma_f32_16x16x32_bf16 v[22:25], v[86:89], v[30:33], v[22:25]
	v_mfma_f32_16x16x32_bf16 v[26:29], v[94:97], v[30:33], v[26:29]
	v_mfma_f32_16x16x32_bf16 v[30:33], v[82:85], v[34:37], 0
	v_mfma_f32_16x16x32_bf16 v[34:37], v[90:93], v[34:37], 0
	v_mfma_f32_16x16x32_bf16 v[30:33], v[86:89], v[38:41], v[30:33]
	v_mfma_f32_16x16x32_bf16 v[34:37], v[94:97], v[38:41], v[34:37]
	v_mfma_f32_16x16x32_bf16 v[38:41], v[82:85], v[42:45], 0
	v_mfma_f32_16x16x32_bf16 v[42:45], v[90:93], v[42:45], 0
	v_mfma_f32_16x16x32_bf16 v[38:41], v[86:89], v[46:49], v[38:41]
	v_mfma_f32_16x16x32_bf16 v[42:45], v[94:97], v[46:49], v[42:45]

; #define LDA(dst, b, h) for (int m = 0; m < 4; ++m) for (int k = 0; k < 2; ++k) \
;     dst[m][k] = *reinterpret_cast<const bf16x8*>((char*)SA(b, h) + a_thr + (m * 2 + k) * 1024)
; #define MMA(ai, bj, At, Btf) do { __builtin_amdgcn_s_setprio(1); \
;     for (int m = 0; m < 4; ++m) for (int n = 0; n < 2; ++n) for (int k = 0; k < 2; ++k) \
;       acc[ai][bj][m][n] = __builtin_amdgcn_mfma_f32_16x16x32_bf16(Btf[n][k], At[m][k], acc[ai][bj][m][n], 0, 0, 0); \
;     __builtin_amdgcn_s_setprio(0); } while (0)
; #define WAIT_V(n) asm volatile("s_waitcnt vmcnt(" #n ")" ::: "memory")
; #define WAIT_L(n) asm volatile("s_waitcnt lgkmcnt(" #n ")" ::: "memory")
; #define BAR __builtin_amdgcn_s_barrier()
; template <bool OVL, bool PANEL = false, class Epi>
; __device__ __forceinline__ void gemm_phase(const bf16_t* __restrict__ A, long lda, const bf16_t* __restrict__ Bt, long ldb, int nM, int nN, int K,
;                                            const Epi& epi, bf16_t* shm, int w0) {
;     ...
;       LDA(At, 0, 1); WAIT_V(4); BAR; WAIT_L(0); MMA(1, 0, At, B0); MMA(1, 1, At, B1); BAR; }
	s_barrier
	ds_read_b128 v[46:49], v144 offset:16384
	ds_read_b128 v[98:101], v144 offset:17408
	ds_read_b128 v[102:105], v144 offset:18432
	ds_read_b128 v[106:109], v144 offset:19456
	ds_read_b128 v[110:113], v144 offset:20480
	ds_read_b128 v[114:117], v144 offset:21504
	ds_read_b128 v[118:121], v144 offset:22528
	ds_read_b128 v[122:125], v144 offset:23552
	s_waitcnt vmcnt(4)
	s_barrier
	s_waitcnt lgkmcnt(0)

; #define LDA(dst, b, h) for (int m = 0; m < 4; ++m) for (int k = 0; k < 2; ++k) \
;     dst[m][k] = *reinterpret_cast<const bf16x8*>((char*)SA(b, h) + a_thr + (m * 2 + k) * 1024)
; #define MMA(ai, bj, At, Btf) do { __builtin_amdgcn_s_setprio(1); \
;     for (int m = 0; m < 4; ++m) for (int n = 0; n < 2; ++n) for (int k = 0; k < 2; ++k) \
;       acc[ai][bj][m][n] = __builtin_amdgcn_mfma_f32_16x16x32_bf16(Btf[n][k], At[m][k], acc[ai][bj][m][n], 0, 0, 0); \
;     __builtin_amdgcn_s_setprio(0); } while (0)
; #define WAIT_V(n) asm volatile("s_waitcnt vmcnt(" #n ")" ::: "memory")
; #define WAIT_L(n) asm volatile("s_waitcnt lgkmcnt(" #n ")" ::: "memory")
; #define BAR __builtin_amdgcn_s_barrier()
; template <bool OVL, bool PANEL = false, class Epi>
; __device__ __forceinline__ void gemm_phase(const bf16_t* __restrict__ A, long lda, const bf16_t* __restrict__ Bt, long ldb, int nM, int nN, int K,
;                                            const Epi& epi, bf16_t* shm, int w0) {
;     ...
;       LDA(At, 0, 1); WAIT_V(4); BAR; WAIT_L(0); MMA(1, 0, At, B0); MMA(1, 1, At, B1); BAR; }
	s_waitcnt lgkmcnt(0)
	v_mfma_f32_16x16x32_bf16 v[126:129], v[2:5], v[46:49], 0
	v_mfma_f32_16x16x32_bf16 v[150:153], v[6:9], v[98:101], v[126:129]
	v_mfma_f32_16x16x32_bf16 v[126:129], v[10:13], v[46:49], 0
	v_mfma_f32_16x16x32_bf16 v[154:157], v[14:17], v[98:101], v[126:129]
	v_mfma_f32_16x16x32_bf16 v[126:129], v[2:5], v[102:105], 0
	v_mfma_f32_16x16x32_bf16 v[158:161], v[6:9], v[106:109], v[126:129]
	v_mfma_f32_16x16x32_bf16 v[126:129], v[10:13], v[102:105], 0
	v_mfma_f32_16x16x32_bf16 v[162:165], v[14:17], v[106:109], v[126:129]
	v_mfma_f32_16x16x32_bf16 v[126:129], v[2:5], v[110:113], 0
	v_mfma_f32_16x16x32_bf16 v[2:5], v[2:5], v[118:121], 0
	v_mfma_f32_16x16x32_bf16 v[166:169], v[6:9], v[114:117], v[126:129]
	v_mfma_f32_16x16x32_bf16 v[2:5], v[6:9], v[122:125], v[2:5]
	v_mfma_f32_16x16x32_bf16 v[6:9], v[10:13], v[118:121], 0
	v_mfma_f32_16x16x32_bf16 v[126:129], v[10:13], v[110:113], 0
	v_mfma_f32_16x16x32_bf16 v[6:9], v[14:17], v[122:125], v[6:9]
	v_mfma_f32_16x16x32_bf16 v[170:173], v[14:17], v[114:117], v[126:129]


; #define LDA(dst, b, h) for (int m = 0; m < 4; ++m) for (int k = 0; k < 2; ++k) \
;     dst[m][k] = *reinterpret_cast<const bf16x8*>((char*)SA(b, h) + a_thr + (m * 2 + k) * 1024)
; #define MMA(ai, bj, At, Btf) do { __builtin_amdgcn_s_setprio(1); \
;     for (int m = 0; m < 4; ++m) for (int n = 0; n < 2; ++n) for (int k = 0; k < 2; ++k) \
;       acc[ai][bj][m][n] = __builtin_amdgcn_mfma_f32_16x16x32_bf16(Btf[n][k], At[m][k], acc[ai][bj][m][n], 0, 0, 0); \
;     __builtin_amdgcn_s_setprio(0); } while (0)
; #define WAIT_V(n) asm volatile("s_waitcnt vmcnt(" #n ")" ::: "memory")
; #define WAIT_L(n) asm volatile("s_waitcnt lgkmcnt(" #n ")" ::: "memory")
; #define BAR __builtin_amdgcn_s_barrier()
; template <bool OVL, bool PANEL = false, class Epi>
; __device__ __forceinline__ void gemm_phase(const bf16_t* __restrict__ A, long lda, const bf16_t* __restrict__ Bt, long ldb, int nM, int nN, int K,
;                                            const Epi& epi, bf16_t* shm, int w0) {
;     ...
;       LDA(At, 0, 1); WAIT_V(4); BAR; WAIT_L(0); MMA(1, 0, At, B0); MMA(1, 1, At, B1); BAR; }
	v_mfma_f32_16x16x32_bf16 v[10:13], v[82:85], v[46:49], 0
	v_mfma_f32_16x16x32_bf16 v[14:17], v[90:93], v[46:49], 0
	v_mfma_f32_16x16x32_bf16 v[46:49], v[82:85], v[102:105], 0
	v_mfma_f32_16x16x32_bf16 v[174:177], v[86:89], v[106:109], v[46:49]
	v_mfma_f32_16x16x32_bf16 v[46:49], v[90:93], v[102:105], 0
	v_mfma_f32_16x16x32_bf16 v[178:181], v[94:97], v[106:109], v[46:49]
	v_mfma_f32_16x16x32_bf16 v[46:49], v[82:85], v[110:113], 0
	v_mfma_f32_16x16x32_bf16 v[182:185], v[86:89], v[114:117], v[46:49]
	v_mfma_f32_16x16x32_bf16 v[46:49], v[90:93], v[110:113], 0
	v_mfma_f32_16x16x32_bf16 v[186:189], v[94:97], v[114:117], v[46:49]
	v_mfma_f32_16x16x32_bf16 v[46:49], v[82:85], v[118:121], 0
	v_mfma_f32_16x16x32_bf16 v[10:13], v[86:89], v[98:101], v[10:13]
	v_mfma_f32_16x16x32_bf16 v[14:17], v[94:97], v[98:101], v[14:17]
	v_mfma_f32_16x16x32_bf16 v[190:193], v[86:89], v[122:125], v[46:49]
	v_mfma_f32_16x16x32_bf16 v[46:49], v[90:93], v[118:121], 0
	v_mfma_f32_16x16x32_bf16 v[194:197], v[94:97], v[122:125], v[46:49]

; #define LDA(dst, b, h) for (int m = 0; m < 4; ++m) for (int k = 0; k < 2; ++k) \
;     dst[m][k] = *reinterpret_cast<const bf16x8*>((char*)SA(b, h) + a_thr + (m * 2 + k) * 1024)
; #define LDB(dst, b, h) for (int n = 0; n < 2; ++n) for (int k = 0; k < 2; ++k) \
;     dst[n][k] = *reinterpret_cast<const bf16x8*>((char*)SB(b, h) + b_thr + (n * 2 + k) * 1024)
; #define MMA(ai, bj, At, Btf) do { __builtin_amdgcn_s_setprio(1); \
;     for (int m = 0; m < 4; ++m) for (int n = 0; n < 2; ++n) for (int k = 0; k < 2; ++k) \
;       acc[ai][bj][m][n] = __builtin_amdgcn_mfma_f32_16x16x32_bf16(Btf[n][k], At[m][k], acc[ai][bj][m][n], 0, 0, 0); \
;     __builtin_amdgcn_s_setprio(0); } while (0)
; #define WAIT_V(n) asm volatile("s_waitcnt vmcnt(" #n ")" ::: "memory")
; #define WAIT_L(n) asm volatile("s_waitcnt lgkmcnt(" #n ")" ::: "memory")
; #define BAR __builtin_amdgcn_s_barrier()
; template <bool OVL, bool PANEL = false, class Epi>
; __device__ __forceinline__ void gemm_phase(const bf16_t* __restrict__ A, long lda, const bf16_t* __restrict__ Bt, long ldb, int nM, int nN, int K,
;                                            const Epi& epi, bf16_t* shm, int w0) {
;     ...
;     { LDB(B0, 1, 0); LDA(At, 1, 0); WAIT_V(2); BAR; WAIT_L(0); MMA(0, 0, At, B0); BAR;
	v_add_u32_e32 v0, s96, v143
	s_barrier
	ds_read_b128 v[198:201], v0
	ds_read_b128 v[202:205], v0 offset:1024
	ds_read_b128 v[206:209], v0 offset:2048
	ds_read_b128 v[210:213], v0 offset:3072
	ds_read_b128 v[46:49], v144 offset:32768
	ds_read_b128 v[82:85], v144 offset:33792
	ds_read_b128 v[214:217], v144 offset:34816
	ds_read_b128 v[218:221], v144 offset:35840
	ds_read_b128 v[222:225], v144 offset:36864
	ds_read_b128 v[228:231], v144 offset:37888
	ds_read_b128 v[232:235], v144 offset:38912
	ds_read_b128 v[236:239], v144 offset:39936
	s_waitcnt vmcnt(2)
	s_barrier
	s_waitcnt lgkmcnt(0)

; #define LDA(dst, b, h) for (int m = 0; m < 4; ++m) for (int k = 0; k < 2; ++k) \
;     dst[m][k] = *reinterpret_cast<const bf16x8*>((char*)SA(b, h) + a_thr + (m * 2 + k) * 1024)
; #define LDB(dst, b, h) for (int n = 0; n < 2; ++n) for (int k = 0; k < 2; ++k) \
;     dst[n][k] = *reinterpret_cast<const bf16x8*>((char*)SB(b, h) + b_thr + (n * 2 + k) * 1024)
; #define MMA(ai, bj, At, Btf) do { __builtin_amdgcn_s_setprio(1); \
;     for (int m = 0; m < 4; ++m) for (int n = 0; n < 2; ++n) for (int k = 0; k < 2; ++k) \
;       acc[ai][bj][m][n] = __builtin_amdgcn_mfma_f32_16x16x32_bf16(Btf[n][k], At[m][k], acc[ai][bj][m][n], 0, 0, 0); \
;     __builtin_amdgcn_s_setprio(0); } while (0)
; #define WAIT_V(n) asm volatile("s_waitcnt vmcnt(" #n ")" ::: "memory")
; #define WAIT_L(n) asm volatile("s_waitcnt lgkmcnt(" #n ")" ::: "memory")
; #define BAR __builtin_amdgcn_s_barrier()
; template <bool OVL, bool PANEL = false, class Epi>
; __device__ __forceinline__ void gemm_phase(const bf16_t* __restrict__ A, long lda, const bf16_t* __restrict__ Bt, long ldb, int nM, int nN, int K,
;                                            const Epi& epi, bf16_t* shm, int w0) {
;     ...
;     { LDB(B0, 1, 0); LDA(At, 1, 0); WAIT_V(2); BAR; WAIT_L(0); MMA(0, 0, At, B0); BAR;
	s_waitcnt lgkmcnt(0)
	v_mfma_f32_16x16x32_bf16 v[50:53], v[198:201], v[46:49], v[50:53]
	v_mfma_f32_16x16x32_bf16 v[126:129], v[202:205], v[82:85], v[50:53]
	v_mfma_f32_16x16x32_bf16 v[50:53], v[206:209], v[46:49], v[54:57]
	v_mfma_f32_16x16x32_bf16 v[122:125], v[210:213], v[82:85], v[50:53]
	v_mfma_f32_16x16x32_bf16 v[50:53], v[198:201], v[214:217], v[58:61]
	v_mfma_f32_16x16x32_bf16 v[118:121], v[202:205], v[218:221], v[50:53]
	v_mfma_f32_16x16x32_bf16 v[50:53], v[206:209], v[214:217], v[62:65]
	v_mfma_f32_16x16x32_bf16 v[114:117], v[210:213], v[218:221], v[50:53]
	v_mfma_f32_16x16x32_bf16 v[50:53], v[198:201], v[222:225], v[66:69]
	v_mfma_f32_16x16x32_bf16 v[110:113], v[202:205], v[228:231], v[50:53]
	v_mfma_f32_16x16x32_bf16 v[50:53], v[206:209], v[222:225], v[70:73]
	v_mfma_f32_16x16x32_bf16 v[106:109], v[210:213], v[228:231], v[50:53]
	v_mfma_f32_16x16x32_bf16 v[50:53], v[198:201], v[232:235], v[74:77]
	v_mfma_f32_16x16x32_bf16 v[102:105], v[202:205], v[236:239], v[50:53]
	v_mfma_f32_16x16x32_bf16 v[50:53], v[206:209], v[232:235], v[78:81]
	v_mfma_f32_16x16x32_bf16 v[98:101], v[210:213], v[236:239], v[50:53]

; #define LDB(dst, b, h) for (int n = 0; n < 2; ++n) for (int k = 0; k < 2; ++k) \
;     dst[n][k] = *reinterpret_cast<const bf16x8*>((char*)SB(b, h) + b_thr + (n * 2 + k) * 1024)
; #define MMA(ai, bj, At, Btf) do { __builtin_amdgcn_s_setprio(1); \
;     for (int m = 0; m < 4; ++m) for (int n = 0; n < 2; ++n) for (int k = 0; k < 2; ++k) \
;       acc[ai][bj][m][n] = __builtin_amdgcn_mfma_f32_16x16x32_bf16(Btf[n][k], At[m][k], acc[ai][bj][m][n], 0, 0, 0); \
;     __builtin_amdgcn_s_setprio(0); } while (0)
; #define WAIT_V(n) asm volatile("s_waitcnt vmcnt(" #n ")" ::: "memory")
; #define WAIT_L(n) asm volatile("s_waitcnt lgkmcnt(" #n ")" ::: "memory")
; #define BAR __builtin_amdgcn_s_barrier()
; template <bool OVL, bool PANEL = false, class Epi>
; __device__ __forceinline__ void gemm_phase(const bf16_t* __restrict__ A, long lda, const bf16_t* __restrict__ Bt, long ldb, int nM, int nN, int K,
;                                            const Epi& epi, bf16_t* shm, int w0) {
;     ...
;       LDB(B1, 1, 1); WAIT_V(0); BAR; WAIT_L(0); MMA(0, 1, At, B1); BAR;
	v_add_u32_e32 v0, s75, v143
	s_barrier
	ds_read_b128 v[240:243], v0
	ds_read_b128 v[244:247], v0 offset:1024
	ds_read_b128 v[138:141], v0 offset:2048
	ds_read_b128 v[130:133], v0 offset:3072
	s_waitcnt vmcnt(0)
	s_barrier
	s_waitcnt lgkmcnt(0)

; #define LDB(dst, b, h) for (int n = 0; n < 2; ++n) for (int k = 0; k < 2; ++k) \
;     dst[n][k] = *reinterpret_cast<const bf16x8*>((char*)SB(b, h) + b_thr + (n * 2 + k) * 1024)
; #define MMA(ai, bj, At, Btf) do { __builtin_amdgcn_s_setprio(1); \
;     for (int m = 0; m < 4; ++m) for (int n = 0; n < 2; ++n) for (int k = 0; k < 2; ++k) \
;       acc[ai][bj][m][n] = __builtin_amdgcn_mfma_f32_16x16x32_bf16(Btf[n][k], At[m][k], acc[ai][bj][m][n], 0, 0, 0); \
;     __builtin_amdgcn_s_setprio(0); } while (0)
; #define WAIT_V(n) asm volatile("s_waitcnt vmcnt(" #n ")" ::: "memory")
; #define WAIT_L(n) asm volatile("s_waitcnt lgkmcnt(" #n ")" ::: "memory")
; #define BAR __builtin_amdgcn_s_barrier()
; template <bool OVL, bool PANEL = false, class Epi>
; __device__ __forceinline__ void gemm_phase(const bf16_t* __restrict__ A, long lda, const bf16_t* __restrict__ Bt, long ldb, int nM, int nN, int K,
;                                            const Epi& epi, bf16_t* shm, int w0) {
;     ...
;       LDB(B1, 1, 1); WAIT_V(0); BAR; WAIT_L(0); MMA(0, 1, At, B1); BAR;
	s_waitcnt lgkmcnt(0)
	v_mfma_f32_16x16x32_bf16 v[18:21], v[138:141], v[46:49], v[18:21]
	v_mfma_f32_16x16x32_bf16 v[90:93], v[130:133], v[82:85], v[18:21]
	v_mfma_f32_16x16x32_bf16 v[18:21], v[240:243], v[214:217], v[22:25]
	v_mfma_f32_16x16x32_bf16 v[50:53], v[240:243], v[46:49], v[146:149]
	v_mfma_f32_16x16x32_bf16 v[86:89], v[244:247], v[218:221], v[18:21]
	v_mfma_f32_16x16x32_bf16 v[18:21], v[138:141], v[214:217], v[26:29]
	v_mfma_f32_16x16x32_bf16 v[94:97], v[244:247], v[82:85], v[50:53]
	v_mfma_f32_16x16x32_bf16 v[82:85], v[130:133], v[218:221], v[18:21]
	v_mfma_f32_16x16x32_bf16 v[18:21], v[240:243], v[222:225], v[30:33]
	v_mfma_f32_16x16x32_bf16 v[78:81], v[244:247], v[228:231], v[18:21]
	v_mfma_f32_16x16x32_bf16 v[18:21], v[138:141], v[222:225], v[34:37]
	v_mfma_f32_16x16x32_bf16 v[74:77], v[130:133], v[228:231], v[18:21]
	v_mfma_f32_16x16x32_bf16 v[18:21], v[240:243], v[232:235], v[38:41]
	v_mfma_f32_16x16x32_bf16 v[70:73], v[244:247], v[236:239], v[18:21]
	v_mfma_f32_16x16x32_bf16 v[18:21], v[138:141], v[232:235], v[42:45]
	v_mfma_f32_16x16x32_bf16 v[66:69], v[130:133], v[236:239], v[18:21]

; #define LDA(dst, b, h) for (int m = 0; m < 4; ++m) for (int k = 0; k < 2; ++k) \
;     dst[m][k] = *reinterpret_cast<const bf16x8*>((char*)SA(b, h) + a_thr + (m * 2 + k) * 1024)
; #define MMA(ai, bj, At, Btf) do { __builtin_amdgcn_s_setprio(1); \
;     for (int m = 0; m < 4; ++m) for (int n = 0; n < 2; ++n) for (int k = 0; k < 2; ++k) \
;       acc[ai][bj][m][n] = __builtin_amdgcn_mfma_f32_16x16x32_bf16(Btf[n][k], At[m][k], acc[ai][bj][m][n], 0, 0, 0); \
;     __builtin_amdgcn_s_setprio(0); } while (0)
; #define WAIT_L(n) asm volatile("s_waitcnt lgkmcnt(" #n ")" ::: "memory")
; #define BAR __builtin_amdgcn_s_barrier()
; template <bool OVL, bool PANEL = false, class Epi>
; __device__ __forceinline__ void gemm_phase(const bf16_t* __restrict__ A, long lda, const bf16_t* __restrict__ Bt, long ldb, int nM, int nN, int K,
;                                            const Epi& epi, bf16_t* shm, int w0) {
;     ...
;       LDA(At, 1, 1); BAR; WAIT_L(0); MMA(1, 0, At, B0); MMA(1, 1, At, B1); BAR; }
	s_barrier
	s_nop 4
	ds_read_b128 v[18:21], v144 offset:49152
	ds_read_b128 v[22:25], v144 offset:50176
	ds_read_b128 v[146:149], v144 offset:51200
	ds_read_b128 v[214:217], v144 offset:52224
	ds_read_b128 v[218:221], v144 offset:53248
	ds_read_b128 v[222:225], v144 offset:54272
	ds_read_b128 v[228:231], v144 offset:55296
	ds_read_b128 v[232:235], v144 offset:56320
	s_barrier
	s_waitcnt lgkmcnt(0)

; #define LDA(dst, b, h) for (int m = 0; m < 4; ++m) for (int k = 0; k < 2; ++k) \
;     dst[m][k] = *reinterpret_cast<const bf16x8*>((char*)SA(b, h) + a_thr + (m * 2 + k) * 1024)
; #define MMA(ai, bj, At, Btf) do { __builtin_amdgcn_s_setprio(1); \
;     for (int m = 0; m < 4; ++m) for (int n = 0; n < 2; ++n) for (int k = 0; k < 2; ++k) \
;       acc[ai][bj][m][n] = __builtin_amdgcn_mfma_f32_16x16x32_bf16(Btf[n][k], At[m][k], acc[ai][bj][m][n], 0, 0, 0); \
;     __builtin_amdgcn_s_setprio(0); } while (0)
; #define WAIT_L(n) asm volatile("s_waitcnt lgkmcnt(" #n ")" ::: "memory")
; #define BAR __builtin_amdgcn_s_barrier()
; template <bool OVL, bool PANEL = false, class Epi>
; __device__ __forceinline__ void gemm_phase(const bf16_t* __restrict__ A, long lda, const bf16_t* __restrict__ Bt, long ldb, int nM, int nN, int K,
;                                            const Epi& epi, bf16_t* shm, int w0) {
;     ...
;       LDA(At, 1, 1); BAR; WAIT_L(0); MMA(1, 0, At, B0); MMA(1, 1, At, B1); BAR; }
	s_waitcnt lgkmcnt(0)
	v_mfma_f32_16x16x32_bf16 v[26:29], v[198:201], v[18:21], v[150:153]
	v_mfma_f32_16x16x32_bf16 v[62:65], v[202:205], v[22:25], v[26:29]
	v_mfma_f32_16x16x32_bf16 v[26:29], v[206:209], v[18:21], v[154:157]
	v_mfma_f32_16x16x32_bf16 v[58:61], v[210:213], v[22:25], v[26:29]
	v_mfma_f32_16x16x32_bf16 v[26:29], v[198:201], v[146:149], v[158:161]
	v_mfma_f32_16x16x32_bf16 v[54:57], v[202:205], v[214:217], v[26:29]
	v_mfma_f32_16x16x32_bf16 v[26:29], v[206:209], v[146:149], v[162:165]
	v_mfma_f32_16x16x32_bf16 v[50:53], v[210:213], v[214:217], v[26:29]
	v_mfma_f32_16x16x32_bf16 v[26:29], v[198:201], v[218:221], v[166:169]
	v_mfma_f32_16x16x32_bf16 v[2:5], v[198:201], v[228:231], v[2:5]
	v_mfma_f32_16x16x32_bf16 v[46:49], v[202:205], v[222:225], v[26:29]
	v_mfma_f32_16x16x32_bf16 v[26:29], v[206:209], v[218:221], v[170:173]
	v_mfma_f32_16x16x32_bf16 v[38:41], v[202:205], v[232:235], v[2:5]
	v_mfma_f32_16x16x32_bf16 v[2:5], v[206:209], v[228:231], v[6:9]
	v_mfma_f32_16x16x32_bf16 v[42:45], v[210:213], v[222:225], v[26:29]
	v_mfma_f32_16x16x32_bf16 v[34:37], v[210:213], v[232:235], v[2:5]


; #define LDA(dst, b, h) for (int m = 0; m < 4; ++m) for (int k = 0; k < 2; ++k) \
;     dst[m][k] = *reinterpret_cast<const bf16x8*>((char*)SA(b, h) + a_thr + (m * 2 + k) * 1024)
; #define MMA(ai, bj, At, Btf) do { __builtin_amdgcn_s_setprio(1); \
;     for (int m = 0; m < 4; ++m) for (int n = 0; n < 2; ++n) for (int k = 0; k < 2; ++k) \
;       acc[ai][bj][m][n] = __builtin_amdgcn_mfma_f32_16x16x32_bf16(Btf[n][k], At[m][k], acc[ai][bj][m][n], 0, 0, 0); \
;     __builtin_amdgcn_s_setprio(0); } while (0)
; #define WAIT_L(n) asm volatile("s_waitcnt lgkmcnt(" #n ")" ::: "memory")
; #define BAR __builtin_amdgcn_s_barrier()
; template <bool OVL, bool PANEL = false, class Epi>
; __device__ __forceinline__ void gemm_phase(const bf16_t* __restrict__ A, long lda, const bf16_t* __restrict__ Bt, long ldb, int nM, int nN, int K,
;                                            const Epi& epi, bf16_t* shm, int w0) {
;     ...
;       LDA(At, 1, 1); BAR; WAIT_L(0); MMA(1, 0, At, B0); MMA(1, 1, At, B1); BAR; }
	v_mfma_f32_16x16x32_bf16 v[2:5], v[240:243], v[18:21], v[10:13]
	v_mfma_f32_16x16x32_bf16 v[30:33], v[244:247], v[22:25], v[2:5]
	v_mfma_f32_16x16x32_bf16 v[2:5], v[138:141], v[18:21], v[14:17]
	v_mfma_f32_16x16x32_bf16 v[26:29], v[130:133], v[22:25], v[2:5]
	v_mfma_f32_16x16x32_bf16 v[2:5], v[240:243], v[146:149], v[174:177]
	v_mfma_f32_16x16x32_bf16 v[22:25], v[244:247], v[214:217], v[2:5]
	v_mfma_f32_16x16x32_bf16 v[2:5], v[138:141], v[146:149], v[178:181]
	v_mfma_f32_16x16x32_bf16 v[18:21], v[130:133], v[214:217], v[2:5]
	v_mfma_f32_16x16x32_bf16 v[2:5], v[240:243], v[218:221], v[182:185]
	v_mfma_f32_16x16x32_bf16 v[14:17], v[244:247], v[222:225], v[2:5]
	v_mfma_f32_16x16x32_bf16 v[2:5], v[138:141], v[218:221], v[186:189]
	v_mfma_f32_16x16x32_bf16 v[10:13], v[130:133], v[222:225], v[2:5]
	v_mfma_f32_16x16x32_bf16 v[2:5], v[240:243], v[228:231], v[190:193]
	v_mfma_f32_16x16x32_bf16 v[6:9], v[244:247], v[232:235], v[2:5]
	v_mfma_f32_16x16x32_bf16 v[2:5], v[138:141], v[228:231], v[194:197]
	v_mfma_f32_16x16x32_bf16 v[2:5], v[130:133], v[232:235], v[2:5]

; #define LDA(dst, b, h) for (int m = 0; m < 4; ++m) for (int k = 0; k < 2; ++k) \
;     dst[m][k] = *reinterpret_cast<const bf16x8*>((char*)SA(b, h) + a_thr + (m * 2 + k) * 1024)
; #define MMA(ai, bj, At, Btf) do { __builtin_amdgcn_s_setprio(1); \
;     for (int m = 0; m < 4; ++m) for (int n = 0; n < 2; ++n) for (int k = 0; k < 2; ++k) \
;       acc[ai][bj][m][n] = __builtin_amdgcn_mfma_f32_16x16x32_bf16(Btf[n][k], At[m][k], acc[ai][bj][m][n], 0, 0, 0); \
;     __builtin_amdgcn_s_setprio(0); } while (0)
; #define WAIT_L(n) asm volatile("s_waitcnt lgkmcnt(" #n ")" ::: "memory")
; #define BAR __builtin_amdgcn_s_barrier()
; template <bool OVL, bool PANEL = false, class Epi>
; __device__ __forceinline__ void gemm_phase(const bf16_t* __restrict__ A, long lda, const bf16_t* __restrict__ Bt, long ldb, int nM, int nN, int K,
;                                            const Epi& epi, bf16_t* shm, int w0) {
;     ...
;       LDA(At, 1, 1); BAR; WAIT_L(0); MMA(1, 0, At, B0); MMA(1, 1, At, B1); BAR; }
;     if (wr == 0) BAR;
	s_barrier
	s_and_saveexec_b64 s[8:9], s[6:7]
	s_cbranch_execz .LBB0_698
	s_barrier

; #define LDA(dst, b, h) for (int m = 0; m < 4; ++m) for (int k = 0; k < 2; ++k) \
;     dst[m][k] = *reinterpret_cast<const bf16x8*>((char*)SA(b, h) + a_thr + (m * 2 + k) * 1024)
; #define LDB(dst, b, h) for (int n = 0; n < 2; ++n) for (int k = 0; k < 2; ++k) \
;     dst[n][k] = *reinterpret_cast<const bf16x8*>((char*)SB(b, h) + b_thr + (n * 2 + k) * 1024)
; #define MMA(ai, bj, At, Btf) do { __builtin_amdgcn_s_setprio(1); \
;     for (int m = 0; m < 4; ++m) for (int n = 0; n < 2; ++n) for (int k = 0; k < 2; ++k) \
;       acc[ai][bj][m][n] = __builtin_amdgcn_mfma_f32_16x16x32_bf16(Btf[n][k], At[m][k], acc[ai][bj][m][n], 0, 0, 0); \
;     __builtin_amdgcn_s_setprio(0); } while (0)
; template <bool OVL, bool PANEL = false, class Epi>
; __device__ __forceinline__ void gemm_phase(const bf16_t* __restrict__ A, long lda, const bf16_t* __restrict__ Bt, long ldb, int nM, int nN, int K,
;                                            const Epi& epi, bf16_t* shm, int w0) {
;     ...
;     if (wr == 1) BAR;
;     WAIT_V(4); BAR;
;     STAGE(SB(1, 0), Bt, ldb, boff, bcol, 1); STAGE(SA(1, 0), A, lda, aoff, brow, 1); STAGE(SB(1, 1), Bt, ldb, boff, bcol + HALF, 1);
;     WAIT_V(6); BAR;
;     for (int t = 0; t < nt - 2; t += 2) {
;       LDB(B0, 0, 0); SCHED; LDA(At, 0, 0); STAGE(SA(1, 1), A, lda, aoff, brow + HALF, t + 1);
;       WAIT_L(8); BAR; WAIT_L(0); MMA(0, 0, At, B0); BAR; SCHED;
;       LDB(B1, 0, 1); STAGE(SB(0, 0), Bt, ldb, boff, bcol, t + 2);
;       BAR; WAIT_L(0); MMA(0, 1, At, B1); BAR;
;       LDA(At, 0, 1); STAGE(SA(0, 0), A, lda, aoff, brow, t + 2);
;       BAR; WAIT_L(0); MMA(1, 0, At, B0); BAR; SCHED;
;       STAGE(SB(0, 1), Bt, ldb, boff, bcol + HALF, t + 2);
;       WAIT_V(6); BAR; MMA(1, 1, At, B1); BAR;
;       LDB(B0, 1, 0); SCHED; LDA(At, 1, 0); STAGE(SA(0, 1), A, lda, aoff, brow + HALF, t + 2);
;       WAIT_L(8); BAR; WAIT_L(0); MMA(0, 0, At, B0); BAR; SCHED;
;       LDB(B1, 1, 1); STAGE(SB(1, 0), Bt, ldb, boff, bcol, t + 3);
;       BAR; WAIT_L(0); MMA(0, 1, At, B1); BAR;
;       LDA(At, 1, 1); STAGE(SA(1, 0), A, lda, aoff, brow, t + 3);
;       BAR; WAIT_L(0); MMA(1, 0, At, B0); BAR; SCHED;
;       STAGE(SB(1, 1), Bt, ldb, boff, bcol + HALF, t + 3);
;       WAIT_V(6); BAR; MMA(1, 1, At, B1); BAR;
;     }
;     { LDB(B0, 0, 0); LDA(At, 0, 0); STAGE(SA(1, 1), A, lda, aoff, brow + HALF, nt - 1);
;       BAR; WAIT_L(0); MMA(0, 0, At, B0); BAR;
.LBB0_828:
	s_or_b64 exec, exec, s[8:9]
	v_readlane_b32 s16, v252, 20
	s_lshl_b32 s14, s13, 8
	s_mul_i32 s2, s13, 0xf8000
	v_readlane_b32 s24, v252, 28
	s_mul_hi_u32 s9, s14, 0xf80
	v_readlane_b32 s25, v252, 29
	s_add_u32 s8, s24, s2
	v_mov_b32_e32 v0, v140
	s_waitcnt vmcnt(4)
	s_barrier
	s_addc_u32 s9, s25, s9
	v_readlane_b32 s17, v252, 21
	v_lshl_add_u64 v[2:3], s[8:9], 0, v[0:1]
	v_add_u32_e32 v0, s96, v138
	s_mov_b64 s[16:17], 0xec0
	v_readfirstlane_b32 s2, v0
	v_add_u32_e32 v0, 0x2000, v0
	v_readlane_b32 s18, v252, 22
	v_readlane_b32 s19, v252, 23
	v_lshl_add_u64 v[4:5], v[2:3], 0, s[16:17]
	s_mov_b32 m0, s2
	v_readfirstlane_b32 s2, v0
	v_readlane_b32 s40, v252, 3
	global_load_lds_dwordx4 v[4:5], off
	s_mov_b64 s[18:19], 0x3eec0
	s_mov_b32 m0, s2
	s_lshl_b32 s2, s15, 17
	v_readlane_b32 s52, v252, 15
	v_lshl_add_u64 v[2:3], v[2:3], 0, s[18:19]
	v_readlane_b32 s53, v252, 16
	s_add_u32 s8, s52, s2
	v_mov_b32_e32 v0, v139
	global_load_lds_dwordx4 v[2:3], off
	s_addc_u32 s9, s53, 0
	s_mov_b64 s[10:11], 0x80
	v_lshl_add_u64 v[2:3], s[8:9], 0, v[0:1]
	v_add_u32_e32 v0, 0x8000, v143
	v_lshl_add_u64 v[4:5], v[2:3], 0, s[10:11]
	v_readfirstlane_b32 s2, v0
	v_add_u32_e32 v0, 0xa000, v143
	s_mov_b32 m0, s2
	v_readfirstlane_b32 s2, v0
	global_load_lds_dwordx4 v[4:5], off
	s_mov_b64 s[10:11], 0x8080
	s_mov_b32 m0, s2
	s_or_b32 s2, s14, 0x80
	v_lshl_add_u64 v[2:3], v[2:3], 0, s[10:11]
	s_mul_hi_u32 s11, s2, 0xf80
	s_mulk_i32 s2, 0xf80
	s_add_u32 s10, s24, s2
	v_mov_b32_e32 v0, v140
	global_load_lds_dwordx4 v[2:3], off
	s_addc_u32 s11, s25, s11
	v_add_u32_e32 v82, 16, v149
	v_lshl_add_u64 v[2:3], s[10:11], 0, v[0:1]
	v_add_u32_e32 v0, s75, v138
	v_lshl_add_u64 v[4:5], v[2:3], 0, s[16:17]
	v_readfirstlane_b32 s2, v0
	v_add_u32_e32 v0, 0x2000, v0
	s_mov_b32 m0, s2
	v_readfirstlane_b32 s2, v0
	global_load_lds_dwordx4 v[4:5], off
	v_lshl_add_u64 v[2:3], v[2:3], 0, s[18:19]
	s_mov_b32 m0, s2
	v_add_u32_e32 v0, 0x10000, v82
	global_load_lds_dwordx4 v[2:3], off
	s_waitcnt vmcnt(6)
	s_barrier
	ds_read_b128 v[2:5], v0
	ds_read_b128 v[6:9], v0 offset:1024
	s_waitcnt vmcnt(0)
	ds_read_b128 v[10:13], v0 offset:2048
	ds_read_b128 v[14:17], v0 offset:3072
	ds_read_b128 v[18:21], v153
	ds_read_b128 v[22:25], v153 offset:1024
	ds_read_b128 v[26:29], v153 offset:2048
	ds_read_b128 v[30:33], v153 offset:3072
	ds_read_b128 v[34:37], v153 offset:4096
	ds_read_b128 v[38:41], v153 offset:5120
	ds_read_b128 v[42:45], v153 offset:6144
	ds_read_b128 v[46:49], v153 offset:7168
	v_mov_b32_e32 v0, v139
	v_readlane_b32 s20, v252, 24
	v_lshl_add_u64 v[50:51], s[8:9], 0, v[0:1]
	v_add_u32_e32 v0, 0xc000, v143
	s_mov_b64 s[8:9], 0x10080
	v_readfirstlane_b32 s2, v0
	v_add_u32_e32 v0, 0xe000, v143
	v_lshl_add_u64 v[52:53], v[50:51], 0, s[8:9]
	s_mov_b32 m0, s2
	s_mov_b64 s[8:9], 0x18080
	v_readfirstlane_b32 s2, v0
	global_load_lds_dwordx4 v[52:53], off
	v_lshl_add_u64 v[50:51], v[50:51], 0, s[8:9]
	s_mov_b32 m0, s2
	v_readlane_b32 s21, v252, 25
	global_load_lds_dwordx4 v[50:51], off
	s_barrier
	s_waitcnt lgkmcnt(0)
	v_readlane_b32 s22, v252, 26
	v_readlane_b32 s23, v252, 27
	v_readlane_b32 s26, v252, 30
	v_readlane_b32 s27, v252, 31
	v_readlane_b32 s28, v252, 32
	v_readlane_b32 s29, v252, 33
	v_readlane_b32 s30, v252, 34
	v_readlane_b32 s31, v252, 35
	v_readlane_b32 s41, v252, 4
	v_readlane_b32 s42, v252, 5
	v_readlane_b32 s43, v252, 6
	v_readlane_b32 s44, v252, 7
	v_readlane_b32 s45, v252, 8
	v_readlane_b32 s46, v252, 9
	v_readlane_b32 s47, v252, 10
	v_readlane_b32 s48, v252, 11
	v_readlane_b32 s49, v252, 12
	v_readlane_b32 s50, v252, 13
	v_readlane_b32 s51, v252, 14
	v_readlane_b32 s54, v252, 17
	v_readlane_b32 s55, v252, 18

; #define MMA(ai, bj, At, Btf) do { __builtin_amdgcn_s_setprio(1); \
;     for (int m = 0; m < 4; ++m) for (int n = 0; n < 2; ++n) for (int k = 0; k < 2; ++k) \
;       acc[ai][bj][m][n] = __builtin_amdgcn_mfma_f32_16x16x32_bf16(Btf[n][k], At[m][k], acc[ai][bj][m][n], 0, 0, 0); \
;     __builtin_amdgcn_s_setprio(0); } while (0)
; #define WAIT_L(n) asm volatile("s_waitcnt lgkmcnt(" #n ")" ::: "memory")
; #define BAR __builtin_amdgcn_s_barrier()
; template <bool OVL, bool PANEL = false, class Epi>
; __device__ __forceinline__ void gemm_phase(const bf16_t* __restrict__ A, long lda, const bf16_t* __restrict__ Bt, long ldb, int nM, int nN, int K,
;                                            const Epi& epi, bf16_t* shm, int w0) {
;     ...
;       BAR; WAIT_L(0); MMA(0, 0, At, B0); BAR;
	s_waitcnt lgkmcnt(0)
	v_mfma_f32_16x16x32_bf16 v[50:53], v[2:5], v[18:21], 0
	v_mfma_f32_16x16x32_bf16 v[54:57], v[10:13], v[18:21], 0
	v_mfma_f32_16x16x32_bf16 v[58:61], v[2:5], v[26:29], 0
	v_mfma_f32_16x16x32_bf16 v[62:65], v[10:13], v[26:29], 0
	v_mfma_f32_16x16x32_bf16 v[66:69], v[2:5], v[34:37], 0
	v_mfma_f32_16x16x32_bf16 v[70:73], v[10:13], v[34:37], 0
	v_mfma_f32_16x16x32_bf16 v[74:77], v[2:5], v[42:45], 0
	v_mfma_f32_16x16x32_bf16 v[78:81], v[10:13], v[42:45], 0
	v_mfma_f32_16x16x32_bf16 v[50:53], v[6:9], v[22:25], v[50:53]
	v_mfma_f32_16x16x32_bf16 v[54:57], v[14:17], v[22:25], v[54:57]
	v_mfma_f32_16x16x32_bf16 v[58:61], v[6:9], v[30:33], v[58:61]
	v_mfma_f32_16x16x32_bf16 v[62:65], v[14:17], v[30:33], v[62:65]
	v_mfma_f32_16x16x32_bf16 v[66:69], v[6:9], v[38:41], v[66:69]
	v_mfma_f32_16x16x32_bf16 v[70:73], v[14:17], v[38:41], v[70:73]
	v_mfma_f32_16x16x32_bf16 v[74:77], v[6:9], v[46:49], v[74:77]
	v_mfma_f32_16x16x32_bf16 v[78:81], v[14:17], v[46:49], v[78:81]

; #define LDB(dst, b, h) for (int n = 0; n < 2; ++n) for (int k = 0; k < 2; ++k) \
;     dst[n][k] = *reinterpret_cast<const bf16x8*>((char*)SB(b, h) + b_thr + (n * 2 + k) * 1024)
; #define MMA(ai, bj, At, Btf) do { __builtin_amdgcn_s_setprio(1); \
;     for (int m = 0; m < 4; ++m) for (int n = 0; n < 2; ++n) for (int k = 0; k < 2; ++k) \
;       acc[ai][bj][m][n] = __builtin_amdgcn_mfma_f32_16x16x32_bf16(Btf[n][k], At[m][k], acc[ai][bj][m][n], 0, 0, 0); \
;     __builtin_amdgcn_s_setprio(0); } while (0)
; #define WAIT_L(n) asm volatile("s_waitcnt lgkmcnt(" #n ")" ::: "memory")
; #define BAR __builtin_amdgcn_s_barrier()
; template <bool OVL, bool PANEL = false, class Epi>
; __device__ __forceinline__ void gemm_phase(const bf16_t* __restrict__ A, long lda, const bf16_t* __restrict__ Bt, long ldb, int nM, int nN, int K,
;                                            const Epi& epi, bf16_t* shm, int w0) {
;     ...
;       LDB(B1, 0, 1); BAR; WAIT_L(0); MMA(0, 1, At, B1); BAR;
	v_add_u32_e32 v0, 0x14000, v82
	s_barrier
	ds_read_b128 v[82:85], v0
	ds_read_b128 v[86:89], v0 offset:1024
	ds_read_b128 v[90:93], v0 offset:2048
	ds_read_b128 v[94:97], v0 offset:3072
	s_barrier
	s_waitcnt lgkmcnt(0)

; #define LDB(dst, b, h) for (int n = 0; n < 2; ++n) for (int k = 0; k < 2; ++k) \
;     dst[n][k] = *reinterpret_cast<const bf16x8*>((char*)SB(b, h) + b_thr + (n * 2 + k) * 1024)
; #define MMA(ai, bj, At, Btf) do { __builtin_amdgcn_s_setprio(1); \
;     for (int m = 0; m < 4; ++m) for (int n = 0; n < 2; ++n) for (int k = 0; k < 2; ++k) \
;       acc[ai][bj][m][n] = __builtin_amdgcn_mfma_f32_16x16x32_bf16(Btf[n][k], At[m][k], acc[ai][bj][m][n], 0, 0, 0); \
;     __builtin_amdgcn_s_setprio(0); } while (0)
; #define WAIT_L(n) asm volatile("s_waitcnt lgkmcnt(" #n ")" ::: "memory")
; #define BAR __builtin_amdgcn_s_barrier()
; template <bool OVL, bool PANEL = false, class Epi>
; __device__ __forceinline__ void gemm_phase(const bf16_t* __restrict__ A, long lda, const bf16_t* __restrict__ Bt, long ldb, int nM, int nN, int K,
;                                            const Epi& epi, bf16_t* shm, int w0) {
;     ...
;       LDB(B1, 0, 1); BAR; WAIT_L(0); MMA(0, 1, At, B1); BAR;
	s_waitcnt lgkmcnt(0)
	v_mfma_f32_16x16x32_bf16 v[98:101], v[82:85], v[18:21], 0
	v_mfma_f32_16x16x32_bf16 v[18:21], v[90:93], v[18:21], 0
	v_mfma_f32_16x16x32_bf16 v[98:101], v[86:89], v[22:25], v[98:101]
	v_mfma_f32_16x16x32_bf16 v[18:21], v[94:97], v[22:25], v[18:21]
	v_mfma_f32_16x16x32_bf16 v[22:25], v[82:85], v[26:29], 0
	v_mfma_f32_16x16x32_bf16 v[26:29], v[90:93], v[26:29], 0
	v_mfma_f32_16x16x32_bf16 v[22:25], v[86:89], v[30:33], v[22:25]
	v_mfma_f32_16x16x32_bf16 v[26:29], v[94:97], v[30:33], v[26:29]
	v_mfma_f32_16x16x32_bf16 v[30:33], v[82:85], v[34:37], 0
	v_mfma_f32_16x16x32_bf16 v[102:105], v[86:89], v[38:41], v[30:33]
	v_mfma_f32_16x16x32_bf16 v[30:33], v[90:93], v[34:37], 0
	v_mfma_f32_16x16x32_bf16 v[34:37], v[94:97], v[38:41], v[30:33]
	v_mfma_f32_16x16x32_bf16 v[30:33], v[82:85], v[42:45], 0
	v_mfma_f32_16x16x32_bf16 v[38:41], v[86:89], v[46:49], v[30:33]
	v_mfma_f32_16x16x32_bf16 v[30:33], v[90:93], v[42:45], 0
	v_mfma_f32_16x16x32_bf16 v[42:45], v[94:97], v[46:49], v[30:33]

; #define LDA(dst, b, h) for (int m = 0; m < 4; ++m) for (int k = 0; k < 2; ++k) \
;     dst[m][k] = *reinterpret_cast<const bf16x8*>((char*)SA(b, h) + a_thr + (m * 2 + k) * 1024)
; #define MMA(ai, bj, At, Btf) do { __builtin_amdgcn_s_setprio(1); \
;     for (int m = 0; m < 4; ++m) for (int n = 0; n < 2; ++n) for (int k = 0; k < 2; ++k) \
;       acc[ai][bj][m][n] = __builtin_amdgcn_mfma_f32_16x16x32_bf16(Btf[n][k], At[m][k], acc[ai][bj][m][n], 0, 0, 0); \
;     __builtin_amdgcn_s_setprio(0); } while (0)
; #define WAIT_V(n) asm volatile("s_waitcnt vmcnt(" #n ")" ::: "memory")
; #define WAIT_L(n) asm volatile("s_waitcnt lgkmcnt(" #n ")" ::: "memory")
; #define BAR __builtin_amdgcn_s_barrier()
; template <bool OVL, bool PANEL = false, class Epi>
; __device__ __forceinline__ void gemm_phase(const bf16_t* __restrict__ A, long lda, const bf16_t* __restrict__ Bt, long ldb, int nM, int nN, int K,
;                                            const Epi& epi, bf16_t* shm, int w0) {
;     ...
;       LDA(At, 0, 1); WAIT_V(4); BAR; WAIT_L(0); MMA(1, 0, At, B0); MMA(1, 1, At, B1); BAR; }
	s_barrier
	s_nop 4
	ds_read_b128 v[30:33], v153 offset:16384
	ds_read_b128 v[46:49], v153 offset:17408
	ds_read_b128 v[106:109], v153 offset:18432
	ds_read_b128 v[110:113], v153 offset:19456
	ds_read_b128 v[114:117], v153 offset:20480
	ds_read_b128 v[118:121], v153 offset:21504
	ds_read_b128 v[122:125], v153 offset:22528
	ds_read_b128 v[126:129], v153 offset:23552
	s_waitcnt vmcnt(4)
	s_barrier
	s_waitcnt lgkmcnt(0)

; #define LDA(dst, b, h) for (int m = 0; m < 4; ++m) for (int k = 0; k < 2; ++k) \
;     dst[m][k] = *reinterpret_cast<const bf16x8*>((char*)SA(b, h) + a_thr + (m * 2 + k) * 1024)
; #define MMA(ai, bj, At, Btf) do { __builtin_amdgcn_s_setprio(1); \
;     for (int m = 0; m < 4; ++m) for (int n = 0; n < 2; ++n) for (int k = 0; k < 2; ++k) \
;       acc[ai][bj][m][n] = __builtin_amdgcn_mfma_f32_16x16x32_bf16(Btf[n][k], At[m][k], acc[ai][bj][m][n], 0, 0, 0); \
;     __builtin_amdgcn_s_setprio(0); } while (0)
; #define WAIT_V(n) asm volatile("s_waitcnt vmcnt(" #n ")" ::: "memory")
; #define WAIT_L(n) asm volatile("s_waitcnt lgkmcnt(" #n ")" ::: "memory")
; #define BAR __builtin_amdgcn_s_barrier()
; template <bool OVL, bool PANEL = false, class Epi>
; __device__ __forceinline__ void gemm_phase(const bf16_t* __restrict__ A, long lda, const bf16_t* __restrict__ Bt, long ldb, int nM, int nN, int K,
;                                            const Epi& epi, bf16_t* shm, int w0) {
;     ...
;       LDA(At, 0, 1); WAIT_V(4); BAR; WAIT_L(0); MMA(1, 0, At, B0); MMA(1, 1, At, B1); BAR; }
	s_waitcnt lgkmcnt(0)
	v_mfma_f32_16x16x32_bf16 v[130:133], v[2:5], v[30:33], 0
	v_mfma_f32_16x16x32_bf16 v[154:157], v[2:5], v[106:109], 0
	v_mfma_f32_16x16x32_bf16 v[162:165], v[2:5], v[114:117], 0
	v_mfma_f32_16x16x32_bf16 v[2:5], v[2:5], v[122:125], 0
	v_mfma_f32_16x16x32_bf16 v[130:133], v[6:9], v[46:49], v[130:133]
	v_mfma_f32_16x16x32_bf16 v[154:157], v[6:9], v[110:113], v[154:157]
	v_mfma_f32_16x16x32_bf16 v[162:165], v[6:9], v[118:121], v[162:165]
	v_mfma_f32_16x16x32_bf16 v[2:5], v[6:9], v[126:129], v[2:5]
	v_mfma_f32_16x16x32_bf16 v[6:9], v[10:13], v[122:125], 0
	v_mfma_f32_16x16x32_bf16 v[134:137], v[10:13], v[30:33], 0
	v_mfma_f32_16x16x32_bf16 v[158:161], v[10:13], v[106:109], 0
	v_mfma_f32_16x16x32_bf16 v[166:169], v[10:13], v[114:117], 0
	v_mfma_f32_16x16x32_bf16 v[6:9], v[14:17], v[126:129], v[6:9]
	v_mfma_f32_16x16x32_bf16 v[134:137], v[14:17], v[46:49], v[134:137]
	v_mfma_f32_16x16x32_bf16 v[158:161], v[14:17], v[110:113], v[158:161]
	v_mfma_f32_16x16x32_bf16 v[166:169], v[14:17], v[118:121], v[166:169]


; #define LDA(dst, b, h) for (int m = 0; m < 4; ++m) for (int k = 0; k < 2; ++k) \
;     dst[m][k] = *reinterpret_cast<const bf16x8*>((char*)SA(b, h) + a_thr + (m * 2 + k) * 1024)
; #define MMA(ai, bj, At, Btf) do { __builtin_amdgcn_s_setprio(1); \
;     for (int m = 0; m < 4; ++m) for (int n = 0; n < 2; ++n) for (int k = 0; k < 2; ++k) \
;       acc[ai][bj][m][n] = __builtin_amdgcn_mfma_f32_16x16x32_bf16(Btf[n][k], At[m][k], acc[ai][bj][m][n], 0, 0, 0); \
;     __builtin_amdgcn_s_setprio(0); } while (0)
; #define WAIT_V(n) asm volatile("s_waitcnt vmcnt(" #n ")" ::: "memory")
; #define WAIT_L(n) asm volatile("s_waitcnt lgkmcnt(" #n ")" ::: "memory")
; #define BAR __builtin_amdgcn_s_barrier()
; template <bool OVL, bool PANEL = false, class Epi>
; __device__ __forceinline__ void gemm_phase(const bf16_t* __restrict__ A, long lda, const bf16_t* __restrict__ Bt, long ldb, int nM, int nN, int K,
;                                            const Epi& epi, bf16_t* shm, int w0) {
;     ...
;       LDA(At, 0, 1); WAIT_V(4); BAR; WAIT_L(0); MMA(1, 0, At, B0); MMA(1, 1, At, B1); BAR; }
	v_mfma_f32_16x16x32_bf16 v[14:17], v[90:93], v[30:33], 0
	v_mfma_f32_16x16x32_bf16 v[170:173], v[94:97], v[46:49], v[14:17]
	v_mfma_f32_16x16x32_bf16 v[14:17], v[82:85], v[106:109], 0
	v_mfma_f32_16x16x32_bf16 v[174:177], v[86:89], v[110:113], v[14:17]
	v_mfma_f32_16x16x32_bf16 v[14:17], v[90:93], v[106:109], 0
	v_mfma_f32_16x16x32_bf16 v[194:197], v[94:97], v[110:113], v[14:17]
	v_mfma_f32_16x16x32_bf16 v[14:17], v[82:85], v[114:117], 0
	v_mfma_f32_16x16x32_bf16 v[198:201], v[86:89], v[118:121], v[14:17]
	v_mfma_f32_16x16x32_bf16 v[14:17], v[90:93], v[114:117], 0
	v_mfma_f32_16x16x32_bf16 v[10:13], v[82:85], v[30:33], 0
	v_mfma_f32_16x16x32_bf16 v[202:205], v[94:97], v[118:121], v[14:17]
	v_mfma_f32_16x16x32_bf16 v[14:17], v[82:85], v[122:125], 0
	v_mfma_f32_16x16x32_bf16 v[10:13], v[86:89], v[46:49], v[10:13]
	v_mfma_f32_16x16x32_bf16 v[206:209], v[86:89], v[126:129], v[14:17]
	v_mfma_f32_16x16x32_bf16 v[14:17], v[90:93], v[122:125], 0
	v_mfma_f32_16x16x32_bf16 v[210:213], v[94:97], v[126:129], v[14:17]

; #define LDA(dst, b, h) for (int m = 0; m < 4; ++m) for (int k = 0; k < 2; ++k) \
;     dst[m][k] = *reinterpret_cast<const bf16x8*>((char*)SA(b, h) + a_thr + (m * 2 + k) * 1024)
; #define LDB(dst, b, h) for (int n = 0; n < 2; ++n) for (int k = 0; k < 2; ++k) \
;     dst[n][k] = *reinterpret_cast<const bf16x8*>((char*)SB(b, h) + b_thr + (n * 2 + k) * 1024)
; #define MMA(ai, bj, At, Btf) do { __builtin_amdgcn_s_setprio(1); \
;     for (int m = 0; m < 4; ++m) for (int n = 0; n < 2; ++n) for (int k = 0; k < 2; ++k) \
;       acc[ai][bj][m][n] = __builtin_amdgcn_mfma_f32_16x16x32_bf16(Btf[n][k], At[m][k], acc[ai][bj][m][n], 0, 0, 0); \
;     __builtin_amdgcn_s_setprio(0); } while (0)
; #define WAIT_V(n) asm volatile("s_waitcnt vmcnt(" #n ")" ::: "memory")
; #define WAIT_L(n) asm volatile("s_waitcnt lgkmcnt(" #n ")" ::: "memory")
; #define BAR __builtin_amdgcn_s_barrier()
; template <bool OVL, bool PANEL = false, class Epi>
; __device__ __forceinline__ void gemm_phase(const bf16_t* __restrict__ A, long lda, const bf16_t* __restrict__ Bt, long ldb, int nM, int nN, int K,
;                                            const Epi& epi, bf16_t* shm, int w0) {
;     ...
;     { LDB(B0, 1, 0); LDA(At, 1, 0); WAIT_V(2); BAR; WAIT_L(0); MMA(0, 0, At, B0); BAR;
	v_add_u32_e32 v0, s96, v149
	s_barrier
	ds_read_b128 v[214:217], v0
	ds_read_b128 v[218:221], v0 offset:1024
	ds_read_b128 v[234:237], v0 offset:2048
	ds_read_b128 v[238:241], v0 offset:3072
	ds_read_b128 v[14:17], v153 offset:32768
	ds_read_b128 v[30:33], v153 offset:33792
	ds_read_b128 v[46:49], v153 offset:34816
	ds_read_b128 v[82:85], v153 offset:35840
	ds_read_b128 v[106:109], v153 offset:36864
	ds_read_b128 v[114:117], v153 offset:37888
	ds_read_b128 v[242:245], v153 offset:38912
	ds_read_b128 v[246:249], v153 offset:39936
	s_waitcnt vmcnt(2)
	s_barrier
	s_waitcnt lgkmcnt(0)

; #define LDA(dst, b, h) for (int m = 0; m < 4; ++m) for (int k = 0; k < 2; ++k) \
;     dst[m][k] = *reinterpret_cast<const bf16x8*>((char*)SA(b, h) + a_thr + (m * 2 + k) * 1024)
; #define LDB(dst, b, h) for (int n = 0; n < 2; ++n) for (int k = 0; k < 2; ++k) \
;     dst[n][k] = *reinterpret_cast<const bf16x8*>((char*)SB(b, h) + b_thr + (n * 2 + k) * 1024)
; #define MMA(ai, bj, At, Btf) do { __builtin_amdgcn_s_setprio(1); \
;     for (int m = 0; m < 4; ++m) for (int n = 0; n < 2; ++n) for (int k = 0; k < 2; ++k) \
;       acc[ai][bj][m][n] = __builtin_amdgcn_mfma_f32_16x16x32_bf16(Btf[n][k], At[m][k], acc[ai][bj][m][n], 0, 0, 0); \
;     __builtin_amdgcn_s_setprio(0); } while (0)
; #define WAIT_V(n) asm volatile("s_waitcnt vmcnt(" #n ")" ::: "memory")
; #define WAIT_L(n) asm volatile("s_waitcnt lgkmcnt(" #n ")" ::: "memory")
; #define BAR __builtin_amdgcn_s_barrier()
; template <bool OVL, bool PANEL = false, class Epi>
; __device__ __forceinline__ void gemm_phase(const bf16_t* __restrict__ A, long lda, const bf16_t* __restrict__ Bt, long ldb, int nM, int nN, int K,
;                                            const Epi& epi, bf16_t* shm, int w0) {
;     ...
;     { LDB(B0, 1, 0); LDA(At, 1, 0); WAIT_V(2); BAR; WAIT_L(0); MMA(0, 0, At, B0); BAR;
	s_waitcnt lgkmcnt(0)
	v_mfma_f32_16x16x32_bf16 v[50:53], v[214:217], v[14:17], v[50:53]
	v_mfma_f32_16x16x32_bf16 v[126:129], v[218:221], v[30:33], v[50:53]
	v_mfma_f32_16x16x32_bf16 v[50:53], v[234:237], v[14:17], v[54:57]
	v_mfma_f32_16x16x32_bf16 v[94:97], v[238:241], v[30:33], v[50:53]
	v_mfma_f32_16x16x32_bf16 v[50:53], v[214:217], v[46:49], v[58:61]
	v_mfma_f32_16x16x32_bf16 v[122:125], v[218:221], v[82:85], v[50:53]
	v_mfma_f32_16x16x32_bf16 v[50:53], v[234:237], v[46:49], v[62:65]
	v_mfma_f32_16x16x32_bf16 v[90:93], v[238:241], v[82:85], v[50:53]
	v_mfma_f32_16x16x32_bf16 v[50:53], v[214:217], v[106:109], v[66:69]
	v_mfma_f32_16x16x32_bf16 v[118:121], v[218:221], v[114:117], v[50:53]
	v_mfma_f32_16x16x32_bf16 v[50:53], v[234:237], v[106:109], v[70:73]
	v_mfma_f32_16x16x32_bf16 v[86:89], v[238:241], v[114:117], v[50:53]
	v_mfma_f32_16x16x32_bf16 v[50:53], v[214:217], v[242:245], v[74:77]
	v_mfma_f32_16x16x32_bf16 v[110:113], v[218:221], v[246:249], v[50:53]
	v_mfma_f32_16x16x32_bf16 v[50:53], v[234:237], v[242:245], v[78:81]
	v_mfma_f32_16x16x32_bf16 v[78:81], v[238:241], v[246:249], v[50:53]

; #define LDB(dst, b, h) for (int n = 0; n < 2; ++n) for (int k = 0; k < 2; ++k) \
;     dst[n][k] = *reinterpret_cast<const bf16x8*>((char*)SB(b, h) + b_thr + (n * 2 + k) * 1024)
; #define MMA(ai, bj, At, Btf) do { __builtin_amdgcn_s_setprio(1); \
;     for (int m = 0; m < 4; ++m) for (int n = 0; n < 2; ++n) for (int k = 0; k < 2; ++k) \
;       acc[ai][bj][m][n] = __builtin_amdgcn_mfma_f32_16x16x32_bf16(Btf[n][k], At[m][k], acc[ai][bj][m][n], 0, 0, 0); \
;     __builtin_amdgcn_s_setprio(0); } while (0)
; #define WAIT_V(n) asm volatile("s_waitcnt vmcnt(" #n ")" ::: "memory")
; #define WAIT_L(n) asm volatile("s_waitcnt lgkmcnt(" #n ")" ::: "memory")
; #define BAR __builtin_amdgcn_s_barrier()
; template <bool OVL, bool PANEL = false, class Epi>
; __device__ __forceinline__ void gemm_phase(const bf16_t* __restrict__ A, long lda, const bf16_t* __restrict__ Bt, long ldb, int nM, int nN, int K,
;                                            const Epi& epi, bf16_t* shm, int w0) {
;     ...
;       LDB(B1, 1, 1); WAIT_V(0); BAR; WAIT_L(0); MMA(0, 1, At, B1); BAR;
	v_add_u32_e32 v0, s75, v149
	s_barrier
	ds_read_b128 v[222:225], v0
	ds_read_b128 v[190:193], v0 offset:1024
	ds_read_b128 v[178:181], v0 offset:2048
	ds_read_b128 v[182:185], v0 offset:3072
	s_waitcnt vmcnt(0)
	s_barrier
	s_waitcnt lgkmcnt(0)

; #define LDB(dst, b, h) for (int n = 0; n < 2; ++n) for (int k = 0; k < 2; ++k) \
;     dst[n][k] = *reinterpret_cast<const bf16x8*>((char*)SB(b, h) + b_thr + (n * 2 + k) * 1024)
; #define MMA(ai, bj, At, Btf) do { __builtin_amdgcn_s_setprio(1); \
;     for (int m = 0; m < 4; ++m) for (int n = 0; n < 2; ++n) for (int k = 0; k < 2; ++k) \
;       acc[ai][bj][m][n] = __builtin_amdgcn_mfma_f32_16x16x32_bf16(Btf[n][k], At[m][k], acc[ai][bj][m][n], 0, 0, 0); \
;     __builtin_amdgcn_s_setprio(0); } while (0)
; #define WAIT_V(n) asm volatile("s_waitcnt vmcnt(" #n ")" ::: "memory")
; #define WAIT_L(n) asm volatile("s_waitcnt lgkmcnt(" #n ")" ::: "memory")
; #define BAR __builtin_amdgcn_s_barrier()
; template <bool OVL, bool PANEL = false, class Epi>
; __device__ __forceinline__ void gemm_phase(const bf16_t* __restrict__ A, long lda, const bf16_t* __restrict__ Bt, long ldb, int nM, int nN, int K,
;                                            const Epi& epi, bf16_t* shm, int w0) {
;     ...
;       LDB(B1, 1, 1); WAIT_V(0); BAR; WAIT_L(0); MMA(0, 1, At, B1); BAR;
	s_waitcnt lgkmcnt(0)
	v_mfma_f32_16x16x32_bf16 v[50:53], v[222:225], v[14:17], v[98:101]
	v_mfma_f32_16x16x32_bf16 v[14:17], v[178:181], v[14:17], v[18:21]
	v_mfma_f32_16x16x32_bf16 v[62:65], v[190:193], v[30:33], v[50:53]
	v_mfma_f32_16x16x32_bf16 v[30:33], v[182:185], v[30:33], v[14:17]
	v_mfma_f32_16x16x32_bf16 v[14:17], v[222:225], v[46:49], v[22:25]
	v_mfma_f32_16x16x32_bf16 v[58:61], v[190:193], v[82:85], v[14:17]
	v_mfma_f32_16x16x32_bf16 v[14:17], v[178:181], v[46:49], v[26:29]
	v_mfma_f32_16x16x32_bf16 v[26:29], v[182:185], v[82:85], v[14:17]
	v_mfma_f32_16x16x32_bf16 v[14:17], v[222:225], v[106:109], v[102:105]
	v_mfma_f32_16x16x32_bf16 v[54:57], v[190:193], v[114:117], v[14:17]
	v_mfma_f32_16x16x32_bf16 v[14:17], v[178:181], v[106:109], v[34:37]
	v_mfma_f32_16x16x32_bf16 v[22:25], v[182:185], v[114:117], v[14:17]
	v_mfma_f32_16x16x32_bf16 v[14:17], v[222:225], v[242:245], v[38:41]
	v_mfma_f32_16x16x32_bf16 v[46:49], v[190:193], v[246:249], v[14:17]
	v_mfma_f32_16x16x32_bf16 v[14:17], v[178:181], v[242:245], v[42:45]
	v_mfma_f32_16x16x32_bf16 v[14:17], v[182:185], v[246:249], v[14:17]

; #define LDA(dst, b, h) for (int m = 0; m < 4; ++m) for (int k = 0; k < 2; ++k) \
;     dst[m][k] = *reinterpret_cast<const bf16x8*>((char*)SA(b, h) + a_thr + (m * 2 + k) * 1024)
; #define MMA(ai, bj, At, Btf) do { __builtin_amdgcn_s_setprio(1); \
;     for (int m = 0; m < 4; ++m) for (int n = 0; n < 2; ++n) for (int k = 0; k < 2; ++k) \
;       acc[ai][bj][m][n] = __builtin_amdgcn_mfma_f32_16x16x32_bf16(Btf[n][k], At[m][k], acc[ai][bj][m][n], 0, 0, 0); \
;     __builtin_amdgcn_s_setprio(0); } while (0)
; #define WAIT_L(n) asm volatile("s_waitcnt lgkmcnt(" #n ")" ::: "memory")
; #define BAR __builtin_amdgcn_s_barrier()
; template <bool OVL, bool PANEL = false, class Epi>
; __device__ __forceinline__ void gemm_phase(const bf16_t* __restrict__ A, long lda, const bf16_t* __restrict__ Bt, long ldb, int nM, int nN, int K,
;                                            const Epi& epi, bf16_t* shm, int w0) {
;     ...
;       LDA(At, 1, 1); BAR; WAIT_L(0); MMA(1, 0, At, B0); MMA(1, 1, At, B1); BAR; }
	s_barrier
	ds_read_b128 v[18:21], v153 offset:49152
	ds_read_b128 v[34:37], v153 offset:50176
	ds_read_b128 v[38:41], v153 offset:51200
	ds_read_b128 v[242:245], v153 offset:52224
	ds_read_b128 v[246:249], v153 offset:53248
	ds_read_b128 v[186:189], v153 offset:54272
	ds_read_b128 v[230:233], v153 offset:55296
	ds_read_b128 v[144:147], v153 offset:56320
	s_barrier
	s_waitcnt lgkmcnt(0)

; #define LDA(dst, b, h) for (int m = 0; m < 4; ++m) for (int k = 0; k < 2; ++k) \
;     dst[m][k] = *reinterpret_cast<const bf16x8*>((char*)SA(b, h) + a_thr + (m * 2 + k) * 1024)
; #define MMA(ai, bj, At, Btf) do { __builtin_amdgcn_s_setprio(1); \
;     for (int m = 0; m < 4; ++m) for (int n = 0; n < 2; ++n) for (int k = 0; k < 2; ++k) \
;       acc[ai][bj][m][n] = __builtin_amdgcn_mfma_f32_16x16x32_bf16(Btf[n][k], At[m][k], acc[ai][bj][m][n], 0, 0, 0); \
;     __builtin_amdgcn_s_setprio(0); } while (0)
; #define WAIT_L(n) asm volatile("s_waitcnt lgkmcnt(" #n ")" ::: "memory")
; #define BAR __builtin_amdgcn_s_barrier()
; template <bool OVL, bool PANEL = false, class Epi>
; __device__ __forceinline__ void gemm_phase(const bf16_t* __restrict__ A, long lda, const bf16_t* __restrict__ Bt, long ldb, int nM, int nN, int K,
;                                            const Epi& epi, bf16_t* shm, int w0) {
;     ...
;       LDA(At, 1, 1); BAR; WAIT_L(0); MMA(1, 0, At, B0); MMA(1, 1, At, B1); BAR; }
	s_waitcnt lgkmcnt(0)
	v_mfma_f32_16x16x32_bf16 v[42:45], v[214:217], v[18:21], v[130:133]
	v_mfma_f32_16x16x32_bf16 v[114:117], v[218:221], v[34:37], v[42:45]
	v_mfma_f32_16x16x32_bf16 v[42:45], v[234:237], v[18:21], v[134:137]
	v_mfma_f32_16x16x32_bf16 v[82:85], v[238:241], v[34:37], v[42:45]
	v_mfma_f32_16x16x32_bf16 v[42:45], v[214:217], v[38:41], v[154:157]
	v_mfma_f32_16x16x32_bf16 v[106:109], v[218:221], v[242:245], v[42:45]
	v_mfma_f32_16x16x32_bf16 v[42:45], v[234:237], v[38:41], v[158:161]
	v_mfma_f32_16x16x32_bf16 v[74:77], v[238:241], v[242:245], v[42:45]
	v_mfma_f32_16x16x32_bf16 v[42:45], v[214:217], v[246:249], v[162:165]
	v_mfma_f32_16x16x32_bf16 v[2:5], v[214:217], v[230:233], v[2:5]
	v_mfma_f32_16x16x32_bf16 v[102:105], v[218:221], v[186:189], v[42:45]
	v_mfma_f32_16x16x32_bf16 v[42:45], v[234:237], v[246:249], v[166:169]
	v_mfma_f32_16x16x32_bf16 v[98:101], v[218:221], v[144:147], v[2:5]
	v_mfma_f32_16x16x32_bf16 v[2:5], v[234:237], v[230:233], v[6:9]
	v_mfma_f32_16x16x32_bf16 v[70:73], v[238:241], v[186:189], v[42:45]
	v_mfma_f32_16x16x32_bf16 v[66:69], v[238:241], v[144:147], v[2:5]


; #define LDA(dst, b, h) for (int m = 0; m < 4; ++m) for (int k = 0; k < 2; ++k) \
;     dst[m][k] = *reinterpret_cast<const bf16x8*>((char*)SA(b, h) + a_thr + (m * 2 + k) * 1024)
; #define MMA(ai, bj, At, Btf) do { __builtin_amdgcn_s_setprio(1); \
;     for (int m = 0; m < 4; ++m) for (int n = 0; n < 2; ++n) for (int k = 0; k < 2; ++k) \
;       acc[ai][bj][m][n] = __builtin_amdgcn_mfma_f32_16x16x32_bf16(Btf[n][k], At[m][k], acc[ai][bj][m][n], 0, 0, 0); \
;     __builtin_amdgcn_s_setprio(0); } while (0)
; #define WAIT_L(n) asm volatile("s_waitcnt lgkmcnt(" #n ")" ::: "memory")
; #define BAR __builtin_amdgcn_s_barrier()
; template <bool OVL, bool PANEL = false, class Epi>
; __device__ __forceinline__ void gemm_phase(const bf16_t* __restrict__ A, long lda, const bf16_t* __restrict__ Bt, long ldb, int nM, int nN, int K,
;                                            const Epi& epi, bf16_t* shm, int w0) {
;     ...
;       LDA(At, 1, 1); BAR; WAIT_L(0); MMA(1, 0, At, B0); MMA(1, 1, At, B1); BAR; }
	v_mfma_f32_16x16x32_bf16 v[2:5], v[222:225], v[18:21], v[10:13]
	v_mfma_f32_16x16x32_bf16 v[50:53], v[190:193], v[34:37], v[2:5]
	v_mfma_f32_16x16x32_bf16 v[2:5], v[178:181], v[18:21], v[170:173]
	v_mfma_f32_16x16x32_bf16 v[18:21], v[182:185], v[34:37], v[2:5]
	v_mfma_f32_16x16x32_bf16 v[2:5], v[222:225], v[38:41], v[174:177]
	v_mfma_f32_16x16x32_bf16 v[42:45], v[190:193], v[242:245], v[2:5]
	v_mfma_f32_16x16x32_bf16 v[2:5], v[178:181], v[38:41], v[194:197]
	v_mfma_f32_16x16x32_bf16 v[10:13], v[182:185], v[242:245], v[2:5]
	v_mfma_f32_16x16x32_bf16 v[2:5], v[222:225], v[246:249], v[198:201]
	v_mfma_f32_16x16x32_bf16 v[38:41], v[190:193], v[186:189], v[2:5]
	v_mfma_f32_16x16x32_bf16 v[2:5], v[178:181], v[246:249], v[202:205]
	v_mfma_f32_16x16x32_bf16 v[6:9], v[182:185], v[186:189], v[2:5]
	v_mfma_f32_16x16x32_bf16 v[2:5], v[222:225], v[230:233], v[206:209]
	v_mfma_f32_16x16x32_bf16 v[34:37], v[190:193], v[144:147], v[2:5]
	v_mfma_f32_16x16x32_bf16 v[2:5], v[178:181], v[230:233], v[210:213]
	v_mfma_f32_16x16x32_bf16 v[2:5], v[182:185], v[144:147], v[2:5]

; #define LDA(dst, b, h) for (int m = 0; m < 4; ++m) for (int k = 0; k < 2; ++k) \
;     dst[m][k] = *reinterpret_cast<const bf16x8*>((char*)SA(b, h) + a_thr + (m * 2 + k) * 1024)
; #define MMA(ai, bj, At, Btf) do { __builtin_amdgcn_s_setprio(1); \
;     for (int m = 0; m < 4; ++m) for (int n = 0; n < 2; ++n) for (int k = 0; k < 2; ++k) \
;       acc[ai][bj][m][n] = __builtin_amdgcn_mfma_f32_16x16x32_bf16(Btf[n][k], At[m][k], acc[ai][bj][m][n], 0, 0, 0); \
;     __builtin_amdgcn_s_setprio(0); } while (0)
; #define WAIT_L(n) asm volatile("s_waitcnt lgkmcnt(" #n ")" ::: "memory")
; #define BAR __builtin_amdgcn_s_barrier()
; template <bool OVL, bool PANEL = false, class Epi>
; __device__ __forceinline__ void gemm_phase(const bf16_t* __restrict__ A, long lda, const bf16_t* __restrict__ Bt, long ldb, int nM, int nN, int K,
;                                            const Epi& epi, bf16_t* shm, int w0) {
;     ...
;       LDA(At, 1, 1); BAR; WAIT_L(0); MMA(1, 0, At, B0); MMA(1, 1, At, B1); BAR; }
;     if (wr == 0) BAR;
	s_barrier
	s_and_saveexec_b64 s[8:9], s[6:7]
	s_cbranch_execz .LBB0_830
	s_barrier

; #define LDA(dst, b, h) for (int m = 0; m < 4; ++m) for (int k = 0; k < 2; ++k) \
;     dst[m][k] = *reinterpret_cast<const bf16x8*>((char*)SA(b, h) + a_thr + (m * 2 + k) * 1024)
; #define LDB(dst, b, h) for (int n = 0; n < 2; ++n) for (int k = 0; k < 2; ++k) \
;     dst[n][k] = *reinterpret_cast<const bf16x8*>((char*)SB(b, h) + b_thr + (n * 2 + k) * 1024)
; #define MMA(ai, bj, At, Btf) do { __builtin_amdgcn_s_setprio(1); \
;     for (int m = 0; m < 4; ++m) for (int n = 0; n < 2; ++n) for (int k = 0; k < 2; ++k) \
;       acc[ai][bj][m][n] = __builtin_amdgcn_mfma_f32_16x16x32_bf16(Btf[n][k], At[m][k], acc[ai][bj][m][n], 0, 0, 0); \
;     __builtin_amdgcn_s_setprio(0); } while (0)
; #define WAIT_V(n) asm volatile("s_waitcnt vmcnt(" #n ")" ::: "memory")
; #define WAIT_L(n) asm volatile("s_waitcnt lgkmcnt(" #n ")" ::: "memory")
; #define BAR __builtin_amdgcn_s_barrier()
; #define SCHED __builtin_amdgcn_sched_barrier(0)
; template <bool OVL, bool PANEL = false, class Epi>
; __device__ __forceinline__ void gemm_phase(const bf16_t* __restrict__ A, long lda, const bf16_t* __restrict__ Bt, long ldb, int nM, int nN, int K,
;                                            const Epi& epi, bf16_t* shm, int w0) {
;     ...
;     for (int t = 0; t < nt - 2; t += 2) {
;       LDB(B0, 0, 0); SCHED; LDA(At, 0, 0); STAGE(SA(1, 1), A, lda, aoff, brow + HALF, t + 1);
;       WAIT_L(8); BAR; WAIT_L(0); MMA(0, 0, At, B0); BAR; SCHED;
;       LDB(B1, 0, 1); STAGE(SB(0, 0), Bt, ldb, boff, bcol, t + 2);
;       BAR; WAIT_L(0); MMA(0, 1, At, B1); BAR;
;       LDA(At, 0, 1); STAGE(SA(0, 0), A, lda, aoff, brow, t + 2);
;       BAR; WAIT_L(0); MMA(1, 0, At, B0); BAR; SCHED;
;       STAGE(SB(0, 1), Bt, ldb, boff, bcol + HALF, t + 2);
;       WAIT_V(6); BAR; MMA(1, 1, At, B1); BAR;
.LBB0_1053:
	ds_read_b128 v[152:155], v184
	ds_read_b128 v[156:159], v184 offset:1024
	ds_read_b128 v[160:163], v184 offset:2048
	ds_read_b128 v[164:167], v184 offset:3072
	s_add_u32 s40, s10, s14
	s_addc_u32 s41, s11, s15
	ds_read_b128 v[168:171], v147
	ds_read_b128 v[172:175], v147 offset:1024
	ds_read_b128 v[176:179], v147 offset:2048
	ds_read_b128 v[194:197], v147 offset:3072
	ds_read_b128 v[198:201], v147 offset:4096
	ds_read_b128 v[202:205], v147 offset:5120
	ds_read_b128 v[206:209], v147 offset:6144
	ds_read_b128 v[210:213], v147 offset:7168
	s_mov_b32 m0, s22
	s_add_u32 s98, s40, s16
	s_addc_u32 s99, s41, s17
	global_load_lds_dwordx4 v135, s[98:99]
	s_mov_b32 m0, s23
	s_add_u32 s98, s40, s36
	s_addc_u32 s99, s41, s37
	global_load_lds_dwordx4 v135, s[98:99]
	s_waitcnt lgkmcnt(8)
	s_waitcnt vmcnt(10)
	s_barrier
	s_waitcnt lgkmcnt(0)
	s_waitcnt lgkmcnt(0)
	v_mfma_f32_16x16x32_bf16 v[126:129], v[152:155], v[168:171], v[126:129]
	v_mfma_f32_16x16x32_bf16 v[122:125], v[160:163], v[168:171], v[122:125]
	v_mfma_f32_16x16x32_bf16 v[118:121], v[152:155], v[176:179], v[118:121]
	v_mfma_f32_16x16x32_bf16 v[114:117], v[160:163], v[176:179], v[114:117]
	v_mfma_f32_16x16x32_bf16 v[110:113], v[152:155], v[198:201], v[110:113]
	v_mfma_f32_16x16x32_bf16 v[106:109], v[160:163], v[198:201], v[106:109]
	v_mfma_f32_16x16x32_bf16 v[102:105], v[152:155], v[206:209], v[102:105]
	v_mfma_f32_16x16x32_bf16 v[98:101], v[160:163], v[206:209], v[98:101]
	v_mfma_f32_16x16x32_bf16 v[126:129], v[156:159], v[172:175], v[126:129]
	v_mfma_f32_16x16x32_bf16 v[122:125], v[164:167], v[172:175], v[122:125]
	v_mfma_f32_16x16x32_bf16 v[118:121], v[156:159], v[194:197], v[118:121]
	v_mfma_f32_16x16x32_bf16 v[114:117], v[164:167], v[194:197], v[114:117]
	v_mfma_f32_16x16x32_bf16 v[110:113], v[156:159], v[202:205], v[110:113]
	v_mfma_f32_16x16x32_bf16 v[106:109], v[164:167], v[202:205], v[106:109]
	v_mfma_f32_16x16x32_bf16 v[102:105], v[156:159], v[210:213], v[102:105]
	v_mfma_f32_16x16x32_bf16 v[98:101], v[164:167], v[210:213], v[98:101]
	s_barrier
	s_add_u32 s42, s8, s14
	ds_read_b128 v[214:217], v185
	ds_read_b128 v[218:221], v185 offset:1024
	ds_read_b128 v[234:237], v185 offset:2048
	ds_read_b128 v[238:241], v185 offset:3072
	s_addc_u32 s43, s9, s15
	s_mov_b32 m0, s24
	s_add_u32 s98, s42, s34
	s_addc_u32 s99, s43, s35
	global_load_lds_dwordx4 v135, s[98:99]
	s_mov_b32 m0, s25
	s_add_u32 s98, s42, s64
	s_addc_u32 s99, s43, s65
	global_load_lds_dwordx4 v135, s[98:99]
	s_waitcnt vmcnt(10)
	s_barrier
	s_waitcnt lgkmcnt(0)
	s_waitcnt lgkmcnt(0)
	v_mfma_f32_16x16x32_bf16 v[94:97], v[214:217], v[168:171], v[94:97]
	v_mfma_f32_16x16x32_bf16 v[90:93], v[234:237], v[168:171], v[90:93]
	v_mfma_f32_16x16x32_bf16 v[86:89], v[214:217], v[176:179], v[86:89]
	v_mfma_f32_16x16x32_bf16 v[82:85], v[234:237], v[176:179], v[82:85]
	v_mfma_f32_16x16x32_bf16 v[78:81], v[214:217], v[198:201], v[78:81]
	v_mfma_f32_16x16x32_bf16 v[74:77], v[234:237], v[198:201], v[74:77]
	v_mfma_f32_16x16x32_bf16 v[70:73], v[214:217], v[206:209], v[70:73]
	v_mfma_f32_16x16x32_bf16 v[66:69], v[234:237], v[206:209], v[66:69]
	v_mfma_f32_16x16x32_bf16 v[94:97], v[218:221], v[172:175], v[94:97]
	v_mfma_f32_16x16x32_bf16 v[90:93], v[238:241], v[172:175], v[90:93]
	v_mfma_f32_16x16x32_bf16 v[86:89], v[218:221], v[194:197], v[86:89]
	v_mfma_f32_16x16x32_bf16 v[82:85], v[238:241], v[194:197], v[82:85]
	v_mfma_f32_16x16x32_bf16 v[78:81], v[218:221], v[202:205], v[78:81]
	v_mfma_f32_16x16x32_bf16 v[74:77], v[238:241], v[202:205], v[74:77]
	v_mfma_f32_16x16x32_bf16 v[70:73], v[218:221], v[210:213], v[70:73]
	v_mfma_f32_16x16x32_bf16 v[66:69], v[238:241], v[210:213], v[66:69]
	s_barrier
	ds_read_b128 v[168:171], v147 offset:16384
	ds_read_b128 v[172:175], v147 offset:17408
	ds_read_b128 v[176:179], v147 offset:18432
	ds_read_b128 v[194:197], v147 offset:19456
	ds_read_b128 v[198:201], v147 offset:20480
	ds_read_b128 v[202:205], v147 offset:21504
	ds_read_b128 v[206:209], v147 offset:22528
	ds_read_b128 v[210:213], v147 offset:23552
	s_mov_b32 m0, s26
	s_add_u32 s98, s40, s34
	s_addc_u32 s99, s41, s35
	global_load_lds_dwordx4 v135, s[98:99]
	s_mov_b32 m0, s27
	s_add_u32 s98, s40, s64
	s_addc_u32 s99, s41, s65
	global_load_lds_dwordx4 v135, s[98:99]
	s_barrier
	s_waitcnt lgkmcnt(0)
	s_waitcnt lgkmcnt(0)
	v_mfma_f32_16x16x32_bf16 v[62:65], v[152:155], v[168:171], v[62:65]
	v_mfma_f32_16x16x32_bf16 v[58:61], v[160:163], v[168:171], v[58:61]
	v_mfma_f32_16x16x32_bf16 v[54:57], v[152:155], v[176:179], v[54:57]
	v_mfma_f32_16x16x32_bf16 v[50:53], v[160:163], v[176:179], v[50:53]
	v_mfma_f32_16x16x32_bf16 v[46:49], v[152:155], v[198:201], v[46:49]
	v_mfma_f32_16x16x32_bf16 v[42:45], v[160:163], v[198:201], v[42:45]
	v_mfma_f32_16x16x32_bf16 v[38:41], v[152:155], v[206:209], v[38:41]
	v_mfma_f32_16x16x32_bf16 v[34:37], v[160:163], v[206:209], v[34:37]
	v_mfma_f32_16x16x32_bf16 v[62:65], v[156:159], v[172:175], v[62:65]
	v_mfma_f32_16x16x32_bf16 v[58:61], v[164:167], v[172:175], v[58:61]
	v_mfma_f32_16x16x32_bf16 v[54:57], v[156:159], v[194:197], v[54:57]
	v_mfma_f32_16x16x32_bf16 v[50:53], v[164:167], v[194:197], v[50:53]
	v_mfma_f32_16x16x32_bf16 v[46:49], v[156:159], v[202:205], v[46:49]
	v_mfma_f32_16x16x32_bf16 v[42:45], v[164:167], v[202:205], v[42:45]
	v_mfma_f32_16x16x32_bf16 v[38:41], v[156:159], v[210:213], v[38:41]
	v_mfma_f32_16x16x32_bf16 v[34:37], v[164:167], v[210:213], v[34:37]
	s_barrier
	s_mov_b32 m0, s28
	s_add_u32 s98, s42, s68
	s_addc_u32 s99, s43, s69
	global_load_lds_dwordx4 v135, s[98:99]
	s_mov_b32 m0, s29
	s_add_u32 s98, s42, s70
	s_addc_u32 s99, s43, s71
	global_load_lds_dwordx4 v135, s[98:99]
	s_waitcnt vmcnt(10)
	s_barrier
; #define LDA(dst, b, h) for (int m = 0; m < 4; ++m) for (int k = 0; k < 2; ++k) \
;     dst[m][k] = *reinterpret_cast<const bf16x8*>((char*)SA(b, h) + a_thr + (m * 2 + k) * 1024)
; #define LDB(dst, b, h) for (int n = 0; n < 2; ++n) for (int k = 0; k < 2; ++k) \
;     dst[n][k] = *reinterpret_cast<const bf16x8*>((char*)SB(b, h) + b_thr + (n * 2 + k) * 1024)
; #define MMA(ai, bj, At, Btf) do { __builtin_amdgcn_s_setprio(1); \
;     for (int m = 0; m < 4; ++m) for (int n = 0; n < 2; ++n) for (int k = 0; k < 2; ++k) \
;       acc[ai][bj][m][n] = __builtin_amdgcn_mfma_f32_16x16x32_bf16(Btf[n][k], At[m][k], acc[ai][bj][m][n], 0, 0, 0); \
;     __builtin_amdgcn_s_setprio(0); } while (0)
; #define WAIT_V(n) asm volatile("s_waitcnt vmcnt(" #n ")" ::: "memory")
; #define WAIT_L(n) asm volatile("s_waitcnt lgkmcnt(" #n ")" ::: "memory")
; #define BAR __builtin_amdgcn_s_barrier()
; #define SCHED __builtin_amdgcn_sched_barrier(0)
; template <bool OVL, bool PANEL = false, class Epi>
; __device__ __forceinline__ void gemm_phase(const bf16_t* __restrict__ A, long lda, const bf16_t* __restrict__ Bt, long ldb, int nM, int nN, int K,
;                                            const Epi& epi, bf16_t* shm, int w0) {
;     ...
;       WAIT_V(6); BAR; MMA(1, 1, At, B1); BAR;
;       LDB(B0, 1, 0); SCHED; LDA(At, 1, 0); STAGE(SA(0, 1), A, lda, aoff, brow + HALF, t + 2);
;       WAIT_L(8); BAR; WAIT_L(0); MMA(0, 0, At, B0); BAR; SCHED;
;       LDB(B1, 1, 1); STAGE(SB(1, 0), Bt, ldb, boff, bcol, t + 3);
;       BAR; WAIT_L(0); MMA(0, 1, At, B1); BAR;
;       LDA(At, 1, 1); STAGE(SA(1, 0), A, lda, aoff, brow, t + 3);
;       BAR; WAIT_L(0); MMA(1, 0, At, B0); BAR; SCHED;
	v_mfma_f32_16x16x32_bf16 v[30:33], v[214:217], v[168:171], v[30:33]
	v_mfma_f32_16x16x32_bf16 v[26:29], v[234:237], v[168:171], v[26:29]
	v_mfma_f32_16x16x32_bf16 v[22:25], v[214:217], v[176:179], v[22:25]
	v_mfma_f32_16x16x32_bf16 v[18:21], v[234:237], v[176:179], v[18:21]
	v_mfma_f32_16x16x32_bf16 v[14:17], v[214:217], v[198:201], v[14:17]
	v_mfma_f32_16x16x32_bf16 v[10:13], v[234:237], v[198:201], v[10:13]
	v_mfma_f32_16x16x32_bf16 v[6:9], v[214:217], v[206:209], v[6:9]
	v_mfma_f32_16x16x32_bf16 v[2:5], v[234:237], v[206:209], v[2:5]
	v_mfma_f32_16x16x32_bf16 v[30:33], v[218:221], v[172:175], v[30:33]
	v_mfma_f32_16x16x32_bf16 v[26:29], v[238:241], v[172:175], v[26:29]
	v_mfma_f32_16x16x32_bf16 v[22:25], v[218:221], v[194:197], v[22:25]
	v_mfma_f32_16x16x32_bf16 v[18:21], v[238:241], v[194:197], v[18:21]
	v_mfma_f32_16x16x32_bf16 v[14:17], v[218:221], v[202:205], v[14:17]
	v_mfma_f32_16x16x32_bf16 v[10:13], v[238:241], v[202:205], v[10:13]
	v_mfma_f32_16x16x32_bf16 v[6:9], v[218:221], v[210:213], v[6:9]
	v_mfma_f32_16x16x32_bf16 v[2:5], v[238:241], v[210:213], v[2:5]
	s_barrier
	ds_read_b128 v[152:155], v186
	ds_read_b128 v[156:159], v186 offset:1024
	ds_read_b128 v[160:163], v186 offset:2048
	ds_read_b128 v[164:167], v186 offset:3072
	ds_read_b128 v[168:171], v147 offset:32768
	ds_read_b128 v[172:175], v147 offset:33792
	ds_read_b128 v[176:179], v147 offset:34816
	ds_read_b128 v[194:197], v147 offset:35840
	ds_read_b128 v[198:201], v147 offset:36864
	ds_read_b128 v[202:205], v147 offset:37888
	ds_read_b128 v[206:209], v147 offset:38912
	ds_read_b128 v[210:213], v147 offset:39936
	s_mov_b32 m0, s30
	s_add_u32 s98, s40, s68
	s_addc_u32 s99, s41, s69
	global_load_lds_dwordx4 v135, s[98:99]
	s_mov_b32 m0, s31
	s_add_u32 s98, s40, s70
	s_addc_u32 s99, s41, s71
	global_load_lds_dwordx4 v135, s[98:99]
	s_waitcnt lgkmcnt(8)
	s_waitcnt vmcnt(10)
	s_barrier
	s_waitcnt lgkmcnt(0)
	s_waitcnt lgkmcnt(0)
	v_mfma_f32_16x16x32_bf16 v[126:129], v[152:155], v[168:171], v[126:129]
	v_mfma_f32_16x16x32_bf16 v[122:125], v[160:163], v[168:171], v[122:125]
	v_mfma_f32_16x16x32_bf16 v[118:121], v[152:155], v[176:179], v[118:121]
	v_mfma_f32_16x16x32_bf16 v[114:117], v[160:163], v[176:179], v[114:117]
	v_mfma_f32_16x16x32_bf16 v[110:113], v[152:155], v[198:201], v[110:113]
	v_mfma_f32_16x16x32_bf16 v[106:109], v[160:163], v[198:201], v[106:109]
	v_mfma_f32_16x16x32_bf16 v[102:105], v[152:155], v[206:209], v[102:105]
	v_mfma_f32_16x16x32_bf16 v[98:101], v[160:163], v[206:209], v[98:101]
	v_mfma_f32_16x16x32_bf16 v[126:129], v[156:159], v[172:175], v[126:129]
	v_mfma_f32_16x16x32_bf16 v[122:125], v[164:167], v[172:175], v[122:125]
	v_mfma_f32_16x16x32_bf16 v[118:121], v[156:159], v[194:197], v[118:121]
	v_mfma_f32_16x16x32_bf16 v[114:117], v[164:167], v[194:197], v[114:117]
	v_mfma_f32_16x16x32_bf16 v[110:113], v[156:159], v[202:205], v[110:113]
	v_mfma_f32_16x16x32_bf16 v[106:109], v[164:167], v[202:205], v[106:109]
	v_mfma_f32_16x16x32_bf16 v[102:105], v[156:159], v[210:213], v[102:105]
	v_mfma_f32_16x16x32_bf16 v[98:101], v[164:167], v[210:213], v[98:101]
	s_barrier
	ds_read_b128 v[214:217], v187
	ds_read_b128 v[218:221], v187 offset:1024
	ds_read_b128 v[234:237], v187 offset:2048
	ds_read_b128 v[238:241], v187 offset:3072
	s_mov_b32 m0, s32
	s_add_u32 s98, s42, s94
	s_addc_u32 s99, s43, s95
	global_load_lds_dwordx4 v135, s[98:99]
	s_mov_b32 m0, s44
	s_add_u32 s98, s42, s72
	s_addc_u32 s99, s43, s73
	global_load_lds_dwordx4 v135, s[98:99]
	s_waitcnt vmcnt(10)
	s_barrier
	s_waitcnt lgkmcnt(0)
	s_waitcnt lgkmcnt(0)
	v_mfma_f32_16x16x32_bf16 v[94:97], v[214:217], v[168:171], v[94:97]
	v_mfma_f32_16x16x32_bf16 v[90:93], v[234:237], v[168:171], v[90:93]
	v_mfma_f32_16x16x32_bf16 v[86:89], v[214:217], v[176:179], v[86:89]
	v_mfma_f32_16x16x32_bf16 v[82:85], v[234:237], v[176:179], v[82:85]
	v_mfma_f32_16x16x32_bf16 v[78:81], v[214:217], v[198:201], v[78:81]
	v_mfma_f32_16x16x32_bf16 v[74:77], v[234:237], v[198:201], v[74:77]
	v_mfma_f32_16x16x32_bf16 v[70:73], v[214:217], v[206:209], v[70:73]
	v_mfma_f32_16x16x32_bf16 v[66:69], v[234:237], v[206:209], v[66:69]
	v_mfma_f32_16x16x32_bf16 v[94:97], v[218:221], v[172:175], v[94:97]
	v_mfma_f32_16x16x32_bf16 v[90:93], v[238:241], v[172:175], v[90:93]
	v_mfma_f32_16x16x32_bf16 v[86:89], v[218:221], v[194:197], v[86:89]
	v_mfma_f32_16x16x32_bf16 v[82:85], v[238:241], v[194:197], v[82:85]
	v_mfma_f32_16x16x32_bf16 v[78:81], v[218:221], v[202:205], v[78:81]
	v_mfma_f32_16x16x32_bf16 v[74:77], v[238:241], v[202:205], v[74:77]
	v_mfma_f32_16x16x32_bf16 v[70:73], v[218:221], v[210:213], v[70:73]
	v_mfma_f32_16x16x32_bf16 v[66:69], v[238:241], v[210:213], v[66:69]
	s_barrier
; #define LDA(dst, b, h) for (int m = 0; m < 4; ++m) for (int k = 0; k < 2; ++k) \
;     dst[m][k] = *reinterpret_cast<const bf16x8*>((char*)SA(b, h) + a_thr + (m * 2 + k) * 1024)
; #define LDB(dst, b, h) for (int n = 0; n < 2; ++n) for (int k = 0; k < 2; ++k) \
;     dst[n][k] = *reinterpret_cast<const bf16x8*>((char*)SB(b, h) + b_thr + (n * 2 + k) * 1024)
; #define MMA(ai, bj, At, Btf) do { __builtin_amdgcn_s_setprio(1); \
;     for (int m = 0; m < 4; ++m) for (int n = 0; n < 2; ++n) for (int k = 0; k < 2; ++k) \
;       acc[ai][bj][m][n] = __builtin_amdgcn_mfma_f32_16x16x32_bf16(Btf[n][k], At[m][k], acc[ai][bj][m][n], 0, 0, 0); \
;     __builtin_amdgcn_s_setprio(0); } while (0)
; #define WAIT_V(n) asm volatile("s_waitcnt vmcnt(" #n ")" ::: "memory")
; #define WAIT_L(n) asm volatile("s_waitcnt lgkmcnt(" #n ")" ::: "memory")
; #define BAR __builtin_amdgcn_s_barrier()
; #define SCHED __builtin_amdgcn_sched_barrier(0)
; template <bool OVL, bool PANEL = false, class Epi>
; __device__ __forceinline__ void gemm_phase(const bf16_t* __restrict__ A, long lda, const bf16_t* __restrict__ Bt, long ldb, int nM, int nN, int K,
;                                            const Epi& epi, bf16_t* shm, int w0) {
;     ...
;       LDA(At, 1, 1); STAGE(SA(1, 0), A, lda, aoff, brow, t + 3);
;       BAR; WAIT_L(0); MMA(1, 0, At, B0); BAR; SCHED;
;       STAGE(SB(1, 1), Bt, ldb, boff, bcol + HALF, t + 3);
;       WAIT_V(6); BAR; MMA(1, 1, At, B1); BAR;
;     }
;     { LDB(B0, 0, 0); LDA(At, 0, 0); STAGE(SA(1, 1), A, lda, aoff, brow + HALF, nt - 1);
;       BAR; WAIT_L(0); MMA(0, 0, At, B0); BAR;
	ds_read_b128 v[168:171], v147 offset:49152
	ds_read_b128 v[172:175], v147 offset:50176
	ds_read_b128 v[176:179], v147 offset:51200
	ds_read_b128 v[194:197], v147 offset:52224
	ds_read_b128 v[198:201], v147 offset:53248
	ds_read_b128 v[202:205], v147 offset:54272
	ds_read_b128 v[206:209], v147 offset:55296
	ds_read_b128 v[210:213], v147 offset:56320
	s_mov_b32 m0, s45
	s_add_u32 s98, s40, s94
	s_addc_u32 s99, s41, s95
	global_load_lds_dwordx4 v135, s[98:99]
	s_mov_b32 m0, s46
	s_add_u32 s98, s40, s72
	s_addc_u32 s99, s41, s73
	global_load_lds_dwordx4 v135, s[98:99]
	s_barrier
	s_waitcnt lgkmcnt(0)
	s_waitcnt lgkmcnt(0)
	v_mfma_f32_16x16x32_bf16 v[62:65], v[152:155], v[168:171], v[62:65]
	v_mfma_f32_16x16x32_bf16 v[58:61], v[160:163], v[168:171], v[58:61]
	v_mfma_f32_16x16x32_bf16 v[54:57], v[152:155], v[176:179], v[54:57]
	v_mfma_f32_16x16x32_bf16 v[50:53], v[160:163], v[176:179], v[50:53]
	v_mfma_f32_16x16x32_bf16 v[46:49], v[152:155], v[198:201], v[46:49]
	v_mfma_f32_16x16x32_bf16 v[42:45], v[160:163], v[198:201], v[42:45]
	v_mfma_f32_16x16x32_bf16 v[38:41], v[152:155], v[206:209], v[38:41]
	v_mfma_f32_16x16x32_bf16 v[34:37], v[160:163], v[206:209], v[34:37]
	v_mfma_f32_16x16x32_bf16 v[62:65], v[156:159], v[172:175], v[62:65]
	v_mfma_f32_16x16x32_bf16 v[58:61], v[164:167], v[172:175], v[58:61]
	v_mfma_f32_16x16x32_bf16 v[54:57], v[156:159], v[194:197], v[54:57]
	v_mfma_f32_16x16x32_bf16 v[50:53], v[164:167], v[194:197], v[50:53]
	v_mfma_f32_16x16x32_bf16 v[46:49], v[156:159], v[202:205], v[46:49]
	v_mfma_f32_16x16x32_bf16 v[42:45], v[164:167], v[202:205], v[42:45]
	v_mfma_f32_16x16x32_bf16 v[38:41], v[156:159], v[210:213], v[38:41]
	v_mfma_f32_16x16x32_bf16 v[34:37], v[164:167], v[210:213], v[34:37]
	s_barrier
	s_mov_b32 m0, s47
	s_add_u32 s98, s42, s18
	s_addc_u32 s99, s43, s19
	global_load_lds_dwordx4 v135, s[98:99]
	s_mov_b32 m0, s48
	s_add_u32 s98, s42, s20
	s_addc_u32 s99, s43, s21
	global_load_lds_dwordx4 v135, s[98:99]
	s_waitcnt vmcnt(10)
	s_barrier
	v_mfma_f32_16x16x32_bf16 v[30:33], v[214:217], v[168:171], v[30:33]
	v_mfma_f32_16x16x32_bf16 v[26:29], v[234:237], v[168:171], v[26:29]
	v_mfma_f32_16x16x32_bf16 v[22:25], v[214:217], v[176:179], v[22:25]
	v_mfma_f32_16x16x32_bf16 v[18:21], v[234:237], v[176:179], v[18:21]
	v_mfma_f32_16x16x32_bf16 v[14:17], v[214:217], v[198:201], v[14:17]
	v_mfma_f32_16x16x32_bf16 v[10:13], v[234:237], v[198:201], v[10:13]
	v_mfma_f32_16x16x32_bf16 v[6:9], v[214:217], v[206:209], v[6:9]
	v_mfma_f32_16x16x32_bf16 v[2:5], v[234:237], v[206:209], v[2:5]
	v_mfma_f32_16x16x32_bf16 v[30:33], v[218:221], v[172:175], v[30:33]
	v_mfma_f32_16x16x32_bf16 v[26:29], v[238:241], v[172:175], v[26:29]
	v_mfma_f32_16x16x32_bf16 v[22:25], v[218:221], v[194:197], v[22:25]
	v_mfma_f32_16x16x32_bf16 v[18:21], v[238:241], v[194:197], v[18:21]
	v_mfma_f32_16x16x32_bf16 v[14:17], v[218:221], v[202:205], v[14:17]
	v_mfma_f32_16x16x32_bf16 v[10:13], v[238:241], v[202:205], v[10:13]
	v_mfma_f32_16x16x32_bf16 v[6:9], v[218:221], v[210:213], v[6:9]
	v_mfma_f32_16x16x32_bf16 v[2:5], v[238:241], v[210:213], v[2:5]
	s_add_i32 s1, s1, 2
	s_add_u32 s14, s14, 0x100
	s_addc_u32 s15, s15, 0
	s_cmp_lt_u32 s1, 12
	s_barrier
	s_cbranch_scc1 .LBB0_1053
	s_waitcnt vmcnt(6)
	s_or_b32 s8, s0, 0x80
	s_ashr_i32 s9, s8, 31
	v_readlane_b32 s40, v252, 20
	s_lshl_b64 s[8:9], s[8:9], 11
	v_readlane_b32 s46, v252, 26
	v_add_u32_e32 v182, 16, v144
	v_readlane_b32 s47, v252, 27
	s_add_u32 s8, s46, s8
	v_add_u32_e32 v0, 0x10000, v182
	s_addc_u32 s9, s47, s9
	ds_read_b128 v[130:133], v0
	ds_read_b128 v[152:155], v0 offset:1024
	ds_read_b128 v[156:159], v0 offset:2048
	ds_read_b128 v[160:163], v0 offset:3072
	ds_read_b128 v[164:167], v147
	ds_read_b128 v[168:171], v147 offset:1024
	ds_read_b128 v[172:175], v147 offset:2048
	ds_read_b128 v[176:179], v147 offset:3072
	ds_read_b128 v[194:197], v147 offset:4096
	ds_read_b128 v[198:201], v147 offset:5120
	ds_read_b128 v[202:205], v147 offset:6144
	ds_read_b128 v[206:209], v147 offset:7168
	v_mov_b32_e32 v0, v135
	v_readfirstlane_b32 s1, v150
	v_lshl_add_u64 v[148:149], s[8:9], 0, v[0:1]
	s_mov_b64 s[8:9], 0x780
	v_lshl_add_u64 v[180:181], v[148:149], 0, s[8:9]
	s_mov_b32 m0, s1
	s_mov_b64 s[8:9], 0x20780
	v_readfirstlane_b32 s1, v151
	global_load_lds_dwordx4 v[180:181], off
	v_lshl_add_u64 v[148:149], v[148:149], 0, s[8:9]
	s_mov_b32 m0, s1
	v_readlane_b32 s41, v252, 21
	global_load_lds_dwordx4 v[148:149], off
	s_barrier
	s_waitcnt lgkmcnt(0)
	v_readlane_b32 s42, v252, 22
	v_readlane_b32 s43, v252, 23
	v_readlane_b32 s44, v252, 24
	v_readlane_b32 s45, v252, 25
	v_readlane_b32 s48, v252, 28
	v_readlane_b32 s49, v252, 29
	v_readlane_b32 s50, v252, 30
	v_readlane_b32 s51, v252, 31
	v_readlane_b32 s52, v252, 32
	v_readlane_b32 s53, v252, 33
	v_readlane_b32 s54, v252, 34
	v_readlane_b32 s55, v252, 35

; #define MMA(ai, bj, At, Btf) do { __builtin_amdgcn_s_setprio(1); \
;     for (int m = 0; m < 4; ++m) for (int n = 0; n < 2; ++n) for (int k = 0; k < 2; ++k) \
;       acc[ai][bj][m][n] = __builtin_amdgcn_mfma_f32_16x16x32_bf16(Btf[n][k], At[m][k], acc[ai][bj][m][n], 0, 0, 0); \
;     __builtin_amdgcn_s_setprio(0); } while (0)
; #define WAIT_L(n) asm volatile("s_waitcnt lgkmcnt(" #n ")" ::: "memory")
; #define BAR __builtin_amdgcn_s_barrier()
; template <bool OVL, bool PANEL = false, class Epi>
; __device__ __forceinline__ void gemm_phase(const bf16_t* __restrict__ A, long lda, const bf16_t* __restrict__ Bt, long ldb, int nM, int nN, int K,
;                                            const Epi& epi, bf16_t* shm, int w0) {
;     ...
;       BAR; WAIT_L(0); MMA(0, 0, At, B0); BAR;
	s_waitcnt lgkmcnt(0)
	v_mfma_f32_16x16x32_bf16 v[126:129], v[130:133], v[164:167], v[126:129]
	v_mfma_f32_16x16x32_bf16 v[122:125], v[156:159], v[164:167], v[122:125]
	v_mfma_f32_16x16x32_bf16 v[118:121], v[130:133], v[172:175], v[118:121]
	v_mfma_f32_16x16x32_bf16 v[114:117], v[156:159], v[172:175], v[114:117]
	v_mfma_f32_16x16x32_bf16 v[110:113], v[130:133], v[194:197], v[110:113]
	v_mfma_f32_16x16x32_bf16 v[106:109], v[156:159], v[194:197], v[106:109]
	v_mfma_f32_16x16x32_bf16 v[102:105], v[130:133], v[202:205], v[102:105]
	v_mfma_f32_16x16x32_bf16 v[98:101], v[156:159], v[202:205], v[98:101]
	v_mfma_f32_16x16x32_bf16 v[126:129], v[152:155], v[168:171], v[126:129]
	v_mfma_f32_16x16x32_bf16 v[122:125], v[160:163], v[168:171], v[122:125]
	v_mfma_f32_16x16x32_bf16 v[118:121], v[152:155], v[176:179], v[118:121]
	v_mfma_f32_16x16x32_bf16 v[114:117], v[160:163], v[176:179], v[114:117]
	v_mfma_f32_16x16x32_bf16 v[110:113], v[152:155], v[198:201], v[110:113]
	v_mfma_f32_16x16x32_bf16 v[106:109], v[160:163], v[198:201], v[106:109]
	v_mfma_f32_16x16x32_bf16 v[102:105], v[152:155], v[206:209], v[102:105]
	v_mfma_f32_16x16x32_bf16 v[98:101], v[160:163], v[206:209], v[98:101]

; #define LDB(dst, b, h) for (int n = 0; n < 2; ++n) for (int k = 0; k < 2; ++k) \
;     dst[n][k] = *reinterpret_cast<const bf16x8*>((char*)SB(b, h) + b_thr + (n * 2 + k) * 1024)
; #define MMA(ai, bj, At, Btf) do { __builtin_amdgcn_s_setprio(1); \
;     for (int m = 0; m < 4; ++m) for (int n = 0; n < 2; ++n) for (int k = 0; k < 2; ++k) \
;       acc[ai][bj][m][n] = __builtin_amdgcn_mfma_f32_16x16x32_bf16(Btf[n][k], At[m][k], acc[ai][bj][m][n], 0, 0, 0); \
;     __builtin_amdgcn_s_setprio(0); } while (0)
; #define WAIT_L(n) asm volatile("s_waitcnt lgkmcnt(" #n ")" ::: "memory")
; #define BAR __builtin_amdgcn_s_barrier()
; template <bool OVL, bool PANEL = false, class Epi>
; __device__ __forceinline__ void gemm_phase(const bf16_t* __restrict__ A, long lda, const bf16_t* __restrict__ Bt, long ldb, int nM, int nN, int K,
;                                            const Epi& epi, bf16_t* shm, int w0) {
;     ...
;       LDB(B1, 0, 1); BAR; WAIT_L(0); MMA(0, 1, At, B1); BAR;
	v_add_u32_e32 v0, 0x14000, v182
	s_barrier
	ds_read_b128 v[148:151], v0
	ds_read_b128 v[210:213], v0 offset:1024
	ds_read_b128 v[214:217], v0 offset:2048
	ds_read_b128 v[218:221], v0 offset:3072
	s_barrier
	s_waitcnt lgkmcnt(0)

; #define LDB(dst, b, h) for (int n = 0; n < 2; ++n) for (int k = 0; k < 2; ++k) \
;     dst[n][k] = *reinterpret_cast<const bf16x8*>((char*)SB(b, h) + b_thr + (n * 2 + k) * 1024)
; #define MMA(ai, bj, At, Btf) do { __builtin_amdgcn_s_setprio(1); \
;     for (int m = 0; m < 4; ++m) for (int n = 0; n < 2; ++n) for (int k = 0; k < 2; ++k) \
;       acc[ai][bj][m][n] = __builtin_amdgcn_mfma_f32_16x16x32_bf16(Btf[n][k], At[m][k], acc[ai][bj][m][n], 0, 0, 0); \
;     __builtin_amdgcn_s_setprio(0); } while (0)
; #define WAIT_L(n) asm volatile("s_waitcnt lgkmcnt(" #n ")" ::: "memory")
; #define BAR __builtin_amdgcn_s_barrier()
; template <bool OVL, bool PANEL = false, class Epi>
; __device__ __forceinline__ void gemm_phase(const bf16_t* __restrict__ A, long lda, const bf16_t* __restrict__ Bt, long ldb, int nM, int nN, int K,
;                                            const Epi& epi, bf16_t* shm, int w0) {
;     ...
;       LDB(B1, 0, 1); BAR; WAIT_L(0); MMA(0, 1, At, B1); BAR;
	s_waitcnt lgkmcnt(0)
	v_mfma_f32_16x16x32_bf16 v[94:97], v[148:151], v[164:167], v[94:97]
	v_mfma_f32_16x16x32_bf16 v[90:93], v[214:217], v[164:167], v[90:93]
	v_mfma_f32_16x16x32_bf16 v[86:89], v[148:151], v[172:175], v[86:89]
	v_mfma_f32_16x16x32_bf16 v[82:85], v[214:217], v[172:175], v[82:85]
	v_mfma_f32_16x16x32_bf16 v[78:81], v[148:151], v[194:197], v[78:81]
	v_mfma_f32_16x16x32_bf16 v[74:77], v[214:217], v[194:197], v[74:77]
	v_mfma_f32_16x16x32_bf16 v[70:73], v[148:151], v[202:205], v[70:73]
	v_mfma_f32_16x16x32_bf16 v[66:69], v[214:217], v[202:205], v[66:69]
	v_mfma_f32_16x16x32_bf16 v[94:97], v[210:213], v[168:171], v[94:97]
	v_mfma_f32_16x16x32_bf16 v[90:93], v[218:221], v[168:171], v[90:93]
	v_mfma_f32_16x16x32_bf16 v[86:89], v[210:213], v[176:179], v[86:89]
	v_mfma_f32_16x16x32_bf16 v[82:85], v[218:221], v[176:179], v[82:85]
	v_mfma_f32_16x16x32_bf16 v[78:81], v[210:213], v[198:201], v[78:81]
	v_mfma_f32_16x16x32_bf16 v[74:77], v[218:221], v[198:201], v[74:77]
	v_mfma_f32_16x16x32_bf16 v[70:73], v[210:213], v[206:209], v[70:73]
	v_mfma_f32_16x16x32_bf16 v[66:69], v[218:221], v[206:209], v[66:69]

; #define LDA(dst, b, h) for (int m = 0; m < 4; ++m) for (int k = 0; k < 2; ++k) \
;     dst[m][k] = *reinterpret_cast<const bf16x8*>((char*)SA(b, h) + a_thr + (m * 2 + k) * 1024)
; #define MMA(ai, bj, At, Btf) do { __builtin_amdgcn_s_setprio(1); \
;     for (int m = 0; m < 4; ++m) for (int n = 0; n < 2; ++n) for (int k = 0; k < 2; ++k) \
;       acc[ai][bj][m][n] = __builtin_amdgcn_mfma_f32_16x16x32_bf16(Btf[n][k], At[m][k], acc[ai][bj][m][n], 0, 0, 0); \
;     __builtin_amdgcn_s_setprio(0); } while (0)
; #define WAIT_V(n) asm volatile("s_waitcnt vmcnt(" #n ")" ::: "memory")
; #define WAIT_L(n) asm volatile("s_waitcnt lgkmcnt(" #n ")" ::: "memory")
; #define BAR __builtin_amdgcn_s_barrier()
; template <bool OVL, bool PANEL = false, class Epi>
; __device__ __forceinline__ void gemm_phase(const bf16_t* __restrict__ A, long lda, const bf16_t* __restrict__ Bt, long ldb, int nM, int nN, int K,
;                                            const Epi& epi, bf16_t* shm, int w0) {
;     ...
;       LDA(At, 0, 1); WAIT_V(4); BAR; WAIT_L(0); MMA(1, 0, At, B0); MMA(1, 1, At, B1); BAR; }
	s_barrier
	ds_read_b128 v[164:167], v147 offset:16384
	ds_read_b128 v[168:171], v147 offset:17408
	ds_read_b128 v[172:175], v147 offset:18432
	ds_read_b128 v[176:179], v147 offset:19456
	ds_read_b128 v[194:197], v147 offset:20480
	ds_read_b128 v[198:201], v147 offset:21504
	ds_read_b128 v[202:205], v147 offset:22528
	ds_read_b128 v[206:209], v147 offset:23552
	s_waitcnt vmcnt(4)
	s_barrier
	s_waitcnt lgkmcnt(0)

; #define LDA(dst, b, h) for (int m = 0; m < 4; ++m) for (int k = 0; k < 2; ++k) \
;     dst[m][k] = *reinterpret_cast<const bf16x8*>((char*)SA(b, h) + a_thr + (m * 2 + k) * 1024)
; #define MMA(ai, bj, At, Btf) do { __builtin_amdgcn_s_setprio(1); \
;     for (int m = 0; m < 4; ++m) for (int n = 0; n < 2; ++n) for (int k = 0; k < 2; ++k) \
;       acc[ai][bj][m][n] = __builtin_amdgcn_mfma_f32_16x16x32_bf16(Btf[n][k], At[m][k], acc[ai][bj][m][n], 0, 0, 0); \
;     __builtin_amdgcn_s_setprio(0); } while (0)
; #define WAIT_V(n) asm volatile("s_waitcnt vmcnt(" #n ")" ::: "memory")
; #define WAIT_L(n) asm volatile("s_waitcnt lgkmcnt(" #n ")" ::: "memory")
; #define BAR __builtin_amdgcn_s_barrier()
; template <bool OVL, bool PANEL = false, class Epi>
; __device__ __forceinline__ void gemm_phase(const bf16_t* __restrict__ A, long lda, const bf16_t* __restrict__ Bt, long ldb, int nM, int nN, int K,
;                                            const Epi& epi, bf16_t* shm, int w0) {
;     ...
;       LDA(At, 0, 1); WAIT_V(4); BAR; WAIT_L(0); MMA(1, 0, At, B0); MMA(1, 1, At, B1); BAR; }
	s_waitcnt lgkmcnt(0)
	v_mfma_f32_16x16x32_bf16 v[62:65], v[130:133], v[164:167], v[62:65]
	v_mfma_f32_16x16x32_bf16 v[58:61], v[156:159], v[164:167], v[58:61]
	v_mfma_f32_16x16x32_bf16 v[54:57], v[130:133], v[172:175], v[54:57]
	v_mfma_f32_16x16x32_bf16 v[50:53], v[156:159], v[172:175], v[50:53]
	v_mfma_f32_16x16x32_bf16 v[46:49], v[130:133], v[194:197], v[46:49]
	v_mfma_f32_16x16x32_bf16 v[42:45], v[156:159], v[194:197], v[42:45]
	v_mfma_f32_16x16x32_bf16 v[38:41], v[130:133], v[202:205], v[38:41]
	v_mfma_f32_16x16x32_bf16 v[34:37], v[156:159], v[202:205], v[34:37]
	v_mfma_f32_16x16x32_bf16 v[62:65], v[152:155], v[168:171], v[62:65]
	v_mfma_f32_16x16x32_bf16 v[58:61], v[160:163], v[168:171], v[58:61]
	v_mfma_f32_16x16x32_bf16 v[54:57], v[152:155], v[176:179], v[54:57]
	v_mfma_f32_16x16x32_bf16 v[50:53], v[160:163], v[176:179], v[50:53]
	v_mfma_f32_16x16x32_bf16 v[46:49], v[152:155], v[198:201], v[46:49]
	v_mfma_f32_16x16x32_bf16 v[42:45], v[160:163], v[198:201], v[42:45]
	v_mfma_f32_16x16x32_bf16 v[38:41], v[152:155], v[206:209], v[38:41]
	v_mfma_f32_16x16x32_bf16 v[34:37], v[160:163], v[206:209], v[34:37]


; #define LDA(dst, b, h) for (int m = 0; m < 4; ++m) for (int k = 0; k < 2; ++k) \
;     dst[m][k] = *reinterpret_cast<const bf16x8*>((char*)SA(b, h) + a_thr + (m * 2 + k) * 1024)
; #define MMA(ai, bj, At, Btf) do { __builtin_amdgcn_s_setprio(1); \
;     for (int m = 0; m < 4; ++m) for (int n = 0; n < 2; ++n) for (int k = 0; k < 2; ++k) \
;       acc[ai][bj][m][n] = __builtin_amdgcn_mfma_f32_16x16x32_bf16(Btf[n][k], At[m][k], acc[ai][bj][m][n], 0, 0, 0); \
;     __builtin_amdgcn_s_setprio(0); } while (0)
; #define WAIT_V(n) asm volatile("s_waitcnt vmcnt(" #n ")" ::: "memory")
; #define WAIT_L(n) asm volatile("s_waitcnt lgkmcnt(" #n ")" ::: "memory")
; #define BAR __builtin_amdgcn_s_barrier()
; template <bool OVL, bool PANEL = false, class Epi>
; __device__ __forceinline__ void gemm_phase(const bf16_t* __restrict__ A, long lda, const bf16_t* __restrict__ Bt, long ldb, int nM, int nN, int K,
;                                            const Epi& epi, bf16_t* shm, int w0) {
;     ...
;       LDA(At, 0, 1); WAIT_V(4); BAR; WAIT_L(0); MMA(1, 0, At, B0); MMA(1, 1, At, B1); BAR; }
	v_mfma_f32_16x16x32_bf16 v[30:33], v[148:151], v[164:167], v[30:33]
	v_mfma_f32_16x16x32_bf16 v[26:29], v[214:217], v[164:167], v[26:29]
	v_mfma_f32_16x16x32_bf16 v[22:25], v[148:151], v[172:175], v[22:25]
	v_mfma_f32_16x16x32_bf16 v[18:21], v[214:217], v[172:175], v[18:21]
	v_mfma_f32_16x16x32_bf16 v[14:17], v[148:151], v[194:197], v[14:17]
	v_mfma_f32_16x16x32_bf16 v[10:13], v[214:217], v[194:197], v[10:13]
	v_mfma_f32_16x16x32_bf16 v[6:9], v[148:151], v[202:205], v[6:9]
	v_mfma_f32_16x16x32_bf16 v[2:5], v[214:217], v[202:205], v[2:5]
	v_mfma_f32_16x16x32_bf16 v[30:33], v[210:213], v[168:171], v[30:33]
	v_mfma_f32_16x16x32_bf16 v[26:29], v[218:221], v[168:171], v[26:29]
	v_mfma_f32_16x16x32_bf16 v[22:25], v[210:213], v[176:179], v[22:25]
	v_mfma_f32_16x16x32_bf16 v[18:21], v[218:221], v[176:179], v[18:21]
	v_mfma_f32_16x16x32_bf16 v[14:17], v[210:213], v[198:201], v[14:17]
	v_mfma_f32_16x16x32_bf16 v[10:13], v[218:221], v[198:201], v[10:13]
	v_mfma_f32_16x16x32_bf16 v[6:9], v[210:213], v[206:209], v[6:9]
	v_mfma_f32_16x16x32_bf16 v[2:5], v[218:221], v[206:209], v[2:5]

; #define LDA(dst, b, h) for (int m = 0; m < 4; ++m) for (int k = 0; k < 2; ++k) \
;     dst[m][k] = *reinterpret_cast<const bf16x8*>((char*)SA(b, h) + a_thr + (m * 2 + k) * 1024)
; #define LDB(dst, b, h) for (int n = 0; n < 2; ++n) for (int k = 0; k < 2; ++k) \
;     dst[n][k] = *reinterpret_cast<const bf16x8*>((char*)SB(b, h) + b_thr + (n * 2 + k) * 1024)
; #define MMA(ai, bj, At, Btf) do { __builtin_amdgcn_s_setprio(1); \
;     for (int m = 0; m < 4; ++m) for (int n = 0; n < 2; ++n) for (int k = 0; k < 2; ++k) \
;       acc[ai][bj][m][n] = __builtin_amdgcn_mfma_f32_16x16x32_bf16(Btf[n][k], At[m][k], acc[ai][bj][m][n], 0, 0, 0); \
;     __builtin_amdgcn_s_setprio(0); } while (0)
; #define WAIT_V(n) asm volatile("s_waitcnt vmcnt(" #n ")" ::: "memory")
; #define WAIT_L(n) asm volatile("s_waitcnt lgkmcnt(" #n ")" ::: "memory")
; #define BAR __builtin_amdgcn_s_barrier()
; template <bool OVL, bool PANEL = false, class Epi>
; __device__ __forceinline__ void gemm_phase(const bf16_t* __restrict__ A, long lda, const bf16_t* __restrict__ Bt, long ldb, int nM, int nN, int K,
;                                            const Epi& epi, bf16_t* shm, int w0) {
;     ...
;     { LDB(B0, 1, 0); LDA(At, 1, 0); WAIT_V(2); BAR; WAIT_L(0); MMA(0, 0, At, B0); BAR;
	v_add_u32_e32 v0, 0x18000, v182
	s_barrier
	ds_read_b128 v[130:133], v0
	ds_read_b128 v[148:151], v0 offset:1024
	ds_read_b128 v[152:155], v0 offset:2048
	ds_read_b128 v[156:159], v0 offset:3072
	ds_read_b128 v[160:163], v147 offset:32768
	ds_read_b128 v[164:167], v147 offset:33792
	ds_read_b128 v[168:171], v147 offset:34816
	ds_read_b128 v[172:175], v147 offset:35840
	ds_read_b128 v[176:179], v147 offset:36864
	ds_read_b128 v[194:197], v147 offset:37888
	ds_read_b128 v[198:201], v147 offset:38912
	ds_read_b128 v[202:205], v147 offset:39936
	s_waitcnt vmcnt(2)
	s_barrier
	s_waitcnt lgkmcnt(0)

; #define LDA(dst, b, h) for (int m = 0; m < 4; ++m) for (int k = 0; k < 2; ++k) \
;     dst[m][k] = *reinterpret_cast<const bf16x8*>((char*)SA(b, h) + a_thr + (m * 2 + k) * 1024)
; #define LDB(dst, b, h) for (int n = 0; n < 2; ++n) for (int k = 0; k < 2; ++k) \
;     dst[n][k] = *reinterpret_cast<const bf16x8*>((char*)SB(b, h) + b_thr + (n * 2 + k) * 1024)
; #define MMA(ai, bj, At, Btf) do { __builtin_amdgcn_s_setprio(1); \
;     for (int m = 0; m < 4; ++m) for (int n = 0; n < 2; ++n) for (int k = 0; k < 2; ++k) \
;       acc[ai][bj][m][n] = __builtin_amdgcn_mfma_f32_16x16x32_bf16(Btf[n][k], At[m][k], acc[ai][bj][m][n], 0, 0, 0); \
;     __builtin_amdgcn_s_setprio(0); } while (0)
; #define WAIT_V(n) asm volatile("s_waitcnt vmcnt(" #n ")" ::: "memory")
; #define WAIT_L(n) asm volatile("s_waitcnt lgkmcnt(" #n ")" ::: "memory")
; #define BAR __builtin_amdgcn_s_barrier()
; template <bool OVL, bool PANEL = false, class Epi>
; __device__ __forceinline__ void gemm_phase(const bf16_t* __restrict__ A, long lda, const bf16_t* __restrict__ Bt, long ldb, int nM, int nN, int K,
;                                            const Epi& epi, bf16_t* shm, int w0) {
;     ...
;     { LDB(B0, 1, 0); LDA(At, 1, 0); WAIT_V(2); BAR; WAIT_L(0); MMA(0, 0, At, B0); BAR;
	s_waitcnt lgkmcnt(0)
	v_mfma_f32_16x16x32_bf16 v[126:129], v[130:133], v[160:163], v[126:129]
	v_mfma_f32_16x16x32_bf16 v[122:125], v[152:155], v[160:163], v[122:125]
	v_mfma_f32_16x16x32_bf16 v[118:121], v[130:133], v[168:171], v[118:121]
	v_mfma_f32_16x16x32_bf16 v[114:117], v[152:155], v[168:171], v[114:117]
	v_mfma_f32_16x16x32_bf16 v[110:113], v[130:133], v[176:179], v[110:113]
	v_mfma_f32_16x16x32_bf16 v[106:109], v[152:155], v[176:179], v[106:109]
	v_mfma_f32_16x16x32_bf16 v[102:105], v[130:133], v[198:201], v[102:105]
	v_mfma_f32_16x16x32_bf16 v[98:101], v[152:155], v[198:201], v[98:101]
	v_mfma_f32_16x16x32_bf16 v[126:129], v[148:151], v[164:167], v[126:129]
	v_mfma_f32_16x16x32_bf16 v[122:125], v[156:159], v[164:167], v[122:125]
	v_mfma_f32_16x16x32_bf16 v[118:121], v[148:151], v[172:175], v[118:121]
	v_mfma_f32_16x16x32_bf16 v[114:117], v[156:159], v[172:175], v[114:117]
	v_mfma_f32_16x16x32_bf16 v[110:113], v[148:151], v[194:197], v[110:113]
	v_mfma_f32_16x16x32_bf16 v[106:109], v[156:159], v[194:197], v[106:109]
	v_mfma_f32_16x16x32_bf16 v[102:105], v[148:151], v[202:205], v[102:105]
	v_mfma_f32_16x16x32_bf16 v[98:101], v[156:159], v[202:205], v[98:101]

; #define LDB(dst, b, h) for (int n = 0; n < 2; ++n) for (int k = 0; k < 2; ++k) \
;     dst[n][k] = *reinterpret_cast<const bf16x8*>((char*)SB(b, h) + b_thr + (n * 2 + k) * 1024)
; #define MMA(ai, bj, At, Btf) do { __builtin_amdgcn_s_setprio(1); \
;     for (int m = 0; m < 4; ++m) for (int n = 0; n < 2; ++n) for (int k = 0; k < 2; ++k) \
;       acc[ai][bj][m][n] = __builtin_amdgcn_mfma_f32_16x16x32_bf16(Btf[n][k], At[m][k], acc[ai][bj][m][n], 0, 0, 0); \
;     __builtin_amdgcn_s_setprio(0); } while (0)
; #define WAIT_V(n) asm volatile("s_waitcnt vmcnt(" #n ")" ::: "memory")
; #define WAIT_L(n) asm volatile("s_waitcnt lgkmcnt(" #n ")" ::: "memory")
; #define BAR __builtin_amdgcn_s_barrier()
; template <bool OVL, bool PANEL = false, class Epi>
; __device__ __forceinline__ void gemm_phase(const bf16_t* __restrict__ A, long lda, const bf16_t* __restrict__ Bt, long ldb, int nM, int nN, int K,
;                                            const Epi& epi, bf16_t* shm, int w0) {
;     ...
;       LDB(B1, 1, 1); WAIT_V(0); BAR; WAIT_L(0); MMA(0, 1, At, B1); BAR;
	v_add_u32_e32 v0, 0x1c000, v182
	s_barrier
	ds_read_b128 v[206:209], v0
	ds_read_b128 v[210:213], v0 offset:1024
	ds_read_b128 v[214:217], v0 offset:2048
	ds_read_b128 v[218:221], v0 offset:3072
	s_waitcnt vmcnt(0)
	s_barrier
	s_waitcnt lgkmcnt(0)

; #define LDB(dst, b, h) for (int n = 0; n < 2; ++n) for (int k = 0; k < 2; ++k) \
;     dst[n][k] = *reinterpret_cast<const bf16x8*>((char*)SB(b, h) + b_thr + (n * 2 + k) * 1024)
; #define MMA(ai, bj, At, Btf) do { __builtin_amdgcn_s_setprio(1); \
;     for (int m = 0; m < 4; ++m) for (int n = 0; n < 2; ++n) for (int k = 0; k < 2; ++k) \
;       acc[ai][bj][m][n] = __builtin_amdgcn_mfma_f32_16x16x32_bf16(Btf[n][k], At[m][k], acc[ai][bj][m][n], 0, 0, 0); \
;     __builtin_amdgcn_s_setprio(0); } while (0)
; #define WAIT_V(n) asm volatile("s_waitcnt vmcnt(" #n ")" ::: "memory")
; #define WAIT_L(n) asm volatile("s_waitcnt lgkmcnt(" #n ")" ::: "memory")
; #define BAR __builtin_amdgcn_s_barrier()
; template <bool OVL, bool PANEL = false, class Epi>
; __device__ __forceinline__ void gemm_phase(const bf16_t* __restrict__ A, long lda, const bf16_t* __restrict__ Bt, long ldb, int nM, int nN, int K,
;                                            const Epi& epi, bf16_t* shm, int w0) {
;     ...
;       LDB(B1, 1, 1); WAIT_V(0); BAR; WAIT_L(0); MMA(0, 1, At, B1); BAR;
	s_waitcnt lgkmcnt(0)
	v_mfma_f32_16x16x32_bf16 v[94:97], v[206:209], v[160:163], v[94:97]
	v_mfma_f32_16x16x32_bf16 v[90:93], v[214:217], v[160:163], v[90:93]
	v_mfma_f32_16x16x32_bf16 v[86:89], v[206:209], v[168:171], v[86:89]
	v_mfma_f32_16x16x32_bf16 v[82:85], v[214:217], v[168:171], v[82:85]
	v_mfma_f32_16x16x32_bf16 v[78:81], v[206:209], v[176:179], v[78:81]
	v_mfma_f32_16x16x32_bf16 v[74:77], v[214:217], v[176:179], v[74:77]
	v_mfma_f32_16x16x32_bf16 v[70:73], v[206:209], v[198:201], v[70:73]
	v_mfma_f32_16x16x32_bf16 v[66:69], v[214:217], v[198:201], v[66:69]
	v_mfma_f32_16x16x32_bf16 v[94:97], v[210:213], v[164:167], v[94:97]
	v_mfma_f32_16x16x32_bf16 v[90:93], v[218:221], v[164:167], v[90:93]
	v_mfma_f32_16x16x32_bf16 v[86:89], v[210:213], v[172:175], v[86:89]
	v_mfma_f32_16x16x32_bf16 v[82:85], v[218:221], v[172:175], v[82:85]
	v_mfma_f32_16x16x32_bf16 v[78:81], v[210:213], v[194:197], v[78:81]
	v_mfma_f32_16x16x32_bf16 v[74:77], v[218:221], v[194:197], v[74:77]
	v_mfma_f32_16x16x32_bf16 v[70:73], v[210:213], v[202:205], v[70:73]
	v_mfma_f32_16x16x32_bf16 v[66:69], v[218:221], v[202:205], v[66:69]

; #define LDA(dst, b, h) for (int m = 0; m < 4; ++m) for (int k = 0; k < 2; ++k) \
;     dst[m][k] = *reinterpret_cast<const bf16x8*>((char*)SA(b, h) + a_thr + (m * 2 + k) * 1024)
; #define MMA(ai, bj, At, Btf) do { __builtin_amdgcn_s_setprio(1); \
;     for (int m = 0; m < 4; ++m) for (int n = 0; n < 2; ++n) for (int k = 0; k < 2; ++k) \
;       acc[ai][bj][m][n] = __builtin_amdgcn_mfma_f32_16x16x32_bf16(Btf[n][k], At[m][k], acc[ai][bj][m][n], 0, 0, 0); \
;     __builtin_amdgcn_s_setprio(0); } while (0)
; #define WAIT_L(n) asm volatile("s_waitcnt lgkmcnt(" #n ")" ::: "memory")
; #define BAR __builtin_amdgcn_s_barrier()
; template <bool OVL, bool PANEL = false, class Epi>
; __device__ __forceinline__ void gemm_phase(const bf16_t* __restrict__ A, long lda, const bf16_t* __restrict__ Bt, long ldb, int nM, int nN, int K,
;                                            const Epi& epi, bf16_t* shm, int w0) {
;     ...
;       LDA(At, 1, 1); BAR; WAIT_L(0); MMA(1, 0, At, B0); MMA(1, 1, At, B1); BAR; }
	s_barrier
	ds_read_b128 v[160:163], v147 offset:49152
	ds_read_b128 v[164:167], v147 offset:50176
	ds_read_b128 v[168:171], v147 offset:51200
	ds_read_b128 v[172:175], v147 offset:52224
	ds_read_b128 v[176:179], v147 offset:53248
	ds_read_b128 v[194:197], v147 offset:54272
	ds_read_b128 v[198:201], v147 offset:55296
	ds_read_b128 v[202:205], v147 offset:56320
	s_barrier
	s_waitcnt lgkmcnt(0)

; #define LDA(dst, b, h) for (int m = 0; m < 4; ++m) for (int k = 0; k < 2; ++k) \
;     dst[m][k] = *reinterpret_cast<const bf16x8*>((char*)SA(b, h) + a_thr + (m * 2 + k) * 1024)
; #define LDB(dst, b, h) for (int n = 0; n < 2; ++n) for (int k = 0; k < 2; ++k) \
;     dst[n][k] = *reinterpret_cast<const bf16x8*>((char*)SB(b, h) + b_thr + (n * 2 + k) * 1024)
; #define MMA(ai, bj, At, Btf) do { __builtin_amdgcn_s_setprio(1); \
;     for (int m = 0; m < 4; ++m) for (int n = 0; n < 2; ++n) for (int k = 0; k < 2; ++k) \
;       acc[ai][bj][m][n] = __builtin_amdgcn_mfma_f32_16x16x32_bf16(Btf[n][k], At[m][k], acc[ai][bj][m][n], 0, 0, 0); \
;     __builtin_amdgcn_s_setprio(0); } while (0)
; #define WAIT_V(n) asm volatile("s_waitcnt vmcnt(" #n ")" ::: "memory")
; #define WAIT_L(n) asm volatile("s_waitcnt lgkmcnt(" #n ")" ::: "memory")
; #define BAR __builtin_amdgcn_s_barrier()
; template <bool OVL, bool PANEL = false, class Epi>
; __device__ __forceinline__ void gemm_phase(const bf16_t* __restrict__ A, long lda, const bf16_t* __restrict__ Bt, long ldb, int nM, int nN, int K,
;                                            const Epi& epi, bf16_t* shm, int w0) {
;     ...
;       LDA(At, 0, 1); WAIT_V(4); BAR; WAIT_L(0); MMA(1, 0, At, B0); MMA(1, 1, At, B1); BAR; }
;     { LDB(B0, 1, 0); LDA(At, 1, 0); WAIT_V(2); BAR; WAIT_L(0); MMA(0, 0, At, B0); BAR;
;       LDB(B1, 1, 1); WAIT_V(0); BAR; WAIT_L(0); MMA(0, 1, At, B1); BAR;
;       LDA(At, 1, 1); BAR; WAIT_L(0); MMA(1, 0, At, B0); MMA(1, 1, At, B1); BAR; }
	s_waitcnt lgkmcnt(0)
	v_mfma_f32_16x16x32_bf16 v[62:65], v[130:133], v[160:163], v[62:65]
	v_mfma_f32_16x16x32_bf16 v[58:61], v[152:155], v[160:163], v[58:61]
	v_mfma_f32_16x16x32_bf16 v[54:57], v[130:133], v[168:171], v[54:57]
	v_mfma_f32_16x16x32_bf16 v[50:53], v[152:155], v[168:171], v[50:53]
	v_mfma_f32_16x16x32_bf16 v[46:49], v[130:133], v[176:179], v[46:49]
	v_mfma_f32_16x16x32_bf16 v[42:45], v[152:155], v[176:179], v[42:45]
	v_mfma_f32_16x16x32_bf16 v[38:41], v[130:133], v[198:201], v[38:41]
	v_mfma_f32_16x16x32_bf16 v[34:37], v[152:155], v[198:201], v[34:37]
	v_mfma_f32_16x16x32_bf16 v[62:65], v[148:151], v[164:167], v[62:65]
	v_mfma_f32_16x16x32_bf16 v[58:61], v[156:159], v[164:167], v[58:61]
	v_mfma_f32_16x16x32_bf16 v[54:57], v[148:151], v[172:175], v[54:57]
	v_mfma_f32_16x16x32_bf16 v[50:53], v[156:159], v[172:175], v[50:53]
	v_mfma_f32_16x16x32_bf16 v[46:49], v[148:151], v[194:197], v[46:49]
	v_mfma_f32_16x16x32_bf16 v[42:45], v[156:159], v[194:197], v[42:45]
	v_mfma_f32_16x16x32_bf16 v[38:41], v[148:151], v[202:205], v[38:41]
	v_mfma_f32_16x16x32_bf16 v[34:37], v[156:159], v[202:205], v[34:37]


; #define LDA(dst, b, h) for (int m = 0; m < 4; ++m) for (int k = 0; k < 2; ++k) \
;     dst[m][k] = *reinterpret_cast<const bf16x8*>((char*)SA(b, h) + a_thr + (m * 2 + k) * 1024)
; #define LDB(dst, b, h) for (int n = 0; n < 2; ++n) for (int k = 0; k < 2; ++k) \
;     dst[n][k] = *reinterpret_cast<const bf16x8*>((char*)SB(b, h) + b_thr + (n * 2 + k) * 1024)
; #define MMA(ai, bj, At, Btf) do { __builtin_amdgcn_s_setprio(1); \
;     for (int m = 0; m < 4; ++m) for (int n = 0; n < 2; ++n) for (int k = 0; k < 2; ++k) \
;       acc[ai][bj][m][n] = __builtin_amdgcn_mfma_f32_16x16x32_bf16(Btf[n][k], At[m][k], acc[ai][bj][m][n], 0, 0, 0); \
;     __builtin_amdgcn_s_setprio(0); } while (0)
; #define WAIT_V(n) asm volatile("s_waitcnt vmcnt(" #n ")" ::: "memory")
; #define WAIT_L(n) asm volatile("s_waitcnt lgkmcnt(" #n ")" ::: "memory")
; #define BAR __builtin_amdgcn_s_barrier()
; template <bool OVL, bool PANEL = false, class Epi>
; __device__ __forceinline__ void gemm_phase(const bf16_t* __restrict__ A, long lda, const bf16_t* __restrict__ Bt, long ldb, int nM, int nN, int K,
;                                            const Epi& epi, bf16_t* shm, int w0) {
;     ...
;       LDA(At, 0, 1); WAIT_V(4); BAR; WAIT_L(0); MMA(1, 0, At, B0); MMA(1, 1, At, B1); BAR; }
;     { LDB(B0, 1, 0); LDA(At, 1, 0); WAIT_V(2); BAR; WAIT_L(0); MMA(0, 0, At, B0); BAR;
;       LDB(B1, 1, 1); WAIT_V(0); BAR; WAIT_L(0); MMA(0, 1, At, B1); BAR;
;       LDA(At, 1, 1); BAR; WAIT_L(0); MMA(1, 0, At, B0); MMA(1, 1, At, B1); BAR; }
	v_mfma_f32_16x16x32_bf16 v[30:33], v[206:209], v[160:163], v[30:33]
	v_mfma_f32_16x16x32_bf16 v[26:29], v[214:217], v[160:163], v[26:29]
	v_mfma_f32_16x16x32_bf16 v[22:25], v[206:209], v[168:171], v[22:25]
	v_mfma_f32_16x16x32_bf16 v[18:21], v[214:217], v[168:171], v[18:21]
	v_mfma_f32_16x16x32_bf16 v[14:17], v[206:209], v[176:179], v[14:17]
	v_mfma_f32_16x16x32_bf16 v[10:13], v[214:217], v[176:179], v[10:13]
	v_mfma_f32_16x16x32_bf16 v[6:9], v[206:209], v[198:201], v[6:9]
	v_mfma_f32_16x16x32_bf16 v[2:5], v[214:217], v[198:201], v[2:5]
	v_mfma_f32_16x16x32_bf16 v[30:33], v[210:213], v[164:167], v[30:33]
	v_mfma_f32_16x16x32_bf16 v[26:29], v[218:221], v[164:167], v[26:29]
	v_mfma_f32_16x16x32_bf16 v[22:25], v[210:213], v[172:175], v[22:25]
	v_mfma_f32_16x16x32_bf16 v[18:21], v[218:221], v[172:175], v[18:21]
	v_mfma_f32_16x16x32_bf16 v[14:17], v[210:213], v[194:197], v[14:17]
	v_mfma_f32_16x16x32_bf16 v[10:13], v[218:221], v[194:197], v[10:13]
	v_mfma_f32_16x16x32_bf16 v[6:9], v[210:213], v[202:205], v[6:9]
	v_mfma_f32_16x16x32_bf16 v[2:5], v[218:221], v[202:205], v[2:5]

; #define LDA(dst, b, h) for (int m = 0; m < 4; ++m) for (int k = 0; k < 2; ++k) \
;     dst[m][k] = *reinterpret_cast<const bf16x8*>((char*)SA(b, h) + a_thr + (m * 2 + k) * 1024)
; #define MMA(ai, bj, At, Btf) do { __builtin_amdgcn_s_setprio(1); \
;     for (int m = 0; m < 4; ++m) for (int n = 0; n < 2; ++n) for (int k = 0; k < 2; ++k) \
;       acc[ai][bj][m][n] = __builtin_amdgcn_mfma_f32_16x16x32_bf16(Btf[n][k], At[m][k], acc[ai][bj][m][n], 0, 0, 0); \
;     __builtin_amdgcn_s_setprio(0); } while (0)
; #define WAIT_L(n) asm volatile("s_waitcnt lgkmcnt(" #n ")" ::: "memory")
; #define BAR __builtin_amdgcn_s_barrier()
; template <bool OVL, bool PANEL = false, class Epi>
; __device__ __forceinline__ void gemm_phase(const bf16_t* __restrict__ A, long lda, const bf16_t* __restrict__ Bt, long ldb, int nM, int nN, int K,
;                                            const Epi& epi, bf16_t* shm, int w0) {
;     ...
;       LDA(At, 1, 1); BAR; WAIT_L(0); MMA(1, 0, At, B0); MMA(1, 1, At, B1); BAR; }
;     if (wr == 0) BAR;
	s_barrier
	s_and_saveexec_b64 s[8:9], s[6:7]
	s_cbranch_execz .LBB0_1056
	s_barrier
